# 76 LDS-DMA tile loads in the GEMM K-loops switched to the SGPR-base + 32-bit VGPR-offset form, removing their 64-bit VALU address adds from the load segments
# baseline (speedup 1.0000x reference)
; #define PG8_STAGE(bufoff, gbase, voff) do { _Pragma("unroll") for (int _i = 0; _i < 2; ++_i) \
;         __builtin_amdgcn_global_load_lds((const unsigned*)((const char*)(gbase) + (voff)[_i]), (PG8_LAS unsigned*)(lds + (bufoff) + ldsw + _i * 8192), 16, 0, 0); } while (0)
; #define PG8_LDA(dst, b, h) do { _Pragma("unroll") for (int m = 0; m < 4; ++m) _Pragma("unroll") for (int k = 0; k < 2; ++k) dst[m][k] = *(const PG8_LAS bf16x8*)(lds + PG8_SA(b, h) + aoff + m * 2048 + k * 1024); } while (0)
; #define PG8_LDB(dst, b, h) do { _Pragma("unroll") for (int n = 0; n < 2; ++n) _Pragma("unroll") for (int k = 0; k < 2; ++k) dst[n][k] = *(const PG8_LAS bf16x8*)(lds + PG8_SB(b, h) + boff + n * 2048 + k * 1024); } while (0)
; #define PG8_WAIT_V(n) asm volatile("s_waitcnt vmcnt(" #n ")" ::: "memory")
; #define PG8_WAIT_L(n) asm volatile("s_waitcnt lgkmcnt(" #n ")" ::: "memory")
; #define PG8_BAR __builtin_amdgcn_s_barrier()
; #define PG8_SCHED __builtin_amdgcn_sched_barrier(0)
; template <class Epi, class Sched, bool ALIGN_EPI = false, bool SP2 = false>
; __device__ __forceinline__ void gemm_phase(PG8_LAS unsigned char* lds, const Gemm g, const Sched& S, const Epi& E) {
;     ...
;         const bool has_next = S.next(ui + 1, nxt);
;         const char* nA = has_next ? (const char*)g.A + (size_t)nxt.pm * tstep : cA; const char* nB = has_next ? (const char*)g.Bt + (size_t)nxt.pn * tstep : cB;
;         for (int t = 0; t < nt; t += 2) {
;             const bool last = (t == nt - 2);
;             const char* a1 = cA + (size_t)(t + 1) * kstep;
;             const char* a2 = last ? nA : cA + (size_t)(t + 2) * kstep; const char* b2 = last ? nB : cB + (size_t)(t + 2) * kstep;
;             const char* a3 = a2 + kstep; const char* b3 = b2 + kstep;
;             if (last && has_next) S.a_ready(nxt);
;             if constexpr (SP2) {
;             PG8_LDB(B0, 0, 0); PG8_LDB(B1, 0, 1); PG8_SCHED; PG8_LDA(At, 0, 0); PG8_STAGE(PG8_SA(1, 1), a1 + hstep, voffA);
;             PG8_WAIT_V(8); PG8_WAIT_L(0); PG8_BAR; PG8_MMA(0, 0, At, B0); PG8_MMA(0, 1, At, B1); PG8_BAR; PG8_SCHED;
;             PG8_LDA(At, 0, 1); PG8_STAGE(PG8_SB(0, 0), b2, voffB); PG8_STAGE(PG8_SB(0, 1), b2 + hstep, voffB); PG8_STAGE(PG8_SA(0, 0), a2, voffA);
;             PG8_WAIT_V(8); PG8_WAIT_L(0); PG8_BAR; PG8_MMA(1, 0, At, B0); PG8_MMA(1, 1, At, B1); PG8_BAR; PG8_SCHED;
.LBB0_300:
	s_ashr_i32 s13, s12, 31
	s_lshl_b64 s[16:17], s[12:13], 19
	s_add_u32 s16, s0, s16
	s_addc_u32 s17, s1, s17
	s_and_b64 s[18:19], s[4:5], exec
	s_cselect_b32 s13, s17, s25
	s_cselect_b32 s21, s16, s24
	s_ashr_i32 s11, s10, 31
	s_lshl_b64 s[18:19], s[10:11], 19
	s_add_u32 s18, s33, s18
	s_addc_u32 s19, s34, s19
	s_and_b64 s[28:29], s[4:5], exec
	s_cselect_b32 s11, s19, s27
	s_cselect_b32 s44, s18, s26
	s_add_u32 s24, s24, 0x40080
	s_addc_u32 s25, s25, 0
	s_add_u32 s45, s26, 0x100
	s_addc_u32 s46, s27, 0
	s_mov_b32 s47, -2
	s_add_u32 s26, s24, 0xfffc0080
	s_addc_u32 s27, s25, -1
	s_add_i32 s48, 0, 0x10000
	s_cmp_eq_u32 s47, 12
	s_cselect_b32 s29, s13, s27
	s_cselect_b32 s28, s21, s26
	v_add_u32_e32 v154, s48, v156
	s_cselect_b32 s27, s11, s46
	s_cselect_b32 s26, s44, s45
	s_add_i32 s50, 0, 0x14000
	ds_read_b128 v[94:97], v154
	ds_read_b128 v[134:137], v154 offset:1024
	ds_read_b128 v[158:161], v154 offset:2048
	ds_read_b128 v[162:165], v154 offset:3072
	v_add_u32_e32 v154, s50, v156
	ds_read_b128 v[166:169], v154
	ds_read_b128 v[170:173], v154 offset:1024
	ds_read_b128 v[174:177], v154 offset:2048
	ds_read_b128 v[186:189], v154 offset:3072
	s_add_i32 m0, s23, 0xc000
	ds_read_b128 v[190:193], v157
	ds_read_b128 v[194:197], v157 offset:1024
	ds_read_b128 v[198:201], v157 offset:2048
	ds_read_b128 v[202:205], v157 offset:3072
	ds_read_b128 v[206:209], v157 offset:4096
	ds_read_b128 v[210:213], v157 offset:5120
	ds_read_b128 v[214:217], v157 offset:6144
	ds_read_b128 v[218:221], v157 offset:7168
	global_load_lds_dwordx4 v150, s[24:25]
	s_add_i32 m0, s23, 0xe000
	s_nop 0
	global_load_lds_dwordx4 v152, s[24:25]
	s_waitcnt vmcnt(8) lgkmcnt(0)
	s_barrier
	s_setprio 1
	v_mfma_f32_16x16x32_bf16 v[130:133], v[94:97], v[190:193], 0
	v_mfma_f32_16x16x32_bf16 v[126:129], v[158:161], v[190:193], 0
	v_mfma_f32_16x16x32_bf16 v[114:117], v[94:97], v[198:201], 0
	v_mfma_f32_16x16x32_bf16 v[110:113], v[158:161], v[198:201], 0
	v_mfma_f32_16x16x32_bf16 v[98:101], v[94:97], v[206:209], 0
	v_mfma_f32_16x16x32_bf16 v[90:93], v[158:161], v[206:209], 0
	v_mfma_f32_16x16x32_bf16 v[78:81], v[94:97], v[214:217], 0
	v_mfma_f32_16x16x32_bf16 v[74:77], v[158:161], v[214:217], 0
	v_mfma_f32_16x16x32_bf16 v[130:133], v[134:137], v[194:197], v[130:133]
	v_mfma_f32_16x16x32_bf16 v[126:129], v[162:165], v[194:197], v[126:129]
	v_mfma_f32_16x16x32_bf16 v[114:117], v[134:137], v[202:205], v[114:117]
	v_mfma_f32_16x16x32_bf16 v[110:113], v[162:165], v[202:205], v[110:113]
	v_mfma_f32_16x16x32_bf16 v[98:101], v[134:137], v[210:213], v[98:101]
	v_mfma_f32_16x16x32_bf16 v[90:93], v[162:165], v[210:213], v[90:93]
	v_mfma_f32_16x16x32_bf16 v[78:81], v[134:137], v[218:221], v[78:81]
	v_mfma_f32_16x16x32_bf16 v[74:77], v[162:165], v[218:221], v[74:77]
	v_mfma_f32_16x16x32_bf16 v[122:125], v[166:169], v[190:193], 0
	v_mfma_f32_16x16x32_bf16 v[118:121], v[174:177], v[190:193], 0
	v_mfma_f32_16x16x32_bf16 v[106:109], v[166:169], v[198:201], 0
	v_mfma_f32_16x16x32_bf16 v[102:105], v[174:177], v[198:201], 0
	v_mfma_f32_16x16x32_bf16 v[86:89], v[166:169], v[206:209], 0
	v_mfma_f32_16x16x32_bf16 v[82:85], v[174:177], v[206:209], 0
	v_mfma_f32_16x16x32_bf16 v[70:73], v[166:169], v[214:217], 0
	v_mfma_f32_16x16x32_bf16 v[66:69], v[174:177], v[214:217], 0
	v_mfma_f32_16x16x32_bf16 v[122:125], v[170:173], v[194:197], v[122:125]
	v_mfma_f32_16x16x32_bf16 v[118:121], v[186:189], v[194:197], v[118:121]
	v_mfma_f32_16x16x32_bf16 v[106:109], v[170:173], v[202:205], v[106:109]
	v_mfma_f32_16x16x32_bf16 v[102:105], v[186:189], v[202:205], v[102:105]
	v_mfma_f32_16x16x32_bf16 v[86:89], v[170:173], v[210:213], v[86:89]
	v_mfma_f32_16x16x32_bf16 v[82:85], v[186:189], v[210:213], v[82:85]
	v_mfma_f32_16x16x32_bf16 v[70:73], v[170:173], v[218:221], v[70:73]
	v_mfma_f32_16x16x32_bf16 v[66:69], v[186:189], v[218:221], v[66:69]
	s_setprio 0
	s_barrier
	s_add_i32 s48, s48, s35
	v_lshl_add_u64 v[154:155], s[26:27], 0, v[142:143]
	s_mov_b32 m0, s48
	ds_read_b128 v[190:193], v157 offset:16384
	ds_read_b128 v[194:197], v157 offset:17408
	ds_read_b128 v[198:201], v157 offset:18432
	ds_read_b128 v[202:205], v157 offset:19456
	ds_read_b128 v[206:209], v157 offset:20480
	ds_read_b128 v[210:213], v157 offset:21504
	ds_read_b128 v[214:217], v157 offset:22528
	ds_read_b128 v[218:221], v157 offset:23552
	global_load_lds_dwordx4 v[154:155], off
	s_add_i32 m0, s48, 0x2000
	s_add_u32 s48, s26, 0x40000
	v_lshl_add_u64 v[180:181], s[26:27], 0, v[138:139]
	s_addc_u32 s49, s27, 0
	s_add_i32 s50, s50, s35
	global_load_lds_dwordx4 v[180:181], off
	v_lshl_add_u64 v[182:183], s[48:49], 0, v[142:143]
	s_mov_b32 m0, s50
	v_lshl_add_u64 v[222:223], s[28:29], 0, v[140:141]
	global_load_lds_dwordx4 v[182:183], off
	s_add_i32 m0, s50, 0x2000
	s_nop 0
	global_load_lds_dwordx4 v138, s[48:49]
	v_lshl_add_u64 v[182:183], s[28:29], 0, v[144:145]
	s_mov_b32 m0, s23
	s_nop 0
	global_load_lds_dwordx4 v[182:183], off
	s_mov_b32 m0, s37
	s_nop 0
	global_load_lds_dwordx4 v[222:223], off
	s_waitcnt vmcnt(8) lgkmcnt(0)
	s_barrier
; #define PG8_STAGE(bufoff, gbase, voff) do { _Pragma("unroll") for (int _i = 0; _i < 2; ++_i) \
;         __builtin_amdgcn_global_load_lds((const unsigned*)((const char*)(gbase) + (voff)[_i]), (PG8_LAS unsigned*)(lds + (bufoff) + ldsw + _i * 8192), 16, 0, 0); } while (0)
; #define PG8_LDA(dst, b, h) do { _Pragma("unroll") for (int m = 0; m < 4; ++m) _Pragma("unroll") for (int k = 0; k < 2; ++k) dst[m][k] = *(const PG8_LAS bf16x8*)(lds + PG8_SA(b, h) + aoff + m * 2048 + k * 1024); } while (0)
; #define PG8_LDB(dst, b, h) do { _Pragma("unroll") for (int n = 0; n < 2; ++n) _Pragma("unroll") for (int k = 0; k < 2; ++k) dst[n][k] = *(const PG8_LAS bf16x8*)(lds + PG8_SB(b, h) + boff + n * 2048 + k * 1024); } while (0)
; #define PG8_MMA(ai, bj, At, Bt) do { __builtin_amdgcn_s_setprio(1); _Pragma("unroll") for (int m = 0; m < 4; ++m) _Pragma("unroll") for (int n = 0; n < 2; ++n) _Pragma("unroll") for (int k = 0; k < 2; ++k) \
;         acc[ai][bj][m][n] = __builtin_amdgcn_mfma_f32_16x16x32_bf16(Bt[n][k], At[m][k], acc[ai][bj][m][n], 0, 0, 0); __builtin_amdgcn_s_setprio(0); } while (0)
; #define PG8_WAIT_V(n) asm volatile("s_waitcnt vmcnt(" #n ")" ::: "memory")
; #define PG8_WAIT_L(n) asm volatile("s_waitcnt lgkmcnt(" #n ")" ::: "memory")
; #define PG8_BAR __builtin_amdgcn_s_barrier()
; #define PG8_SCHED __builtin_amdgcn_sched_barrier(0)
; template <class Epi, class Sched, bool ALIGN_EPI = false, bool SP2 = false>
; __device__ __forceinline__ void gemm_phase(PG8_LAS unsigned char* lds, const Gemm g, const Sched& S, const Epi& E) {
;     ...
;             PG8_WAIT_V(8); PG8_WAIT_L(0); PG8_BAR; PG8_MMA(0, 0, At, B0); PG8_MMA(0, 1, At, B1); PG8_BAR; PG8_SCHED;
;             PG8_LDA(At, 0, 1); PG8_STAGE(PG8_SB(0, 0), b2, voffB); PG8_STAGE(PG8_SB(0, 1), b2 + hstep, voffB); PG8_STAGE(PG8_SA(0, 0), a2, voffA);
;             PG8_WAIT_V(8); PG8_WAIT_L(0); PG8_BAR; PG8_MMA(1, 0, At, B0); PG8_MMA(1, 1, At, B1); PG8_BAR; PG8_SCHED;
;             PG8_LDB(B0, 1, 0); PG8_LDB(B1, 1, 1); PG8_SCHED; PG8_LDA(At, 1, 0); PG8_STAGE(PG8_SA(0, 1), a2 + hstep, voffA);
;             PG8_WAIT_V(8); PG8_WAIT_L(0); PG8_BAR; PG8_MMA(0, 0, At, B0); PG8_MMA(0, 1, At, B1); PG8_BAR; PG8_SCHED;
;             PG8_LDA(At, 1, 1); PG8_STAGE(PG8_SB(1, 0), b3, voffB); PG8_STAGE(PG8_SB(1, 1), b3 + hstep, voffB); PG8_STAGE(PG8_SA(1, 0), a3, voffA);
	s_setprio 1
	v_mfma_f32_16x16x32_bf16 v[62:65], v[94:97], v[190:193], 0
	v_mfma_f32_16x16x32_bf16 v[58:61], v[158:161], v[190:193], 0
	v_mfma_f32_16x16x32_bf16 v[50:53], v[94:97], v[198:201], 0
	v_mfma_f32_16x16x32_bf16 v[42:45], v[158:161], v[198:201], 0
	v_mfma_f32_16x16x32_bf16 v[34:37], v[94:97], v[206:209], 0
	v_mfma_f32_16x16x32_bf16 v[26:29], v[158:161], v[206:209], 0
	v_mfma_f32_16x16x32_bf16 v[18:21], v[94:97], v[214:217], 0
	v_mfma_f32_16x16x32_bf16 v[10:13], v[158:161], v[214:217], 0
	v_mfma_f32_16x16x32_bf16 v[62:65], v[134:137], v[194:197], v[62:65]
	v_mfma_f32_16x16x32_bf16 v[58:61], v[162:165], v[194:197], v[58:61]
	v_mfma_f32_16x16x32_bf16 v[50:53], v[134:137], v[202:205], v[50:53]
	v_mfma_f32_16x16x32_bf16 v[42:45], v[162:165], v[202:205], v[42:45]
	v_mfma_f32_16x16x32_bf16 v[34:37], v[134:137], v[210:213], v[34:37]
	v_mfma_f32_16x16x32_bf16 v[26:29], v[162:165], v[210:213], v[26:29]
	v_mfma_f32_16x16x32_bf16 v[18:21], v[134:137], v[218:221], v[18:21]
	v_mfma_f32_16x16x32_bf16 v[10:13], v[162:165], v[218:221], v[10:13]
	v_mfma_f32_16x16x32_bf16 v[54:57], v[166:169], v[190:193], 0
	v_mfma_f32_16x16x32_bf16 v[46:49], v[174:177], v[190:193], 0
	v_mfma_f32_16x16x32_bf16 v[38:41], v[166:169], v[198:201], 0
	v_mfma_f32_16x16x32_bf16 v[30:33], v[174:177], v[198:201], 0
	v_mfma_f32_16x16x32_bf16 v[22:25], v[166:169], v[206:209], 0
	v_mfma_f32_16x16x32_bf16 v[14:17], v[174:177], v[206:209], 0
	v_mfma_f32_16x16x32_bf16 v[6:9], v[166:169], v[214:217], 0
	v_mfma_f32_16x16x32_bf16 v[2:5], v[174:177], v[214:217], 0
	v_mfma_f32_16x16x32_bf16 v[54:57], v[170:173], v[194:197], v[54:57]
	v_mfma_f32_16x16x32_bf16 v[46:49], v[186:189], v[194:197], v[46:49]
	v_mfma_f32_16x16x32_bf16 v[38:41], v[170:173], v[202:205], v[38:41]
	v_mfma_f32_16x16x32_bf16 v[30:33], v[186:189], v[202:205], v[30:33]
	v_mfma_f32_16x16x32_bf16 v[22:25], v[170:173], v[210:213], v[22:25]
	v_mfma_f32_16x16x32_bf16 v[14:17], v[186:189], v[210:213], v[14:17]
	v_mfma_f32_16x16x32_bf16 v[6:9], v[170:173], v[218:221], v[6:9]
	v_mfma_f32_16x16x32_bf16 v[2:5], v[186:189], v[218:221], v[2:5]
	s_setprio 0
	s_barrier
	s_add_i32 s48, 0, 0x18000
	s_add_i32 s49, 0, 0x1c000
	v_add_u32_e32 v162, s48, v156
	v_add_u32_e32 v179, s49, v156
	ds_read_b128 v[94:97], v162
	ds_read_b128 v[134:137], v162 offset:1024
	ds_read_b128 v[158:161], v162 offset:2048
	ds_read_b128 v[162:165], v162 offset:3072
	ds_read_b128 v[166:169], v179
	ds_read_b128 v[170:173], v179 offset:1024
	ds_read_b128 v[174:177], v179 offset:2048
	ds_read_b128 v[186:189], v179 offset:3072
	s_add_u32 s28, s28, 0x40000
	s_addc_u32 s29, s29, 0
	s_mov_b32 m0, s38
	ds_read_b128 v[190:193], v157 offset:32768
	ds_read_b128 v[194:197], v157 offset:33792
	ds_read_b128 v[198:201], v157 offset:34816
	ds_read_b128 v[202:205], v157 offset:35840
	ds_read_b128 v[206:209], v157 offset:36864
	ds_read_b128 v[210:213], v157 offset:37888
	ds_read_b128 v[214:217], v157 offset:38912
	ds_read_b128 v[218:221], v157 offset:39936
	global_load_lds_dwordx4 v144, s[28:29]
	v_lshl_add_u64 v[240:241], s[28:29], 0, v[140:141]
	s_mov_b32 m0, s39
	s_nop 0
	global_load_lds_dwordx4 v[240:241], off
	s_waitcnt vmcnt(8) lgkmcnt(0)
	s_barrier
	s_setprio 1
	v_mfma_f32_16x16x32_bf16 v[130:133], v[94:97], v[190:193], v[130:133]
	v_mfma_f32_16x16x32_bf16 v[126:129], v[158:161], v[190:193], v[126:129]
	v_mfma_f32_16x16x32_bf16 v[114:117], v[94:97], v[198:201], v[114:117]
	v_mfma_f32_16x16x32_bf16 v[110:113], v[158:161], v[198:201], v[110:113]
	v_mfma_f32_16x16x32_bf16 v[98:101], v[94:97], v[206:209], v[98:101]
	v_mfma_f32_16x16x32_bf16 v[90:93], v[158:161], v[206:209], v[90:93]
	v_mfma_f32_16x16x32_bf16 v[78:81], v[94:97], v[214:217], v[78:81]
	v_mfma_f32_16x16x32_bf16 v[74:77], v[158:161], v[214:217], v[74:77]
	v_mfma_f32_16x16x32_bf16 v[130:133], v[134:137], v[194:197], v[130:133]
	v_mfma_f32_16x16x32_bf16 v[126:129], v[162:165], v[194:197], v[126:129]
	v_mfma_f32_16x16x32_bf16 v[114:117], v[134:137], v[202:205], v[114:117]
	v_mfma_f32_16x16x32_bf16 v[110:113], v[162:165], v[202:205], v[110:113]
	v_mfma_f32_16x16x32_bf16 v[98:101], v[134:137], v[210:213], v[98:101]
	v_mfma_f32_16x16x32_bf16 v[90:93], v[162:165], v[210:213], v[90:93]
	v_mfma_f32_16x16x32_bf16 v[78:81], v[134:137], v[218:221], v[78:81]
	v_mfma_f32_16x16x32_bf16 v[74:77], v[162:165], v[218:221], v[74:77]
	v_mfma_f32_16x16x32_bf16 v[122:125], v[166:169], v[190:193], v[122:125]
	v_mfma_f32_16x16x32_bf16 v[118:121], v[174:177], v[190:193], v[118:121]
	v_mfma_f32_16x16x32_bf16 v[106:109], v[166:169], v[198:201], v[106:109]
	v_mfma_f32_16x16x32_bf16 v[102:105], v[174:177], v[198:201], v[102:105]
	v_mfma_f32_16x16x32_bf16 v[86:89], v[166:169], v[206:209], v[86:89]
	v_mfma_f32_16x16x32_bf16 v[82:85], v[174:177], v[206:209], v[82:85]
	v_mfma_f32_16x16x32_bf16 v[70:73], v[166:169], v[214:217], v[70:73]
	v_mfma_f32_16x16x32_bf16 v[66:69], v[174:177], v[214:217], v[66:69]
	v_mfma_f32_16x16x32_bf16 v[122:125], v[170:173], v[194:197], v[122:125]
	v_mfma_f32_16x16x32_bf16 v[118:121], v[186:189], v[194:197], v[118:121]
	v_mfma_f32_16x16x32_bf16 v[106:109], v[170:173], v[202:205], v[106:109]
	v_mfma_f32_16x16x32_bf16 v[102:105], v[186:189], v[202:205], v[102:105]
	v_mfma_f32_16x16x32_bf16 v[86:89], v[170:173], v[210:213], v[86:89]
	v_mfma_f32_16x16x32_bf16 v[82:85], v[186:189], v[210:213], v[82:85]
	v_mfma_f32_16x16x32_bf16 v[70:73], v[170:173], v[218:221], v[70:73]
	v_mfma_f32_16x16x32_bf16 v[66:69], v[186:189], v[218:221], v[66:69]
	s_setprio 0
	s_barrier
; #define PG8_STAGE(bufoff, gbase, voff) do { _Pragma("unroll") for (int _i = 0; _i < 2; ++_i) \
;         __builtin_amdgcn_global_load_lds((const unsigned*)((const char*)(gbase) + (voff)[_i]), (PG8_LAS unsigned*)(lds + (bufoff) + ldsw + _i * 8192), 16, 0, 0); } while (0)
; #define PG8_LDA(dst, b, h) do { _Pragma("unroll") for (int m = 0; m < 4; ++m) _Pragma("unroll") for (int k = 0; k < 2; ++k) dst[m][k] = *(const PG8_LAS bf16x8*)(lds + PG8_SA(b, h) + aoff + m * 2048 + k * 1024); } while (0)
; #define PG8_LDB(dst, b, h) do { _Pragma("unroll") for (int n = 0; n < 2; ++n) _Pragma("unroll") for (int k = 0; k < 2; ++k) dst[n][k] = *(const PG8_LAS bf16x8*)(lds + PG8_SB(b, h) + boff + n * 2048 + k * 1024); } while (0)
; template <class Epi, class Sched, bool ALIGN_EPI = false, bool SP2 = false>
; __device__ __forceinline__ void gemm_phase(PG8_LAS unsigned char* lds, const Gemm g, const Sched& S, const Epi& E) {
;     ...
;         for (int t = 0; t < nt; t += 2) {
;             const bool last = (t == nt - 2);
;             const char* a1 = cA + (size_t)(t + 1) * kstep;
;             const char* a2 = last ? nA : cA + (size_t)(t + 2) * kstep; const char* b2 = last ? nB : cB + (size_t)(t + 2) * kstep;
;             const char* a3 = a2 + kstep; const char* b3 = b2 + kstep;
;             if (last && has_next) S.a_ready(nxt);
;             if constexpr (SP2) {
;             PG8_LDB(B0, 0, 0); PG8_LDB(B1, 0, 1); PG8_SCHED; PG8_LDA(At, 0, 0); PG8_STAGE(PG8_SA(1, 1), a1 + hstep, voffA);
;             PG8_WAIT_V(8); PG8_WAIT_L(0); PG8_BAR; PG8_MMA(0, 0, At, B0); PG8_MMA(0, 1, At, B1); PG8_BAR; PG8_SCHED;
;             PG8_LDA(At, 0, 1); PG8_STAGE(PG8_SB(0, 0), b2, voffB); PG8_STAGE(PG8_SB(0, 1), b2 + hstep, voffB); PG8_STAGE(PG8_SA(0, 0), a2, voffA);
;             PG8_WAIT_V(8); PG8_WAIT_L(0); PG8_BAR; PG8_MMA(1, 0, At, B0); PG8_MMA(1, 1, At, B1); PG8_BAR; PG8_SCHED;
;             PG8_LDB(B0, 1, 0); PG8_LDB(B1, 1, 1); PG8_SCHED; PG8_LDA(At, 1, 0); PG8_STAGE(PG8_SA(0, 1), a2 + hstep, voffA);
;             PG8_WAIT_V(8); PG8_WAIT_L(0); PG8_BAR; PG8_MMA(0, 0, At, B0); PG8_MMA(0, 1, At, B1); PG8_BAR; PG8_SCHED;
;             PG8_LDA(At, 1, 1); PG8_STAGE(PG8_SB(1, 0), b3, voffB); PG8_STAGE(PG8_SB(1, 1), b3 + hstep, voffB); PG8_STAGE(PG8_SA(1, 0), a3, voffA);
;             PG8_WAIT_V(8); PG8_WAIT_L(0); PG8_BAR; PG8_MMA(1, 0, At, B0); PG8_MMA(1, 1, At, B1); PG8_BAR; PG8_SCHED;
	s_add_i32 s28, s48, s35
	v_lshl_add_u64 v[154:155], v[154:155], 0, s[80:81]
	s_mov_b32 m0, s28
	ds_read_b128 v[190:193], v157 offset:49152
	ds_read_b128 v[194:197], v157 offset:50176
	ds_read_b128 v[198:201], v157 offset:51200
	ds_read_b128 v[202:205], v157 offset:52224
	ds_read_b128 v[206:209], v157 offset:53248
	ds_read_b128 v[210:213], v157 offset:54272
	ds_read_b128 v[214:217], v157 offset:55296
	ds_read_b128 v[218:221], v157 offset:56320
	global_load_lds_dwordx4 v[154:155], off
	s_add_i32 m0, s28, 0x2000
	s_add_u32 s26, s26, 0x40080
	v_lshl_add_u64 v[154:155], v[180:181], 0, s[80:81]
	s_addc_u32 s27, s27, 0
	s_add_i32 s28, s49, s35
	global_load_lds_dwordx4 v[154:155], off
	s_mov_b32 m0, s28
	s_nop 0
	global_load_lds_dwordx4 v142, s[26:27]
	s_add_i32 m0, s28, 0x2000
	s_nop 0
	global_load_lds_dwordx4 v138, s[26:27]
	v_lshl_add_u64 v[154:155], v[182:183], 0, s[80:81]
	s_mov_b32 m0, s40
	s_nop 0
	global_load_lds_dwordx4 v[154:155], off
	v_lshl_add_u64 v[154:155], v[222:223], 0, s[80:81]
	s_mov_b32 m0, s41
	s_nop 0
	global_load_lds_dwordx4 v[154:155], off
	s_waitcnt vmcnt(8) lgkmcnt(0)
	s_barrier
	s_setprio 1
	v_mfma_f32_16x16x32_bf16 v[62:65], v[94:97], v[190:193], v[62:65]
	v_mfma_f32_16x16x32_bf16 v[58:61], v[158:161], v[190:193], v[58:61]
	v_mfma_f32_16x16x32_bf16 v[50:53], v[94:97], v[198:201], v[50:53]
	v_mfma_f32_16x16x32_bf16 v[42:45], v[158:161], v[198:201], v[42:45]
	v_mfma_f32_16x16x32_bf16 v[34:37], v[94:97], v[206:209], v[34:37]
	v_mfma_f32_16x16x32_bf16 v[26:29], v[158:161], v[206:209], v[26:29]
	v_mfma_f32_16x16x32_bf16 v[18:21], v[94:97], v[214:217], v[18:21]
	v_mfma_f32_16x16x32_bf16 v[10:13], v[158:161], v[214:217], v[10:13]
	v_mfma_f32_16x16x32_bf16 v[62:65], v[134:137], v[194:197], v[62:65]
	v_mfma_f32_16x16x32_bf16 v[58:61], v[162:165], v[194:197], v[58:61]
	v_mfma_f32_16x16x32_bf16 v[50:53], v[134:137], v[202:205], v[50:53]
	v_mfma_f32_16x16x32_bf16 v[42:45], v[162:165], v[202:205], v[42:45]
	v_mfma_f32_16x16x32_bf16 v[34:37], v[134:137], v[210:213], v[34:37]
	v_mfma_f32_16x16x32_bf16 v[26:29], v[162:165], v[210:213], v[26:29]
	v_mfma_f32_16x16x32_bf16 v[18:21], v[134:137], v[218:221], v[18:21]
	v_mfma_f32_16x16x32_bf16 v[10:13], v[162:165], v[218:221], v[10:13]
	v_mfma_f32_16x16x32_bf16 v[54:57], v[166:169], v[190:193], v[54:57]
	v_mfma_f32_16x16x32_bf16 v[46:49], v[174:177], v[190:193], v[46:49]
	v_mfma_f32_16x16x32_bf16 v[38:41], v[166:169], v[198:201], v[38:41]
	v_mfma_f32_16x16x32_bf16 v[30:33], v[174:177], v[198:201], v[30:33]
	v_mfma_f32_16x16x32_bf16 v[22:25], v[166:169], v[206:209], v[22:25]
	v_mfma_f32_16x16x32_bf16 v[14:17], v[174:177], v[206:209], v[14:17]
	v_mfma_f32_16x16x32_bf16 v[6:9], v[166:169], v[214:217], v[6:9]
	v_mfma_f32_16x16x32_bf16 v[2:5], v[174:177], v[214:217], v[2:5]
	v_mfma_f32_16x16x32_bf16 v[54:57], v[170:173], v[194:197], v[54:57]
	v_mfma_f32_16x16x32_bf16 v[46:49], v[186:189], v[194:197], v[46:49]
	v_mfma_f32_16x16x32_bf16 v[38:41], v[170:173], v[202:205], v[38:41]
	v_mfma_f32_16x16x32_bf16 v[30:33], v[186:189], v[202:205], v[30:33]
	v_mfma_f32_16x16x32_bf16 v[22:25], v[170:173], v[210:213], v[22:25]
	v_mfma_f32_16x16x32_bf16 v[14:17], v[186:189], v[210:213], v[14:17]
	v_mfma_f32_16x16x32_bf16 v[6:9], v[170:173], v[218:221], v[6:9]
	v_mfma_f32_16x16x32_bf16 v[2:5], v[186:189], v[218:221], v[2:5]
	s_setprio 0
	s_barrier
	s_add_i32 s47, s47, 2
	s_add_u32 s24, s24, 0x100
	s_addc_u32 s25, s25, 0
	s_add_u32 s45, s45, 0x100
	s_addc_u32 s46, s46, 0
	s_cmp_gt_u32 s47, 13
	s_branch .LBB0_301
.LBB0_301:
	s_add_u32 s26, s24, 0xfffc0080
	s_addc_u32 s27, s25, -1
	s_add_i32 s48, 0, 0x10000
	s_cmp_eq_u32 s47, 12
	s_cselect_b32 s29, s13, s27
	s_cselect_b32 s28, s21, s26
	v_add_u32_e32 v154, s48, v156
	s_cselect_b32 s27, s11, s46
	s_cselect_b32 s26, s44, s45
	s_add_i32 s50, 0, 0x14000
	ds_read_b128 v[94:97], v154
	ds_read_b128 v[134:137], v154 offset:1024
	ds_read_b128 v[158:161], v154 offset:2048
	ds_read_b128 v[162:165], v154 offset:3072
	v_add_u32_e32 v154, s50, v156
	ds_read_b128 v[166:169], v154
	ds_read_b128 v[170:173], v154 offset:1024
	ds_read_b128 v[174:177], v154 offset:2048
	ds_read_b128 v[186:189], v154 offset:3072
	s_add_i32 m0, s23, 0xc000
	ds_read_b128 v[190:193], v157
	ds_read_b128 v[194:197], v157 offset:1024
	ds_read_b128 v[198:201], v157 offset:2048
	ds_read_b128 v[202:205], v157 offset:3072
	ds_read_b128 v[206:209], v157 offset:4096
	ds_read_b128 v[210:213], v157 offset:5120
	ds_read_b128 v[214:217], v157 offset:6144
	ds_read_b128 v[218:221], v157 offset:7168
	global_load_lds_dwordx4 v150, s[24:25]
	s_add_i32 m0, s23, 0xe000
	s_nop 0
	global_load_lds_dwordx4 v152, s[24:25]
	s_waitcnt vmcnt(8) lgkmcnt(0)
	s_barrier
; #define PG8_STAGE(bufoff, gbase, voff) do { _Pragma("unroll") for (int _i = 0; _i < 2; ++_i) \
;         __builtin_amdgcn_global_load_lds((const unsigned*)((const char*)(gbase) + (voff)[_i]), (PG8_LAS unsigned*)(lds + (bufoff) + ldsw + _i * 8192), 16, 0, 0); } while (0)
; #define PG8_LDA(dst, b, h) do { _Pragma("unroll") for (int m = 0; m < 4; ++m) _Pragma("unroll") for (int k = 0; k < 2; ++k) dst[m][k] = *(const PG8_LAS bf16x8*)(lds + PG8_SA(b, h) + aoff + m * 2048 + k * 1024); } while (0)
; #define PG8_LDB(dst, b, h) do { _Pragma("unroll") for (int n = 0; n < 2; ++n) _Pragma("unroll") for (int k = 0; k < 2; ++k) dst[n][k] = *(const PG8_LAS bf16x8*)(lds + PG8_SB(b, h) + boff + n * 2048 + k * 1024); } while (0)
; #define PG8_MMA(ai, bj, At, Bt) do { __builtin_amdgcn_s_setprio(1); _Pragma("unroll") for (int m = 0; m < 4; ++m) _Pragma("unroll") for (int n = 0; n < 2; ++n) _Pragma("unroll") for (int k = 0; k < 2; ++k) \
;         acc[ai][bj][m][n] = __builtin_amdgcn_mfma_f32_16x16x32_bf16(Bt[n][k], At[m][k], acc[ai][bj][m][n], 0, 0, 0); __builtin_amdgcn_s_setprio(0); } while (0)
; #define PG8_WAIT_V(n) asm volatile("s_waitcnt vmcnt(" #n ")" ::: "memory")
; #define PG8_WAIT_L(n) asm volatile("s_waitcnt lgkmcnt(" #n ")" ::: "memory")
; #define PG8_BAR __builtin_amdgcn_s_barrier()
; #define PG8_SCHED __builtin_amdgcn_sched_barrier(0)
; template <class Epi, class Sched, bool ALIGN_EPI = false, bool SP2 = false>
; __device__ __forceinline__ void gemm_phase(PG8_LAS unsigned char* lds, const Gemm g, const Sched& S, const Epi& E) {
;     ...
;             PG8_LDB(B0, 0, 0); PG8_LDB(B1, 0, 1); PG8_SCHED; PG8_LDA(At, 0, 0); PG8_STAGE(PG8_SA(1, 1), a1 + hstep, voffA);
;             PG8_WAIT_V(8); PG8_WAIT_L(0); PG8_BAR; PG8_MMA(0, 0, At, B0); PG8_MMA(0, 1, At, B1); PG8_BAR; PG8_SCHED;
;             PG8_LDA(At, 0, 1); PG8_STAGE(PG8_SB(0, 0), b2, voffB); PG8_STAGE(PG8_SB(0, 1), b2 + hstep, voffB); PG8_STAGE(PG8_SA(0, 0), a2, voffA);
;             PG8_WAIT_V(8); PG8_WAIT_L(0); PG8_BAR; PG8_MMA(1, 0, At, B0); PG8_MMA(1, 1, At, B1); PG8_BAR; PG8_SCHED;
	s_setprio 1
	v_mfma_f32_16x16x32_bf16 v[130:133], v[94:97], v[190:193], v[130:133]
	v_mfma_f32_16x16x32_bf16 v[126:129], v[158:161], v[190:193], v[126:129]
	v_mfma_f32_16x16x32_bf16 v[114:117], v[94:97], v[198:201], v[114:117]
	v_mfma_f32_16x16x32_bf16 v[110:113], v[158:161], v[198:201], v[110:113]
	v_mfma_f32_16x16x32_bf16 v[98:101], v[94:97], v[206:209], v[98:101]
	v_mfma_f32_16x16x32_bf16 v[90:93], v[158:161], v[206:209], v[90:93]
	v_mfma_f32_16x16x32_bf16 v[78:81], v[94:97], v[214:217], v[78:81]
	v_mfma_f32_16x16x32_bf16 v[74:77], v[158:161], v[214:217], v[74:77]
	v_mfma_f32_16x16x32_bf16 v[130:133], v[134:137], v[194:197], v[130:133]
	v_mfma_f32_16x16x32_bf16 v[126:129], v[162:165], v[194:197], v[126:129]
	v_mfma_f32_16x16x32_bf16 v[114:117], v[134:137], v[202:205], v[114:117]
	v_mfma_f32_16x16x32_bf16 v[110:113], v[162:165], v[202:205], v[110:113]
	v_mfma_f32_16x16x32_bf16 v[98:101], v[134:137], v[210:213], v[98:101]
	v_mfma_f32_16x16x32_bf16 v[90:93], v[162:165], v[210:213], v[90:93]
	v_mfma_f32_16x16x32_bf16 v[78:81], v[134:137], v[218:221], v[78:81]
	v_mfma_f32_16x16x32_bf16 v[74:77], v[162:165], v[218:221], v[74:77]
	v_mfma_f32_16x16x32_bf16 v[122:125], v[166:169], v[190:193], v[122:125]
	v_mfma_f32_16x16x32_bf16 v[118:121], v[174:177], v[190:193], v[118:121]
	v_mfma_f32_16x16x32_bf16 v[106:109], v[166:169], v[198:201], v[106:109]
	v_mfma_f32_16x16x32_bf16 v[102:105], v[174:177], v[198:201], v[102:105]
	v_mfma_f32_16x16x32_bf16 v[86:89], v[166:169], v[206:209], v[86:89]
	v_mfma_f32_16x16x32_bf16 v[82:85], v[174:177], v[206:209], v[82:85]
	v_mfma_f32_16x16x32_bf16 v[70:73], v[166:169], v[214:217], v[70:73]
	v_mfma_f32_16x16x32_bf16 v[66:69], v[174:177], v[214:217], v[66:69]
	v_mfma_f32_16x16x32_bf16 v[122:125], v[170:173], v[194:197], v[122:125]
	v_mfma_f32_16x16x32_bf16 v[118:121], v[186:189], v[194:197], v[118:121]
	v_mfma_f32_16x16x32_bf16 v[106:109], v[170:173], v[202:205], v[106:109]
	v_mfma_f32_16x16x32_bf16 v[102:105], v[186:189], v[202:205], v[102:105]
	v_mfma_f32_16x16x32_bf16 v[86:89], v[170:173], v[210:213], v[86:89]
	v_mfma_f32_16x16x32_bf16 v[82:85], v[186:189], v[210:213], v[82:85]
	v_mfma_f32_16x16x32_bf16 v[70:73], v[170:173], v[218:221], v[70:73]
	v_mfma_f32_16x16x32_bf16 v[66:69], v[186:189], v[218:221], v[66:69]
	s_setprio 0
	s_barrier
	s_add_i32 s48, s48, s35
	v_lshl_add_u64 v[154:155], s[26:27], 0, v[142:143]
	s_mov_b32 m0, s48
	ds_read_b128 v[190:193], v157 offset:16384
	ds_read_b128 v[194:197], v157 offset:17408
	ds_read_b128 v[198:201], v157 offset:18432
	ds_read_b128 v[202:205], v157 offset:19456
	ds_read_b128 v[206:209], v157 offset:20480
	ds_read_b128 v[210:213], v157 offset:21504
	ds_read_b128 v[214:217], v157 offset:22528
	ds_read_b128 v[218:221], v157 offset:23552
	global_load_lds_dwordx4 v[154:155], off
	s_add_i32 m0, s48, 0x2000
	s_add_u32 s48, s26, 0x40000
	v_lshl_add_u64 v[180:181], s[26:27], 0, v[138:139]
	s_addc_u32 s49, s27, 0
	s_add_i32 s50, s50, s35
	global_load_lds_dwordx4 v[180:181], off
	v_lshl_add_u64 v[182:183], s[48:49], 0, v[142:143]
	s_mov_b32 m0, s50
	v_lshl_add_u64 v[222:223], s[28:29], 0, v[140:141]
	global_load_lds_dwordx4 v[182:183], off
	s_add_i32 m0, s50, 0x2000
	s_nop 0
	global_load_lds_dwordx4 v138, s[48:49]
	v_lshl_add_u64 v[182:183], s[28:29], 0, v[144:145]
	s_mov_b32 m0, s23
	s_nop 0
	global_load_lds_dwordx4 v[182:183], off
	s_mov_b32 m0, s37
	s_nop 0
	global_load_lds_dwordx4 v[222:223], off
	s_waitcnt vmcnt(8) lgkmcnt(0)
	s_barrier
	s_setprio 1
	v_mfma_f32_16x16x32_bf16 v[62:65], v[94:97], v[190:193], v[62:65]
	v_mfma_f32_16x16x32_bf16 v[58:61], v[158:161], v[190:193], v[58:61]
	v_mfma_f32_16x16x32_bf16 v[50:53], v[94:97], v[198:201], v[50:53]
	v_mfma_f32_16x16x32_bf16 v[42:45], v[158:161], v[198:201], v[42:45]
	v_mfma_f32_16x16x32_bf16 v[34:37], v[94:97], v[206:209], v[34:37]
	v_mfma_f32_16x16x32_bf16 v[26:29], v[158:161], v[206:209], v[26:29]
	v_mfma_f32_16x16x32_bf16 v[18:21], v[94:97], v[214:217], v[18:21]
	v_mfma_f32_16x16x32_bf16 v[10:13], v[158:161], v[214:217], v[10:13]
	v_mfma_f32_16x16x32_bf16 v[62:65], v[134:137], v[194:197], v[62:65]
	v_mfma_f32_16x16x32_bf16 v[58:61], v[162:165], v[194:197], v[58:61]
	v_mfma_f32_16x16x32_bf16 v[50:53], v[134:137], v[202:205], v[50:53]
	v_mfma_f32_16x16x32_bf16 v[42:45], v[162:165], v[202:205], v[42:45]
	v_mfma_f32_16x16x32_bf16 v[34:37], v[134:137], v[210:213], v[34:37]
	v_mfma_f32_16x16x32_bf16 v[26:29], v[162:165], v[210:213], v[26:29]
	v_mfma_f32_16x16x32_bf16 v[18:21], v[134:137], v[218:221], v[18:21]
	v_mfma_f32_16x16x32_bf16 v[10:13], v[162:165], v[218:221], v[10:13]
	v_mfma_f32_16x16x32_bf16 v[54:57], v[166:169], v[190:193], v[54:57]
	v_mfma_f32_16x16x32_bf16 v[46:49], v[174:177], v[190:193], v[46:49]
	v_mfma_f32_16x16x32_bf16 v[38:41], v[166:169], v[198:201], v[38:41]
	v_mfma_f32_16x16x32_bf16 v[30:33], v[174:177], v[198:201], v[30:33]
	v_mfma_f32_16x16x32_bf16 v[22:25], v[166:169], v[206:209], v[22:25]
	v_mfma_f32_16x16x32_bf16 v[14:17], v[174:177], v[206:209], v[14:17]
	v_mfma_f32_16x16x32_bf16 v[6:9], v[166:169], v[214:217], v[6:9]
	v_mfma_f32_16x16x32_bf16 v[2:5], v[174:177], v[214:217], v[2:5]
	v_mfma_f32_16x16x32_bf16 v[54:57], v[170:173], v[194:197], v[54:57]
	v_mfma_f32_16x16x32_bf16 v[46:49], v[186:189], v[194:197], v[46:49]
	v_mfma_f32_16x16x32_bf16 v[38:41], v[170:173], v[202:205], v[38:41]
	v_mfma_f32_16x16x32_bf16 v[30:33], v[186:189], v[202:205], v[30:33]
	v_mfma_f32_16x16x32_bf16 v[22:25], v[170:173], v[210:213], v[22:25]
	v_mfma_f32_16x16x32_bf16 v[14:17], v[186:189], v[210:213], v[14:17]
	v_mfma_f32_16x16x32_bf16 v[6:9], v[170:173], v[218:221], v[6:9]
	v_mfma_f32_16x16x32_bf16 v[2:5], v[186:189], v[218:221], v[2:5]
	s_setprio 0
	s_barrier
; #define PG8_STAGE(bufoff, gbase, voff) do { _Pragma("unroll") for (int _i = 0; _i < 2; ++_i) \
;         __builtin_amdgcn_global_load_lds((const unsigned*)((const char*)(gbase) + (voff)[_i]), (PG8_LAS unsigned*)(lds + (bufoff) + ldsw + _i * 8192), 16, 0, 0); } while (0)
; #define PG8_LDA(dst, b, h) do { _Pragma("unroll") for (int m = 0; m < 4; ++m) _Pragma("unroll") for (int k = 0; k < 2; ++k) dst[m][k] = *(const PG8_LAS bf16x8*)(lds + PG8_SA(b, h) + aoff + m * 2048 + k * 1024); } while (0)
; #define PG8_LDB(dst, b, h) do { _Pragma("unroll") for (int n = 0; n < 2; ++n) _Pragma("unroll") for (int k = 0; k < 2; ++k) dst[n][k] = *(const PG8_LAS bf16x8*)(lds + PG8_SB(b, h) + boff + n * 2048 + k * 1024); } while (0)
; #define PG8_MMA(ai, bj, At, Bt) do { __builtin_amdgcn_s_setprio(1); _Pragma("unroll") for (int m = 0; m < 4; ++m) _Pragma("unroll") for (int n = 0; n < 2; ++n) _Pragma("unroll") for (int k = 0; k < 2; ++k) \
;         acc[ai][bj][m][n] = __builtin_amdgcn_mfma_f32_16x16x32_bf16(Bt[n][k], At[m][k], acc[ai][bj][m][n], 0, 0, 0); __builtin_amdgcn_s_setprio(0); } while (0)
; #define PG8_WAIT_V(n) asm volatile("s_waitcnt vmcnt(" #n ")" ::: "memory")
; #define PG8_WAIT_L(n) asm volatile("s_waitcnt lgkmcnt(" #n ")" ::: "memory")
; #define PG8_BAR __builtin_amdgcn_s_barrier()
; #define PG8_SCHED __builtin_amdgcn_sched_barrier(0)
; template <class Epi, class Sched, bool ALIGN_EPI = false, bool SP2 = false>
; __device__ __forceinline__ void gemm_phase(PG8_LAS unsigned char* lds, const Gemm g, const Sched& S, const Epi& E) {
;     ...
;             PG8_LDB(B0, 1, 0); PG8_LDB(B1, 1, 1); PG8_SCHED; PG8_LDA(At, 1, 0); PG8_STAGE(PG8_SA(0, 1), a2 + hstep, voffA);
;             PG8_WAIT_V(8); PG8_WAIT_L(0); PG8_BAR; PG8_MMA(0, 0, At, B0); PG8_MMA(0, 1, At, B1); PG8_BAR; PG8_SCHED;
;             PG8_LDA(At, 1, 1); PG8_STAGE(PG8_SB(1, 0), b3, voffB); PG8_STAGE(PG8_SB(1, 1), b3 + hstep, voffB); PG8_STAGE(PG8_SA(1, 0), a3, voffA);
;             PG8_WAIT_V(8); PG8_WAIT_L(0); PG8_BAR; PG8_MMA(1, 0, At, B0); PG8_MMA(1, 1, At, B1); PG8_BAR; PG8_SCHED;
;     ...
;         if constexpr (ALIGN_EPI) { if (wr == 0) PG8_BAR; }
	s_add_i32 s48, 0, 0x18000
	s_add_i32 s49, 0, 0x1c000
	v_add_u32_e32 v162, s48, v156
	v_add_u32_e32 v179, s49, v156
	ds_read_b128 v[94:97], v162
	ds_read_b128 v[134:137], v162 offset:1024
	ds_read_b128 v[158:161], v162 offset:2048
	ds_read_b128 v[162:165], v162 offset:3072
	ds_read_b128 v[166:169], v179
	ds_read_b128 v[170:173], v179 offset:1024
	ds_read_b128 v[174:177], v179 offset:2048
	ds_read_b128 v[186:189], v179 offset:3072
	s_add_u32 s28, s28, 0x40000
	s_addc_u32 s29, s29, 0
	s_mov_b32 m0, s38
	ds_read_b128 v[190:193], v157 offset:32768
	ds_read_b128 v[194:197], v157 offset:33792
	ds_read_b128 v[198:201], v157 offset:34816
	ds_read_b128 v[202:205], v157 offset:35840
	ds_read_b128 v[206:209], v157 offset:36864
	ds_read_b128 v[210:213], v157 offset:37888
	ds_read_b128 v[214:217], v157 offset:38912
	ds_read_b128 v[218:221], v157 offset:39936
	global_load_lds_dwordx4 v144, s[28:29]
	v_lshl_add_u64 v[240:241], s[28:29], 0, v[140:141]
	s_mov_b32 m0, s39
	s_nop 0
	global_load_lds_dwordx4 v[240:241], off
	s_waitcnt vmcnt(8) lgkmcnt(0)
	s_barrier
	s_setprio 1
	v_mfma_f32_16x16x32_bf16 v[130:133], v[94:97], v[190:193], v[130:133]
	v_mfma_f32_16x16x32_bf16 v[126:129], v[158:161], v[190:193], v[126:129]
	v_mfma_f32_16x16x32_bf16 v[114:117], v[94:97], v[198:201], v[114:117]
	v_mfma_f32_16x16x32_bf16 v[110:113], v[158:161], v[198:201], v[110:113]
	v_mfma_f32_16x16x32_bf16 v[98:101], v[94:97], v[206:209], v[98:101]
	v_mfma_f32_16x16x32_bf16 v[90:93], v[158:161], v[206:209], v[90:93]
	v_mfma_f32_16x16x32_bf16 v[78:81], v[94:97], v[214:217], v[78:81]
	v_mfma_f32_16x16x32_bf16 v[74:77], v[158:161], v[214:217], v[74:77]
	v_mfma_f32_16x16x32_bf16 v[130:133], v[134:137], v[194:197], v[130:133]
	v_mfma_f32_16x16x32_bf16 v[126:129], v[162:165], v[194:197], v[126:129]
	v_mfma_f32_16x16x32_bf16 v[114:117], v[134:137], v[202:205], v[114:117]
	v_mfma_f32_16x16x32_bf16 v[110:113], v[162:165], v[202:205], v[110:113]
	v_mfma_f32_16x16x32_bf16 v[98:101], v[134:137], v[210:213], v[98:101]
	v_mfma_f32_16x16x32_bf16 v[90:93], v[162:165], v[210:213], v[90:93]
	v_mfma_f32_16x16x32_bf16 v[78:81], v[134:137], v[218:221], v[78:81]
	v_mfma_f32_16x16x32_bf16 v[74:77], v[162:165], v[218:221], v[74:77]
	v_mfma_f32_16x16x32_bf16 v[122:125], v[166:169], v[190:193], v[122:125]
	v_mfma_f32_16x16x32_bf16 v[118:121], v[174:177], v[190:193], v[118:121]
	v_mfma_f32_16x16x32_bf16 v[106:109], v[166:169], v[198:201], v[106:109]
	v_mfma_f32_16x16x32_bf16 v[102:105], v[174:177], v[198:201], v[102:105]
	v_mfma_f32_16x16x32_bf16 v[86:89], v[166:169], v[206:209], v[86:89]
	v_mfma_f32_16x16x32_bf16 v[82:85], v[174:177], v[206:209], v[82:85]
	v_mfma_f32_16x16x32_bf16 v[70:73], v[166:169], v[214:217], v[70:73]
	v_mfma_f32_16x16x32_bf16 v[66:69], v[174:177], v[214:217], v[66:69]
	v_mfma_f32_16x16x32_bf16 v[122:125], v[170:173], v[194:197], v[122:125]
	v_mfma_f32_16x16x32_bf16 v[118:121], v[186:189], v[194:197], v[118:121]
	v_mfma_f32_16x16x32_bf16 v[106:109], v[170:173], v[202:205], v[106:109]
	v_mfma_f32_16x16x32_bf16 v[102:105], v[186:189], v[202:205], v[102:105]
	v_mfma_f32_16x16x32_bf16 v[86:89], v[170:173], v[210:213], v[86:89]
	v_mfma_f32_16x16x32_bf16 v[82:85], v[186:189], v[210:213], v[82:85]
	v_mfma_f32_16x16x32_bf16 v[70:73], v[170:173], v[218:221], v[70:73]
	v_mfma_f32_16x16x32_bf16 v[66:69], v[186:189], v[218:221], v[66:69]
	s_setprio 0
	s_barrier
	s_add_i32 s28, s48, s35
	v_lshl_add_u64 v[154:155], v[154:155], 0, s[80:81]
	s_mov_b32 m0, s28
	ds_read_b128 v[190:193], v157 offset:49152
	ds_read_b128 v[194:197], v157 offset:50176
	ds_read_b128 v[198:201], v157 offset:51200
	ds_read_b128 v[202:205], v157 offset:52224
	ds_read_b128 v[206:209], v157 offset:53248
	ds_read_b128 v[210:213], v157 offset:54272
	ds_read_b128 v[214:217], v157 offset:55296
	ds_read_b128 v[218:221], v157 offset:56320
	global_load_lds_dwordx4 v[154:155], off
	s_add_i32 m0, s28, 0x2000
	s_add_u32 s26, s26, 0x40080
	v_lshl_add_u64 v[154:155], v[180:181], 0, s[80:81]
	s_addc_u32 s27, s27, 0
	s_add_i32 s28, s49, s35
	global_load_lds_dwordx4 v[154:155], off
	s_mov_b32 m0, s28
	s_nop 0
	global_load_lds_dwordx4 v142, s[26:27]
	s_add_i32 m0, s28, 0x2000
	s_nop 0
	global_load_lds_dwordx4 v138, s[26:27]
	v_lshl_add_u64 v[154:155], v[182:183], 0, s[80:81]
	s_mov_b32 m0, s40
	s_nop 0
	global_load_lds_dwordx4 v[154:155], off
	v_lshl_add_u64 v[154:155], v[222:223], 0, s[80:81]
	s_mov_b32 m0, s41
	s_nop 0
	global_load_lds_dwordx4 v[154:155], off
	s_waitcnt vmcnt(8) lgkmcnt(0)
	s_barrier
	s_setprio 1
	v_mfma_f32_16x16x32_bf16 v[62:65], v[94:97], v[190:193], v[62:65]
	v_mfma_f32_16x16x32_bf16 v[58:61], v[158:161], v[190:193], v[58:61]
	v_mfma_f32_16x16x32_bf16 v[50:53], v[94:97], v[198:201], v[50:53]
	v_mfma_f32_16x16x32_bf16 v[42:45], v[158:161], v[198:201], v[42:45]
	v_mfma_f32_16x16x32_bf16 v[34:37], v[94:97], v[206:209], v[34:37]
	v_mfma_f32_16x16x32_bf16 v[26:29], v[158:161], v[206:209], v[26:29]
	v_mfma_f32_16x16x32_bf16 v[18:21], v[94:97], v[214:217], v[18:21]
	v_mfma_f32_16x16x32_bf16 v[10:13], v[158:161], v[214:217], v[10:13]
	v_mfma_f32_16x16x32_bf16 v[62:65], v[134:137], v[194:197], v[62:65]
	v_mfma_f32_16x16x32_bf16 v[58:61], v[162:165], v[194:197], v[58:61]
	v_mfma_f32_16x16x32_bf16 v[50:53], v[134:137], v[202:205], v[50:53]
	v_mfma_f32_16x16x32_bf16 v[42:45], v[162:165], v[202:205], v[42:45]
	v_mfma_f32_16x16x32_bf16 v[34:37], v[134:137], v[210:213], v[34:37]
	v_mfma_f32_16x16x32_bf16 v[26:29], v[162:165], v[210:213], v[26:29]
	v_mfma_f32_16x16x32_bf16 v[18:21], v[134:137], v[218:221], v[18:21]
	v_mfma_f32_16x16x32_bf16 v[10:13], v[162:165], v[218:221], v[10:13]
	v_mfma_f32_16x16x32_bf16 v[54:57], v[166:169], v[190:193], v[54:57]
	v_mfma_f32_16x16x32_bf16 v[46:49], v[174:177], v[190:193], v[46:49]
	v_mfma_f32_16x16x32_bf16 v[38:41], v[166:169], v[198:201], v[38:41]
	v_mfma_f32_16x16x32_bf16 v[30:33], v[174:177], v[198:201], v[30:33]
	v_mfma_f32_16x16x32_bf16 v[22:25], v[166:169], v[206:209], v[22:25]
	v_mfma_f32_16x16x32_bf16 v[14:17], v[174:177], v[206:209], v[14:17]
	v_mfma_f32_16x16x32_bf16 v[6:9], v[166:169], v[214:217], v[6:9]
	v_mfma_f32_16x16x32_bf16 v[2:5], v[174:177], v[214:217], v[2:5]
	v_mfma_f32_16x16x32_bf16 v[54:57], v[170:173], v[194:197], v[54:57]
	v_mfma_f32_16x16x32_bf16 v[46:49], v[186:189], v[194:197], v[46:49]
	v_mfma_f32_16x16x32_bf16 v[38:41], v[170:173], v[202:205], v[38:41]
	v_mfma_f32_16x16x32_bf16 v[30:33], v[186:189], v[202:205], v[30:33]
	v_mfma_f32_16x16x32_bf16 v[22:25], v[170:173], v[210:213], v[22:25]
	v_mfma_f32_16x16x32_bf16 v[14:17], v[186:189], v[210:213], v[14:17]
	v_mfma_f32_16x16x32_bf16 v[6:9], v[170:173], v[218:221], v[6:9]
	v_mfma_f32_16x16x32_bf16 v[2:5], v[186:189], v[218:221], v[2:5]
	s_setprio 0
	s_barrier
	s_add_i32 s47, s47, 2
	s_add_u32 s24, s24, 0x100
	s_addc_u32 s25, s25, 0
	s_add_u32 s45, s45, 0x100
	s_addc_u32 s46, s46, 0
	s_cmp_gt_u32 s47, 13
	s_cbranch_scc0 .LBB0_301
	s_and_b64 vcc, exec, s[8:9]
	s_cbranch_vccz .LBB0_304
	s_barrier

; #define PG8_STAGE(bufoff, gbase, voff) do { _Pragma("unroll") for (int _i = 0; _i < 2; ++_i) \
;         __builtin_amdgcn_global_load_lds((const unsigned*)((const char*)(gbase) + (voff)[_i]), (PG8_LAS unsigned*)(lds + (bufoff) + ldsw + _i * 8192), 16, 0, 0); } while (0)
; #define PG8_LDA(dst, b, h) do { _Pragma("unroll") for (int m = 0; m < 4; ++m) _Pragma("unroll") for (int k = 0; k < 2; ++k) dst[m][k] = *(const PG8_LAS bf16x8*)(lds + PG8_SA(b, h) + aoff + m * 2048 + k * 1024); } while (0)
; #define PG8_LDB(dst, b, h) do { _Pragma("unroll") for (int n = 0; n < 2; ++n) _Pragma("unroll") for (int k = 0; k < 2; ++k) dst[n][k] = *(const PG8_LAS bf16x8*)(lds + PG8_SB(b, h) + boff + n * 2048 + k * 1024); } while (0)
; #define PG8_WAIT_V(n) asm volatile("s_waitcnt vmcnt(" #n ")" ::: "memory")
; #define PG8_WAIT_L(n) asm volatile("s_waitcnt lgkmcnt(" #n ")" ::: "memory")
; #define PG8_BAR __builtin_amdgcn_s_barrier()
; #define PG8_SCHED __builtin_amdgcn_sched_barrier(0)
; template <class Epi, class Sched, bool ALIGN_EPI = false, bool SP2 = false>
; __device__ __forceinline__ void gemm_phase(PG8_LAS unsigned char* lds, const Gemm g, const Sched& S, const Epi& E) {
;     ...
;         const bool has_next = S.next(ui + 1, nxt);
;         const char* nA = has_next ? (const char*)g.A + (size_t)nxt.pm * tstep : cA; const char* nB = has_next ? (const char*)g.Bt + (size_t)nxt.pn * tstep : cB;
;         for (int t = 0; t < nt; t += 2) {
;             const bool last = (t == nt - 2);
;             const char* a1 = cA + (size_t)(t + 1) * kstep;
;             const char* a2 = last ? nA : cA + (size_t)(t + 2) * kstep; const char* b2 = last ? nB : cB + (size_t)(t + 2) * kstep;
;             const char* a3 = a2 + kstep; const char* b3 = b2 + kstep;
;             if (last && has_next) S.a_ready(nxt);
;             if constexpr (SP2) {
;             PG8_LDB(B0, 0, 0); PG8_LDB(B1, 0, 1); PG8_SCHED; PG8_LDA(At, 0, 0); PG8_STAGE(PG8_SA(1, 1), a1 + hstep, voffA);
;             PG8_WAIT_V(8); PG8_WAIT_L(0); PG8_BAR; PG8_MMA(0, 0, At, B0); PG8_MMA(0, 1, At, B1); PG8_BAR; PG8_SCHED;
;             PG8_LDA(At, 0, 1); PG8_STAGE(PG8_SB(0, 0), b2, voffB); PG8_STAGE(PG8_SB(0, 1), b2 + hstep, voffB); PG8_STAGE(PG8_SA(0, 0), a2, voffA);
;             PG8_WAIT_V(8); PG8_WAIT_L(0); PG8_BAR; PG8_MMA(1, 0, At, B0); PG8_MMA(1, 1, At, B1); PG8_BAR; PG8_SCHED;
.LBB0_317:
	s_ashr_i32 s13, s12, 31
	s_lshl_b64 s[16:17], s[12:13], 19
	s_add_u32 s16, s8, s16
	s_addc_u32 s17, s9, s17
	s_and_b64 s[18:19], s[4:5], exec
	s_cselect_b32 s13, s17, s25
	s_cselect_b32 s21, s16, s24
	s_ashr_i32 s11, s10, 31
	s_lshl_b64 s[18:19], s[10:11], 19
	s_add_u32 s18, s33, s18
	s_addc_u32 s19, s34, s19
	s_and_b64 s[28:29], s[4:5], exec
	s_cselect_b32 s11, s19, s27
	s_cselect_b32 s44, s18, s26
	s_add_u32 s24, s24, 0x40080
	s_addc_u32 s25, s25, 0
	s_add_u32 s45, s26, 0x100
	s_addc_u32 s46, s27, 0
	s_mov_b32 s47, -2
	s_add_u32 s26, s24, 0xfffc0080
	s_addc_u32 s27, s25, -1
	s_add_i32 s48, 0, 0x10000
	s_cmp_eq_u32 s47, 12
	s_cselect_b32 s29, s13, s27
	s_cselect_b32 s28, s21, s26
	v_add_u32_e32 v154, s48, v156
	s_cselect_b32 s27, s11, s46
	s_cselect_b32 s26, s44, s45
	s_add_i32 s50, 0, 0x14000
	ds_read_b128 v[94:97], v154
	ds_read_b128 v[134:137], v154 offset:1024
	ds_read_b128 v[158:161], v154 offset:2048
	ds_read_b128 v[162:165], v154 offset:3072
	v_add_u32_e32 v154, s50, v156
	ds_read_b128 v[166:169], v154
	ds_read_b128 v[170:173], v154 offset:1024
	ds_read_b128 v[174:177], v154 offset:2048
	ds_read_b128 v[186:189], v154 offset:3072
	s_add_i32 m0, s23, 0xc000
	ds_read_b128 v[190:193], v157
	ds_read_b128 v[194:197], v157 offset:1024
	ds_read_b128 v[198:201], v157 offset:2048
	ds_read_b128 v[202:205], v157 offset:3072
	ds_read_b128 v[206:209], v157 offset:4096
	ds_read_b128 v[210:213], v157 offset:5120
	ds_read_b128 v[214:217], v157 offset:6144
	ds_read_b128 v[218:221], v157 offset:7168
	global_load_lds_dwordx4 v150, s[24:25]
	s_add_i32 m0, s23, 0xe000
	s_nop 0
	global_load_lds_dwordx4 v152, s[24:25]
	s_waitcnt vmcnt(8) lgkmcnt(0)
	s_barrier
	s_setprio 1
	v_mfma_f32_16x16x32_bf16 v[130:133], v[94:97], v[190:193], 0
	v_mfma_f32_16x16x32_bf16 v[126:129], v[158:161], v[190:193], 0
	v_mfma_f32_16x16x32_bf16 v[114:117], v[94:97], v[198:201], 0
	v_mfma_f32_16x16x32_bf16 v[110:113], v[158:161], v[198:201], 0
	v_mfma_f32_16x16x32_bf16 v[98:101], v[94:97], v[206:209], 0
	v_mfma_f32_16x16x32_bf16 v[90:93], v[158:161], v[206:209], 0
	v_mfma_f32_16x16x32_bf16 v[78:81], v[94:97], v[214:217], 0
	v_mfma_f32_16x16x32_bf16 v[74:77], v[158:161], v[214:217], 0
	v_mfma_f32_16x16x32_bf16 v[130:133], v[134:137], v[194:197], v[130:133]
	v_mfma_f32_16x16x32_bf16 v[126:129], v[162:165], v[194:197], v[126:129]
	v_mfma_f32_16x16x32_bf16 v[114:117], v[134:137], v[202:205], v[114:117]
	v_mfma_f32_16x16x32_bf16 v[110:113], v[162:165], v[202:205], v[110:113]
	v_mfma_f32_16x16x32_bf16 v[98:101], v[134:137], v[210:213], v[98:101]
	v_mfma_f32_16x16x32_bf16 v[90:93], v[162:165], v[210:213], v[90:93]
	v_mfma_f32_16x16x32_bf16 v[78:81], v[134:137], v[218:221], v[78:81]
	v_mfma_f32_16x16x32_bf16 v[74:77], v[162:165], v[218:221], v[74:77]
	v_mfma_f32_16x16x32_bf16 v[122:125], v[166:169], v[190:193], 0
	v_mfma_f32_16x16x32_bf16 v[118:121], v[174:177], v[190:193], 0
	v_mfma_f32_16x16x32_bf16 v[106:109], v[166:169], v[198:201], 0
	v_mfma_f32_16x16x32_bf16 v[102:105], v[174:177], v[198:201], 0
	v_mfma_f32_16x16x32_bf16 v[86:89], v[166:169], v[206:209], 0
	v_mfma_f32_16x16x32_bf16 v[82:85], v[174:177], v[206:209], 0
	v_mfma_f32_16x16x32_bf16 v[70:73], v[166:169], v[214:217], 0
	v_mfma_f32_16x16x32_bf16 v[66:69], v[174:177], v[214:217], 0
	v_mfma_f32_16x16x32_bf16 v[122:125], v[170:173], v[194:197], v[122:125]
	v_mfma_f32_16x16x32_bf16 v[118:121], v[186:189], v[194:197], v[118:121]
	v_mfma_f32_16x16x32_bf16 v[106:109], v[170:173], v[202:205], v[106:109]
	v_mfma_f32_16x16x32_bf16 v[102:105], v[186:189], v[202:205], v[102:105]
	v_mfma_f32_16x16x32_bf16 v[86:89], v[170:173], v[210:213], v[86:89]
	v_mfma_f32_16x16x32_bf16 v[82:85], v[186:189], v[210:213], v[82:85]
	v_mfma_f32_16x16x32_bf16 v[70:73], v[170:173], v[218:221], v[70:73]
	v_mfma_f32_16x16x32_bf16 v[66:69], v[186:189], v[218:221], v[66:69]
	s_setprio 0
	s_barrier
	s_add_i32 s48, s48, s35
	v_lshl_add_u64 v[154:155], s[26:27], 0, v[142:143]
	s_mov_b32 m0, s48
	ds_read_b128 v[190:193], v157 offset:16384
	ds_read_b128 v[194:197], v157 offset:17408
	ds_read_b128 v[198:201], v157 offset:18432
	ds_read_b128 v[202:205], v157 offset:19456
	ds_read_b128 v[206:209], v157 offset:20480
	ds_read_b128 v[210:213], v157 offset:21504
	ds_read_b128 v[214:217], v157 offset:22528
	ds_read_b128 v[218:221], v157 offset:23552
	global_load_lds_dwordx4 v[154:155], off
	s_add_i32 m0, s48, 0x2000
	s_add_u32 s48, s26, 0x40000
	v_lshl_add_u64 v[180:181], s[26:27], 0, v[138:139]
	s_addc_u32 s49, s27, 0
	s_add_i32 s50, s50, s35
	global_load_lds_dwordx4 v[180:181], off
	v_lshl_add_u64 v[182:183], s[48:49], 0, v[142:143]
	s_mov_b32 m0, s50
	v_lshl_add_u64 v[222:223], s[28:29], 0, v[140:141]
	global_load_lds_dwordx4 v[182:183], off
	s_add_i32 m0, s50, 0x2000
	s_nop 0
	global_load_lds_dwordx4 v138, s[48:49]
	v_lshl_add_u64 v[182:183], s[28:29], 0, v[144:145]
	s_mov_b32 m0, s23
	s_nop 0
	global_load_lds_dwordx4 v[182:183], off
	s_mov_b32 m0, s37
	s_nop 0
	global_load_lds_dwordx4 v[222:223], off
	s_waitcnt vmcnt(8) lgkmcnt(0)
	s_barrier
; #define PG8_STAGE(bufoff, gbase, voff) do { _Pragma("unroll") for (int _i = 0; _i < 2; ++_i) \
;         __builtin_amdgcn_global_load_lds((const unsigned*)((const char*)(gbase) + (voff)[_i]), (PG8_LAS unsigned*)(lds + (bufoff) + ldsw + _i * 8192), 16, 0, 0); } while (0)
; #define PG8_LDA(dst, b, h) do { _Pragma("unroll") for (int m = 0; m < 4; ++m) _Pragma("unroll") for (int k = 0; k < 2; ++k) dst[m][k] = *(const PG8_LAS bf16x8*)(lds + PG8_SA(b, h) + aoff + m * 2048 + k * 1024); } while (0)
; #define PG8_LDB(dst, b, h) do { _Pragma("unroll") for (int n = 0; n < 2; ++n) _Pragma("unroll") for (int k = 0; k < 2; ++k) dst[n][k] = *(const PG8_LAS bf16x8*)(lds + PG8_SB(b, h) + boff + n * 2048 + k * 1024); } while (0)
; #define PG8_MMA(ai, bj, At, Bt) do { __builtin_amdgcn_s_setprio(1); _Pragma("unroll") for (int m = 0; m < 4; ++m) _Pragma("unroll") for (int n = 0; n < 2; ++n) _Pragma("unroll") for (int k = 0; k < 2; ++k) \
;         acc[ai][bj][m][n] = __builtin_amdgcn_mfma_f32_16x16x32_bf16(Bt[n][k], At[m][k], acc[ai][bj][m][n], 0, 0, 0); __builtin_amdgcn_s_setprio(0); } while (0)
; #define PG8_WAIT_V(n) asm volatile("s_waitcnt vmcnt(" #n ")" ::: "memory")
; #define PG8_WAIT_L(n) asm volatile("s_waitcnt lgkmcnt(" #n ")" ::: "memory")
; #define PG8_BAR __builtin_amdgcn_s_barrier()
; #define PG8_SCHED __builtin_amdgcn_sched_barrier(0)
; template <class Epi, class Sched, bool ALIGN_EPI = false, bool SP2 = false>
; __device__ __forceinline__ void gemm_phase(PG8_LAS unsigned char* lds, const Gemm g, const Sched& S, const Epi& E) {
;     ...
;             PG8_WAIT_V(8); PG8_WAIT_L(0); PG8_BAR; PG8_MMA(1, 0, At, B0); PG8_MMA(1, 1, At, B1); PG8_BAR; PG8_SCHED;
;             PG8_LDB(B0, 1, 0); PG8_LDB(B1, 1, 1); PG8_SCHED; PG8_LDA(At, 1, 0); PG8_STAGE(PG8_SA(0, 1), a2 + hstep, voffA);
;             PG8_WAIT_V(8); PG8_WAIT_L(0); PG8_BAR; PG8_MMA(0, 0, At, B0); PG8_MMA(0, 1, At, B1); PG8_BAR; PG8_SCHED;
	s_setprio 1
	v_mfma_f32_16x16x32_bf16 v[62:65], v[94:97], v[190:193], 0
	v_mfma_f32_16x16x32_bf16 v[58:61], v[158:161], v[190:193], 0
	v_mfma_f32_16x16x32_bf16 v[50:53], v[94:97], v[198:201], 0
	v_mfma_f32_16x16x32_bf16 v[42:45], v[158:161], v[198:201], 0
	v_mfma_f32_16x16x32_bf16 v[34:37], v[94:97], v[206:209], 0
	v_mfma_f32_16x16x32_bf16 v[26:29], v[158:161], v[206:209], 0
	v_mfma_f32_16x16x32_bf16 v[18:21], v[94:97], v[214:217], 0
	v_mfma_f32_16x16x32_bf16 v[10:13], v[158:161], v[214:217], 0
	v_mfma_f32_16x16x32_bf16 v[62:65], v[134:137], v[194:197], v[62:65]
	v_mfma_f32_16x16x32_bf16 v[58:61], v[162:165], v[194:197], v[58:61]
	v_mfma_f32_16x16x32_bf16 v[50:53], v[134:137], v[202:205], v[50:53]
	v_mfma_f32_16x16x32_bf16 v[42:45], v[162:165], v[202:205], v[42:45]
	v_mfma_f32_16x16x32_bf16 v[34:37], v[134:137], v[210:213], v[34:37]
	v_mfma_f32_16x16x32_bf16 v[26:29], v[162:165], v[210:213], v[26:29]
	v_mfma_f32_16x16x32_bf16 v[18:21], v[134:137], v[218:221], v[18:21]
	v_mfma_f32_16x16x32_bf16 v[10:13], v[162:165], v[218:221], v[10:13]
	v_mfma_f32_16x16x32_bf16 v[54:57], v[166:169], v[190:193], 0
	v_mfma_f32_16x16x32_bf16 v[46:49], v[174:177], v[190:193], 0
	v_mfma_f32_16x16x32_bf16 v[38:41], v[166:169], v[198:201], 0
	v_mfma_f32_16x16x32_bf16 v[30:33], v[174:177], v[198:201], 0
	v_mfma_f32_16x16x32_bf16 v[22:25], v[166:169], v[206:209], 0
	v_mfma_f32_16x16x32_bf16 v[14:17], v[174:177], v[206:209], 0
	v_mfma_f32_16x16x32_bf16 v[6:9], v[166:169], v[214:217], 0
	v_mfma_f32_16x16x32_bf16 v[2:5], v[174:177], v[214:217], 0
	v_mfma_f32_16x16x32_bf16 v[54:57], v[170:173], v[194:197], v[54:57]
	v_mfma_f32_16x16x32_bf16 v[46:49], v[186:189], v[194:197], v[46:49]
	v_mfma_f32_16x16x32_bf16 v[38:41], v[170:173], v[202:205], v[38:41]
	v_mfma_f32_16x16x32_bf16 v[30:33], v[186:189], v[202:205], v[30:33]
	v_mfma_f32_16x16x32_bf16 v[22:25], v[170:173], v[210:213], v[22:25]
	v_mfma_f32_16x16x32_bf16 v[14:17], v[186:189], v[210:213], v[14:17]
	v_mfma_f32_16x16x32_bf16 v[6:9], v[170:173], v[218:221], v[6:9]
	v_mfma_f32_16x16x32_bf16 v[2:5], v[186:189], v[218:221], v[2:5]
	s_setprio 0
	s_barrier
	s_add_i32 s48, 0, 0x18000
	s_add_i32 s49, 0, 0x1c000
	v_add_u32_e32 v162, s48, v156
	v_add_u32_e32 v179, s49, v156
	ds_read_b128 v[94:97], v162
	ds_read_b128 v[134:137], v162 offset:1024
	ds_read_b128 v[158:161], v162 offset:2048
	ds_read_b128 v[162:165], v162 offset:3072
	ds_read_b128 v[166:169], v179
	ds_read_b128 v[170:173], v179 offset:1024
	ds_read_b128 v[174:177], v179 offset:2048
	ds_read_b128 v[186:189], v179 offset:3072
	s_add_u32 s28, s28, 0x40000
	s_addc_u32 s29, s29, 0
	s_mov_b32 m0, s38
	ds_read_b128 v[190:193], v157 offset:32768
	ds_read_b128 v[194:197], v157 offset:33792
	ds_read_b128 v[198:201], v157 offset:34816
	ds_read_b128 v[202:205], v157 offset:35840
	ds_read_b128 v[206:209], v157 offset:36864
	ds_read_b128 v[210:213], v157 offset:37888
	ds_read_b128 v[214:217], v157 offset:38912
	ds_read_b128 v[218:221], v157 offset:39936
	global_load_lds_dwordx4 v144, s[28:29]
	v_lshl_add_u64 v[240:241], s[28:29], 0, v[140:141]
	s_mov_b32 m0, s39
	s_nop 0
	global_load_lds_dwordx4 v[240:241], off
	s_waitcnt vmcnt(8) lgkmcnt(0)
	s_barrier
	s_setprio 1
	v_mfma_f32_16x16x32_bf16 v[130:133], v[94:97], v[190:193], v[130:133]
	v_mfma_f32_16x16x32_bf16 v[126:129], v[158:161], v[190:193], v[126:129]
	v_mfma_f32_16x16x32_bf16 v[114:117], v[94:97], v[198:201], v[114:117]
	v_mfma_f32_16x16x32_bf16 v[110:113], v[158:161], v[198:201], v[110:113]
	v_mfma_f32_16x16x32_bf16 v[98:101], v[94:97], v[206:209], v[98:101]
	v_mfma_f32_16x16x32_bf16 v[90:93], v[158:161], v[206:209], v[90:93]
	v_mfma_f32_16x16x32_bf16 v[78:81], v[94:97], v[214:217], v[78:81]
	v_mfma_f32_16x16x32_bf16 v[74:77], v[158:161], v[214:217], v[74:77]
	v_mfma_f32_16x16x32_bf16 v[130:133], v[134:137], v[194:197], v[130:133]
	v_mfma_f32_16x16x32_bf16 v[126:129], v[162:165], v[194:197], v[126:129]
	v_mfma_f32_16x16x32_bf16 v[114:117], v[134:137], v[202:205], v[114:117]
	v_mfma_f32_16x16x32_bf16 v[110:113], v[162:165], v[202:205], v[110:113]
	v_mfma_f32_16x16x32_bf16 v[98:101], v[134:137], v[210:213], v[98:101]
	v_mfma_f32_16x16x32_bf16 v[90:93], v[162:165], v[210:213], v[90:93]
	v_mfma_f32_16x16x32_bf16 v[78:81], v[134:137], v[218:221], v[78:81]
	v_mfma_f32_16x16x32_bf16 v[74:77], v[162:165], v[218:221], v[74:77]
	v_mfma_f32_16x16x32_bf16 v[122:125], v[166:169], v[190:193], v[122:125]
	v_mfma_f32_16x16x32_bf16 v[118:121], v[174:177], v[190:193], v[118:121]
	v_mfma_f32_16x16x32_bf16 v[106:109], v[166:169], v[198:201], v[106:109]
	v_mfma_f32_16x16x32_bf16 v[102:105], v[174:177], v[198:201], v[102:105]
	v_mfma_f32_16x16x32_bf16 v[86:89], v[166:169], v[206:209], v[86:89]
	v_mfma_f32_16x16x32_bf16 v[82:85], v[174:177], v[206:209], v[82:85]
	v_mfma_f32_16x16x32_bf16 v[70:73], v[166:169], v[214:217], v[70:73]
	v_mfma_f32_16x16x32_bf16 v[66:69], v[174:177], v[214:217], v[66:69]
	v_mfma_f32_16x16x32_bf16 v[122:125], v[170:173], v[194:197], v[122:125]
	v_mfma_f32_16x16x32_bf16 v[118:121], v[186:189], v[194:197], v[118:121]
	v_mfma_f32_16x16x32_bf16 v[106:109], v[170:173], v[202:205], v[106:109]
	v_mfma_f32_16x16x32_bf16 v[102:105], v[186:189], v[202:205], v[102:105]
	v_mfma_f32_16x16x32_bf16 v[86:89], v[170:173], v[210:213], v[86:89]
	v_mfma_f32_16x16x32_bf16 v[82:85], v[186:189], v[210:213], v[82:85]
	v_mfma_f32_16x16x32_bf16 v[70:73], v[170:173], v[218:221], v[70:73]
	v_mfma_f32_16x16x32_bf16 v[66:69], v[186:189], v[218:221], v[66:69]
	s_setprio 0
	s_barrier
; #define PG8_STAGE(bufoff, gbase, voff) do { _Pragma("unroll") for (int _i = 0; _i < 2; ++_i) \
;         __builtin_amdgcn_global_load_lds((const unsigned*)((const char*)(gbase) + (voff)[_i]), (PG8_LAS unsigned*)(lds + (bufoff) + ldsw + _i * 8192), 16, 0, 0); } while (0)
; #define PG8_LDA(dst, b, h) do { _Pragma("unroll") for (int m = 0; m < 4; ++m) _Pragma("unroll") for (int k = 0; k < 2; ++k) dst[m][k] = *(const PG8_LAS bf16x8*)(lds + PG8_SA(b, h) + aoff + m * 2048 + k * 1024); } while (0)
; #define PG8_LDB(dst, b, h) do { _Pragma("unroll") for (int n = 0; n < 2; ++n) _Pragma("unroll") for (int k = 0; k < 2; ++k) dst[n][k] = *(const PG8_LAS bf16x8*)(lds + PG8_SB(b, h) + boff + n * 2048 + k * 1024); } while (0)
; template <class Epi, class Sched, bool ALIGN_EPI = false, bool SP2 = false>
; __device__ __forceinline__ void gemm_phase(PG8_LAS unsigned char* lds, const Gemm g, const Sched& S, const Epi& E) {
;     ...
;         for (int t = 0; t < nt; t += 2) {
;             const bool last = (t == nt - 2);
;             const char* a1 = cA + (size_t)(t + 1) * kstep;
;             const char* a2 = last ? nA : cA + (size_t)(t + 2) * kstep; const char* b2 = last ? nB : cB + (size_t)(t + 2) * kstep;
;             const char* a3 = a2 + kstep; const char* b3 = b2 + kstep;
;             if (last && has_next) S.a_ready(nxt);
;             if constexpr (SP2) {
;             PG8_LDB(B0, 0, 0); PG8_LDB(B1, 0, 1); PG8_SCHED; PG8_LDA(At, 0, 0); PG8_STAGE(PG8_SA(1, 1), a1 + hstep, voffA);
;             PG8_WAIT_V(8); PG8_WAIT_L(0); PG8_BAR; PG8_MMA(0, 0, At, B0); PG8_MMA(0, 1, At, B1); PG8_BAR; PG8_SCHED;
;             PG8_LDA(At, 0, 1); PG8_STAGE(PG8_SB(0, 0), b2, voffB); PG8_STAGE(PG8_SB(0, 1), b2 + hstep, voffB); PG8_STAGE(PG8_SA(0, 0), a2, voffA);
;             PG8_WAIT_V(8); PG8_WAIT_L(0); PG8_BAR; PG8_MMA(1, 0, At, B0); PG8_MMA(1, 1, At, B1); PG8_BAR; PG8_SCHED;
;             PG8_LDB(B0, 1, 0); PG8_LDB(B1, 1, 1); PG8_SCHED; PG8_LDA(At, 1, 0); PG8_STAGE(PG8_SA(0, 1), a2 + hstep, voffA);
;             PG8_WAIT_V(8); PG8_WAIT_L(0); PG8_BAR; PG8_MMA(0, 0, At, B0); PG8_MMA(0, 1, At, B1); PG8_BAR; PG8_SCHED;
;             PG8_LDA(At, 1, 1); PG8_STAGE(PG8_SB(1, 0), b3, voffB); PG8_STAGE(PG8_SB(1, 1), b3 + hstep, voffB); PG8_STAGE(PG8_SA(1, 0), a3, voffA);
;             PG8_WAIT_V(8); PG8_WAIT_L(0); PG8_BAR; PG8_MMA(1, 0, At, B0); PG8_MMA(1, 1, At, B1); PG8_BAR; PG8_SCHED;
	s_add_i32 s28, s48, s35
	v_lshl_add_u64 v[154:155], v[154:155], 0, s[80:81]
	s_mov_b32 m0, s28
	ds_read_b128 v[190:193], v157 offset:49152
	ds_read_b128 v[194:197], v157 offset:50176
	ds_read_b128 v[198:201], v157 offset:51200
	ds_read_b128 v[202:205], v157 offset:52224
	ds_read_b128 v[206:209], v157 offset:53248
	ds_read_b128 v[210:213], v157 offset:54272
	ds_read_b128 v[214:217], v157 offset:55296
	ds_read_b128 v[218:221], v157 offset:56320
	global_load_lds_dwordx4 v[154:155], off
	s_add_i32 m0, s28, 0x2000
	s_add_u32 s26, s26, 0x40080
	v_lshl_add_u64 v[154:155], v[180:181], 0, s[80:81]
	s_addc_u32 s27, s27, 0
	s_add_i32 s28, s49, s35
	global_load_lds_dwordx4 v[154:155], off
	s_mov_b32 m0, s28
	s_nop 0
	global_load_lds_dwordx4 v142, s[26:27]
	s_add_i32 m0, s28, 0x2000
	s_nop 0
	global_load_lds_dwordx4 v138, s[26:27]
	v_lshl_add_u64 v[154:155], v[182:183], 0, s[80:81]
	s_mov_b32 m0, s40
	s_nop 0
	global_load_lds_dwordx4 v[154:155], off
	v_lshl_add_u64 v[154:155], v[222:223], 0, s[80:81]
	s_mov_b32 m0, s41
	s_nop 0
	global_load_lds_dwordx4 v[154:155], off
	s_waitcnt vmcnt(8) lgkmcnt(0)
	s_barrier
	s_setprio 1
	v_mfma_f32_16x16x32_bf16 v[62:65], v[94:97], v[190:193], v[62:65]
	v_mfma_f32_16x16x32_bf16 v[58:61], v[158:161], v[190:193], v[58:61]
	v_mfma_f32_16x16x32_bf16 v[50:53], v[94:97], v[198:201], v[50:53]
	v_mfma_f32_16x16x32_bf16 v[42:45], v[158:161], v[198:201], v[42:45]
	v_mfma_f32_16x16x32_bf16 v[34:37], v[94:97], v[206:209], v[34:37]
	v_mfma_f32_16x16x32_bf16 v[26:29], v[158:161], v[206:209], v[26:29]
	v_mfma_f32_16x16x32_bf16 v[18:21], v[94:97], v[214:217], v[18:21]
	v_mfma_f32_16x16x32_bf16 v[10:13], v[158:161], v[214:217], v[10:13]
	v_mfma_f32_16x16x32_bf16 v[62:65], v[134:137], v[194:197], v[62:65]
	v_mfma_f32_16x16x32_bf16 v[58:61], v[162:165], v[194:197], v[58:61]
	v_mfma_f32_16x16x32_bf16 v[50:53], v[134:137], v[202:205], v[50:53]
	v_mfma_f32_16x16x32_bf16 v[42:45], v[162:165], v[202:205], v[42:45]
	v_mfma_f32_16x16x32_bf16 v[34:37], v[134:137], v[210:213], v[34:37]
	v_mfma_f32_16x16x32_bf16 v[26:29], v[162:165], v[210:213], v[26:29]
	v_mfma_f32_16x16x32_bf16 v[18:21], v[134:137], v[218:221], v[18:21]
	v_mfma_f32_16x16x32_bf16 v[10:13], v[162:165], v[218:221], v[10:13]
	v_mfma_f32_16x16x32_bf16 v[54:57], v[166:169], v[190:193], v[54:57]
	v_mfma_f32_16x16x32_bf16 v[46:49], v[174:177], v[190:193], v[46:49]
	v_mfma_f32_16x16x32_bf16 v[38:41], v[166:169], v[198:201], v[38:41]
	v_mfma_f32_16x16x32_bf16 v[30:33], v[174:177], v[198:201], v[30:33]
	v_mfma_f32_16x16x32_bf16 v[22:25], v[166:169], v[206:209], v[22:25]
	v_mfma_f32_16x16x32_bf16 v[14:17], v[174:177], v[206:209], v[14:17]
	v_mfma_f32_16x16x32_bf16 v[6:9], v[166:169], v[214:217], v[6:9]
	v_mfma_f32_16x16x32_bf16 v[2:5], v[174:177], v[214:217], v[2:5]
	v_mfma_f32_16x16x32_bf16 v[54:57], v[170:173], v[194:197], v[54:57]
	v_mfma_f32_16x16x32_bf16 v[46:49], v[186:189], v[194:197], v[46:49]
	v_mfma_f32_16x16x32_bf16 v[38:41], v[170:173], v[202:205], v[38:41]
	v_mfma_f32_16x16x32_bf16 v[30:33], v[186:189], v[202:205], v[30:33]
	v_mfma_f32_16x16x32_bf16 v[22:25], v[170:173], v[210:213], v[22:25]
	v_mfma_f32_16x16x32_bf16 v[14:17], v[186:189], v[210:213], v[14:17]
	v_mfma_f32_16x16x32_bf16 v[6:9], v[170:173], v[218:221], v[6:9]
	v_mfma_f32_16x16x32_bf16 v[2:5], v[186:189], v[218:221], v[2:5]
	s_setprio 0
	s_barrier
	s_add_i32 s47, s47, 2
	s_add_u32 s24, s24, 0x100
	s_addc_u32 s25, s25, 0
	s_add_u32 s45, s45, 0x100
	s_addc_u32 s46, s46, 0
	s_cmp_gt_u32 s47, 13
	s_branch .LBB0_318
.LBB0_318:
	s_add_u32 s26, s24, 0xfffc0080
	s_addc_u32 s27, s25, -1
	s_add_i32 s48, 0, 0x10000
	s_cmp_eq_u32 s47, 12
	s_cselect_b32 s29, s13, s27
	s_cselect_b32 s28, s21, s26
	v_add_u32_e32 v154, s48, v156
	s_cselect_b32 s27, s11, s46
	s_cselect_b32 s26, s44, s45
	s_add_i32 s50, 0, 0x14000
	ds_read_b128 v[94:97], v154
	ds_read_b128 v[134:137], v154 offset:1024
	ds_read_b128 v[158:161], v154 offset:2048
	ds_read_b128 v[162:165], v154 offset:3072
	v_add_u32_e32 v154, s50, v156
	ds_read_b128 v[166:169], v154
	ds_read_b128 v[170:173], v154 offset:1024
	ds_read_b128 v[174:177], v154 offset:2048
	ds_read_b128 v[186:189], v154 offset:3072
	s_add_i32 m0, s23, 0xc000
	ds_read_b128 v[190:193], v157
	ds_read_b128 v[194:197], v157 offset:1024
	ds_read_b128 v[198:201], v157 offset:2048
	ds_read_b128 v[202:205], v157 offset:3072
	ds_read_b128 v[206:209], v157 offset:4096
	ds_read_b128 v[210:213], v157 offset:5120
	ds_read_b128 v[214:217], v157 offset:6144
	ds_read_b128 v[218:221], v157 offset:7168
	global_load_lds_dwordx4 v150, s[24:25]
	s_add_i32 m0, s23, 0xe000
	s_nop 0
	global_load_lds_dwordx4 v152, s[24:25]
	s_waitcnt vmcnt(8) lgkmcnt(0)
	s_barrier
; #define PG8_STAGE(bufoff, gbase, voff) do { _Pragma("unroll") for (int _i = 0; _i < 2; ++_i) \
;         __builtin_amdgcn_global_load_lds((const unsigned*)((const char*)(gbase) + (voff)[_i]), (PG8_LAS unsigned*)(lds + (bufoff) + ldsw + _i * 8192), 16, 0, 0); } while (0)
; #define PG8_LDA(dst, b, h) do { _Pragma("unroll") for (int m = 0; m < 4; ++m) _Pragma("unroll") for (int k = 0; k < 2; ++k) dst[m][k] = *(const PG8_LAS bf16x8*)(lds + PG8_SA(b, h) + aoff + m * 2048 + k * 1024); } while (0)
; #define PG8_LDB(dst, b, h) do { _Pragma("unroll") for (int n = 0; n < 2; ++n) _Pragma("unroll") for (int k = 0; k < 2; ++k) dst[n][k] = *(const PG8_LAS bf16x8*)(lds + PG8_SB(b, h) + boff + n * 2048 + k * 1024); } while (0)
; #define PG8_MMA(ai, bj, At, Bt) do { __builtin_amdgcn_s_setprio(1); _Pragma("unroll") for (int m = 0; m < 4; ++m) _Pragma("unroll") for (int n = 0; n < 2; ++n) _Pragma("unroll") for (int k = 0; k < 2; ++k) \
;         acc[ai][bj][m][n] = __builtin_amdgcn_mfma_f32_16x16x32_bf16(Bt[n][k], At[m][k], acc[ai][bj][m][n], 0, 0, 0); __builtin_amdgcn_s_setprio(0); } while (0)
; #define PG8_WAIT_V(n) asm volatile("s_waitcnt vmcnt(" #n ")" ::: "memory")
; #define PG8_WAIT_L(n) asm volatile("s_waitcnt lgkmcnt(" #n ")" ::: "memory")
; #define PG8_BAR __builtin_amdgcn_s_barrier()
; #define PG8_SCHED __builtin_amdgcn_sched_barrier(0)
; template <class Epi, class Sched, bool ALIGN_EPI = false, bool SP2 = false>
; __device__ __forceinline__ void gemm_phase(PG8_LAS unsigned char* lds, const Gemm g, const Sched& S, const Epi& E) {
;     ...
;             PG8_LDB(B0, 0, 0); PG8_LDB(B1, 0, 1); PG8_SCHED; PG8_LDA(At, 0, 0); PG8_STAGE(PG8_SA(1, 1), a1 + hstep, voffA);
;             PG8_WAIT_V(8); PG8_WAIT_L(0); PG8_BAR; PG8_MMA(0, 0, At, B0); PG8_MMA(0, 1, At, B1); PG8_BAR; PG8_SCHED;
;             PG8_LDA(At, 0, 1); PG8_STAGE(PG8_SB(0, 0), b2, voffB); PG8_STAGE(PG8_SB(0, 1), b2 + hstep, voffB); PG8_STAGE(PG8_SA(0, 0), a2, voffA);
;             PG8_WAIT_V(8); PG8_WAIT_L(0); PG8_BAR; PG8_MMA(1, 0, At, B0); PG8_MMA(1, 1, At, B1); PG8_BAR; PG8_SCHED;
	s_setprio 1
	v_mfma_f32_16x16x32_bf16 v[130:133], v[94:97], v[190:193], v[130:133]
	v_mfma_f32_16x16x32_bf16 v[126:129], v[158:161], v[190:193], v[126:129]
	v_mfma_f32_16x16x32_bf16 v[114:117], v[94:97], v[198:201], v[114:117]
	v_mfma_f32_16x16x32_bf16 v[110:113], v[158:161], v[198:201], v[110:113]
	v_mfma_f32_16x16x32_bf16 v[98:101], v[94:97], v[206:209], v[98:101]
	v_mfma_f32_16x16x32_bf16 v[90:93], v[158:161], v[206:209], v[90:93]
	v_mfma_f32_16x16x32_bf16 v[78:81], v[94:97], v[214:217], v[78:81]
	v_mfma_f32_16x16x32_bf16 v[74:77], v[158:161], v[214:217], v[74:77]
	v_mfma_f32_16x16x32_bf16 v[130:133], v[134:137], v[194:197], v[130:133]
	v_mfma_f32_16x16x32_bf16 v[126:129], v[162:165], v[194:197], v[126:129]
	v_mfma_f32_16x16x32_bf16 v[114:117], v[134:137], v[202:205], v[114:117]
	v_mfma_f32_16x16x32_bf16 v[110:113], v[162:165], v[202:205], v[110:113]
	v_mfma_f32_16x16x32_bf16 v[98:101], v[134:137], v[210:213], v[98:101]
	v_mfma_f32_16x16x32_bf16 v[90:93], v[162:165], v[210:213], v[90:93]
	v_mfma_f32_16x16x32_bf16 v[78:81], v[134:137], v[218:221], v[78:81]
	v_mfma_f32_16x16x32_bf16 v[74:77], v[162:165], v[218:221], v[74:77]
	v_mfma_f32_16x16x32_bf16 v[122:125], v[166:169], v[190:193], v[122:125]
	v_mfma_f32_16x16x32_bf16 v[118:121], v[174:177], v[190:193], v[118:121]
	v_mfma_f32_16x16x32_bf16 v[106:109], v[166:169], v[198:201], v[106:109]
	v_mfma_f32_16x16x32_bf16 v[102:105], v[174:177], v[198:201], v[102:105]
	v_mfma_f32_16x16x32_bf16 v[86:89], v[166:169], v[206:209], v[86:89]
	v_mfma_f32_16x16x32_bf16 v[82:85], v[174:177], v[206:209], v[82:85]
	v_mfma_f32_16x16x32_bf16 v[70:73], v[166:169], v[214:217], v[70:73]
	v_mfma_f32_16x16x32_bf16 v[66:69], v[174:177], v[214:217], v[66:69]
	v_mfma_f32_16x16x32_bf16 v[122:125], v[170:173], v[194:197], v[122:125]
	v_mfma_f32_16x16x32_bf16 v[118:121], v[186:189], v[194:197], v[118:121]
	v_mfma_f32_16x16x32_bf16 v[106:109], v[170:173], v[202:205], v[106:109]
	v_mfma_f32_16x16x32_bf16 v[102:105], v[186:189], v[202:205], v[102:105]
	v_mfma_f32_16x16x32_bf16 v[86:89], v[170:173], v[210:213], v[86:89]
	v_mfma_f32_16x16x32_bf16 v[82:85], v[186:189], v[210:213], v[82:85]
	v_mfma_f32_16x16x32_bf16 v[70:73], v[170:173], v[218:221], v[70:73]
	v_mfma_f32_16x16x32_bf16 v[66:69], v[186:189], v[218:221], v[66:69]
	s_setprio 0
	s_barrier
	s_add_i32 s48, s48, s35
	v_lshl_add_u64 v[154:155], s[26:27], 0, v[142:143]
	s_mov_b32 m0, s48
	ds_read_b128 v[190:193], v157 offset:16384
	ds_read_b128 v[194:197], v157 offset:17408
	ds_read_b128 v[198:201], v157 offset:18432
	ds_read_b128 v[202:205], v157 offset:19456
	ds_read_b128 v[206:209], v157 offset:20480
	ds_read_b128 v[210:213], v157 offset:21504
	ds_read_b128 v[214:217], v157 offset:22528
	ds_read_b128 v[218:221], v157 offset:23552
	global_load_lds_dwordx4 v[154:155], off
	s_add_i32 m0, s48, 0x2000
	s_add_u32 s48, s26, 0x40000
	v_lshl_add_u64 v[180:181], s[26:27], 0, v[138:139]
	s_addc_u32 s49, s27, 0
	s_add_i32 s50, s50, s35
	global_load_lds_dwordx4 v[180:181], off
	v_lshl_add_u64 v[182:183], s[48:49], 0, v[142:143]
	s_mov_b32 m0, s50
	v_lshl_add_u64 v[222:223], s[28:29], 0, v[140:141]
	global_load_lds_dwordx4 v[182:183], off
	s_add_i32 m0, s50, 0x2000
	s_nop 0
	global_load_lds_dwordx4 v138, s[48:49]
	v_lshl_add_u64 v[182:183], s[28:29], 0, v[144:145]
	s_mov_b32 m0, s23
	s_nop 0
	global_load_lds_dwordx4 v[182:183], off
	s_mov_b32 m0, s37
	s_nop 0
	global_load_lds_dwordx4 v[222:223], off
	s_waitcnt vmcnt(8) lgkmcnt(0)
	s_barrier
	s_setprio 1
	v_mfma_f32_16x16x32_bf16 v[62:65], v[94:97], v[190:193], v[62:65]
	v_mfma_f32_16x16x32_bf16 v[58:61], v[158:161], v[190:193], v[58:61]
	v_mfma_f32_16x16x32_bf16 v[50:53], v[94:97], v[198:201], v[50:53]
	v_mfma_f32_16x16x32_bf16 v[42:45], v[158:161], v[198:201], v[42:45]
	v_mfma_f32_16x16x32_bf16 v[34:37], v[94:97], v[206:209], v[34:37]
	v_mfma_f32_16x16x32_bf16 v[26:29], v[158:161], v[206:209], v[26:29]
	v_mfma_f32_16x16x32_bf16 v[18:21], v[94:97], v[214:217], v[18:21]
	v_mfma_f32_16x16x32_bf16 v[10:13], v[158:161], v[214:217], v[10:13]
	v_mfma_f32_16x16x32_bf16 v[62:65], v[134:137], v[194:197], v[62:65]
	v_mfma_f32_16x16x32_bf16 v[58:61], v[162:165], v[194:197], v[58:61]
	v_mfma_f32_16x16x32_bf16 v[50:53], v[134:137], v[202:205], v[50:53]
	v_mfma_f32_16x16x32_bf16 v[42:45], v[162:165], v[202:205], v[42:45]
	v_mfma_f32_16x16x32_bf16 v[34:37], v[134:137], v[210:213], v[34:37]
	v_mfma_f32_16x16x32_bf16 v[26:29], v[162:165], v[210:213], v[26:29]
	v_mfma_f32_16x16x32_bf16 v[18:21], v[134:137], v[218:221], v[18:21]
	v_mfma_f32_16x16x32_bf16 v[10:13], v[162:165], v[218:221], v[10:13]
	v_mfma_f32_16x16x32_bf16 v[54:57], v[166:169], v[190:193], v[54:57]
	v_mfma_f32_16x16x32_bf16 v[46:49], v[174:177], v[190:193], v[46:49]
	v_mfma_f32_16x16x32_bf16 v[38:41], v[166:169], v[198:201], v[38:41]
	v_mfma_f32_16x16x32_bf16 v[30:33], v[174:177], v[198:201], v[30:33]
	v_mfma_f32_16x16x32_bf16 v[22:25], v[166:169], v[206:209], v[22:25]
	v_mfma_f32_16x16x32_bf16 v[14:17], v[174:177], v[206:209], v[14:17]
	v_mfma_f32_16x16x32_bf16 v[6:9], v[166:169], v[214:217], v[6:9]
	v_mfma_f32_16x16x32_bf16 v[2:5], v[174:177], v[214:217], v[2:5]
	v_mfma_f32_16x16x32_bf16 v[54:57], v[170:173], v[194:197], v[54:57]
	v_mfma_f32_16x16x32_bf16 v[46:49], v[186:189], v[194:197], v[46:49]
	v_mfma_f32_16x16x32_bf16 v[38:41], v[170:173], v[202:205], v[38:41]
	v_mfma_f32_16x16x32_bf16 v[30:33], v[186:189], v[202:205], v[30:33]
	v_mfma_f32_16x16x32_bf16 v[22:25], v[170:173], v[210:213], v[22:25]
	v_mfma_f32_16x16x32_bf16 v[14:17], v[186:189], v[210:213], v[14:17]
	v_mfma_f32_16x16x32_bf16 v[6:9], v[170:173], v[218:221], v[6:9]
	v_mfma_f32_16x16x32_bf16 v[2:5], v[186:189], v[218:221], v[2:5]
	s_setprio 0
	s_barrier
; #define PG8_STAGE(bufoff, gbase, voff) do { _Pragma("unroll") for (int _i = 0; _i < 2; ++_i) \
;         __builtin_amdgcn_global_load_lds((const unsigned*)((const char*)(gbase) + (voff)[_i]), (PG8_LAS unsigned*)(lds + (bufoff) + ldsw + _i * 8192), 16, 0, 0); } while (0)
; #define PG8_LDA(dst, b, h) do { _Pragma("unroll") for (int m = 0; m < 4; ++m) _Pragma("unroll") for (int k = 0; k < 2; ++k) dst[m][k] = *(const PG8_LAS bf16x8*)(lds + PG8_SA(b, h) + aoff + m * 2048 + k * 1024); } while (0)
; #define PG8_LDB(dst, b, h) do { _Pragma("unroll") for (int n = 0; n < 2; ++n) _Pragma("unroll") for (int k = 0; k < 2; ++k) dst[n][k] = *(const PG8_LAS bf16x8*)(lds + PG8_SB(b, h) + boff + n * 2048 + k * 1024); } while (0)
; #define PG8_MMA(ai, bj, At, Bt) do { __builtin_amdgcn_s_setprio(1); _Pragma("unroll") for (int m = 0; m < 4; ++m) _Pragma("unroll") for (int n = 0; n < 2; ++n) _Pragma("unroll") for (int k = 0; k < 2; ++k) \
;         acc[ai][bj][m][n] = __builtin_amdgcn_mfma_f32_16x16x32_bf16(Bt[n][k], At[m][k], acc[ai][bj][m][n], 0, 0, 0); __builtin_amdgcn_s_setprio(0); } while (0)
; #define PG8_WAIT_V(n) asm volatile("s_waitcnt vmcnt(" #n ")" ::: "memory")
; #define PG8_WAIT_L(n) asm volatile("s_waitcnt lgkmcnt(" #n ")" ::: "memory")
; #define PG8_BAR __builtin_amdgcn_s_barrier()
; #define PG8_SCHED __builtin_amdgcn_sched_barrier(0)
; template <class Epi, class Sched, bool ALIGN_EPI = false, bool SP2 = false>
; __device__ __forceinline__ void gemm_phase(PG8_LAS unsigned char* lds, const Gemm g, const Sched& S, const Epi& E) {
;     ...
;             PG8_LDB(B0, 1, 0); PG8_LDB(B1, 1, 1); PG8_SCHED; PG8_LDA(At, 1, 0); PG8_STAGE(PG8_SA(0, 1), a2 + hstep, voffA);
;             PG8_WAIT_V(8); PG8_WAIT_L(0); PG8_BAR; PG8_MMA(0, 0, At, B0); PG8_MMA(0, 1, At, B1); PG8_BAR; PG8_SCHED;
;             PG8_LDA(At, 1, 1); PG8_STAGE(PG8_SB(1, 0), b3, voffB); PG8_STAGE(PG8_SB(1, 1), b3 + hstep, voffB); PG8_STAGE(PG8_SA(1, 0), a3, voffA);
;             PG8_WAIT_V(8); PG8_WAIT_L(0); PG8_BAR; PG8_MMA(1, 0, At, B0); PG8_MMA(1, 1, At, B1); PG8_BAR; PG8_SCHED;
;     ...
;         if constexpr (ALIGN_EPI) { if (wr == 0) PG8_BAR; }
	s_add_i32 s48, 0, 0x18000
	s_add_i32 s49, 0, 0x1c000
	v_add_u32_e32 v162, s48, v156
	v_add_u32_e32 v179, s49, v156
	ds_read_b128 v[94:97], v162
	ds_read_b128 v[134:137], v162 offset:1024
	ds_read_b128 v[158:161], v162 offset:2048
	ds_read_b128 v[162:165], v162 offset:3072
	ds_read_b128 v[166:169], v179
	ds_read_b128 v[170:173], v179 offset:1024
	ds_read_b128 v[174:177], v179 offset:2048
	ds_read_b128 v[186:189], v179 offset:3072
	s_add_u32 s28, s28, 0x40000
	s_addc_u32 s29, s29, 0
	s_mov_b32 m0, s38
	ds_read_b128 v[190:193], v157 offset:32768
	ds_read_b128 v[194:197], v157 offset:33792
	ds_read_b128 v[198:201], v157 offset:34816
	ds_read_b128 v[202:205], v157 offset:35840
	ds_read_b128 v[206:209], v157 offset:36864
	ds_read_b128 v[210:213], v157 offset:37888
	ds_read_b128 v[214:217], v157 offset:38912
	ds_read_b128 v[218:221], v157 offset:39936
	global_load_lds_dwordx4 v144, s[28:29]
	v_lshl_add_u64 v[240:241], s[28:29], 0, v[140:141]
	s_mov_b32 m0, s39
	s_nop 0
	global_load_lds_dwordx4 v[240:241], off
	s_waitcnt vmcnt(8) lgkmcnt(0)
	s_barrier
	s_setprio 1
	v_mfma_f32_16x16x32_bf16 v[130:133], v[94:97], v[190:193], v[130:133]
	v_mfma_f32_16x16x32_bf16 v[126:129], v[158:161], v[190:193], v[126:129]
	v_mfma_f32_16x16x32_bf16 v[114:117], v[94:97], v[198:201], v[114:117]
	v_mfma_f32_16x16x32_bf16 v[110:113], v[158:161], v[198:201], v[110:113]
	v_mfma_f32_16x16x32_bf16 v[98:101], v[94:97], v[206:209], v[98:101]
	v_mfma_f32_16x16x32_bf16 v[90:93], v[158:161], v[206:209], v[90:93]
	v_mfma_f32_16x16x32_bf16 v[78:81], v[94:97], v[214:217], v[78:81]
	v_mfma_f32_16x16x32_bf16 v[74:77], v[158:161], v[214:217], v[74:77]
	v_mfma_f32_16x16x32_bf16 v[130:133], v[134:137], v[194:197], v[130:133]
	v_mfma_f32_16x16x32_bf16 v[126:129], v[162:165], v[194:197], v[126:129]
	v_mfma_f32_16x16x32_bf16 v[114:117], v[134:137], v[202:205], v[114:117]
	v_mfma_f32_16x16x32_bf16 v[110:113], v[162:165], v[202:205], v[110:113]
	v_mfma_f32_16x16x32_bf16 v[98:101], v[134:137], v[210:213], v[98:101]
	v_mfma_f32_16x16x32_bf16 v[90:93], v[162:165], v[210:213], v[90:93]
	v_mfma_f32_16x16x32_bf16 v[78:81], v[134:137], v[218:221], v[78:81]
	v_mfma_f32_16x16x32_bf16 v[74:77], v[162:165], v[218:221], v[74:77]
	v_mfma_f32_16x16x32_bf16 v[122:125], v[166:169], v[190:193], v[122:125]
	v_mfma_f32_16x16x32_bf16 v[118:121], v[174:177], v[190:193], v[118:121]
	v_mfma_f32_16x16x32_bf16 v[106:109], v[166:169], v[198:201], v[106:109]
	v_mfma_f32_16x16x32_bf16 v[102:105], v[174:177], v[198:201], v[102:105]
	v_mfma_f32_16x16x32_bf16 v[86:89], v[166:169], v[206:209], v[86:89]
	v_mfma_f32_16x16x32_bf16 v[82:85], v[174:177], v[206:209], v[82:85]
	v_mfma_f32_16x16x32_bf16 v[70:73], v[166:169], v[214:217], v[70:73]
	v_mfma_f32_16x16x32_bf16 v[66:69], v[174:177], v[214:217], v[66:69]
	v_mfma_f32_16x16x32_bf16 v[122:125], v[170:173], v[194:197], v[122:125]
	v_mfma_f32_16x16x32_bf16 v[118:121], v[186:189], v[194:197], v[118:121]
	v_mfma_f32_16x16x32_bf16 v[106:109], v[170:173], v[202:205], v[106:109]
	v_mfma_f32_16x16x32_bf16 v[102:105], v[186:189], v[202:205], v[102:105]
	v_mfma_f32_16x16x32_bf16 v[86:89], v[170:173], v[210:213], v[86:89]
	v_mfma_f32_16x16x32_bf16 v[82:85], v[186:189], v[210:213], v[82:85]
	v_mfma_f32_16x16x32_bf16 v[70:73], v[170:173], v[218:221], v[70:73]
	v_mfma_f32_16x16x32_bf16 v[66:69], v[186:189], v[218:221], v[66:69]
	s_setprio 0
	s_barrier
	s_add_i32 s28, s48, s35
	v_lshl_add_u64 v[154:155], v[154:155], 0, s[80:81]
	s_mov_b32 m0, s28
	ds_read_b128 v[190:193], v157 offset:49152
	ds_read_b128 v[194:197], v157 offset:50176
	ds_read_b128 v[198:201], v157 offset:51200
	ds_read_b128 v[202:205], v157 offset:52224
	ds_read_b128 v[206:209], v157 offset:53248
	ds_read_b128 v[210:213], v157 offset:54272
	ds_read_b128 v[214:217], v157 offset:55296
	ds_read_b128 v[218:221], v157 offset:56320
	global_load_lds_dwordx4 v[154:155], off
	s_add_i32 m0, s28, 0x2000
	s_add_u32 s26, s26, 0x40080
	v_lshl_add_u64 v[154:155], v[180:181], 0, s[80:81]
	s_addc_u32 s27, s27, 0
	s_add_i32 s28, s49, s35
	global_load_lds_dwordx4 v[154:155], off
	s_mov_b32 m0, s28
	s_nop 0
	global_load_lds_dwordx4 v142, s[26:27]
	s_add_i32 m0, s28, 0x2000
	s_nop 0
	global_load_lds_dwordx4 v138, s[26:27]
	v_lshl_add_u64 v[154:155], v[182:183], 0, s[80:81]
	s_mov_b32 m0, s40
	s_nop 0
	global_load_lds_dwordx4 v[154:155], off
	v_lshl_add_u64 v[154:155], v[222:223], 0, s[80:81]
	s_mov_b32 m0, s41
	s_nop 0
	global_load_lds_dwordx4 v[154:155], off
	s_waitcnt vmcnt(8) lgkmcnt(0)
	s_barrier
	s_setprio 1
	v_mfma_f32_16x16x32_bf16 v[62:65], v[94:97], v[190:193], v[62:65]
	v_mfma_f32_16x16x32_bf16 v[58:61], v[158:161], v[190:193], v[58:61]
	v_mfma_f32_16x16x32_bf16 v[50:53], v[94:97], v[198:201], v[50:53]
	v_mfma_f32_16x16x32_bf16 v[42:45], v[158:161], v[198:201], v[42:45]
	v_mfma_f32_16x16x32_bf16 v[34:37], v[94:97], v[206:209], v[34:37]
	v_mfma_f32_16x16x32_bf16 v[26:29], v[158:161], v[206:209], v[26:29]
	v_mfma_f32_16x16x32_bf16 v[18:21], v[94:97], v[214:217], v[18:21]
	v_mfma_f32_16x16x32_bf16 v[10:13], v[158:161], v[214:217], v[10:13]
	v_mfma_f32_16x16x32_bf16 v[62:65], v[134:137], v[194:197], v[62:65]
	v_mfma_f32_16x16x32_bf16 v[58:61], v[162:165], v[194:197], v[58:61]
	v_mfma_f32_16x16x32_bf16 v[50:53], v[134:137], v[202:205], v[50:53]
	v_mfma_f32_16x16x32_bf16 v[42:45], v[162:165], v[202:205], v[42:45]
	v_mfma_f32_16x16x32_bf16 v[34:37], v[134:137], v[210:213], v[34:37]
	v_mfma_f32_16x16x32_bf16 v[26:29], v[162:165], v[210:213], v[26:29]
	v_mfma_f32_16x16x32_bf16 v[18:21], v[134:137], v[218:221], v[18:21]
	v_mfma_f32_16x16x32_bf16 v[10:13], v[162:165], v[218:221], v[10:13]
	v_mfma_f32_16x16x32_bf16 v[54:57], v[166:169], v[190:193], v[54:57]
	v_mfma_f32_16x16x32_bf16 v[46:49], v[174:177], v[190:193], v[46:49]
	v_mfma_f32_16x16x32_bf16 v[38:41], v[166:169], v[198:201], v[38:41]
	v_mfma_f32_16x16x32_bf16 v[30:33], v[174:177], v[198:201], v[30:33]
	v_mfma_f32_16x16x32_bf16 v[22:25], v[166:169], v[206:209], v[22:25]
	v_mfma_f32_16x16x32_bf16 v[14:17], v[174:177], v[206:209], v[14:17]
	v_mfma_f32_16x16x32_bf16 v[6:9], v[166:169], v[214:217], v[6:9]
	v_mfma_f32_16x16x32_bf16 v[2:5], v[174:177], v[214:217], v[2:5]
	v_mfma_f32_16x16x32_bf16 v[54:57], v[170:173], v[194:197], v[54:57]
	v_mfma_f32_16x16x32_bf16 v[46:49], v[186:189], v[194:197], v[46:49]
	v_mfma_f32_16x16x32_bf16 v[38:41], v[170:173], v[202:205], v[38:41]
	v_mfma_f32_16x16x32_bf16 v[30:33], v[186:189], v[202:205], v[30:33]
	v_mfma_f32_16x16x32_bf16 v[22:25], v[170:173], v[210:213], v[22:25]
	v_mfma_f32_16x16x32_bf16 v[14:17], v[186:189], v[210:213], v[14:17]
	v_mfma_f32_16x16x32_bf16 v[6:9], v[170:173], v[218:221], v[6:9]
	v_mfma_f32_16x16x32_bf16 v[2:5], v[186:189], v[218:221], v[2:5]
	s_setprio 0
	s_barrier
	s_add_i32 s47, s47, 2
	s_add_u32 s24, s24, 0x100
	s_addc_u32 s25, s25, 0
	s_add_u32 s45, s45, 0x100
	s_addc_u32 s46, s46, 0
	s_cmp_gt_u32 s47, 13
	s_cbranch_scc0 .LBB0_318
	s_and_b64 vcc, exec, s[6:7]
	s_cbranch_vccz .LBB0_321
	s_barrier

; #define PG8_STAGE(bufoff, gbase, voff) do { _Pragma("unroll") for (int _i = 0; _i < 2; ++_i) \
;         __builtin_amdgcn_global_load_lds((const unsigned*)((const char*)(gbase) + (voff)[_i]), (PG8_LAS unsigned*)(lds + (bufoff) + ldsw + _i * 8192), 16, 0, 0); } while (0)
; #define PG8_LDA(dst, b, h) do { _Pragma("unroll") for (int m = 0; m < 4; ++m) _Pragma("unroll") for (int k = 0; k < 2; ++k) dst[m][k] = *(const PG8_LAS bf16x8*)(lds + PG8_SA(b, h) + aoff + m * 2048 + k * 1024); } while (0)
; #define PG8_LDB(dst, b, h) do { _Pragma("unroll") for (int n = 0; n < 2; ++n) _Pragma("unroll") for (int k = 0; k < 2; ++k) dst[n][k] = *(const PG8_LAS bf16x8*)(lds + PG8_SB(b, h) + boff + n * 2048 + k * 1024); } while (0)
; #define PG8_WAIT_V(n) asm volatile("s_waitcnt vmcnt(" #n ")" ::: "memory")
; #define PG8_WAIT_L(n) asm volatile("s_waitcnt lgkmcnt(" #n ")" ::: "memory")
; #define PG8_BAR __builtin_amdgcn_s_barrier()
; #define PG8_SCHED __builtin_amdgcn_sched_barrier(0)
; template <class Epi, class Sched, bool ALIGN_EPI = false, bool SP2 = false>
; __device__ __forceinline__ void gemm_phase(PG8_LAS unsigned char* lds, const Gemm g, const Sched& S, const Epi& E) {
;     ...
;         const bool has_next = S.next(ui + 1, nxt);
;         const char* nA = has_next ? (const char*)g.A + (size_t)nxt.pm * tstep : cA; const char* nB = has_next ? (const char*)g.Bt + (size_t)nxt.pn * tstep : cB;
;         for (int t = 0; t < nt; t += 2) {
;             const bool last = (t == nt - 2);
;             const char* a1 = cA + (size_t)(t + 1) * kstep;
;             const char* a2 = last ? nA : cA + (size_t)(t + 2) * kstep; const char* b2 = last ? nB : cB + (size_t)(t + 2) * kstep;
;             const char* a3 = a2 + kstep; const char* b3 = b2 + kstep;
;             if (last && has_next) S.a_ready(nxt);
;             if constexpr (SP2) {
;             PG8_LDB(B0, 0, 0); PG8_LDB(B1, 0, 1); PG8_SCHED; PG8_LDA(At, 0, 0); PG8_STAGE(PG8_SA(1, 1), a1 + hstep, voffA);
;             PG8_WAIT_V(8); PG8_WAIT_L(0); PG8_BAR; PG8_MMA(0, 0, At, B0); PG8_MMA(0, 1, At, B1); PG8_BAR; PG8_SCHED;
;             PG8_LDA(At, 0, 1); PG8_STAGE(PG8_SB(0, 0), b2, voffB); PG8_STAGE(PG8_SB(0, 1), b2 + hstep, voffB); PG8_STAGE(PG8_SA(0, 0), a2, voffA);
;             PG8_WAIT_V(8); PG8_WAIT_L(0); PG8_BAR; PG8_MMA(1, 0, At, B0); PG8_MMA(1, 1, At, B1); PG8_BAR; PG8_SCHED;
.LBB0_1061:
	s_ashr_i32 s23, s22, 31
	s_lshl_b64 s[24:25], s[22:23], 19
	s_add_u32 s24, s42, s24
	s_addc_u32 s25, s43, s25
	s_and_b64 s[26:27], s[6:7], exec
	s_cselect_b32 s23, s25, s35
	s_cselect_b32 s29, s24, s34
	s_ashr_i32 s21, s20, 31
	s_lshl_b64 s[26:27], s[20:21], 19
	s_add_u32 s26, s40, s26
	s_addc_u32 s27, s41, s27
	s_and_b64 s[38:39], s[6:7], exec
	s_cselect_b32 s21, s27, s37
	s_cselect_b32 s31, s26, s36
	s_add_u32 s34, s34, 0x40080
	s_addc_u32 s35, s35, 0
	s_add_u32 s56, s36, 0x100
	s_addc_u32 s57, s37, 0
	s_mov_b32 s58, -2
	s_waitcnt lgkmcnt(0)
	s_add_u32 s36, s34, 0xfffc0080
	s_addc_u32 s37, s35, -1
	s_add_i32 s59, 0, 0x10000
	s_cmp_eq_u32 s58, 12
	s_cselect_b32 s39, s23, s37
	s_cselect_b32 s38, s29, s36
	s_cselect_b32 s37, s21, s57
	s_cselect_b32 s36, s31, s56
	s_add_i32 s62, 0, 0x14000
	v_add_u32_e32 v142, s59, v179
	v_add_u32_e32 v170, s62, v179
	ds_read_b128 v[130:133], v142
	ds_read_b128 v[134:137], v142 offset:1024
	ds_read_b128 v[138:141], v142 offset:2048
	ds_read_b128 v[142:145], v142 offset:3072
	ds_read_b128 v[146:149], v170
	ds_read_b128 v[150:153], v170 offset:1024
	ds_read_b128 v[166:169], v170 offset:2048
	ds_read_b128 v[170:173], v170 offset:3072
	s_add_i32 m0, s46, 0xc000
	ds_read_b128 v[174:177], v187
	ds_read_b128 v[180:183], v187 offset:1024
	ds_read_b128 v[188:191], v187 offset:2048
	ds_read_b128 v[192:195], v187 offset:3072
	ds_read_b128 v[196:199], v187 offset:4096
	ds_read_b128 v[200:203], v187 offset:5120
	ds_read_b128 v[204:207], v187 offset:6144
	ds_read_b128 v[208:211], v187 offset:7168
	global_load_lds_dwordx4 v162, s[34:35]
	s_add_i32 m0, s46, 0xe000
	s_nop 0
	global_load_lds_dwordx4 v164, s[34:35]
	s_waitcnt vmcnt(8) lgkmcnt(0)
	s_barrier
	s_setprio 1
	v_mfma_f32_16x16x32_bf16 v[126:129], v[130:133], v[174:177], 0
	v_mfma_f32_16x16x32_bf16 v[122:125], v[138:141], v[174:177], 0
	v_mfma_f32_16x16x32_bf16 v[110:113], v[130:133], v[188:191], 0
	v_mfma_f32_16x16x32_bf16 v[106:109], v[138:141], v[188:191], 0
	v_mfma_f32_16x16x32_bf16 v[94:97], v[130:133], v[196:199], 0
	v_mfma_f32_16x16x32_bf16 v[90:93], v[138:141], v[196:199], 0
	v_mfma_f32_16x16x32_bf16 v[78:81], v[130:133], v[204:207], 0
	v_mfma_f32_16x16x32_bf16 v[74:77], v[138:141], v[204:207], 0
	v_mfma_f32_16x16x32_bf16 v[126:129], v[134:137], v[180:183], v[126:129]
	v_mfma_f32_16x16x32_bf16 v[122:125], v[142:145], v[180:183], v[122:125]
	v_mfma_f32_16x16x32_bf16 v[110:113], v[134:137], v[192:195], v[110:113]
	v_mfma_f32_16x16x32_bf16 v[106:109], v[142:145], v[192:195], v[106:109]
	v_mfma_f32_16x16x32_bf16 v[94:97], v[134:137], v[200:203], v[94:97]
	v_mfma_f32_16x16x32_bf16 v[90:93], v[142:145], v[200:203], v[90:93]
	v_mfma_f32_16x16x32_bf16 v[78:81], v[134:137], v[208:211], v[78:81]
	v_mfma_f32_16x16x32_bf16 v[74:77], v[142:145], v[208:211], v[74:77]
	v_mfma_f32_16x16x32_bf16 v[118:121], v[146:149], v[174:177], 0
	v_mfma_f32_16x16x32_bf16 v[114:117], v[166:169], v[174:177], 0
	v_mfma_f32_16x16x32_bf16 v[102:105], v[146:149], v[188:191], 0
	v_mfma_f32_16x16x32_bf16 v[98:101], v[166:169], v[188:191], 0
	v_mfma_f32_16x16x32_bf16 v[86:89], v[146:149], v[196:199], 0
	v_mfma_f32_16x16x32_bf16 v[82:85], v[166:169], v[196:199], 0
	v_mfma_f32_16x16x32_bf16 v[70:73], v[146:149], v[204:207], 0
	v_mfma_f32_16x16x32_bf16 v[66:69], v[166:169], v[204:207], 0
	v_mfma_f32_16x16x32_bf16 v[118:121], v[150:153], v[180:183], v[118:121]
	v_mfma_f32_16x16x32_bf16 v[114:117], v[170:173], v[180:183], v[114:117]
	v_mfma_f32_16x16x32_bf16 v[102:105], v[150:153], v[192:195], v[102:105]
	v_mfma_f32_16x16x32_bf16 v[98:101], v[170:173], v[192:195], v[98:101]
	v_mfma_f32_16x16x32_bf16 v[86:89], v[150:153], v[200:203], v[86:89]
	v_mfma_f32_16x16x32_bf16 v[82:85], v[170:173], v[200:203], v[82:85]
	v_mfma_f32_16x16x32_bf16 v[70:73], v[150:153], v[208:211], v[70:73]
	v_mfma_f32_16x16x32_bf16 v[66:69], v[170:173], v[208:211], v[66:69]
	s_setprio 0
	s_barrier
	s_add_i32 s59, s59, s33
	v_lshl_add_u64 v[212:213], s[36:37], 0, v[156:157]
	s_mov_b32 m0, s59
	ds_read_b128 v[174:177], v187 offset:16384
	ds_read_b128 v[180:183], v187 offset:17408
	ds_read_b128 v[188:191], v187 offset:18432
	ds_read_b128 v[192:195], v187 offset:19456
	ds_read_b128 v[196:199], v187 offset:20480
	ds_read_b128 v[200:203], v187 offset:21504
	ds_read_b128 v[204:207], v187 offset:22528
	ds_read_b128 v[208:211], v187 offset:23552
	global_load_lds_dwordx4 v[212:213], off
	s_add_i32 m0, s59, 0x2000
	s_add_u32 s60, s36, 0x40000
	v_lshl_add_u64 v[214:215], s[36:37], 0, v[160:161]
	s_addc_u32 s61, s37, 0
	s_add_i32 s59, s62, s33
	global_load_lds_dwordx4 v[214:215], off
	v_lshl_add_u64 v[216:217], s[60:61], 0, v[156:157]
	s_mov_b32 m0, s59
	v_lshl_add_u64 v[218:219], s[38:39], 0, v[158:159]
	global_load_lds_dwordx4 v[216:217], off
	s_add_i32 m0, s59, 0x2000
	s_nop 0
	global_load_lds_dwordx4 v160, s[60:61]
	v_lshl_add_u64 v[216:217], s[38:39], 0, v[154:155]
	s_mov_b32 m0, s46
	s_nop 0
	global_load_lds_dwordx4 v[216:217], off
	s_mov_b32 m0, s47
	s_nop 0
	global_load_lds_dwordx4 v[218:219], off
	s_waitcnt vmcnt(8) lgkmcnt(0)
	s_barrier
; #define PG8_STAGE(bufoff, gbase, voff) do { _Pragma("unroll") for (int _i = 0; _i < 2; ++_i) \
;         __builtin_amdgcn_global_load_lds((const unsigned*)((const char*)(gbase) + (voff)[_i]), (PG8_LAS unsigned*)(lds + (bufoff) + ldsw + _i * 8192), 16, 0, 0); } while (0)
; #define PG8_LDA(dst, b, h) do { _Pragma("unroll") for (int m = 0; m < 4; ++m) _Pragma("unroll") for (int k = 0; k < 2; ++k) dst[m][k] = *(const PG8_LAS bf16x8*)(lds + PG8_SA(b, h) + aoff + m * 2048 + k * 1024); } while (0)
; #define PG8_LDB(dst, b, h) do { _Pragma("unroll") for (int n = 0; n < 2; ++n) _Pragma("unroll") for (int k = 0; k < 2; ++k) dst[n][k] = *(const PG8_LAS bf16x8*)(lds + PG8_SB(b, h) + boff + n * 2048 + k * 1024); } while (0)
; #define PG8_MMA(ai, bj, At, Bt) do { __builtin_amdgcn_s_setprio(1); _Pragma("unroll") for (int m = 0; m < 4; ++m) _Pragma("unroll") for (int n = 0; n < 2; ++n) _Pragma("unroll") for (int k = 0; k < 2; ++k) \
;         acc[ai][bj][m][n] = __builtin_amdgcn_mfma_f32_16x16x32_bf16(Bt[n][k], At[m][k], acc[ai][bj][m][n], 0, 0, 0); __builtin_amdgcn_s_setprio(0); } while (0)
; #define PG8_WAIT_V(n) asm volatile("s_waitcnt vmcnt(" #n ")" ::: "memory")
; #define PG8_WAIT_L(n) asm volatile("s_waitcnt lgkmcnt(" #n ")" ::: "memory")
; #define PG8_BAR __builtin_amdgcn_s_barrier()
; #define PG8_SCHED __builtin_amdgcn_sched_barrier(0)
; template <class Epi, class Sched, bool ALIGN_EPI = false, bool SP2 = false>
; __device__ __forceinline__ void gemm_phase(PG8_LAS unsigned char* lds, const Gemm g, const Sched& S, const Epi& E) {
;     ...
;             PG8_WAIT_V(8); PG8_WAIT_L(0); PG8_BAR; PG8_MMA(1, 0, At, B0); PG8_MMA(1, 1, At, B1); PG8_BAR; PG8_SCHED;
;             PG8_LDB(B0, 1, 0); PG8_LDB(B1, 1, 1); PG8_SCHED; PG8_LDA(At, 1, 0); PG8_STAGE(PG8_SA(0, 1), a2 + hstep, voffA);
;             PG8_WAIT_V(8); PG8_WAIT_L(0); PG8_BAR; PG8_MMA(0, 0, At, B0); PG8_MMA(0, 1, At, B1); PG8_BAR; PG8_SCHED;
	s_setprio 1
	v_mfma_f32_16x16x32_bf16 v[62:65], v[130:133], v[174:177], 0
	v_mfma_f32_16x16x32_bf16 v[58:61], v[138:141], v[174:177], 0
	v_mfma_f32_16x16x32_bf16 v[46:49], v[130:133], v[188:191], 0
	v_mfma_f32_16x16x32_bf16 v[42:45], v[138:141], v[188:191], 0
	v_mfma_f32_16x16x32_bf16 v[30:33], v[130:133], v[196:199], 0
	v_mfma_f32_16x16x32_bf16 v[26:29], v[138:141], v[196:199], 0
	v_mfma_f32_16x16x32_bf16 v[14:17], v[130:133], v[204:207], 0
	v_mfma_f32_16x16x32_bf16 v[10:13], v[138:141], v[204:207], 0
	v_mfma_f32_16x16x32_bf16 v[62:65], v[134:137], v[180:183], v[62:65]
	v_mfma_f32_16x16x32_bf16 v[58:61], v[142:145], v[180:183], v[58:61]
	v_mfma_f32_16x16x32_bf16 v[46:49], v[134:137], v[192:195], v[46:49]
	v_mfma_f32_16x16x32_bf16 v[42:45], v[142:145], v[192:195], v[42:45]
	v_mfma_f32_16x16x32_bf16 v[30:33], v[134:137], v[200:203], v[30:33]
	v_mfma_f32_16x16x32_bf16 v[26:29], v[142:145], v[200:203], v[26:29]
	v_mfma_f32_16x16x32_bf16 v[14:17], v[134:137], v[208:211], v[14:17]
	v_mfma_f32_16x16x32_bf16 v[10:13], v[142:145], v[208:211], v[10:13]
	v_mfma_f32_16x16x32_bf16 v[54:57], v[146:149], v[174:177], 0
	v_mfma_f32_16x16x32_bf16 v[50:53], v[166:169], v[174:177], 0
	v_mfma_f32_16x16x32_bf16 v[38:41], v[146:149], v[188:191], 0
	v_mfma_f32_16x16x32_bf16 v[34:37], v[166:169], v[188:191], 0
	v_mfma_f32_16x16x32_bf16 v[22:25], v[146:149], v[196:199], 0
	v_mfma_f32_16x16x32_bf16 v[18:21], v[166:169], v[196:199], 0
	v_mfma_f32_16x16x32_bf16 v[6:9], v[146:149], v[204:207], 0
	v_mfma_f32_16x16x32_bf16 v[2:5], v[166:169], v[204:207], 0
	v_mfma_f32_16x16x32_bf16 v[54:57], v[150:153], v[180:183], v[54:57]
	v_mfma_f32_16x16x32_bf16 v[50:53], v[170:173], v[180:183], v[50:53]
	v_mfma_f32_16x16x32_bf16 v[38:41], v[150:153], v[192:195], v[38:41]
	v_mfma_f32_16x16x32_bf16 v[34:37], v[170:173], v[192:195], v[34:37]
	v_mfma_f32_16x16x32_bf16 v[22:25], v[150:153], v[200:203], v[22:25]
	v_mfma_f32_16x16x32_bf16 v[18:21], v[170:173], v[200:203], v[18:21]
	v_mfma_f32_16x16x32_bf16 v[6:9], v[150:153], v[208:211], v[6:9]
	v_mfma_f32_16x16x32_bf16 v[2:5], v[170:173], v[208:211], v[2:5]
	s_setprio 0
	s_barrier
	s_add_i32 s59, 0, 0x18000
	s_add_i32 s60, 0, 0x1c000
	v_add_u32_e32 v142, s59, v179
	v_add_u32_e32 v170, s60, v179
	ds_read_b128 v[130:133], v142
	ds_read_b128 v[134:137], v142 offset:1024
	ds_read_b128 v[138:141], v142 offset:2048
	ds_read_b128 v[142:145], v142 offset:3072
	ds_read_b128 v[146:149], v170
	ds_read_b128 v[150:153], v170 offset:1024
	ds_read_b128 v[166:169], v170 offset:2048
	ds_read_b128 v[170:173], v170 offset:3072
	s_add_u32 s38, s38, 0x40000
	s_addc_u32 s39, s39, 0
	s_mov_b32 m0, s48
	ds_read_b128 v[174:177], v187 offset:32768
	ds_read_b128 v[180:183], v187 offset:33792
	ds_read_b128 v[188:191], v187 offset:34816
	ds_read_b128 v[192:195], v187 offset:35840
	ds_read_b128 v[196:199], v187 offset:36864
	ds_read_b128 v[200:203], v187 offset:37888
	ds_read_b128 v[204:207], v187 offset:38912
	ds_read_b128 v[208:211], v187 offset:39936
	global_load_lds_dwordx4 v154, s[38:39]
	v_lshl_add_u64 v[220:221], s[38:39], 0, v[158:159]
	s_mov_b32 m0, s49
	s_nop 0
	global_load_lds_dwordx4 v[220:221], off
	s_waitcnt vmcnt(8) lgkmcnt(0)
	s_barrier
	s_setprio 1
	v_mfma_f32_16x16x32_bf16 v[126:129], v[130:133], v[174:177], v[126:129]
	v_mfma_f32_16x16x32_bf16 v[122:125], v[138:141], v[174:177], v[122:125]
	v_mfma_f32_16x16x32_bf16 v[110:113], v[130:133], v[188:191], v[110:113]
	v_mfma_f32_16x16x32_bf16 v[106:109], v[138:141], v[188:191], v[106:109]
	v_mfma_f32_16x16x32_bf16 v[94:97], v[130:133], v[196:199], v[94:97]
	v_mfma_f32_16x16x32_bf16 v[90:93], v[138:141], v[196:199], v[90:93]
	v_mfma_f32_16x16x32_bf16 v[78:81], v[130:133], v[204:207], v[78:81]
	v_mfma_f32_16x16x32_bf16 v[74:77], v[138:141], v[204:207], v[74:77]
	v_mfma_f32_16x16x32_bf16 v[126:129], v[134:137], v[180:183], v[126:129]
	v_mfma_f32_16x16x32_bf16 v[122:125], v[142:145], v[180:183], v[122:125]
	v_mfma_f32_16x16x32_bf16 v[110:113], v[134:137], v[192:195], v[110:113]
	v_mfma_f32_16x16x32_bf16 v[106:109], v[142:145], v[192:195], v[106:109]
	v_mfma_f32_16x16x32_bf16 v[94:97], v[134:137], v[200:203], v[94:97]
	v_mfma_f32_16x16x32_bf16 v[90:93], v[142:145], v[200:203], v[90:93]
	v_mfma_f32_16x16x32_bf16 v[78:81], v[134:137], v[208:211], v[78:81]
	v_mfma_f32_16x16x32_bf16 v[74:77], v[142:145], v[208:211], v[74:77]
	v_mfma_f32_16x16x32_bf16 v[118:121], v[146:149], v[174:177], v[118:121]
	v_mfma_f32_16x16x32_bf16 v[114:117], v[166:169], v[174:177], v[114:117]
	v_mfma_f32_16x16x32_bf16 v[102:105], v[146:149], v[188:191], v[102:105]
	v_mfma_f32_16x16x32_bf16 v[98:101], v[166:169], v[188:191], v[98:101]
	v_mfma_f32_16x16x32_bf16 v[86:89], v[146:149], v[196:199], v[86:89]
	v_mfma_f32_16x16x32_bf16 v[82:85], v[166:169], v[196:199], v[82:85]
	v_mfma_f32_16x16x32_bf16 v[70:73], v[146:149], v[204:207], v[70:73]
	v_mfma_f32_16x16x32_bf16 v[66:69], v[166:169], v[204:207], v[66:69]
	v_mfma_f32_16x16x32_bf16 v[118:121], v[150:153], v[180:183], v[118:121]
	v_mfma_f32_16x16x32_bf16 v[114:117], v[170:173], v[180:183], v[114:117]
	v_mfma_f32_16x16x32_bf16 v[102:105], v[150:153], v[192:195], v[102:105]
	v_mfma_f32_16x16x32_bf16 v[98:101], v[170:173], v[192:195], v[98:101]
	v_mfma_f32_16x16x32_bf16 v[86:89], v[150:153], v[200:203], v[86:89]
	v_mfma_f32_16x16x32_bf16 v[82:85], v[170:173], v[200:203], v[82:85]
	v_mfma_f32_16x16x32_bf16 v[70:73], v[150:153], v[208:211], v[70:73]
	v_mfma_f32_16x16x32_bf16 v[66:69], v[170:173], v[208:211], v[66:69]
	s_setprio 0
	s_barrier
; #define PG8_STAGE(bufoff, gbase, voff) do { _Pragma("unroll") for (int _i = 0; _i < 2; ++_i) \
;         __builtin_amdgcn_global_load_lds((const unsigned*)((const char*)(gbase) + (voff)[_i]), (PG8_LAS unsigned*)(lds + (bufoff) + ldsw + _i * 8192), 16, 0, 0); } while (0)
; #define PG8_LDA(dst, b, h) do { _Pragma("unroll") for (int m = 0; m < 4; ++m) _Pragma("unroll") for (int k = 0; k < 2; ++k) dst[m][k] = *(const PG8_LAS bf16x8*)(lds + PG8_SA(b, h) + aoff + m * 2048 + k * 1024); } while (0)
; #define PG8_LDB(dst, b, h) do { _Pragma("unroll") for (int n = 0; n < 2; ++n) _Pragma("unroll") for (int k = 0; k < 2; ++k) dst[n][k] = *(const PG8_LAS bf16x8*)(lds + PG8_SB(b, h) + boff + n * 2048 + k * 1024); } while (0)
; template <class Epi, class Sched, bool ALIGN_EPI = false, bool SP2 = false>
; __device__ __forceinline__ void gemm_phase(PG8_LAS unsigned char* lds, const Gemm g, const Sched& S, const Epi& E) {
;     ...
;         for (int t = 0; t < nt; t += 2) {
;             const bool last = (t == nt - 2);
;             const char* a1 = cA + (size_t)(t + 1) * kstep;
;             const char* a2 = last ? nA : cA + (size_t)(t + 2) * kstep; const char* b2 = last ? nB : cB + (size_t)(t + 2) * kstep;
;             const char* a3 = a2 + kstep; const char* b3 = b2 + kstep;
;             if (last && has_next) S.a_ready(nxt);
;             if constexpr (SP2) {
;             PG8_LDB(B0, 0, 0); PG8_LDB(B1, 0, 1); PG8_SCHED; PG8_LDA(At, 0, 0); PG8_STAGE(PG8_SA(1, 1), a1 + hstep, voffA);
;             PG8_WAIT_V(8); PG8_WAIT_L(0); PG8_BAR; PG8_MMA(0, 0, At, B0); PG8_MMA(0, 1, At, B1); PG8_BAR; PG8_SCHED;
;             PG8_LDA(At, 0, 1); PG8_STAGE(PG8_SB(0, 0), b2, voffB); PG8_STAGE(PG8_SB(0, 1), b2 + hstep, voffB); PG8_STAGE(PG8_SA(0, 0), a2, voffA);
;             PG8_WAIT_V(8); PG8_WAIT_L(0); PG8_BAR; PG8_MMA(1, 0, At, B0); PG8_MMA(1, 1, At, B1); PG8_BAR; PG8_SCHED;
;             PG8_LDB(B0, 1, 0); PG8_LDB(B1, 1, 1); PG8_SCHED; PG8_LDA(At, 1, 0); PG8_STAGE(PG8_SA(0, 1), a2 + hstep, voffA);
;             PG8_WAIT_V(8); PG8_WAIT_L(0); PG8_BAR; PG8_MMA(0, 0, At, B0); PG8_MMA(0, 1, At, B1); PG8_BAR; PG8_SCHED;
;             PG8_LDA(At, 1, 1); PG8_STAGE(PG8_SB(1, 0), b3, voffB); PG8_STAGE(PG8_SB(1, 1), b3 + hstep, voffB); PG8_STAGE(PG8_SA(1, 0), a3, voffA);
;             PG8_WAIT_V(8); PG8_WAIT_L(0); PG8_BAR; PG8_MMA(1, 0, At, B0); PG8_MMA(1, 1, At, B1); PG8_BAR; PG8_SCHED;
	s_add_i32 s38, s59, s33
	v_lshl_add_u64 v[212:213], v[212:213], 0, s[80:81]
	s_mov_b32 m0, s38
	ds_read_b128 v[174:177], v187 offset:49152
	ds_read_b128 v[180:183], v187 offset:50176
	ds_read_b128 v[188:191], v187 offset:51200
	ds_read_b128 v[192:195], v187 offset:52224
	ds_read_b128 v[196:199], v187 offset:53248
	ds_read_b128 v[200:203], v187 offset:54272
	ds_read_b128 v[204:207], v187 offset:55296
	ds_read_b128 v[208:211], v187 offset:56320
	global_load_lds_dwordx4 v[212:213], off
	s_add_i32 m0, s38, 0x2000
	s_add_u32 s36, s36, 0x40080
	v_lshl_add_u64 v[212:213], v[214:215], 0, s[80:81]
	s_addc_u32 s37, s37, 0
	s_add_i32 s38, s60, s33
	global_load_lds_dwordx4 v[212:213], off
	s_mov_b32 m0, s38
	s_nop 0
	global_load_lds_dwordx4 v156, s[36:37]
	s_add_i32 m0, s38, 0x2000
	s_nop 0
	global_load_lds_dwordx4 v160, s[36:37]
	v_lshl_add_u64 v[212:213], v[216:217], 0, s[80:81]
	s_mov_b32 m0, s51
	s_nop 0
	global_load_lds_dwordx4 v[212:213], off
	v_lshl_add_u64 v[212:213], v[218:219], 0, s[80:81]
	s_mov_b32 m0, s52
	s_nop 0
	global_load_lds_dwordx4 v[212:213], off
	s_waitcnt vmcnt(8) lgkmcnt(0)
	s_barrier
	s_setprio 1
	v_mfma_f32_16x16x32_bf16 v[62:65], v[130:133], v[174:177], v[62:65]
	v_mfma_f32_16x16x32_bf16 v[58:61], v[138:141], v[174:177], v[58:61]
	v_mfma_f32_16x16x32_bf16 v[46:49], v[130:133], v[188:191], v[46:49]
	v_mfma_f32_16x16x32_bf16 v[42:45], v[138:141], v[188:191], v[42:45]
	v_mfma_f32_16x16x32_bf16 v[30:33], v[130:133], v[196:199], v[30:33]
	v_mfma_f32_16x16x32_bf16 v[26:29], v[138:141], v[196:199], v[26:29]
	v_mfma_f32_16x16x32_bf16 v[14:17], v[130:133], v[204:207], v[14:17]
	v_mfma_f32_16x16x32_bf16 v[10:13], v[138:141], v[204:207], v[10:13]
	v_mfma_f32_16x16x32_bf16 v[62:65], v[134:137], v[180:183], v[62:65]
	v_mfma_f32_16x16x32_bf16 v[58:61], v[142:145], v[180:183], v[58:61]
	v_mfma_f32_16x16x32_bf16 v[46:49], v[134:137], v[192:195], v[46:49]
	v_mfma_f32_16x16x32_bf16 v[42:45], v[142:145], v[192:195], v[42:45]
	v_mfma_f32_16x16x32_bf16 v[30:33], v[134:137], v[200:203], v[30:33]
	v_mfma_f32_16x16x32_bf16 v[26:29], v[142:145], v[200:203], v[26:29]
	v_mfma_f32_16x16x32_bf16 v[14:17], v[134:137], v[208:211], v[14:17]
	v_mfma_f32_16x16x32_bf16 v[10:13], v[142:145], v[208:211], v[10:13]
	v_mfma_f32_16x16x32_bf16 v[54:57], v[146:149], v[174:177], v[54:57]
	v_mfma_f32_16x16x32_bf16 v[50:53], v[166:169], v[174:177], v[50:53]
	v_mfma_f32_16x16x32_bf16 v[38:41], v[146:149], v[188:191], v[38:41]
	v_mfma_f32_16x16x32_bf16 v[34:37], v[166:169], v[188:191], v[34:37]
	v_mfma_f32_16x16x32_bf16 v[22:25], v[146:149], v[196:199], v[22:25]
	v_mfma_f32_16x16x32_bf16 v[18:21], v[166:169], v[196:199], v[18:21]
	v_mfma_f32_16x16x32_bf16 v[6:9], v[146:149], v[204:207], v[6:9]
	v_mfma_f32_16x16x32_bf16 v[2:5], v[166:169], v[204:207], v[2:5]
	v_mfma_f32_16x16x32_bf16 v[54:57], v[150:153], v[180:183], v[54:57]
	v_mfma_f32_16x16x32_bf16 v[50:53], v[170:173], v[180:183], v[50:53]
	v_mfma_f32_16x16x32_bf16 v[38:41], v[150:153], v[192:195], v[38:41]
	v_mfma_f32_16x16x32_bf16 v[34:37], v[170:173], v[192:195], v[34:37]
	v_mfma_f32_16x16x32_bf16 v[22:25], v[150:153], v[200:203], v[22:25]
	v_mfma_f32_16x16x32_bf16 v[18:21], v[170:173], v[200:203], v[18:21]
	v_mfma_f32_16x16x32_bf16 v[6:9], v[150:153], v[208:211], v[6:9]
	v_mfma_f32_16x16x32_bf16 v[2:5], v[170:173], v[208:211], v[2:5]
	s_setprio 0
	s_barrier
	s_add_i32 s58, s58, 2
	s_add_u32 s34, s34, 0x100
	s_addc_u32 s35, s35, 0
	s_add_u32 s56, s56, 0x100
	s_addc_u32 s57, s57, 0
	s_cmp_gt_u32 s58, 13
	s_branch .LBB0_1062
.LBB0_1062:
	s_add_u32 s36, s34, 0xfffc0080
	s_addc_u32 s37, s35, -1
	s_add_i32 s59, 0, 0x10000
	s_cmp_eq_u32 s58, 12
	s_cselect_b32 s39, s23, s37
	s_cselect_b32 s38, s29, s36
	s_cselect_b32 s37, s21, s57
	s_cselect_b32 s36, s31, s56
	s_add_i32 s62, 0, 0x14000
	v_add_u32_e32 v142, s59, v179
	v_add_u32_e32 v170, s62, v179
	ds_read_b128 v[130:133], v142
	ds_read_b128 v[134:137], v142 offset:1024
	ds_read_b128 v[138:141], v142 offset:2048
	ds_read_b128 v[142:145], v142 offset:3072
	ds_read_b128 v[146:149], v170
	ds_read_b128 v[150:153], v170 offset:1024
	ds_read_b128 v[166:169], v170 offset:2048
	ds_read_b128 v[170:173], v170 offset:3072
	s_add_i32 m0, s46, 0xc000
	ds_read_b128 v[174:177], v187
	ds_read_b128 v[180:183], v187 offset:1024
	ds_read_b128 v[188:191], v187 offset:2048
	ds_read_b128 v[192:195], v187 offset:3072
	ds_read_b128 v[196:199], v187 offset:4096
	ds_read_b128 v[200:203], v187 offset:5120
	ds_read_b128 v[204:207], v187 offset:6144
	ds_read_b128 v[208:211], v187 offset:7168
	global_load_lds_dwordx4 v162, s[34:35]
	s_add_i32 m0, s46, 0xe000
	s_nop 0
	global_load_lds_dwordx4 v164, s[34:35]
	s_waitcnt vmcnt(8) lgkmcnt(0)
	s_barrier
; #define PG8_STAGE(bufoff, gbase, voff) do { _Pragma("unroll") for (int _i = 0; _i < 2; ++_i) \
;         __builtin_amdgcn_global_load_lds((const unsigned*)((const char*)(gbase) + (voff)[_i]), (PG8_LAS unsigned*)(lds + (bufoff) + ldsw + _i * 8192), 16, 0, 0); } while (0)
; #define PG8_LDA(dst, b, h) do { _Pragma("unroll") for (int m = 0; m < 4; ++m) _Pragma("unroll") for (int k = 0; k < 2; ++k) dst[m][k] = *(const PG8_LAS bf16x8*)(lds + PG8_SA(b, h) + aoff + m * 2048 + k * 1024); } while (0)
; #define PG8_LDB(dst, b, h) do { _Pragma("unroll") for (int n = 0; n < 2; ++n) _Pragma("unroll") for (int k = 0; k < 2; ++k) dst[n][k] = *(const PG8_LAS bf16x8*)(lds + PG8_SB(b, h) + boff + n * 2048 + k * 1024); } while (0)
; #define PG8_MMA(ai, bj, At, Bt) do { __builtin_amdgcn_s_setprio(1); _Pragma("unroll") for (int m = 0; m < 4; ++m) _Pragma("unroll") for (int n = 0; n < 2; ++n) _Pragma("unroll") for (int k = 0; k < 2; ++k) \
;         acc[ai][bj][m][n] = __builtin_amdgcn_mfma_f32_16x16x32_bf16(Bt[n][k], At[m][k], acc[ai][bj][m][n], 0, 0, 0); __builtin_amdgcn_s_setprio(0); } while (0)
; #define PG8_WAIT_V(n) asm volatile("s_waitcnt vmcnt(" #n ")" ::: "memory")
; #define PG8_WAIT_L(n) asm volatile("s_waitcnt lgkmcnt(" #n ")" ::: "memory")
; #define PG8_BAR __builtin_amdgcn_s_barrier()
; #define PG8_SCHED __builtin_amdgcn_sched_barrier(0)
; template <class Epi, class Sched, bool ALIGN_EPI = false, bool SP2 = false>
; __device__ __forceinline__ void gemm_phase(PG8_LAS unsigned char* lds, const Gemm g, const Sched& S, const Epi& E) {
;     ...
;             PG8_LDB(B0, 0, 0); PG8_LDB(B1, 0, 1); PG8_SCHED; PG8_LDA(At, 0, 0); PG8_STAGE(PG8_SA(1, 1), a1 + hstep, voffA);
;             PG8_WAIT_V(8); PG8_WAIT_L(0); PG8_BAR; PG8_MMA(0, 0, At, B0); PG8_MMA(0, 1, At, B1); PG8_BAR; PG8_SCHED;
;             PG8_LDA(At, 0, 1); PG8_STAGE(PG8_SB(0, 0), b2, voffB); PG8_STAGE(PG8_SB(0, 1), b2 + hstep, voffB); PG8_STAGE(PG8_SA(0, 0), a2, voffA);
;             PG8_WAIT_V(8); PG8_WAIT_L(0); PG8_BAR; PG8_MMA(1, 0, At, B0); PG8_MMA(1, 1, At, B1); PG8_BAR; PG8_SCHED;
	s_setprio 1
	v_mfma_f32_16x16x32_bf16 v[126:129], v[130:133], v[174:177], v[126:129]
	v_mfma_f32_16x16x32_bf16 v[122:125], v[138:141], v[174:177], v[122:125]
	v_mfma_f32_16x16x32_bf16 v[110:113], v[130:133], v[188:191], v[110:113]
	v_mfma_f32_16x16x32_bf16 v[106:109], v[138:141], v[188:191], v[106:109]
	v_mfma_f32_16x16x32_bf16 v[94:97], v[130:133], v[196:199], v[94:97]
	v_mfma_f32_16x16x32_bf16 v[90:93], v[138:141], v[196:199], v[90:93]
	v_mfma_f32_16x16x32_bf16 v[78:81], v[130:133], v[204:207], v[78:81]
	v_mfma_f32_16x16x32_bf16 v[74:77], v[138:141], v[204:207], v[74:77]
	v_mfma_f32_16x16x32_bf16 v[126:129], v[134:137], v[180:183], v[126:129]
	v_mfma_f32_16x16x32_bf16 v[122:125], v[142:145], v[180:183], v[122:125]
	v_mfma_f32_16x16x32_bf16 v[110:113], v[134:137], v[192:195], v[110:113]
	v_mfma_f32_16x16x32_bf16 v[106:109], v[142:145], v[192:195], v[106:109]
	v_mfma_f32_16x16x32_bf16 v[94:97], v[134:137], v[200:203], v[94:97]
	v_mfma_f32_16x16x32_bf16 v[90:93], v[142:145], v[200:203], v[90:93]
	v_mfma_f32_16x16x32_bf16 v[78:81], v[134:137], v[208:211], v[78:81]
	v_mfma_f32_16x16x32_bf16 v[74:77], v[142:145], v[208:211], v[74:77]
	v_mfma_f32_16x16x32_bf16 v[118:121], v[146:149], v[174:177], v[118:121]
	v_mfma_f32_16x16x32_bf16 v[114:117], v[166:169], v[174:177], v[114:117]
	v_mfma_f32_16x16x32_bf16 v[102:105], v[146:149], v[188:191], v[102:105]
	v_mfma_f32_16x16x32_bf16 v[98:101], v[166:169], v[188:191], v[98:101]
	v_mfma_f32_16x16x32_bf16 v[86:89], v[146:149], v[196:199], v[86:89]
	v_mfma_f32_16x16x32_bf16 v[82:85], v[166:169], v[196:199], v[82:85]
	v_mfma_f32_16x16x32_bf16 v[70:73], v[146:149], v[204:207], v[70:73]
	v_mfma_f32_16x16x32_bf16 v[66:69], v[166:169], v[204:207], v[66:69]
	v_mfma_f32_16x16x32_bf16 v[118:121], v[150:153], v[180:183], v[118:121]
	v_mfma_f32_16x16x32_bf16 v[114:117], v[170:173], v[180:183], v[114:117]
	v_mfma_f32_16x16x32_bf16 v[102:105], v[150:153], v[192:195], v[102:105]
	v_mfma_f32_16x16x32_bf16 v[98:101], v[170:173], v[192:195], v[98:101]
	v_mfma_f32_16x16x32_bf16 v[86:89], v[150:153], v[200:203], v[86:89]
	v_mfma_f32_16x16x32_bf16 v[82:85], v[170:173], v[200:203], v[82:85]
	v_mfma_f32_16x16x32_bf16 v[70:73], v[150:153], v[208:211], v[70:73]
	v_mfma_f32_16x16x32_bf16 v[66:69], v[170:173], v[208:211], v[66:69]
	s_setprio 0
	s_barrier
	s_add_i32 s59, s59, s33
	v_lshl_add_u64 v[212:213], s[36:37], 0, v[156:157]
	s_mov_b32 m0, s59
	ds_read_b128 v[174:177], v187 offset:16384
	ds_read_b128 v[180:183], v187 offset:17408
	ds_read_b128 v[188:191], v187 offset:18432
	ds_read_b128 v[192:195], v187 offset:19456
	ds_read_b128 v[196:199], v187 offset:20480
	ds_read_b128 v[200:203], v187 offset:21504
	ds_read_b128 v[204:207], v187 offset:22528
	ds_read_b128 v[208:211], v187 offset:23552
	global_load_lds_dwordx4 v[212:213], off
	s_add_i32 m0, s59, 0x2000
	s_add_u32 s60, s36, 0x40000
	v_lshl_add_u64 v[214:215], s[36:37], 0, v[160:161]
	s_addc_u32 s61, s37, 0
	s_add_i32 s59, s62, s33
	global_load_lds_dwordx4 v[214:215], off
	v_lshl_add_u64 v[216:217], s[60:61], 0, v[156:157]
	s_mov_b32 m0, s59
	v_lshl_add_u64 v[218:219], s[38:39], 0, v[158:159]
	global_load_lds_dwordx4 v[216:217], off
	s_add_i32 m0, s59, 0x2000
	s_nop 0
	global_load_lds_dwordx4 v160, s[60:61]
	v_lshl_add_u64 v[216:217], s[38:39], 0, v[154:155]
	s_mov_b32 m0, s46
	s_nop 0
	global_load_lds_dwordx4 v[216:217], off
	s_mov_b32 m0, s47
	s_nop 0
	global_load_lds_dwordx4 v[218:219], off
	s_waitcnt vmcnt(8) lgkmcnt(0)
	s_barrier
	s_setprio 1
	v_mfma_f32_16x16x32_bf16 v[62:65], v[130:133], v[174:177], v[62:65]
	v_mfma_f32_16x16x32_bf16 v[58:61], v[138:141], v[174:177], v[58:61]
	v_mfma_f32_16x16x32_bf16 v[46:49], v[130:133], v[188:191], v[46:49]
	v_mfma_f32_16x16x32_bf16 v[42:45], v[138:141], v[188:191], v[42:45]
	v_mfma_f32_16x16x32_bf16 v[30:33], v[130:133], v[196:199], v[30:33]
	v_mfma_f32_16x16x32_bf16 v[26:29], v[138:141], v[196:199], v[26:29]
	v_mfma_f32_16x16x32_bf16 v[14:17], v[130:133], v[204:207], v[14:17]
	v_mfma_f32_16x16x32_bf16 v[10:13], v[138:141], v[204:207], v[10:13]
	v_mfma_f32_16x16x32_bf16 v[62:65], v[134:137], v[180:183], v[62:65]
	v_mfma_f32_16x16x32_bf16 v[58:61], v[142:145], v[180:183], v[58:61]
	v_mfma_f32_16x16x32_bf16 v[46:49], v[134:137], v[192:195], v[46:49]
	v_mfma_f32_16x16x32_bf16 v[42:45], v[142:145], v[192:195], v[42:45]
	v_mfma_f32_16x16x32_bf16 v[30:33], v[134:137], v[200:203], v[30:33]
	v_mfma_f32_16x16x32_bf16 v[26:29], v[142:145], v[200:203], v[26:29]
	v_mfma_f32_16x16x32_bf16 v[14:17], v[134:137], v[208:211], v[14:17]
	v_mfma_f32_16x16x32_bf16 v[10:13], v[142:145], v[208:211], v[10:13]
	v_mfma_f32_16x16x32_bf16 v[54:57], v[146:149], v[174:177], v[54:57]
	v_mfma_f32_16x16x32_bf16 v[50:53], v[166:169], v[174:177], v[50:53]
	v_mfma_f32_16x16x32_bf16 v[38:41], v[146:149], v[188:191], v[38:41]
	v_mfma_f32_16x16x32_bf16 v[34:37], v[166:169], v[188:191], v[34:37]
	v_mfma_f32_16x16x32_bf16 v[22:25], v[146:149], v[196:199], v[22:25]
	v_mfma_f32_16x16x32_bf16 v[18:21], v[166:169], v[196:199], v[18:21]
	v_mfma_f32_16x16x32_bf16 v[6:9], v[146:149], v[204:207], v[6:9]
	v_mfma_f32_16x16x32_bf16 v[2:5], v[166:169], v[204:207], v[2:5]
	v_mfma_f32_16x16x32_bf16 v[54:57], v[150:153], v[180:183], v[54:57]
	v_mfma_f32_16x16x32_bf16 v[50:53], v[170:173], v[180:183], v[50:53]
	v_mfma_f32_16x16x32_bf16 v[38:41], v[150:153], v[192:195], v[38:41]
	v_mfma_f32_16x16x32_bf16 v[34:37], v[170:173], v[192:195], v[34:37]
	v_mfma_f32_16x16x32_bf16 v[22:25], v[150:153], v[200:203], v[22:25]
	v_mfma_f32_16x16x32_bf16 v[18:21], v[170:173], v[200:203], v[18:21]
	v_mfma_f32_16x16x32_bf16 v[6:9], v[150:153], v[208:211], v[6:9]
	v_mfma_f32_16x16x32_bf16 v[2:5], v[170:173], v[208:211], v[2:5]
	s_setprio 0
	s_barrier
; #define PG8_STAGE(bufoff, gbase, voff) do { _Pragma("unroll") for (int _i = 0; _i < 2; ++_i) \
;         __builtin_amdgcn_global_load_lds((const unsigned*)((const char*)(gbase) + (voff)[_i]), (PG8_LAS unsigned*)(lds + (bufoff) + ldsw + _i * 8192), 16, 0, 0); } while (0)
; #define PG8_LDA(dst, b, h) do { _Pragma("unroll") for (int m = 0; m < 4; ++m) _Pragma("unroll") for (int k = 0; k < 2; ++k) dst[m][k] = *(const PG8_LAS bf16x8*)(lds + PG8_SA(b, h) + aoff + m * 2048 + k * 1024); } while (0)
; #define PG8_LDB(dst, b, h) do { _Pragma("unroll") for (int n = 0; n < 2; ++n) _Pragma("unroll") for (int k = 0; k < 2; ++k) dst[n][k] = *(const PG8_LAS bf16x8*)(lds + PG8_SB(b, h) + boff + n * 2048 + k * 1024); } while (0)
; #define PG8_MMA(ai, bj, At, Bt) do { __builtin_amdgcn_s_setprio(1); _Pragma("unroll") for (int m = 0; m < 4; ++m) _Pragma("unroll") for (int n = 0; n < 2; ++n) _Pragma("unroll") for (int k = 0; k < 2; ++k) \
;         acc[ai][bj][m][n] = __builtin_amdgcn_mfma_f32_16x16x32_bf16(Bt[n][k], At[m][k], acc[ai][bj][m][n], 0, 0, 0); __builtin_amdgcn_s_setprio(0); } while (0)
; #define PG8_WAIT_V(n) asm volatile("s_waitcnt vmcnt(" #n ")" ::: "memory")
; #define PG8_WAIT_L(n) asm volatile("s_waitcnt lgkmcnt(" #n ")" ::: "memory")
; #define PG8_BAR __builtin_amdgcn_s_barrier()
; #define PG8_SCHED __builtin_amdgcn_sched_barrier(0)
; template <class Epi, class Sched, bool ALIGN_EPI = false, bool SP2 = false>
; __device__ __forceinline__ void gemm_phase(PG8_LAS unsigned char* lds, const Gemm g, const Sched& S, const Epi& E) {
;     ...
;             PG8_LDB(B0, 1, 0); PG8_LDB(B1, 1, 1); PG8_SCHED; PG8_LDA(At, 1, 0); PG8_STAGE(PG8_SA(0, 1), a2 + hstep, voffA);
;             PG8_WAIT_V(8); PG8_WAIT_L(0); PG8_BAR; PG8_MMA(0, 0, At, B0); PG8_MMA(0, 1, At, B1); PG8_BAR; PG8_SCHED;
;             PG8_LDA(At, 1, 1); PG8_STAGE(PG8_SB(1, 0), b3, voffB); PG8_STAGE(PG8_SB(1, 1), b3 + hstep, voffB); PG8_STAGE(PG8_SA(1, 0), a3, voffA);
;             PG8_WAIT_V(8); PG8_WAIT_L(0); PG8_BAR; PG8_MMA(1, 0, At, B0); PG8_MMA(1, 1, At, B1); PG8_BAR; PG8_SCHED;
;     ...
;         if constexpr (ALIGN_EPI) { if (wr == 0) PG8_BAR; }
	s_add_i32 s59, 0, 0x18000
	s_add_i32 s60, 0, 0x1c000
	v_add_u32_e32 v142, s59, v179
	v_add_u32_e32 v170, s60, v179
	ds_read_b128 v[130:133], v142
	ds_read_b128 v[134:137], v142 offset:1024
	ds_read_b128 v[138:141], v142 offset:2048
	ds_read_b128 v[142:145], v142 offset:3072
	ds_read_b128 v[146:149], v170
	ds_read_b128 v[150:153], v170 offset:1024
	ds_read_b128 v[166:169], v170 offset:2048
	ds_read_b128 v[170:173], v170 offset:3072
	s_add_u32 s38, s38, 0x40000
	s_addc_u32 s39, s39, 0
	s_mov_b32 m0, s48
	ds_read_b128 v[174:177], v187 offset:32768
	ds_read_b128 v[180:183], v187 offset:33792
	ds_read_b128 v[188:191], v187 offset:34816
	ds_read_b128 v[192:195], v187 offset:35840
	ds_read_b128 v[196:199], v187 offset:36864
	ds_read_b128 v[200:203], v187 offset:37888
	ds_read_b128 v[204:207], v187 offset:38912
	ds_read_b128 v[208:211], v187 offset:39936
	global_load_lds_dwordx4 v154, s[38:39]
	v_lshl_add_u64 v[220:221], s[38:39], 0, v[158:159]
	s_mov_b32 m0, s49
	s_nop 0
	global_load_lds_dwordx4 v[220:221], off
	s_waitcnt vmcnt(8) lgkmcnt(0)
	s_barrier
	s_setprio 1
	v_mfma_f32_16x16x32_bf16 v[126:129], v[130:133], v[174:177], v[126:129]
	v_mfma_f32_16x16x32_bf16 v[122:125], v[138:141], v[174:177], v[122:125]
	v_mfma_f32_16x16x32_bf16 v[110:113], v[130:133], v[188:191], v[110:113]
	v_mfma_f32_16x16x32_bf16 v[106:109], v[138:141], v[188:191], v[106:109]
	v_mfma_f32_16x16x32_bf16 v[94:97], v[130:133], v[196:199], v[94:97]
	v_mfma_f32_16x16x32_bf16 v[90:93], v[138:141], v[196:199], v[90:93]
	v_mfma_f32_16x16x32_bf16 v[78:81], v[130:133], v[204:207], v[78:81]
	v_mfma_f32_16x16x32_bf16 v[74:77], v[138:141], v[204:207], v[74:77]
	v_mfma_f32_16x16x32_bf16 v[126:129], v[134:137], v[180:183], v[126:129]
	v_mfma_f32_16x16x32_bf16 v[122:125], v[142:145], v[180:183], v[122:125]
	v_mfma_f32_16x16x32_bf16 v[110:113], v[134:137], v[192:195], v[110:113]
	v_mfma_f32_16x16x32_bf16 v[106:109], v[142:145], v[192:195], v[106:109]
	v_mfma_f32_16x16x32_bf16 v[94:97], v[134:137], v[200:203], v[94:97]
	v_mfma_f32_16x16x32_bf16 v[90:93], v[142:145], v[200:203], v[90:93]
	v_mfma_f32_16x16x32_bf16 v[78:81], v[134:137], v[208:211], v[78:81]
	v_mfma_f32_16x16x32_bf16 v[74:77], v[142:145], v[208:211], v[74:77]
	v_mfma_f32_16x16x32_bf16 v[118:121], v[146:149], v[174:177], v[118:121]
	v_mfma_f32_16x16x32_bf16 v[114:117], v[166:169], v[174:177], v[114:117]
	v_mfma_f32_16x16x32_bf16 v[102:105], v[146:149], v[188:191], v[102:105]
	v_mfma_f32_16x16x32_bf16 v[98:101], v[166:169], v[188:191], v[98:101]
	v_mfma_f32_16x16x32_bf16 v[86:89], v[146:149], v[196:199], v[86:89]
	v_mfma_f32_16x16x32_bf16 v[82:85], v[166:169], v[196:199], v[82:85]
	v_mfma_f32_16x16x32_bf16 v[70:73], v[146:149], v[204:207], v[70:73]
	v_mfma_f32_16x16x32_bf16 v[66:69], v[166:169], v[204:207], v[66:69]
	v_mfma_f32_16x16x32_bf16 v[118:121], v[150:153], v[180:183], v[118:121]
	v_mfma_f32_16x16x32_bf16 v[114:117], v[170:173], v[180:183], v[114:117]
	v_mfma_f32_16x16x32_bf16 v[102:105], v[150:153], v[192:195], v[102:105]
	v_mfma_f32_16x16x32_bf16 v[98:101], v[170:173], v[192:195], v[98:101]
	v_mfma_f32_16x16x32_bf16 v[86:89], v[150:153], v[200:203], v[86:89]
	v_mfma_f32_16x16x32_bf16 v[82:85], v[170:173], v[200:203], v[82:85]
	v_mfma_f32_16x16x32_bf16 v[70:73], v[150:153], v[208:211], v[70:73]
	v_mfma_f32_16x16x32_bf16 v[66:69], v[170:173], v[208:211], v[66:69]
	s_setprio 0
	s_barrier
	s_add_i32 s38, s59, s33
	v_lshl_add_u64 v[212:213], v[212:213], 0, s[80:81]
	s_mov_b32 m0, s38
	ds_read_b128 v[174:177], v187 offset:49152
	ds_read_b128 v[180:183], v187 offset:50176
	ds_read_b128 v[188:191], v187 offset:51200
	ds_read_b128 v[192:195], v187 offset:52224
	ds_read_b128 v[196:199], v187 offset:53248
	ds_read_b128 v[200:203], v187 offset:54272
	ds_read_b128 v[204:207], v187 offset:55296
	ds_read_b128 v[208:211], v187 offset:56320
	global_load_lds_dwordx4 v[212:213], off
	s_add_i32 m0, s38, 0x2000
	s_add_u32 s36, s36, 0x40080
	v_lshl_add_u64 v[212:213], v[214:215], 0, s[80:81]
	s_addc_u32 s37, s37, 0
	s_add_i32 s38, s60, s33
	global_load_lds_dwordx4 v[212:213], off
	s_mov_b32 m0, s38
	s_nop 0
	global_load_lds_dwordx4 v156, s[36:37]
	s_add_i32 m0, s38, 0x2000
	s_nop 0
	global_load_lds_dwordx4 v160, s[36:37]
	v_lshl_add_u64 v[212:213], v[216:217], 0, s[80:81]
	s_mov_b32 m0, s51
	s_nop 0
	global_load_lds_dwordx4 v[212:213], off
	v_lshl_add_u64 v[212:213], v[218:219], 0, s[80:81]
	s_mov_b32 m0, s52
	s_nop 0
	global_load_lds_dwordx4 v[212:213], off
	s_waitcnt vmcnt(8) lgkmcnt(0)
	s_barrier
	s_setprio 1
	v_mfma_f32_16x16x32_bf16 v[62:65], v[130:133], v[174:177], v[62:65]
	v_mfma_f32_16x16x32_bf16 v[58:61], v[138:141], v[174:177], v[58:61]
	v_mfma_f32_16x16x32_bf16 v[46:49], v[130:133], v[188:191], v[46:49]
	v_mfma_f32_16x16x32_bf16 v[42:45], v[138:141], v[188:191], v[42:45]
	v_mfma_f32_16x16x32_bf16 v[30:33], v[130:133], v[196:199], v[30:33]
	v_mfma_f32_16x16x32_bf16 v[26:29], v[138:141], v[196:199], v[26:29]
	v_mfma_f32_16x16x32_bf16 v[14:17], v[130:133], v[204:207], v[14:17]
	v_mfma_f32_16x16x32_bf16 v[10:13], v[138:141], v[204:207], v[10:13]
	v_mfma_f32_16x16x32_bf16 v[62:65], v[134:137], v[180:183], v[62:65]
	v_mfma_f32_16x16x32_bf16 v[58:61], v[142:145], v[180:183], v[58:61]
	v_mfma_f32_16x16x32_bf16 v[46:49], v[134:137], v[192:195], v[46:49]
	v_mfma_f32_16x16x32_bf16 v[42:45], v[142:145], v[192:195], v[42:45]
	v_mfma_f32_16x16x32_bf16 v[30:33], v[134:137], v[200:203], v[30:33]
	v_mfma_f32_16x16x32_bf16 v[26:29], v[142:145], v[200:203], v[26:29]
	v_mfma_f32_16x16x32_bf16 v[14:17], v[134:137], v[208:211], v[14:17]
	v_mfma_f32_16x16x32_bf16 v[10:13], v[142:145], v[208:211], v[10:13]
	v_mfma_f32_16x16x32_bf16 v[54:57], v[146:149], v[174:177], v[54:57]
	v_mfma_f32_16x16x32_bf16 v[50:53], v[166:169], v[174:177], v[50:53]
	v_mfma_f32_16x16x32_bf16 v[38:41], v[146:149], v[188:191], v[38:41]
	v_mfma_f32_16x16x32_bf16 v[34:37], v[166:169], v[188:191], v[34:37]
	v_mfma_f32_16x16x32_bf16 v[22:25], v[146:149], v[196:199], v[22:25]
	v_mfma_f32_16x16x32_bf16 v[18:21], v[166:169], v[196:199], v[18:21]
	v_mfma_f32_16x16x32_bf16 v[6:9], v[146:149], v[204:207], v[6:9]
	v_mfma_f32_16x16x32_bf16 v[2:5], v[166:169], v[204:207], v[2:5]
	v_mfma_f32_16x16x32_bf16 v[54:57], v[150:153], v[180:183], v[54:57]
	v_mfma_f32_16x16x32_bf16 v[50:53], v[170:173], v[180:183], v[50:53]
	v_mfma_f32_16x16x32_bf16 v[38:41], v[150:153], v[192:195], v[38:41]
	v_mfma_f32_16x16x32_bf16 v[34:37], v[170:173], v[192:195], v[34:37]
	v_mfma_f32_16x16x32_bf16 v[22:25], v[150:153], v[200:203], v[22:25]
	v_mfma_f32_16x16x32_bf16 v[18:21], v[170:173], v[200:203], v[18:21]
	v_mfma_f32_16x16x32_bf16 v[6:9], v[150:153], v[208:211], v[6:9]
	v_mfma_f32_16x16x32_bf16 v[2:5], v[170:173], v[208:211], v[2:5]
	s_setprio 0
	s_barrier
	s_add_i32 s58, s58, 2
	s_add_u32 s34, s34, 0x100
	s_addc_u32 s35, s35, 0
	s_add_u32 s56, s56, 0x100
	s_addc_u32 s57, s57, 0
	s_cmp_gt_u32 s58, 13
	s_cbranch_scc0 .LBB0_1062
	s_and_b64 vcc, exec, s[18:19]
	s_cbranch_vccz .LBB0_1065
	s_barrier

; #define PG8_STAGE(bufoff, gbase, voff) do { _Pragma("unroll") for (int _i = 0; _i < 2; ++_i) \
;         __builtin_amdgcn_global_load_lds((const unsigned*)((const char*)(gbase) + (voff)[_i]), (PG8_LAS unsigned*)(lds + (bufoff) + ldsw + _i * 8192), 16, 0, 0); } while (0)
; #define PG8_LDA(dst, b, h) do { _Pragma("unroll") for (int m = 0; m < 4; ++m) _Pragma("unroll") for (int k = 0; k < 2; ++k) dst[m][k] = *(const PG8_LAS bf16x8*)(lds + PG8_SA(b, h) + aoff + m * 2048 + k * 1024); } while (0)
; #define PG8_LDB(dst, b, h) do { _Pragma("unroll") for (int n = 0; n < 2; ++n) _Pragma("unroll") for (int k = 0; k < 2; ++k) dst[n][k] = *(const PG8_LAS bf16x8*)(lds + PG8_SB(b, h) + boff + n * 2048 + k * 1024); } while (0)
; #define PG8_WAIT_V(n) asm volatile("s_waitcnt vmcnt(" #n ")" ::: "memory")
; #define PG8_WAIT_L(n) asm volatile("s_waitcnt lgkmcnt(" #n ")" ::: "memory")
; #define PG8_BAR __builtin_amdgcn_s_barrier()
; #define PG8_SCHED __builtin_amdgcn_sched_barrier(0)
; template <class Epi, class Sched, bool ALIGN_EPI = false, bool SP2 = false>
; __device__ __forceinline__ void gemm_phase(PG8_LAS unsigned char* lds, const Gemm g, const Sched& S, const Epi& E) {
;     ...
;         const bool has_next = S.next(ui + 1, nxt);
;         const char* nA = has_next ? (const char*)g.A + (size_t)nxt.pm * tstep : cA; const char* nB = has_next ? (const char*)g.Bt + (size_t)nxt.pn * tstep : cB;
;         for (int t = 0; t < nt; t += 2) {
;             const bool last = (t == nt - 2);
;             const char* a1 = cA + (size_t)(t + 1) * kstep;
;             const char* a2 = last ? nA : cA + (size_t)(t + 2) * kstep; const char* b2 = last ? nB : cB + (size_t)(t + 2) * kstep;
;             const char* a3 = a2 + kstep; const char* b3 = b2 + kstep;
;             if (last && has_next) S.a_ready(nxt);
;             if constexpr (SP2) {
;             PG8_LDB(B0, 0, 0); PG8_LDB(B1, 0, 1); PG8_SCHED; PG8_LDA(At, 0, 0); PG8_STAGE(PG8_SA(1, 1), a1 + hstep, voffA);
;             PG8_WAIT_V(8); PG8_WAIT_L(0); PG8_BAR; PG8_MMA(0, 0, At, B0); PG8_MMA(0, 1, At, B1); PG8_BAR; PG8_SCHED;
;             PG8_LDA(At, 0, 1); PG8_STAGE(PG8_SB(0, 0), b2, voffB); PG8_STAGE(PG8_SB(0, 1), b2 + hstep, voffB); PG8_STAGE(PG8_SA(0, 0), a2, voffA);
;             PG8_WAIT_V(8); PG8_WAIT_L(0); PG8_BAR; PG8_MMA(1, 0, At, B0); PG8_MMA(1, 1, At, B1); PG8_BAR; PG8_SCHED;
.LBB0_1105:
	s_ashr_i32 s19, s18, 31
	s_lshl_b64 s[20:21], s[18:19], 19
	s_add_u32 s20, s42, s20
	s_addc_u32 s21, s43, s21
	s_and_b64 s[22:23], s[6:7], exec
	s_cselect_b32 s19, s21, s29
	s_cselect_b32 s25, s20, s28
	s_ashr_i32 s17, s16, 31
	s_lshl_b64 s[22:23], s[16:17], 19
	s_add_u32 s22, s40, s22
	s_addc_u32 s23, s41, s23
	s_and_b64 s[34:35], s[6:7], exec
	s_cselect_b32 s17, s23, s31
	s_cselect_b32 s27, s22, s30
	s_add_u32 s28, s28, 0x40080
	s_addc_u32 s29, s29, 0
	s_add_u32 s52, s30, 0x100
	s_addc_u32 s53, s31, 0
	s_mov_b32 s54, -2
	s_waitcnt lgkmcnt(0)
	s_add_u32 s30, s28, 0xfffc0080
	s_addc_u32 s31, s29, -1
	s_add_i32 s55, 0, 0x10000
	s_cmp_eq_u32 s54, 12
	s_cselect_b32 s35, s19, s31
	s_cselect_b32 s34, s25, s30
	s_cselect_b32 s31, s17, s53
	s_cselect_b32 s30, s27, s52
	s_add_i32 s58, 0, 0x14000
	v_add_u32_e32 v142, s55, v179
	v_add_u32_e32 v158, s58, v179
	ds_read_b128 v[130:133], v142
	ds_read_b128 v[134:137], v142 offset:1024
	ds_read_b128 v[138:141], v142 offset:2048
	ds_read_b128 v[142:145], v142 offset:3072
	ds_read_b128 v[146:149], v158
	ds_read_b128 v[150:153], v158 offset:1024
	ds_read_b128 v[154:157], v158 offset:2048
	ds_read_b128 v[158:161], v158 offset:3072
	s_add_i32 m0, s36, 0xc000
	ds_read_b128 v[162:165], v211
	ds_read_b128 v[166:169], v211 offset:1024
	ds_read_b128 v[170:173], v211 offset:2048
	ds_read_b128 v[174:177], v211 offset:3072
	ds_read_b128 v[180:183], v211 offset:4096
	ds_read_b128 v[198:201], v211 offset:5120
	ds_read_b128 v[202:205], v211 offset:6144
	ds_read_b128 v[206:209], v211 offset:7168
	global_load_lds_dwordx4 v194, s[28:29]
	s_add_i32 m0, s36, 0xe000
	s_nop 0
	global_load_lds_dwordx4 v196, s[28:29]
	s_waitcnt vmcnt(8) lgkmcnt(0)
	s_barrier
	s_setprio 1
	v_mfma_f32_16x16x32_bf16 v[126:129], v[130:133], v[162:165], 0
	v_mfma_f32_16x16x32_bf16 v[122:125], v[138:141], v[162:165], 0
	v_mfma_f32_16x16x32_bf16 v[110:113], v[130:133], v[170:173], 0
	v_mfma_f32_16x16x32_bf16 v[106:109], v[138:141], v[170:173], 0
	v_mfma_f32_16x16x32_bf16 v[94:97], v[130:133], v[180:183], 0
	v_mfma_f32_16x16x32_bf16 v[90:93], v[138:141], v[180:183], 0
	v_mfma_f32_16x16x32_bf16 v[78:81], v[130:133], v[202:205], 0
	v_mfma_f32_16x16x32_bf16 v[74:77], v[138:141], v[202:205], 0
	v_mfma_f32_16x16x32_bf16 v[126:129], v[134:137], v[166:169], v[126:129]
	v_mfma_f32_16x16x32_bf16 v[122:125], v[142:145], v[166:169], v[122:125]
	v_mfma_f32_16x16x32_bf16 v[110:113], v[134:137], v[174:177], v[110:113]
	v_mfma_f32_16x16x32_bf16 v[106:109], v[142:145], v[174:177], v[106:109]
	v_mfma_f32_16x16x32_bf16 v[94:97], v[134:137], v[198:201], v[94:97]
	v_mfma_f32_16x16x32_bf16 v[90:93], v[142:145], v[198:201], v[90:93]
	v_mfma_f32_16x16x32_bf16 v[78:81], v[134:137], v[206:209], v[78:81]
	v_mfma_f32_16x16x32_bf16 v[74:77], v[142:145], v[206:209], v[74:77]
	v_mfma_f32_16x16x32_bf16 v[118:121], v[146:149], v[162:165], 0
	v_mfma_f32_16x16x32_bf16 v[114:117], v[154:157], v[162:165], 0
	v_mfma_f32_16x16x32_bf16 v[102:105], v[146:149], v[170:173], 0
	v_mfma_f32_16x16x32_bf16 v[98:101], v[154:157], v[170:173], 0
	v_mfma_f32_16x16x32_bf16 v[86:89], v[146:149], v[180:183], 0
	v_mfma_f32_16x16x32_bf16 v[82:85], v[154:157], v[180:183], 0
	v_mfma_f32_16x16x32_bf16 v[70:73], v[146:149], v[202:205], 0
	v_mfma_f32_16x16x32_bf16 v[66:69], v[154:157], v[202:205], 0
	v_mfma_f32_16x16x32_bf16 v[118:121], v[150:153], v[166:169], v[118:121]
	v_mfma_f32_16x16x32_bf16 v[114:117], v[158:161], v[166:169], v[114:117]
	v_mfma_f32_16x16x32_bf16 v[102:105], v[150:153], v[174:177], v[102:105]
	v_mfma_f32_16x16x32_bf16 v[98:101], v[158:161], v[174:177], v[98:101]
	v_mfma_f32_16x16x32_bf16 v[86:89], v[150:153], v[198:201], v[86:89]
	v_mfma_f32_16x16x32_bf16 v[82:85], v[158:161], v[198:201], v[82:85]
	v_mfma_f32_16x16x32_bf16 v[70:73], v[150:153], v[206:209], v[70:73]
	v_mfma_f32_16x16x32_bf16 v[66:69], v[158:161], v[206:209], v[66:69]
	s_setprio 0
	s_barrier
	s_add_i32 s55, s55, s33
	v_lshl_add_u64 v[212:213], s[30:31], 0, v[188:189]
	s_mov_b32 m0, s55
	ds_read_b128 v[162:165], v211 offset:16384
	ds_read_b128 v[166:169], v211 offset:17408
	ds_read_b128 v[170:173], v211 offset:18432
	ds_read_b128 v[174:177], v211 offset:19456
	ds_read_b128 v[180:183], v211 offset:20480
	ds_read_b128 v[198:201], v211 offset:21504
	ds_read_b128 v[202:205], v211 offset:22528
	ds_read_b128 v[206:209], v211 offset:23552
	global_load_lds_dwordx4 v[212:213], off
	s_add_i32 m0, s55, 0x2000
	s_add_u32 s56, s30, 0x40000
	v_lshl_add_u64 v[214:215], s[30:31], 0, v[192:193]
	s_addc_u32 s57, s31, 0
	s_add_i32 s55, s58, s33
	global_load_lds_dwordx4 v[214:215], off
	v_lshl_add_u64 v[216:217], s[56:57], 0, v[188:189]
	s_mov_b32 m0, s55
	v_lshl_add_u64 v[218:219], s[34:35], 0, v[190:191]
	global_load_lds_dwordx4 v[216:217], off
	s_add_i32 m0, s55, 0x2000
	s_nop 0
	global_load_lds_dwordx4 v192, s[56:57]
	v_lshl_add_u64 v[216:217], s[34:35], 0, v[186:187]
	s_mov_b32 m0, s36
	s_nop 0
	global_load_lds_dwordx4 v[216:217], off
	s_mov_b32 m0, s37
	s_nop 0
	global_load_lds_dwordx4 v[218:219], off
	s_waitcnt vmcnt(8) lgkmcnt(0)
	s_barrier
; #define PG8_STAGE(bufoff, gbase, voff) do { _Pragma("unroll") for (int _i = 0; _i < 2; ++_i) \
;         __builtin_amdgcn_global_load_lds((const unsigned*)((const char*)(gbase) + (voff)[_i]), (PG8_LAS unsigned*)(lds + (bufoff) + ldsw + _i * 8192), 16, 0, 0); } while (0)
; #define PG8_LDA(dst, b, h) do { _Pragma("unroll") for (int m = 0; m < 4; ++m) _Pragma("unroll") for (int k = 0; k < 2; ++k) dst[m][k] = *(const PG8_LAS bf16x8*)(lds + PG8_SA(b, h) + aoff + m * 2048 + k * 1024); } while (0)
; #define PG8_LDB(dst, b, h) do { _Pragma("unroll") for (int n = 0; n < 2; ++n) _Pragma("unroll") for (int k = 0; k < 2; ++k) dst[n][k] = *(const PG8_LAS bf16x8*)(lds + PG8_SB(b, h) + boff + n * 2048 + k * 1024); } while (0)
; #define PG8_MMA(ai, bj, At, Bt) do { __builtin_amdgcn_s_setprio(1); _Pragma("unroll") for (int m = 0; m < 4; ++m) _Pragma("unroll") for (int n = 0; n < 2; ++n) _Pragma("unroll") for (int k = 0; k < 2; ++k) \
;         acc[ai][bj][m][n] = __builtin_amdgcn_mfma_f32_16x16x32_bf16(Bt[n][k], At[m][k], acc[ai][bj][m][n], 0, 0, 0); __builtin_amdgcn_s_setprio(0); } while (0)
; #define PG8_WAIT_V(n) asm volatile("s_waitcnt vmcnt(" #n ")" ::: "memory")
; #define PG8_WAIT_L(n) asm volatile("s_waitcnt lgkmcnt(" #n ")" ::: "memory")
; #define PG8_BAR __builtin_amdgcn_s_barrier()
; #define PG8_SCHED __builtin_amdgcn_sched_barrier(0)
; template <class Epi, class Sched, bool ALIGN_EPI = false, bool SP2 = false>
; __device__ __forceinline__ void gemm_phase(PG8_LAS unsigned char* lds, const Gemm g, const Sched& S, const Epi& E) {
;     ...
;             PG8_WAIT_V(8); PG8_WAIT_L(0); PG8_BAR; PG8_MMA(1, 0, At, B0); PG8_MMA(1, 1, At, B1); PG8_BAR; PG8_SCHED;
;             PG8_LDB(B0, 1, 0); PG8_LDB(B1, 1, 1); PG8_SCHED; PG8_LDA(At, 1, 0); PG8_STAGE(PG8_SA(0, 1), a2 + hstep, voffA);
;             PG8_WAIT_V(8); PG8_WAIT_L(0); PG8_BAR; PG8_MMA(0, 0, At, B0); PG8_MMA(0, 1, At, B1); PG8_BAR; PG8_SCHED;
	s_setprio 1
	v_mfma_f32_16x16x32_bf16 v[62:65], v[130:133], v[162:165], 0
	v_mfma_f32_16x16x32_bf16 v[58:61], v[138:141], v[162:165], 0
	v_mfma_f32_16x16x32_bf16 v[46:49], v[130:133], v[170:173], 0
	v_mfma_f32_16x16x32_bf16 v[42:45], v[138:141], v[170:173], 0
	v_mfma_f32_16x16x32_bf16 v[30:33], v[130:133], v[180:183], 0
	v_mfma_f32_16x16x32_bf16 v[26:29], v[138:141], v[180:183], 0
	v_mfma_f32_16x16x32_bf16 v[14:17], v[130:133], v[202:205], 0
	v_mfma_f32_16x16x32_bf16 v[10:13], v[138:141], v[202:205], 0
	v_mfma_f32_16x16x32_bf16 v[62:65], v[134:137], v[166:169], v[62:65]
	v_mfma_f32_16x16x32_bf16 v[58:61], v[142:145], v[166:169], v[58:61]
	v_mfma_f32_16x16x32_bf16 v[46:49], v[134:137], v[174:177], v[46:49]
	v_mfma_f32_16x16x32_bf16 v[42:45], v[142:145], v[174:177], v[42:45]
	v_mfma_f32_16x16x32_bf16 v[30:33], v[134:137], v[198:201], v[30:33]
	v_mfma_f32_16x16x32_bf16 v[26:29], v[142:145], v[198:201], v[26:29]
	v_mfma_f32_16x16x32_bf16 v[14:17], v[134:137], v[206:209], v[14:17]
	v_mfma_f32_16x16x32_bf16 v[10:13], v[142:145], v[206:209], v[10:13]
	v_mfma_f32_16x16x32_bf16 v[54:57], v[146:149], v[162:165], 0
	v_mfma_f32_16x16x32_bf16 v[50:53], v[154:157], v[162:165], 0
	v_mfma_f32_16x16x32_bf16 v[38:41], v[146:149], v[170:173], 0
	v_mfma_f32_16x16x32_bf16 v[34:37], v[154:157], v[170:173], 0
	v_mfma_f32_16x16x32_bf16 v[22:25], v[146:149], v[180:183], 0
	v_mfma_f32_16x16x32_bf16 v[18:21], v[154:157], v[180:183], 0
	v_mfma_f32_16x16x32_bf16 v[6:9], v[146:149], v[202:205], 0
	v_mfma_f32_16x16x32_bf16 v[2:5], v[154:157], v[202:205], 0
	v_mfma_f32_16x16x32_bf16 v[54:57], v[150:153], v[166:169], v[54:57]
	v_mfma_f32_16x16x32_bf16 v[50:53], v[158:161], v[166:169], v[50:53]
	v_mfma_f32_16x16x32_bf16 v[38:41], v[150:153], v[174:177], v[38:41]
	v_mfma_f32_16x16x32_bf16 v[34:37], v[158:161], v[174:177], v[34:37]
	v_mfma_f32_16x16x32_bf16 v[22:25], v[150:153], v[198:201], v[22:25]
	v_mfma_f32_16x16x32_bf16 v[18:21], v[158:161], v[198:201], v[18:21]
	v_mfma_f32_16x16x32_bf16 v[6:9], v[150:153], v[206:209], v[6:9]
	v_mfma_f32_16x16x32_bf16 v[2:5], v[158:161], v[206:209], v[2:5]
	s_setprio 0
	s_barrier
	s_add_i32 s55, 0, 0x18000
	s_add_i32 s56, 0, 0x1c000
	v_add_u32_e32 v142, s55, v179
	v_add_u32_e32 v158, s56, v179
	ds_read_b128 v[130:133], v142
	ds_read_b128 v[134:137], v142 offset:1024
	ds_read_b128 v[138:141], v142 offset:2048
	ds_read_b128 v[142:145], v142 offset:3072
	ds_read_b128 v[146:149], v158
	ds_read_b128 v[150:153], v158 offset:1024
	ds_read_b128 v[154:157], v158 offset:2048
	ds_read_b128 v[158:161], v158 offset:3072
	s_add_u32 s34, s34, 0x40000
	s_addc_u32 s35, s35, 0
	s_mov_b32 m0, s38
	ds_read_b128 v[162:165], v211 offset:32768
	ds_read_b128 v[166:169], v211 offset:33792
	ds_read_b128 v[170:173], v211 offset:34816
	ds_read_b128 v[174:177], v211 offset:35840
	ds_read_b128 v[180:183], v211 offset:36864
	ds_read_b128 v[198:201], v211 offset:37888
	ds_read_b128 v[202:205], v211 offset:38912
	ds_read_b128 v[206:209], v211 offset:39936
	global_load_lds_dwordx4 v186, s[34:35]
	v_lshl_add_u64 v[220:221], s[34:35], 0, v[190:191]
	s_mov_b32 m0, s39
	s_nop 0
	global_load_lds_dwordx4 v[220:221], off
	s_waitcnt vmcnt(8) lgkmcnt(0)
	s_barrier
	s_setprio 1
	v_mfma_f32_16x16x32_bf16 v[126:129], v[130:133], v[162:165], v[126:129]
	v_mfma_f32_16x16x32_bf16 v[122:125], v[138:141], v[162:165], v[122:125]
	v_mfma_f32_16x16x32_bf16 v[110:113], v[130:133], v[170:173], v[110:113]
	v_mfma_f32_16x16x32_bf16 v[106:109], v[138:141], v[170:173], v[106:109]
	v_mfma_f32_16x16x32_bf16 v[94:97], v[130:133], v[180:183], v[94:97]
	v_mfma_f32_16x16x32_bf16 v[90:93], v[138:141], v[180:183], v[90:93]
	v_mfma_f32_16x16x32_bf16 v[78:81], v[130:133], v[202:205], v[78:81]
	v_mfma_f32_16x16x32_bf16 v[74:77], v[138:141], v[202:205], v[74:77]
	v_mfma_f32_16x16x32_bf16 v[126:129], v[134:137], v[166:169], v[126:129]
	v_mfma_f32_16x16x32_bf16 v[122:125], v[142:145], v[166:169], v[122:125]
	v_mfma_f32_16x16x32_bf16 v[110:113], v[134:137], v[174:177], v[110:113]
	v_mfma_f32_16x16x32_bf16 v[106:109], v[142:145], v[174:177], v[106:109]
	v_mfma_f32_16x16x32_bf16 v[94:97], v[134:137], v[198:201], v[94:97]
	v_mfma_f32_16x16x32_bf16 v[90:93], v[142:145], v[198:201], v[90:93]
	v_mfma_f32_16x16x32_bf16 v[78:81], v[134:137], v[206:209], v[78:81]
	v_mfma_f32_16x16x32_bf16 v[74:77], v[142:145], v[206:209], v[74:77]
	v_mfma_f32_16x16x32_bf16 v[118:121], v[146:149], v[162:165], v[118:121]
	v_mfma_f32_16x16x32_bf16 v[114:117], v[154:157], v[162:165], v[114:117]
	v_mfma_f32_16x16x32_bf16 v[102:105], v[146:149], v[170:173], v[102:105]
	v_mfma_f32_16x16x32_bf16 v[98:101], v[154:157], v[170:173], v[98:101]
	v_mfma_f32_16x16x32_bf16 v[86:89], v[146:149], v[180:183], v[86:89]
	v_mfma_f32_16x16x32_bf16 v[82:85], v[154:157], v[180:183], v[82:85]
	v_mfma_f32_16x16x32_bf16 v[70:73], v[146:149], v[202:205], v[70:73]
	v_mfma_f32_16x16x32_bf16 v[66:69], v[154:157], v[202:205], v[66:69]
	v_mfma_f32_16x16x32_bf16 v[118:121], v[150:153], v[166:169], v[118:121]
	v_mfma_f32_16x16x32_bf16 v[114:117], v[158:161], v[166:169], v[114:117]
	v_mfma_f32_16x16x32_bf16 v[102:105], v[150:153], v[174:177], v[102:105]
	v_mfma_f32_16x16x32_bf16 v[98:101], v[158:161], v[174:177], v[98:101]
	v_mfma_f32_16x16x32_bf16 v[86:89], v[150:153], v[198:201], v[86:89]
	v_mfma_f32_16x16x32_bf16 v[82:85], v[158:161], v[198:201], v[82:85]
	v_mfma_f32_16x16x32_bf16 v[70:73], v[150:153], v[206:209], v[70:73]
	v_mfma_f32_16x16x32_bf16 v[66:69], v[158:161], v[206:209], v[66:69]
	s_setprio 0
	s_barrier
; #define PG8_STAGE(bufoff, gbase, voff) do { _Pragma("unroll") for (int _i = 0; _i < 2; ++_i) \
;         __builtin_amdgcn_global_load_lds((const unsigned*)((const char*)(gbase) + (voff)[_i]), (PG8_LAS unsigned*)(lds + (bufoff) + ldsw + _i * 8192), 16, 0, 0); } while (0)
; #define PG8_LDA(dst, b, h) do { _Pragma("unroll") for (int m = 0; m < 4; ++m) _Pragma("unroll") for (int k = 0; k < 2; ++k) dst[m][k] = *(const PG8_LAS bf16x8*)(lds + PG8_SA(b, h) + aoff + m * 2048 + k * 1024); } while (0)
; #define PG8_LDB(dst, b, h) do { _Pragma("unroll") for (int n = 0; n < 2; ++n) _Pragma("unroll") for (int k = 0; k < 2; ++k) dst[n][k] = *(const PG8_LAS bf16x8*)(lds + PG8_SB(b, h) + boff + n * 2048 + k * 1024); } while (0)
; template <class Epi, class Sched, bool ALIGN_EPI = false, bool SP2 = false>
; __device__ __forceinline__ void gemm_phase(PG8_LAS unsigned char* lds, const Gemm g, const Sched& S, const Epi& E) {
;     ...
;         for (int t = 0; t < nt; t += 2) {
;             const bool last = (t == nt - 2);
;             const char* a1 = cA + (size_t)(t + 1) * kstep;
;             const char* a2 = last ? nA : cA + (size_t)(t + 2) * kstep; const char* b2 = last ? nB : cB + (size_t)(t + 2) * kstep;
;             const char* a3 = a2 + kstep; const char* b3 = b2 + kstep;
;             if (last && has_next) S.a_ready(nxt);
;             if constexpr (SP2) {
;             PG8_LDB(B0, 0, 0); PG8_LDB(B1, 0, 1); PG8_SCHED; PG8_LDA(At, 0, 0); PG8_STAGE(PG8_SA(1, 1), a1 + hstep, voffA);
;             PG8_WAIT_V(8); PG8_WAIT_L(0); PG8_BAR; PG8_MMA(0, 0, At, B0); PG8_MMA(0, 1, At, B1); PG8_BAR; PG8_SCHED;
;             PG8_LDA(At, 0, 1); PG8_STAGE(PG8_SB(0, 0), b2, voffB); PG8_STAGE(PG8_SB(0, 1), b2 + hstep, voffB); PG8_STAGE(PG8_SA(0, 0), a2, voffA);
;             PG8_WAIT_V(8); PG8_WAIT_L(0); PG8_BAR; PG8_MMA(1, 0, At, B0); PG8_MMA(1, 1, At, B1); PG8_BAR; PG8_SCHED;
;             PG8_LDB(B0, 1, 0); PG8_LDB(B1, 1, 1); PG8_SCHED; PG8_LDA(At, 1, 0); PG8_STAGE(PG8_SA(0, 1), a2 + hstep, voffA);
;             PG8_WAIT_V(8); PG8_WAIT_L(0); PG8_BAR; PG8_MMA(0, 0, At, B0); PG8_MMA(0, 1, At, B1); PG8_BAR; PG8_SCHED;
;             PG8_LDA(At, 1, 1); PG8_STAGE(PG8_SB(1, 0), b3, voffB); PG8_STAGE(PG8_SB(1, 1), b3 + hstep, voffB); PG8_STAGE(PG8_SA(1, 0), a3, voffA);
;             PG8_WAIT_V(8); PG8_WAIT_L(0); PG8_BAR; PG8_MMA(1, 0, At, B0); PG8_MMA(1, 1, At, B1); PG8_BAR; PG8_SCHED;
	s_add_i32 s34, s55, s33
	v_lshl_add_u64 v[212:213], v[212:213], 0, s[80:81]
	s_mov_b32 m0, s34
	ds_read_b128 v[162:165], v211 offset:49152
	ds_read_b128 v[166:169], v211 offset:50176
	ds_read_b128 v[170:173], v211 offset:51200
	ds_read_b128 v[174:177], v211 offset:52224
	ds_read_b128 v[180:183], v211 offset:53248
	ds_read_b128 v[198:201], v211 offset:54272
	ds_read_b128 v[202:205], v211 offset:55296
	ds_read_b128 v[206:209], v211 offset:56320
	global_load_lds_dwordx4 v[212:213], off
	s_add_i32 m0, s34, 0x2000
	s_add_u32 s30, s30, 0x40080
	v_lshl_add_u64 v[212:213], v[214:215], 0, s[80:81]
	s_addc_u32 s31, s31, 0
	s_add_i32 s34, s56, s33
	global_load_lds_dwordx4 v[212:213], off
	s_mov_b32 m0, s34
	s_nop 0
	global_load_lds_dwordx4 v188, s[30:31]
	s_add_i32 m0, s34, 0x2000
	s_nop 0
	global_load_lds_dwordx4 v192, s[30:31]
	v_lshl_add_u64 v[212:213], v[216:217], 0, s[80:81]
	s_mov_b32 m0, s47
	s_nop 0
	global_load_lds_dwordx4 v[212:213], off
	v_lshl_add_u64 v[212:213], v[218:219], 0, s[80:81]
	s_mov_b32 m0, s48
	s_nop 0
	global_load_lds_dwordx4 v[212:213], off
	s_waitcnt vmcnt(8) lgkmcnt(0)
	s_barrier
	s_setprio 1
	v_mfma_f32_16x16x32_bf16 v[62:65], v[130:133], v[162:165], v[62:65]
	v_mfma_f32_16x16x32_bf16 v[58:61], v[138:141], v[162:165], v[58:61]
	v_mfma_f32_16x16x32_bf16 v[46:49], v[130:133], v[170:173], v[46:49]
	v_mfma_f32_16x16x32_bf16 v[42:45], v[138:141], v[170:173], v[42:45]
	v_mfma_f32_16x16x32_bf16 v[30:33], v[130:133], v[180:183], v[30:33]
	v_mfma_f32_16x16x32_bf16 v[26:29], v[138:141], v[180:183], v[26:29]
	v_mfma_f32_16x16x32_bf16 v[14:17], v[130:133], v[202:205], v[14:17]
	v_mfma_f32_16x16x32_bf16 v[10:13], v[138:141], v[202:205], v[10:13]
	v_mfma_f32_16x16x32_bf16 v[62:65], v[134:137], v[166:169], v[62:65]
	v_mfma_f32_16x16x32_bf16 v[58:61], v[142:145], v[166:169], v[58:61]
	v_mfma_f32_16x16x32_bf16 v[46:49], v[134:137], v[174:177], v[46:49]
	v_mfma_f32_16x16x32_bf16 v[42:45], v[142:145], v[174:177], v[42:45]
	v_mfma_f32_16x16x32_bf16 v[30:33], v[134:137], v[198:201], v[30:33]
	v_mfma_f32_16x16x32_bf16 v[26:29], v[142:145], v[198:201], v[26:29]
	v_mfma_f32_16x16x32_bf16 v[14:17], v[134:137], v[206:209], v[14:17]
	v_mfma_f32_16x16x32_bf16 v[10:13], v[142:145], v[206:209], v[10:13]
	v_mfma_f32_16x16x32_bf16 v[54:57], v[146:149], v[162:165], v[54:57]
	v_mfma_f32_16x16x32_bf16 v[50:53], v[154:157], v[162:165], v[50:53]
	v_mfma_f32_16x16x32_bf16 v[38:41], v[146:149], v[170:173], v[38:41]
	v_mfma_f32_16x16x32_bf16 v[34:37], v[154:157], v[170:173], v[34:37]
	v_mfma_f32_16x16x32_bf16 v[22:25], v[146:149], v[180:183], v[22:25]
	v_mfma_f32_16x16x32_bf16 v[18:21], v[154:157], v[180:183], v[18:21]
	v_mfma_f32_16x16x32_bf16 v[6:9], v[146:149], v[202:205], v[6:9]
	v_mfma_f32_16x16x32_bf16 v[2:5], v[154:157], v[202:205], v[2:5]
	v_mfma_f32_16x16x32_bf16 v[54:57], v[150:153], v[166:169], v[54:57]
	v_mfma_f32_16x16x32_bf16 v[50:53], v[158:161], v[166:169], v[50:53]
	v_mfma_f32_16x16x32_bf16 v[38:41], v[150:153], v[174:177], v[38:41]
	v_mfma_f32_16x16x32_bf16 v[34:37], v[158:161], v[174:177], v[34:37]
	v_mfma_f32_16x16x32_bf16 v[22:25], v[150:153], v[198:201], v[22:25]
	v_mfma_f32_16x16x32_bf16 v[18:21], v[158:161], v[198:201], v[18:21]
	v_mfma_f32_16x16x32_bf16 v[6:9], v[150:153], v[206:209], v[6:9]
	v_mfma_f32_16x16x32_bf16 v[2:5], v[158:161], v[206:209], v[2:5]
	s_setprio 0
	s_barrier
	s_add_i32 s54, s54, 2
	s_add_u32 s28, s28, 0x100
	s_addc_u32 s29, s29, 0
	s_add_u32 s52, s52, 0x100
	s_addc_u32 s53, s53, 0
	s_cmp_gt_u32 s54, 13
	s_branch .LBB0_1106
.LBB0_1106:
	s_add_u32 s30, s28, 0xfffc0080
	s_addc_u32 s31, s29, -1
	s_add_i32 s55, 0, 0x10000
	s_cmp_eq_u32 s54, 12
	s_cselect_b32 s35, s19, s31
	s_cselect_b32 s34, s25, s30
	s_cselect_b32 s31, s17, s53
	s_cselect_b32 s30, s27, s52
	s_add_i32 s58, 0, 0x14000
	v_add_u32_e32 v142, s55, v179
	v_add_u32_e32 v158, s58, v179
	ds_read_b128 v[130:133], v142
	ds_read_b128 v[134:137], v142 offset:1024
	ds_read_b128 v[138:141], v142 offset:2048
	ds_read_b128 v[142:145], v142 offset:3072
	ds_read_b128 v[146:149], v158
	ds_read_b128 v[150:153], v158 offset:1024
	ds_read_b128 v[154:157], v158 offset:2048
	ds_read_b128 v[158:161], v158 offset:3072
	s_add_i32 m0, s36, 0xc000
	ds_read_b128 v[162:165], v211
	ds_read_b128 v[166:169], v211 offset:1024
	ds_read_b128 v[170:173], v211 offset:2048
	ds_read_b128 v[174:177], v211 offset:3072
	ds_read_b128 v[180:183], v211 offset:4096
	ds_read_b128 v[198:201], v211 offset:5120
	ds_read_b128 v[202:205], v211 offset:6144
	ds_read_b128 v[206:209], v211 offset:7168
	global_load_lds_dwordx4 v194, s[28:29]
	s_add_i32 m0, s36, 0xe000
	s_nop 0
	global_load_lds_dwordx4 v196, s[28:29]
	s_waitcnt vmcnt(8) lgkmcnt(0)
	s_barrier
; #define PG8_STAGE(bufoff, gbase, voff) do { _Pragma("unroll") for (int _i = 0; _i < 2; ++_i) \
;         __builtin_amdgcn_global_load_lds((const unsigned*)((const char*)(gbase) + (voff)[_i]), (PG8_LAS unsigned*)(lds + (bufoff) + ldsw + _i * 8192), 16, 0, 0); } while (0)
; #define PG8_LDA(dst, b, h) do { _Pragma("unroll") for (int m = 0; m < 4; ++m) _Pragma("unroll") for (int k = 0; k < 2; ++k) dst[m][k] = *(const PG8_LAS bf16x8*)(lds + PG8_SA(b, h) + aoff + m * 2048 + k * 1024); } while (0)
; #define PG8_LDB(dst, b, h) do { _Pragma("unroll") for (int n = 0; n < 2; ++n) _Pragma("unroll") for (int k = 0; k < 2; ++k) dst[n][k] = *(const PG8_LAS bf16x8*)(lds + PG8_SB(b, h) + boff + n * 2048 + k * 1024); } while (0)
; #define PG8_MMA(ai, bj, At, Bt) do { __builtin_amdgcn_s_setprio(1); _Pragma("unroll") for (int m = 0; m < 4; ++m) _Pragma("unroll") for (int n = 0; n < 2; ++n) _Pragma("unroll") for (int k = 0; k < 2; ++k) \
;         acc[ai][bj][m][n] = __builtin_amdgcn_mfma_f32_16x16x32_bf16(Bt[n][k], At[m][k], acc[ai][bj][m][n], 0, 0, 0); __builtin_amdgcn_s_setprio(0); } while (0)
; #define PG8_WAIT_V(n) asm volatile("s_waitcnt vmcnt(" #n ")" ::: "memory")
; #define PG8_WAIT_L(n) asm volatile("s_waitcnt lgkmcnt(" #n ")" ::: "memory")
; #define PG8_BAR __builtin_amdgcn_s_barrier()
; #define PG8_SCHED __builtin_amdgcn_sched_barrier(0)
; template <class Epi, class Sched, bool ALIGN_EPI = false, bool SP2 = false>
; __device__ __forceinline__ void gemm_phase(PG8_LAS unsigned char* lds, const Gemm g, const Sched& S, const Epi& E) {
;     ...
;             PG8_LDB(B0, 0, 0); PG8_LDB(B1, 0, 1); PG8_SCHED; PG8_LDA(At, 0, 0); PG8_STAGE(PG8_SA(1, 1), a1 + hstep, voffA);
;             PG8_WAIT_V(8); PG8_WAIT_L(0); PG8_BAR; PG8_MMA(0, 0, At, B0); PG8_MMA(0, 1, At, B1); PG8_BAR; PG8_SCHED;
;             PG8_LDA(At, 0, 1); PG8_STAGE(PG8_SB(0, 0), b2, voffB); PG8_STAGE(PG8_SB(0, 1), b2 + hstep, voffB); PG8_STAGE(PG8_SA(0, 0), a2, voffA);
;             PG8_WAIT_V(8); PG8_WAIT_L(0); PG8_BAR; PG8_MMA(1, 0, At, B0); PG8_MMA(1, 1, At, B1); PG8_BAR; PG8_SCHED;
	s_setprio 1
	v_mfma_f32_16x16x32_bf16 v[126:129], v[130:133], v[162:165], v[126:129]
	v_mfma_f32_16x16x32_bf16 v[122:125], v[138:141], v[162:165], v[122:125]
	v_mfma_f32_16x16x32_bf16 v[110:113], v[130:133], v[170:173], v[110:113]
	v_mfma_f32_16x16x32_bf16 v[106:109], v[138:141], v[170:173], v[106:109]
	v_mfma_f32_16x16x32_bf16 v[94:97], v[130:133], v[180:183], v[94:97]
	v_mfma_f32_16x16x32_bf16 v[90:93], v[138:141], v[180:183], v[90:93]
	v_mfma_f32_16x16x32_bf16 v[78:81], v[130:133], v[202:205], v[78:81]
	v_mfma_f32_16x16x32_bf16 v[74:77], v[138:141], v[202:205], v[74:77]
	v_mfma_f32_16x16x32_bf16 v[126:129], v[134:137], v[166:169], v[126:129]
	v_mfma_f32_16x16x32_bf16 v[122:125], v[142:145], v[166:169], v[122:125]
	v_mfma_f32_16x16x32_bf16 v[110:113], v[134:137], v[174:177], v[110:113]
	v_mfma_f32_16x16x32_bf16 v[106:109], v[142:145], v[174:177], v[106:109]
	v_mfma_f32_16x16x32_bf16 v[94:97], v[134:137], v[198:201], v[94:97]
	v_mfma_f32_16x16x32_bf16 v[90:93], v[142:145], v[198:201], v[90:93]
	v_mfma_f32_16x16x32_bf16 v[78:81], v[134:137], v[206:209], v[78:81]
	v_mfma_f32_16x16x32_bf16 v[74:77], v[142:145], v[206:209], v[74:77]
	v_mfma_f32_16x16x32_bf16 v[118:121], v[146:149], v[162:165], v[118:121]
	v_mfma_f32_16x16x32_bf16 v[114:117], v[154:157], v[162:165], v[114:117]
	v_mfma_f32_16x16x32_bf16 v[102:105], v[146:149], v[170:173], v[102:105]
	v_mfma_f32_16x16x32_bf16 v[98:101], v[154:157], v[170:173], v[98:101]
	v_mfma_f32_16x16x32_bf16 v[86:89], v[146:149], v[180:183], v[86:89]
	v_mfma_f32_16x16x32_bf16 v[82:85], v[154:157], v[180:183], v[82:85]
	v_mfma_f32_16x16x32_bf16 v[70:73], v[146:149], v[202:205], v[70:73]
	v_mfma_f32_16x16x32_bf16 v[66:69], v[154:157], v[202:205], v[66:69]
	v_mfma_f32_16x16x32_bf16 v[118:121], v[150:153], v[166:169], v[118:121]
	v_mfma_f32_16x16x32_bf16 v[114:117], v[158:161], v[166:169], v[114:117]
	v_mfma_f32_16x16x32_bf16 v[102:105], v[150:153], v[174:177], v[102:105]
	v_mfma_f32_16x16x32_bf16 v[98:101], v[158:161], v[174:177], v[98:101]
	v_mfma_f32_16x16x32_bf16 v[86:89], v[150:153], v[198:201], v[86:89]
	v_mfma_f32_16x16x32_bf16 v[82:85], v[158:161], v[198:201], v[82:85]
	v_mfma_f32_16x16x32_bf16 v[70:73], v[150:153], v[206:209], v[70:73]
	v_mfma_f32_16x16x32_bf16 v[66:69], v[158:161], v[206:209], v[66:69]
	s_setprio 0
	s_barrier
	s_add_i32 s55, s55, s33
	v_lshl_add_u64 v[212:213], s[30:31], 0, v[188:189]
	s_mov_b32 m0, s55
	ds_read_b128 v[162:165], v211 offset:16384
	ds_read_b128 v[166:169], v211 offset:17408
	ds_read_b128 v[170:173], v211 offset:18432
	ds_read_b128 v[174:177], v211 offset:19456
	ds_read_b128 v[180:183], v211 offset:20480
	ds_read_b128 v[198:201], v211 offset:21504
	ds_read_b128 v[202:205], v211 offset:22528
	ds_read_b128 v[206:209], v211 offset:23552
	global_load_lds_dwordx4 v[212:213], off
	s_add_i32 m0, s55, 0x2000
	s_add_u32 s56, s30, 0x40000
	v_lshl_add_u64 v[214:215], s[30:31], 0, v[192:193]
	s_addc_u32 s57, s31, 0
	s_add_i32 s55, s58, s33
	global_load_lds_dwordx4 v[214:215], off
	v_lshl_add_u64 v[216:217], s[56:57], 0, v[188:189]
	s_mov_b32 m0, s55
	v_lshl_add_u64 v[218:219], s[34:35], 0, v[190:191]
	global_load_lds_dwordx4 v[216:217], off
	s_add_i32 m0, s55, 0x2000
	s_nop 0
	global_load_lds_dwordx4 v192, s[56:57]
	v_lshl_add_u64 v[216:217], s[34:35], 0, v[186:187]
	s_mov_b32 m0, s36
	s_nop 0
	global_load_lds_dwordx4 v[216:217], off
	s_mov_b32 m0, s37
	s_nop 0
	global_load_lds_dwordx4 v[218:219], off
	s_waitcnt vmcnt(8) lgkmcnt(0)
	s_barrier
	s_setprio 1
	v_mfma_f32_16x16x32_bf16 v[62:65], v[130:133], v[162:165], v[62:65]
	v_mfma_f32_16x16x32_bf16 v[58:61], v[138:141], v[162:165], v[58:61]
	v_mfma_f32_16x16x32_bf16 v[46:49], v[130:133], v[170:173], v[46:49]
	v_mfma_f32_16x16x32_bf16 v[42:45], v[138:141], v[170:173], v[42:45]
	v_mfma_f32_16x16x32_bf16 v[30:33], v[130:133], v[180:183], v[30:33]
	v_mfma_f32_16x16x32_bf16 v[26:29], v[138:141], v[180:183], v[26:29]
	v_mfma_f32_16x16x32_bf16 v[14:17], v[130:133], v[202:205], v[14:17]
	v_mfma_f32_16x16x32_bf16 v[10:13], v[138:141], v[202:205], v[10:13]
	v_mfma_f32_16x16x32_bf16 v[62:65], v[134:137], v[166:169], v[62:65]
	v_mfma_f32_16x16x32_bf16 v[58:61], v[142:145], v[166:169], v[58:61]
	v_mfma_f32_16x16x32_bf16 v[46:49], v[134:137], v[174:177], v[46:49]
	v_mfma_f32_16x16x32_bf16 v[42:45], v[142:145], v[174:177], v[42:45]
	v_mfma_f32_16x16x32_bf16 v[30:33], v[134:137], v[198:201], v[30:33]
	v_mfma_f32_16x16x32_bf16 v[26:29], v[142:145], v[198:201], v[26:29]
	v_mfma_f32_16x16x32_bf16 v[14:17], v[134:137], v[206:209], v[14:17]
	v_mfma_f32_16x16x32_bf16 v[10:13], v[142:145], v[206:209], v[10:13]
	v_mfma_f32_16x16x32_bf16 v[54:57], v[146:149], v[162:165], v[54:57]
	v_mfma_f32_16x16x32_bf16 v[50:53], v[154:157], v[162:165], v[50:53]
	v_mfma_f32_16x16x32_bf16 v[38:41], v[146:149], v[170:173], v[38:41]
	v_mfma_f32_16x16x32_bf16 v[34:37], v[154:157], v[170:173], v[34:37]
	v_mfma_f32_16x16x32_bf16 v[22:25], v[146:149], v[180:183], v[22:25]
	v_mfma_f32_16x16x32_bf16 v[18:21], v[154:157], v[180:183], v[18:21]
	v_mfma_f32_16x16x32_bf16 v[6:9], v[146:149], v[202:205], v[6:9]
	v_mfma_f32_16x16x32_bf16 v[2:5], v[154:157], v[202:205], v[2:5]
	v_mfma_f32_16x16x32_bf16 v[54:57], v[150:153], v[166:169], v[54:57]
	v_mfma_f32_16x16x32_bf16 v[50:53], v[158:161], v[166:169], v[50:53]
	v_mfma_f32_16x16x32_bf16 v[38:41], v[150:153], v[174:177], v[38:41]
	v_mfma_f32_16x16x32_bf16 v[34:37], v[158:161], v[174:177], v[34:37]
	v_mfma_f32_16x16x32_bf16 v[22:25], v[150:153], v[198:201], v[22:25]
	v_mfma_f32_16x16x32_bf16 v[18:21], v[158:161], v[198:201], v[18:21]
	v_mfma_f32_16x16x32_bf16 v[6:9], v[150:153], v[206:209], v[6:9]
	v_mfma_f32_16x16x32_bf16 v[2:5], v[158:161], v[206:209], v[2:5]
	s_setprio 0
	s_barrier
; #define PG8_STAGE(bufoff, gbase, voff) do { _Pragma("unroll") for (int _i = 0; _i < 2; ++_i) \
;         __builtin_amdgcn_global_load_lds((const unsigned*)((const char*)(gbase) + (voff)[_i]), (PG8_LAS unsigned*)(lds + (bufoff) + ldsw + _i * 8192), 16, 0, 0); } while (0)
; #define PG8_LDA(dst, b, h) do { _Pragma("unroll") for (int m = 0; m < 4; ++m) _Pragma("unroll") for (int k = 0; k < 2; ++k) dst[m][k] = *(const PG8_LAS bf16x8*)(lds + PG8_SA(b, h) + aoff + m * 2048 + k * 1024); } while (0)
; #define PG8_LDB(dst, b, h) do { _Pragma("unroll") for (int n = 0; n < 2; ++n) _Pragma("unroll") for (int k = 0; k < 2; ++k) dst[n][k] = *(const PG8_LAS bf16x8*)(lds + PG8_SB(b, h) + boff + n * 2048 + k * 1024); } while (0)
; #define PG8_MMA(ai, bj, At, Bt) do { __builtin_amdgcn_s_setprio(1); _Pragma("unroll") for (int m = 0; m < 4; ++m) _Pragma("unroll") for (int n = 0; n < 2; ++n) _Pragma("unroll") for (int k = 0; k < 2; ++k) \
;         acc[ai][bj][m][n] = __builtin_amdgcn_mfma_f32_16x16x32_bf16(Bt[n][k], At[m][k], acc[ai][bj][m][n], 0, 0, 0); __builtin_amdgcn_s_setprio(0); } while (0)
; #define PG8_WAIT_V(n) asm volatile("s_waitcnt vmcnt(" #n ")" ::: "memory")
; #define PG8_WAIT_L(n) asm volatile("s_waitcnt lgkmcnt(" #n ")" ::: "memory")
; #define PG8_BAR __builtin_amdgcn_s_barrier()
; #define PG8_SCHED __builtin_amdgcn_sched_barrier(0)
; template <class Epi, class Sched, bool ALIGN_EPI = false, bool SP2 = false>
; __device__ __forceinline__ void gemm_phase(PG8_LAS unsigned char* lds, const Gemm g, const Sched& S, const Epi& E) {
;     ...
;             PG8_LDB(B0, 1, 0); PG8_LDB(B1, 1, 1); PG8_SCHED; PG8_LDA(At, 1, 0); PG8_STAGE(PG8_SA(0, 1), a2 + hstep, voffA);
;             PG8_WAIT_V(8); PG8_WAIT_L(0); PG8_BAR; PG8_MMA(0, 0, At, B0); PG8_MMA(0, 1, At, B1); PG8_BAR; PG8_SCHED;
;             PG8_LDA(At, 1, 1); PG8_STAGE(PG8_SB(1, 0), b3, voffB); PG8_STAGE(PG8_SB(1, 1), b3 + hstep, voffB); PG8_STAGE(PG8_SA(1, 0), a3, voffA);
;             PG8_WAIT_V(8); PG8_WAIT_L(0); PG8_BAR; PG8_MMA(1, 0, At, B0); PG8_MMA(1, 1, At, B1); PG8_BAR; PG8_SCHED;
;     ...
;         if constexpr (ALIGN_EPI) { if (wr == 0) PG8_BAR; }
	s_add_i32 s55, 0, 0x18000
	s_add_i32 s56, 0, 0x1c000
	v_add_u32_e32 v142, s55, v179
	v_add_u32_e32 v158, s56, v179
	ds_read_b128 v[130:133], v142
	ds_read_b128 v[134:137], v142 offset:1024
	ds_read_b128 v[138:141], v142 offset:2048
	ds_read_b128 v[142:145], v142 offset:3072
	ds_read_b128 v[146:149], v158
	ds_read_b128 v[150:153], v158 offset:1024
	ds_read_b128 v[154:157], v158 offset:2048
	ds_read_b128 v[158:161], v158 offset:3072
	s_add_u32 s34, s34, 0x40000
	s_addc_u32 s35, s35, 0
	s_mov_b32 m0, s38
	ds_read_b128 v[162:165], v211 offset:32768
	ds_read_b128 v[166:169], v211 offset:33792
	ds_read_b128 v[170:173], v211 offset:34816
	ds_read_b128 v[174:177], v211 offset:35840
	ds_read_b128 v[180:183], v211 offset:36864
	ds_read_b128 v[198:201], v211 offset:37888
	ds_read_b128 v[202:205], v211 offset:38912
	ds_read_b128 v[206:209], v211 offset:39936
	global_load_lds_dwordx4 v186, s[34:35]
	v_lshl_add_u64 v[220:221], s[34:35], 0, v[190:191]
	s_mov_b32 m0, s39
	s_nop 0
	global_load_lds_dwordx4 v[220:221], off
	s_waitcnt vmcnt(8) lgkmcnt(0)
	s_barrier
	s_setprio 1
	v_mfma_f32_16x16x32_bf16 v[126:129], v[130:133], v[162:165], v[126:129]
	v_mfma_f32_16x16x32_bf16 v[122:125], v[138:141], v[162:165], v[122:125]
	v_mfma_f32_16x16x32_bf16 v[110:113], v[130:133], v[170:173], v[110:113]
	v_mfma_f32_16x16x32_bf16 v[106:109], v[138:141], v[170:173], v[106:109]
	v_mfma_f32_16x16x32_bf16 v[94:97], v[130:133], v[180:183], v[94:97]
	v_mfma_f32_16x16x32_bf16 v[90:93], v[138:141], v[180:183], v[90:93]
	v_mfma_f32_16x16x32_bf16 v[78:81], v[130:133], v[202:205], v[78:81]
	v_mfma_f32_16x16x32_bf16 v[74:77], v[138:141], v[202:205], v[74:77]
	v_mfma_f32_16x16x32_bf16 v[126:129], v[134:137], v[166:169], v[126:129]
	v_mfma_f32_16x16x32_bf16 v[122:125], v[142:145], v[166:169], v[122:125]
	v_mfma_f32_16x16x32_bf16 v[110:113], v[134:137], v[174:177], v[110:113]
	v_mfma_f32_16x16x32_bf16 v[106:109], v[142:145], v[174:177], v[106:109]
	v_mfma_f32_16x16x32_bf16 v[94:97], v[134:137], v[198:201], v[94:97]
	v_mfma_f32_16x16x32_bf16 v[90:93], v[142:145], v[198:201], v[90:93]
	v_mfma_f32_16x16x32_bf16 v[78:81], v[134:137], v[206:209], v[78:81]
	v_mfma_f32_16x16x32_bf16 v[74:77], v[142:145], v[206:209], v[74:77]
	v_mfma_f32_16x16x32_bf16 v[118:121], v[146:149], v[162:165], v[118:121]
	v_mfma_f32_16x16x32_bf16 v[114:117], v[154:157], v[162:165], v[114:117]
	v_mfma_f32_16x16x32_bf16 v[102:105], v[146:149], v[170:173], v[102:105]
	v_mfma_f32_16x16x32_bf16 v[98:101], v[154:157], v[170:173], v[98:101]
	v_mfma_f32_16x16x32_bf16 v[86:89], v[146:149], v[180:183], v[86:89]
	v_mfma_f32_16x16x32_bf16 v[82:85], v[154:157], v[180:183], v[82:85]
	v_mfma_f32_16x16x32_bf16 v[70:73], v[146:149], v[202:205], v[70:73]
	v_mfma_f32_16x16x32_bf16 v[66:69], v[154:157], v[202:205], v[66:69]
	v_mfma_f32_16x16x32_bf16 v[118:121], v[150:153], v[166:169], v[118:121]
	v_mfma_f32_16x16x32_bf16 v[114:117], v[158:161], v[166:169], v[114:117]
	v_mfma_f32_16x16x32_bf16 v[102:105], v[150:153], v[174:177], v[102:105]
	v_mfma_f32_16x16x32_bf16 v[98:101], v[158:161], v[174:177], v[98:101]
	v_mfma_f32_16x16x32_bf16 v[86:89], v[150:153], v[198:201], v[86:89]
	v_mfma_f32_16x16x32_bf16 v[82:85], v[158:161], v[198:201], v[82:85]
	v_mfma_f32_16x16x32_bf16 v[70:73], v[150:153], v[206:209], v[70:73]
	v_mfma_f32_16x16x32_bf16 v[66:69], v[158:161], v[206:209], v[66:69]
	s_setprio 0
	s_barrier
	s_add_i32 s34, s55, s33
	v_lshl_add_u64 v[212:213], v[212:213], 0, s[80:81]
	s_mov_b32 m0, s34
	ds_read_b128 v[162:165], v211 offset:49152
	ds_read_b128 v[166:169], v211 offset:50176
	ds_read_b128 v[170:173], v211 offset:51200
	ds_read_b128 v[174:177], v211 offset:52224
	ds_read_b128 v[180:183], v211 offset:53248
	ds_read_b128 v[198:201], v211 offset:54272
	ds_read_b128 v[202:205], v211 offset:55296
	ds_read_b128 v[206:209], v211 offset:56320
	global_load_lds_dwordx4 v[212:213], off
	s_add_i32 m0, s34, 0x2000
	s_add_u32 s30, s30, 0x40080
	v_lshl_add_u64 v[212:213], v[214:215], 0, s[80:81]
	s_addc_u32 s31, s31, 0
	s_add_i32 s34, s56, s33
	global_load_lds_dwordx4 v[212:213], off
	s_mov_b32 m0, s34
	s_nop 0
	global_load_lds_dwordx4 v188, s[30:31]
	s_add_i32 m0, s34, 0x2000
	s_nop 0
	global_load_lds_dwordx4 v192, s[30:31]
	v_lshl_add_u64 v[212:213], v[216:217], 0, s[80:81]
	s_mov_b32 m0, s47
	s_nop 0
	global_load_lds_dwordx4 v[212:213], off
	v_lshl_add_u64 v[212:213], v[218:219], 0, s[80:81]
	s_mov_b32 m0, s48
	s_nop 0
	global_load_lds_dwordx4 v[212:213], off
	s_waitcnt vmcnt(8) lgkmcnt(0)
	s_barrier
	s_setprio 1
	v_mfma_f32_16x16x32_bf16 v[62:65], v[130:133], v[162:165], v[62:65]
	v_mfma_f32_16x16x32_bf16 v[58:61], v[138:141], v[162:165], v[58:61]
	v_mfma_f32_16x16x32_bf16 v[46:49], v[130:133], v[170:173], v[46:49]
	v_mfma_f32_16x16x32_bf16 v[42:45], v[138:141], v[170:173], v[42:45]
	v_mfma_f32_16x16x32_bf16 v[30:33], v[130:133], v[180:183], v[30:33]
	v_mfma_f32_16x16x32_bf16 v[26:29], v[138:141], v[180:183], v[26:29]
	v_mfma_f32_16x16x32_bf16 v[14:17], v[130:133], v[202:205], v[14:17]
	v_mfma_f32_16x16x32_bf16 v[10:13], v[138:141], v[202:205], v[10:13]
	v_mfma_f32_16x16x32_bf16 v[62:65], v[134:137], v[166:169], v[62:65]
	v_mfma_f32_16x16x32_bf16 v[58:61], v[142:145], v[166:169], v[58:61]
	v_mfma_f32_16x16x32_bf16 v[46:49], v[134:137], v[174:177], v[46:49]
	v_mfma_f32_16x16x32_bf16 v[42:45], v[142:145], v[174:177], v[42:45]
	v_mfma_f32_16x16x32_bf16 v[30:33], v[134:137], v[198:201], v[30:33]
	v_mfma_f32_16x16x32_bf16 v[26:29], v[142:145], v[198:201], v[26:29]
	v_mfma_f32_16x16x32_bf16 v[14:17], v[134:137], v[206:209], v[14:17]
	v_mfma_f32_16x16x32_bf16 v[10:13], v[142:145], v[206:209], v[10:13]
	v_mfma_f32_16x16x32_bf16 v[54:57], v[146:149], v[162:165], v[54:57]
	v_mfma_f32_16x16x32_bf16 v[50:53], v[154:157], v[162:165], v[50:53]
	v_mfma_f32_16x16x32_bf16 v[38:41], v[146:149], v[170:173], v[38:41]
	v_mfma_f32_16x16x32_bf16 v[34:37], v[154:157], v[170:173], v[34:37]
	v_mfma_f32_16x16x32_bf16 v[22:25], v[146:149], v[180:183], v[22:25]
	v_mfma_f32_16x16x32_bf16 v[18:21], v[154:157], v[180:183], v[18:21]
	v_mfma_f32_16x16x32_bf16 v[6:9], v[146:149], v[202:205], v[6:9]
	v_mfma_f32_16x16x32_bf16 v[2:5], v[154:157], v[202:205], v[2:5]
	v_mfma_f32_16x16x32_bf16 v[54:57], v[150:153], v[166:169], v[54:57]
	v_mfma_f32_16x16x32_bf16 v[50:53], v[158:161], v[166:169], v[50:53]
	v_mfma_f32_16x16x32_bf16 v[38:41], v[150:153], v[174:177], v[38:41]
	v_mfma_f32_16x16x32_bf16 v[34:37], v[158:161], v[174:177], v[34:37]
	v_mfma_f32_16x16x32_bf16 v[22:25], v[150:153], v[198:201], v[22:25]
	v_mfma_f32_16x16x32_bf16 v[18:21], v[158:161], v[198:201], v[18:21]
	v_mfma_f32_16x16x32_bf16 v[6:9], v[150:153], v[206:209], v[6:9]
	v_mfma_f32_16x16x32_bf16 v[2:5], v[158:161], v[206:209], v[2:5]
	s_setprio 0
	s_barrier
	s_add_i32 s54, s54, 2
	s_add_u32 s28, s28, 0x100
	s_addc_u32 s29, s29, 0
	s_add_u32 s52, s52, 0x100
	s_addc_u32 s53, s53, 0
	s_cmp_gt_u32 s54, 13
	s_cbranch_scc0 .LBB0_1106
	s_and_b64 vcc, exec, s[14:15]
	s_cbranch_vccz .LBB0_1109
	s_barrier

; #define PG8_STAGE(bufoff, gbase, voff) do { _Pragma("unroll") for (int _i = 0; _i < 2; ++_i) \
;         __builtin_amdgcn_global_load_lds((const unsigned*)((const char*)(gbase) + (voff)[_i]), (PG8_LAS unsigned*)(lds + (bufoff) + ldsw + _i * 8192), 16, 0, 0); } while (0)
; #define PG8_LDA(dst, b, h) do { _Pragma("unroll") for (int m = 0; m < 4; ++m) _Pragma("unroll") for (int k = 0; k < 2; ++k) dst[m][k] = *(const PG8_LAS bf16x8*)(lds + PG8_SA(b, h) + aoff + m * 2048 + k * 1024); } while (0)
; #define PG8_LDB(dst, b, h) do { _Pragma("unroll") for (int n = 0; n < 2; ++n) _Pragma("unroll") for (int k = 0; k < 2; ++k) dst[n][k] = *(const PG8_LAS bf16x8*)(lds + PG8_SB(b, h) + boff + n * 2048 + k * 1024); } while (0)
; #define PG8_WAIT_V(n) asm volatile("s_waitcnt vmcnt(" #n ")" ::: "memory")
; #define PG8_WAIT_L(n) asm volatile("s_waitcnt lgkmcnt(" #n ")" ::: "memory")
; #define PG8_BAR __builtin_amdgcn_s_barrier()
; #define PG8_SCHED __builtin_amdgcn_sched_barrier(0)
; template <class Epi, class Sched, bool ALIGN_EPI = false, bool SP2 = false>
; __device__ __forceinline__ void gemm_phase(PG8_LAS unsigned char* lds, const Gemm g, const Sched& S, const Epi& E) {
;     ...
;         const bool has_next = S.next(ui + 1, nxt);
;         const char* nA = has_next ? (const char*)g.A + (size_t)nxt.pm * tstep : cA; const char* nB = has_next ? (const char*)g.Bt + (size_t)nxt.pn * tstep : cB;
;         for (int t = 0; t < nt; t += 2) {
;             const bool last = (t == nt - 2);
;             const char* a1 = cA + (size_t)(t + 1) * kstep;
;             const char* a2 = last ? nA : cA + (size_t)(t + 2) * kstep; const char* b2 = last ? nB : cB + (size_t)(t + 2) * kstep;
;             const char* a3 = a2 + kstep; const char* b3 = b2 + kstep;
;             if (last && has_next) S.a_ready(nxt);
;             if constexpr (SP2) {
;             PG8_LDB(B0, 0, 0); PG8_LDB(B1, 0, 1); PG8_SCHED; PG8_LDA(At, 0, 0); PG8_STAGE(PG8_SA(1, 1), a1 + hstep, voffA);
;             PG8_WAIT_V(8); PG8_WAIT_L(0); PG8_BAR; PG8_MMA(0, 0, At, B0); PG8_MMA(0, 1, At, B1); PG8_BAR; PG8_SCHED;
;             PG8_LDA(At, 0, 1); PG8_STAGE(PG8_SB(0, 0), b2, voffB); PG8_STAGE(PG8_SB(0, 1), b2 + hstep, voffB); PG8_STAGE(PG8_SA(0, 0), a2, voffA);
;             PG8_WAIT_V(8); PG8_WAIT_L(0); PG8_BAR; PG8_MMA(1, 0, At, B0); PG8_MMA(1, 1, At, B1); PG8_BAR; PG8_SCHED;
.LBB0_1248:
	s_ashr_i32 s17, s16, 31
	s_lshl_b64 s[18:19], s[16:17], 19
	s_add_u32 s18, s0, s18
	s_addc_u32 s19, s1, s19
	s_and_b64 s[20:21], s[4:5], exec
	s_cselect_b32 s17, s19, s25
	s_cselect_b32 s45, s18, s24
	s_ashr_i32 s15, s14, 31
	s_lshl_b64 s[20:21], s[14:15], 19
	s_add_u32 s20, s34, s20
	s_addc_u32 s21, s35, s21
	s_and_b64 s[28:29], s[4:5], exec
	s_cselect_b32 s15, s21, s27
	s_cselect_b32 s46, s20, s26
	s_add_u32 s24, s24, 0x40080
	s_addc_u32 s25, s25, 0
	s_add_u32 s47, s26, 0x100
	s_addc_u32 s48, s27, 0
	s_mov_b32 s49, -2
	s_add_u32 s26, s24, 0xfffc0080
	s_addc_u32 s27, s25, -1
	s_add_i32 s50, 0, 0x10000
	s_cmp_eq_u32 s49, 12
	s_cselect_b32 s29, s17, s27
	s_cselect_b32 s28, s45, s26
	v_add_u32_e32 v156, s50, v158
	s_cselect_b32 s27, s15, s48
	s_cselect_b32 s26, s46, s47
	s_add_i32 s52, 0, 0x14000
	ds_read_b128 v[66:69], v156
	ds_read_b128 v[118:121], v156 offset:1024
	ds_read_b128 v[152:155], v156 offset:2048
	ds_read_b128 v[162:165], v156 offset:3072
	v_add_u32_e32 v156, s52, v158
	ds_read_b128 v[166:169], v156
	ds_read_b128 v[170:173], v156 offset:1024
	ds_read_b128 v[174:177], v156 offset:2048
	ds_read_b128 v[180:183], v156 offset:3072
	s_add_i32 m0, s33, 0xc000
	ds_read_b128 v[186:189], v160
	ds_read_b128 v[190:193], v160 offset:1024
	ds_read_b128 v[194:197], v160 offset:2048
	ds_read_b128 v[198:201], v160 offset:3072
	ds_read_b128 v[202:205], v160 offset:4096
	ds_read_b128 v[206:209], v160 offset:5120
	ds_read_b128 v[210:213], v160 offset:6144
	ds_read_b128 v[214:217], v160 offset:7168
	global_load_lds_dwordx4 v148, s[24:25]
	s_add_i32 m0, s33, 0xe000
	s_nop 0
	global_load_lds_dwordx4 v150, s[24:25]
	s_waitcnt vmcnt(8) lgkmcnt(0)
	s_barrier
	s_setprio 1
	v_mfma_f32_16x16x32_bf16 v[134:137], v[66:69], v[186:189], 0
	v_mfma_f32_16x16x32_bf16 v[126:129], v[152:155], v[186:189], 0
	v_mfma_f32_16x16x32_bf16 v[114:117], v[66:69], v[194:197], 0
	v_mfma_f32_16x16x32_bf16 v[110:113], v[152:155], v[194:197], 0
	v_mfma_f32_16x16x32_bf16 v[98:101], v[66:69], v[202:205], 0
	v_mfma_f32_16x16x32_bf16 v[94:97], v[152:155], v[202:205], 0
	v_mfma_f32_16x16x32_bf16 v[82:85], v[66:69], v[210:213], 0
	v_mfma_f32_16x16x32_bf16 v[78:81], v[152:155], v[210:213], 0
	v_mfma_f32_16x16x32_bf16 v[134:137], v[118:121], v[190:193], v[134:137]
	v_mfma_f32_16x16x32_bf16 v[126:129], v[162:165], v[190:193], v[126:129]
	v_mfma_f32_16x16x32_bf16 v[114:117], v[118:121], v[198:201], v[114:117]
	v_mfma_f32_16x16x32_bf16 v[110:113], v[162:165], v[198:201], v[110:113]
	v_mfma_f32_16x16x32_bf16 v[98:101], v[118:121], v[206:209], v[98:101]
	v_mfma_f32_16x16x32_bf16 v[94:97], v[162:165], v[206:209], v[94:97]
	v_mfma_f32_16x16x32_bf16 v[82:85], v[118:121], v[214:217], v[82:85]
	v_mfma_f32_16x16x32_bf16 v[78:81], v[162:165], v[214:217], v[78:81]
	v_mfma_f32_16x16x32_bf16 v[130:133], v[166:169], v[186:189], 0
	v_mfma_f32_16x16x32_bf16 v[122:125], v[174:177], v[186:189], 0
	v_mfma_f32_16x16x32_bf16 v[106:109], v[166:169], v[194:197], 0
	v_mfma_f32_16x16x32_bf16 v[102:105], v[174:177], v[194:197], 0
	v_mfma_f32_16x16x32_bf16 v[90:93], v[166:169], v[202:205], 0
	v_mfma_f32_16x16x32_bf16 v[86:89], v[174:177], v[202:205], 0
	v_mfma_f32_16x16x32_bf16 v[74:77], v[166:169], v[210:213], 0
	v_mfma_f32_16x16x32_bf16 v[70:73], v[174:177], v[210:213], 0
	v_mfma_f32_16x16x32_bf16 v[130:133], v[170:173], v[190:193], v[130:133]
	v_mfma_f32_16x16x32_bf16 v[122:125], v[180:183], v[190:193], v[122:125]
	v_mfma_f32_16x16x32_bf16 v[106:109], v[170:173], v[198:201], v[106:109]
	v_mfma_f32_16x16x32_bf16 v[102:105], v[180:183], v[198:201], v[102:105]
	v_mfma_f32_16x16x32_bf16 v[90:93], v[170:173], v[206:209], v[90:93]
	v_mfma_f32_16x16x32_bf16 v[86:89], v[180:183], v[206:209], v[86:89]
	v_mfma_f32_16x16x32_bf16 v[74:77], v[170:173], v[214:217], v[74:77]
	v_mfma_f32_16x16x32_bf16 v[70:73], v[180:183], v[214:217], v[70:73]
	s_setprio 0
	s_barrier
	s_add_i32 s50, s50, s36
	v_lshl_add_u64 v[156:157], s[26:27], 0, v[142:143]
	s_mov_b32 m0, s50
	ds_read_b128 v[186:189], v160 offset:16384
	ds_read_b128 v[190:193], v160 offset:17408
	ds_read_b128 v[194:197], v160 offset:18432
	ds_read_b128 v[198:201], v160 offset:19456
	ds_read_b128 v[202:205], v160 offset:20480
	ds_read_b128 v[206:209], v160 offset:21504
	ds_read_b128 v[210:213], v160 offset:22528
	ds_read_b128 v[214:217], v160 offset:23552
	global_load_lds_dwordx4 v[156:157], off
	s_add_i32 m0, s50, 0x2000
	s_add_u32 s50, s26, 0x40000
	v_lshl_add_u64 v[218:219], s[26:27], 0, v[138:139]
	s_addc_u32 s51, s27, 0
	s_add_i32 s52, s52, s36
	global_load_lds_dwordx4 v[218:219], off
	v_lshl_add_u64 v[220:221], s[50:51], 0, v[142:143]
	s_mov_b32 m0, s52
	v_lshl_add_u64 v[222:223], s[28:29], 0, v[140:141]
	global_load_lds_dwordx4 v[220:221], off
	s_add_i32 m0, s52, 0x2000
	s_nop 0
	global_load_lds_dwordx4 v138, s[50:51]
	v_lshl_add_u64 v[220:221], s[28:29], 0, v[144:145]
	s_mov_b32 m0, s33
	s_nop 0
	global_load_lds_dwordx4 v[220:221], off
	s_mov_b32 m0, s38
	s_nop 0
	global_load_lds_dwordx4 v[222:223], off
	s_waitcnt vmcnt(8) lgkmcnt(0)
	s_barrier
; #define PG8_STAGE(bufoff, gbase, voff) do { _Pragma("unroll") for (int _i = 0; _i < 2; ++_i) \
;         __builtin_amdgcn_global_load_lds((const unsigned*)((const char*)(gbase) + (voff)[_i]), (PG8_LAS unsigned*)(lds + (bufoff) + ldsw + _i * 8192), 16, 0, 0); } while (0)
; #define PG8_LDA(dst, b, h) do { _Pragma("unroll") for (int m = 0; m < 4; ++m) _Pragma("unroll") for (int k = 0; k < 2; ++k) dst[m][k] = *(const PG8_LAS bf16x8*)(lds + PG8_SA(b, h) + aoff + m * 2048 + k * 1024); } while (0)
; #define PG8_LDB(dst, b, h) do { _Pragma("unroll") for (int n = 0; n < 2; ++n) _Pragma("unroll") for (int k = 0; k < 2; ++k) dst[n][k] = *(const PG8_LAS bf16x8*)(lds + PG8_SB(b, h) + boff + n * 2048 + k * 1024); } while (0)
; #define PG8_MMA(ai, bj, At, Bt) do { __builtin_amdgcn_s_setprio(1); _Pragma("unroll") for (int m = 0; m < 4; ++m) _Pragma("unroll") for (int n = 0; n < 2; ++n) _Pragma("unroll") for (int k = 0; k < 2; ++k) \
;         acc[ai][bj][m][n] = __builtin_amdgcn_mfma_f32_16x16x32_bf16(Bt[n][k], At[m][k], acc[ai][bj][m][n], 0, 0, 0); __builtin_amdgcn_s_setprio(0); } while (0)
; #define PG8_WAIT_V(n) asm volatile("s_waitcnt vmcnt(" #n ")" ::: "memory")
; #define PG8_WAIT_L(n) asm volatile("s_waitcnt lgkmcnt(" #n ")" ::: "memory")
; #define PG8_BAR __builtin_amdgcn_s_barrier()
; #define PG8_SCHED __builtin_amdgcn_sched_barrier(0)
; template <class Epi, class Sched, bool ALIGN_EPI = false, bool SP2 = false>
; __device__ __forceinline__ void gemm_phase(PG8_LAS unsigned char* lds, const Gemm g, const Sched& S, const Epi& E) {
;     ...
;             PG8_WAIT_V(8); PG8_WAIT_L(0); PG8_BAR; PG8_MMA(1, 0, At, B0); PG8_MMA(1, 1, At, B1); PG8_BAR; PG8_SCHED;
;             PG8_LDB(B0, 1, 0); PG8_LDB(B1, 1, 1); PG8_SCHED; PG8_LDA(At, 1, 0); PG8_STAGE(PG8_SA(0, 1), a2 + hstep, voffA);
;             PG8_WAIT_V(8); PG8_WAIT_L(0); PG8_BAR; PG8_MMA(0, 0, At, B0); PG8_MMA(0, 1, At, B1); PG8_BAR; PG8_SCHED;
	s_setprio 1
	v_mfma_f32_16x16x32_bf16 v[62:65], v[66:69], v[186:189], 0
	v_mfma_f32_16x16x32_bf16 v[58:61], v[152:155], v[186:189], 0
	v_mfma_f32_16x16x32_bf16 v[46:49], v[66:69], v[194:197], 0
	v_mfma_f32_16x16x32_bf16 v[42:45], v[152:155], v[194:197], 0
	v_mfma_f32_16x16x32_bf16 v[30:33], v[66:69], v[202:205], 0
	v_mfma_f32_16x16x32_bf16 v[26:29], v[152:155], v[202:205], 0
	v_mfma_f32_16x16x32_bf16 v[14:17], v[66:69], v[210:213], 0
	v_mfma_f32_16x16x32_bf16 v[10:13], v[152:155], v[210:213], 0
	v_mfma_f32_16x16x32_bf16 v[62:65], v[118:121], v[190:193], v[62:65]
	v_mfma_f32_16x16x32_bf16 v[58:61], v[162:165], v[190:193], v[58:61]
	v_mfma_f32_16x16x32_bf16 v[46:49], v[118:121], v[198:201], v[46:49]
	v_mfma_f32_16x16x32_bf16 v[42:45], v[162:165], v[198:201], v[42:45]
	v_mfma_f32_16x16x32_bf16 v[30:33], v[118:121], v[206:209], v[30:33]
	v_mfma_f32_16x16x32_bf16 v[26:29], v[162:165], v[206:209], v[26:29]
	v_mfma_f32_16x16x32_bf16 v[14:17], v[118:121], v[214:217], v[14:17]
	v_mfma_f32_16x16x32_bf16 v[10:13], v[162:165], v[214:217], v[10:13]
	v_mfma_f32_16x16x32_bf16 v[54:57], v[166:169], v[186:189], 0
	v_mfma_f32_16x16x32_bf16 v[50:53], v[174:177], v[186:189], 0
	v_mfma_f32_16x16x32_bf16 v[38:41], v[166:169], v[194:197], 0
	v_mfma_f32_16x16x32_bf16 v[34:37], v[174:177], v[194:197], 0
	v_mfma_f32_16x16x32_bf16 v[22:25], v[166:169], v[202:205], 0
	v_mfma_f32_16x16x32_bf16 v[18:21], v[174:177], v[202:205], 0
	v_mfma_f32_16x16x32_bf16 v[6:9], v[166:169], v[210:213], 0
	v_mfma_f32_16x16x32_bf16 v[2:5], v[174:177], v[210:213], 0
	v_mfma_f32_16x16x32_bf16 v[54:57], v[170:173], v[190:193], v[54:57]
	v_mfma_f32_16x16x32_bf16 v[50:53], v[180:183], v[190:193], v[50:53]
	v_mfma_f32_16x16x32_bf16 v[38:41], v[170:173], v[198:201], v[38:41]
	v_mfma_f32_16x16x32_bf16 v[34:37], v[180:183], v[198:201], v[34:37]
	v_mfma_f32_16x16x32_bf16 v[22:25], v[170:173], v[206:209], v[22:25]
	v_mfma_f32_16x16x32_bf16 v[18:21], v[180:183], v[206:209], v[18:21]
	v_mfma_f32_16x16x32_bf16 v[6:9], v[170:173], v[214:217], v[6:9]
	v_mfma_f32_16x16x32_bf16 v[2:5], v[180:183], v[214:217], v[2:5]
	s_setprio 0
	s_barrier
	s_add_i32 s50, 0, 0x18000
	v_add_u32_e32 v161, s50, v158
	s_add_i32 s51, 0, 0x1c000
	ds_read_b128 v[66:69], v161
	ds_read_b128 v[118:121], v161 offset:1024
	ds_read_b128 v[152:155], v161 offset:2048
	ds_read_b128 v[162:165], v161 offset:3072
	v_add_u32_e32 v161, s51, v158
	ds_read_b128 v[166:169], v161
	ds_read_b128 v[170:173], v161 offset:1024
	ds_read_b128 v[174:177], v161 offset:2048
	ds_read_b128 v[180:183], v161 offset:3072
	s_add_u32 s28, s28, 0x40000
	s_addc_u32 s29, s29, 0
	s_mov_b32 m0, s39
	ds_read_b128 v[186:189], v160 offset:32768
	ds_read_b128 v[190:193], v160 offset:33792
	ds_read_b128 v[194:197], v160 offset:34816
	ds_read_b128 v[198:201], v160 offset:35840
	ds_read_b128 v[202:205], v160 offset:36864
	ds_read_b128 v[206:209], v160 offset:37888
	ds_read_b128 v[210:213], v160 offset:38912
	ds_read_b128 v[214:217], v160 offset:39936
	global_load_lds_dwordx4 v144, s[28:29]
	v_lshl_add_u64 v[240:241], s[28:29], 0, v[140:141]
	s_mov_b32 m0, s40
	s_nop 0
	global_load_lds_dwordx4 v[240:241], off
	s_waitcnt vmcnt(8) lgkmcnt(0)
	s_barrier
	s_setprio 1
	v_mfma_f32_16x16x32_bf16 v[134:137], v[66:69], v[186:189], v[134:137]
	v_mfma_f32_16x16x32_bf16 v[126:129], v[152:155], v[186:189], v[126:129]
	v_mfma_f32_16x16x32_bf16 v[114:117], v[66:69], v[194:197], v[114:117]
	v_mfma_f32_16x16x32_bf16 v[110:113], v[152:155], v[194:197], v[110:113]
	v_mfma_f32_16x16x32_bf16 v[98:101], v[66:69], v[202:205], v[98:101]
	v_mfma_f32_16x16x32_bf16 v[94:97], v[152:155], v[202:205], v[94:97]
	v_mfma_f32_16x16x32_bf16 v[82:85], v[66:69], v[210:213], v[82:85]
	v_mfma_f32_16x16x32_bf16 v[78:81], v[152:155], v[210:213], v[78:81]
	v_mfma_f32_16x16x32_bf16 v[134:137], v[118:121], v[190:193], v[134:137]
	v_mfma_f32_16x16x32_bf16 v[126:129], v[162:165], v[190:193], v[126:129]
	v_mfma_f32_16x16x32_bf16 v[114:117], v[118:121], v[198:201], v[114:117]
	v_mfma_f32_16x16x32_bf16 v[110:113], v[162:165], v[198:201], v[110:113]
	v_mfma_f32_16x16x32_bf16 v[98:101], v[118:121], v[206:209], v[98:101]
	v_mfma_f32_16x16x32_bf16 v[94:97], v[162:165], v[206:209], v[94:97]
	v_mfma_f32_16x16x32_bf16 v[82:85], v[118:121], v[214:217], v[82:85]
	v_mfma_f32_16x16x32_bf16 v[78:81], v[162:165], v[214:217], v[78:81]
	v_mfma_f32_16x16x32_bf16 v[130:133], v[166:169], v[186:189], v[130:133]
	v_mfma_f32_16x16x32_bf16 v[122:125], v[174:177], v[186:189], v[122:125]
	v_mfma_f32_16x16x32_bf16 v[106:109], v[166:169], v[194:197], v[106:109]
	v_mfma_f32_16x16x32_bf16 v[102:105], v[174:177], v[194:197], v[102:105]
	v_mfma_f32_16x16x32_bf16 v[90:93], v[166:169], v[202:205], v[90:93]
	v_mfma_f32_16x16x32_bf16 v[86:89], v[174:177], v[202:205], v[86:89]
	v_mfma_f32_16x16x32_bf16 v[74:77], v[166:169], v[210:213], v[74:77]
	v_mfma_f32_16x16x32_bf16 v[70:73], v[174:177], v[210:213], v[70:73]
	v_mfma_f32_16x16x32_bf16 v[130:133], v[170:173], v[190:193], v[130:133]
	v_mfma_f32_16x16x32_bf16 v[122:125], v[180:183], v[190:193], v[122:125]
	v_mfma_f32_16x16x32_bf16 v[106:109], v[170:173], v[198:201], v[106:109]
	v_mfma_f32_16x16x32_bf16 v[102:105], v[180:183], v[198:201], v[102:105]
	v_mfma_f32_16x16x32_bf16 v[90:93], v[170:173], v[206:209], v[90:93]
	v_mfma_f32_16x16x32_bf16 v[86:89], v[180:183], v[206:209], v[86:89]
	v_mfma_f32_16x16x32_bf16 v[74:77], v[170:173], v[214:217], v[74:77]
	v_mfma_f32_16x16x32_bf16 v[70:73], v[180:183], v[214:217], v[70:73]
	s_setprio 0
	s_barrier
; #define PG8_STAGE(bufoff, gbase, voff) do { _Pragma("unroll") for (int _i = 0; _i < 2; ++_i) \
;         __builtin_amdgcn_global_load_lds((const unsigned*)((const char*)(gbase) + (voff)[_i]), (PG8_LAS unsigned*)(lds + (bufoff) + ldsw + _i * 8192), 16, 0, 0); } while (0)
; #define PG8_LDA(dst, b, h) do { _Pragma("unroll") for (int m = 0; m < 4; ++m) _Pragma("unroll") for (int k = 0; k < 2; ++k) dst[m][k] = *(const PG8_LAS bf16x8*)(lds + PG8_SA(b, h) + aoff + m * 2048 + k * 1024); } while (0)
; #define PG8_LDB(dst, b, h) do { _Pragma("unroll") for (int n = 0; n < 2; ++n) _Pragma("unroll") for (int k = 0; k < 2; ++k) dst[n][k] = *(const PG8_LAS bf16x8*)(lds + PG8_SB(b, h) + boff + n * 2048 + k * 1024); } while (0)
; #define PG8_MMA(ai, bj, At, Bt) do { __builtin_amdgcn_s_setprio(1); _Pragma("unroll") for (int m = 0; m < 4; ++m) _Pragma("unroll") for (int n = 0; n < 2; ++n) _Pragma("unroll") for (int k = 0; k < 2; ++k) \
;         acc[ai][bj][m][n] = __builtin_amdgcn_mfma_f32_16x16x32_bf16(Bt[n][k], At[m][k], acc[ai][bj][m][n], 0, 0, 0); __builtin_amdgcn_s_setprio(0); } while (0)
; #define PG8_WAIT_V(n) asm volatile("s_waitcnt vmcnt(" #n ")" ::: "memory")
; template <class Epi, class Sched, bool ALIGN_EPI = false, bool SP2 = false>
; __device__ __forceinline__ void gemm_phase(PG8_LAS unsigned char* lds, const Gemm g, const Sched& S, const Epi& E) {
;     ...
;             PG8_LDB(B0, 0, 0); PG8_LDB(B1, 0, 1); PG8_SCHED; PG8_LDA(At, 0, 0); PG8_STAGE(PG8_SA(1, 1), a1 + hstep, voffA);
;             PG8_WAIT_V(8); PG8_WAIT_L(0); PG8_BAR; PG8_MMA(0, 0, At, B0); PG8_MMA(0, 1, At, B1); PG8_BAR; PG8_SCHED;
;             PG8_LDA(At, 0, 1); PG8_STAGE(PG8_SB(0, 0), b2, voffB); PG8_STAGE(PG8_SB(0, 1), b2 + hstep, voffB); PG8_STAGE(PG8_SA(0, 0), a2, voffA);
;             PG8_WAIT_V(8); PG8_WAIT_L(0); PG8_BAR; PG8_MMA(1, 0, At, B0); PG8_MMA(1, 1, At, B1); PG8_BAR; PG8_SCHED;
;             PG8_LDB(B0, 1, 0); PG8_LDB(B1, 1, 1); PG8_SCHED; PG8_LDA(At, 1, 0); PG8_STAGE(PG8_SA(0, 1), a2 + hstep, voffA);
;             PG8_WAIT_V(8); PG8_WAIT_L(0); PG8_BAR; PG8_MMA(0, 0, At, B0); PG8_MMA(0, 1, At, B1); PG8_BAR; PG8_SCHED;
;             PG8_LDA(At, 1, 1); PG8_STAGE(PG8_SB(1, 0), b3, voffB); PG8_STAGE(PG8_SB(1, 1), b3 + hstep, voffB); PG8_STAGE(PG8_SA(1, 0), a3, voffA);
;             PG8_WAIT_V(8); PG8_WAIT_L(0); PG8_BAR; PG8_MMA(1, 0, At, B0); PG8_MMA(1, 1, At, B1); PG8_BAR; PG8_SCHED;
	s_add_i32 s28, s50, s36
	v_lshl_add_u64 v[156:157], v[156:157], 0, s[80:81]
	s_mov_b32 m0, s28
	ds_read_b128 v[186:189], v160 offset:49152
	ds_read_b128 v[190:193], v160 offset:50176
	ds_read_b128 v[194:197], v160 offset:51200
	ds_read_b128 v[198:201], v160 offset:52224
	ds_read_b128 v[202:205], v160 offset:53248
	ds_read_b128 v[206:209], v160 offset:54272
	ds_read_b128 v[210:213], v160 offset:55296
	ds_read_b128 v[214:217], v160 offset:56320
	global_load_lds_dwordx4 v[156:157], off
	s_add_i32 m0, s28, 0x2000
	s_add_u32 s26, s26, 0x40080
	v_lshl_add_u64 v[156:157], v[218:219], 0, s[80:81]
	s_addc_u32 s27, s27, 0
	s_add_i32 s28, s51, s36
	global_load_lds_dwordx4 v[156:157], off
	s_mov_b32 m0, s28
	s_nop 0
	global_load_lds_dwordx4 v142, s[26:27]
	s_add_i32 m0, s28, 0x2000
	s_nop 0
	global_load_lds_dwordx4 v138, s[26:27]
	v_lshl_add_u64 v[156:157], v[220:221], 0, s[80:81]
	s_mov_b32 m0, s41
	s_nop 0
	global_load_lds_dwordx4 v[156:157], off
	v_lshl_add_u64 v[156:157], v[222:223], 0, s[80:81]
	s_mov_b32 m0, s42
	s_nop 0
	global_load_lds_dwordx4 v[156:157], off
	s_waitcnt vmcnt(8) lgkmcnt(0)
	s_barrier
	s_setprio 1
	v_mfma_f32_16x16x32_bf16 v[62:65], v[66:69], v[186:189], v[62:65]
	v_mfma_f32_16x16x32_bf16 v[58:61], v[152:155], v[186:189], v[58:61]
	v_mfma_f32_16x16x32_bf16 v[46:49], v[66:69], v[194:197], v[46:49]
	v_mfma_f32_16x16x32_bf16 v[42:45], v[152:155], v[194:197], v[42:45]
	v_mfma_f32_16x16x32_bf16 v[30:33], v[66:69], v[202:205], v[30:33]
	v_mfma_f32_16x16x32_bf16 v[26:29], v[152:155], v[202:205], v[26:29]
	v_mfma_f32_16x16x32_bf16 v[14:17], v[66:69], v[210:213], v[14:17]
	v_mfma_f32_16x16x32_bf16 v[10:13], v[152:155], v[210:213], v[10:13]
	v_mfma_f32_16x16x32_bf16 v[62:65], v[118:121], v[190:193], v[62:65]
	v_mfma_f32_16x16x32_bf16 v[58:61], v[162:165], v[190:193], v[58:61]
	v_mfma_f32_16x16x32_bf16 v[46:49], v[118:121], v[198:201], v[46:49]
	v_mfma_f32_16x16x32_bf16 v[42:45], v[162:165], v[198:201], v[42:45]
	v_mfma_f32_16x16x32_bf16 v[30:33], v[118:121], v[206:209], v[30:33]
	v_mfma_f32_16x16x32_bf16 v[26:29], v[162:165], v[206:209], v[26:29]
	v_mfma_f32_16x16x32_bf16 v[14:17], v[118:121], v[214:217], v[14:17]
	v_mfma_f32_16x16x32_bf16 v[10:13], v[162:165], v[214:217], v[10:13]
	v_mfma_f32_16x16x32_bf16 v[54:57], v[166:169], v[186:189], v[54:57]
	v_mfma_f32_16x16x32_bf16 v[50:53], v[174:177], v[186:189], v[50:53]
	v_mfma_f32_16x16x32_bf16 v[38:41], v[166:169], v[194:197], v[38:41]
	v_mfma_f32_16x16x32_bf16 v[34:37], v[174:177], v[194:197], v[34:37]
	v_mfma_f32_16x16x32_bf16 v[22:25], v[166:169], v[202:205], v[22:25]
	v_mfma_f32_16x16x32_bf16 v[18:21], v[174:177], v[202:205], v[18:21]
	v_mfma_f32_16x16x32_bf16 v[6:9], v[166:169], v[210:213], v[6:9]
	v_mfma_f32_16x16x32_bf16 v[2:5], v[174:177], v[210:213], v[2:5]
	v_mfma_f32_16x16x32_bf16 v[54:57], v[170:173], v[190:193], v[54:57]
	v_mfma_f32_16x16x32_bf16 v[50:53], v[180:183], v[190:193], v[50:53]
	v_mfma_f32_16x16x32_bf16 v[38:41], v[170:173], v[198:201], v[38:41]
	v_mfma_f32_16x16x32_bf16 v[34:37], v[180:183], v[198:201], v[34:37]
	v_mfma_f32_16x16x32_bf16 v[22:25], v[170:173], v[206:209], v[22:25]
	v_mfma_f32_16x16x32_bf16 v[18:21], v[180:183], v[206:209], v[18:21]
	v_mfma_f32_16x16x32_bf16 v[6:9], v[170:173], v[214:217], v[6:9]
	v_mfma_f32_16x16x32_bf16 v[2:5], v[180:183], v[214:217], v[2:5]
	s_setprio 0
	s_barrier
	s_add_i32 s49, s49, 2
	s_add_u32 s24, s24, 0x100
	s_addc_u32 s25, s25, 0
	s_add_u32 s47, s47, 0x100
	s_addc_u32 s48, s48, 0
	s_cmp_gt_u32 s49, 13
	s_branch .LBB0_1249
.LBB0_1249:
	s_add_u32 s26, s24, 0xfffc0080
	s_addc_u32 s27, s25, -1
	s_add_i32 s50, 0, 0x10000
	s_cmp_eq_u32 s49, 12
	s_cselect_b32 s29, s17, s27
	s_cselect_b32 s28, s45, s26
	v_add_u32_e32 v156, s50, v158
	s_cselect_b32 s27, s15, s48
	s_cselect_b32 s26, s46, s47
	s_add_i32 s52, 0, 0x14000
	ds_read_b128 v[66:69], v156
	ds_read_b128 v[118:121], v156 offset:1024
	ds_read_b128 v[152:155], v156 offset:2048
	ds_read_b128 v[162:165], v156 offset:3072
	v_add_u32_e32 v156, s52, v158
	ds_read_b128 v[166:169], v156
	ds_read_b128 v[170:173], v156 offset:1024
	ds_read_b128 v[174:177], v156 offset:2048
	ds_read_b128 v[180:183], v156 offset:3072
	s_add_i32 m0, s33, 0xc000
	ds_read_b128 v[186:189], v160
	ds_read_b128 v[190:193], v160 offset:1024
	ds_read_b128 v[194:197], v160 offset:2048
	ds_read_b128 v[198:201], v160 offset:3072
	ds_read_b128 v[202:205], v160 offset:4096
	ds_read_b128 v[206:209], v160 offset:5120
	ds_read_b128 v[210:213], v160 offset:6144
	ds_read_b128 v[214:217], v160 offset:7168
	global_load_lds_dwordx4 v148, s[24:25]
	s_add_i32 m0, s33, 0xe000
	s_nop 0
	global_load_lds_dwordx4 v150, s[24:25]
	s_waitcnt vmcnt(8) lgkmcnt(0)
	s_barrier
; #define PG8_STAGE(bufoff, gbase, voff) do { _Pragma("unroll") for (int _i = 0; _i < 2; ++_i) \
;         __builtin_amdgcn_global_load_lds((const unsigned*)((const char*)(gbase) + (voff)[_i]), (PG8_LAS unsigned*)(lds + (bufoff) + ldsw + _i * 8192), 16, 0, 0); } while (0)
; #define PG8_LDA(dst, b, h) do { _Pragma("unroll") for (int m = 0; m < 4; ++m) _Pragma("unroll") for (int k = 0; k < 2; ++k) dst[m][k] = *(const PG8_LAS bf16x8*)(lds + PG8_SA(b, h) + aoff + m * 2048 + k * 1024); } while (0)
; #define PG8_LDB(dst, b, h) do { _Pragma("unroll") for (int n = 0; n < 2; ++n) _Pragma("unroll") for (int k = 0; k < 2; ++k) dst[n][k] = *(const PG8_LAS bf16x8*)(lds + PG8_SB(b, h) + boff + n * 2048 + k * 1024); } while (0)
; #define PG8_MMA(ai, bj, At, Bt) do { __builtin_amdgcn_s_setprio(1); _Pragma("unroll") for (int m = 0; m < 4; ++m) _Pragma("unroll") for (int n = 0; n < 2; ++n) _Pragma("unroll") for (int k = 0; k < 2; ++k) \
;         acc[ai][bj][m][n] = __builtin_amdgcn_mfma_f32_16x16x32_bf16(Bt[n][k], At[m][k], acc[ai][bj][m][n], 0, 0, 0); __builtin_amdgcn_s_setprio(0); } while (0)
; #define PG8_WAIT_V(n) asm volatile("s_waitcnt vmcnt(" #n ")" ::: "memory")
; template <class Epi, class Sched, bool ALIGN_EPI = false, bool SP2 = false>
; __device__ __forceinline__ void gemm_phase(PG8_LAS unsigned char* lds, const Gemm g, const Sched& S, const Epi& E) {
;     ...
;             PG8_LDB(B0, 0, 0); PG8_LDB(B1, 0, 1); PG8_SCHED; PG8_LDA(At, 0, 0); PG8_STAGE(PG8_SA(1, 1), a1 + hstep, voffA);
;             PG8_WAIT_V(8); PG8_WAIT_L(0); PG8_BAR; PG8_MMA(0, 0, At, B0); PG8_MMA(0, 1, At, B1); PG8_BAR; PG8_SCHED;
;             PG8_LDA(At, 0, 1); PG8_STAGE(PG8_SB(0, 0), b2, voffB); PG8_STAGE(PG8_SB(0, 1), b2 + hstep, voffB); PG8_STAGE(PG8_SA(0, 0), a2, voffA);
;             PG8_WAIT_V(8); PG8_WAIT_L(0); PG8_BAR; PG8_MMA(1, 0, At, B0); PG8_MMA(1, 1, At, B1); PG8_BAR; PG8_SCHED;
;             PG8_LDB(B0, 1, 0); PG8_LDB(B1, 1, 1); PG8_SCHED; PG8_LDA(At, 1, 0); PG8_STAGE(PG8_SA(0, 1), a2 + hstep, voffA);
;             PG8_WAIT_V(8); PG8_WAIT_L(0); PG8_BAR; PG8_MMA(0, 0, At, B0); PG8_MMA(0, 1, At, B1); PG8_BAR; PG8_SCHED;
;             PG8_LDA(At, 1, 1); PG8_STAGE(PG8_SB(1, 0), b3, voffB); PG8_STAGE(PG8_SB(1, 1), b3 + hstep, voffB); PG8_STAGE(PG8_SA(1, 0), a3, voffA);
;             PG8_WAIT_V(8); PG8_WAIT_L(0); PG8_BAR; PG8_MMA(1, 0, At, B0); PG8_MMA(1, 1, At, B1); PG8_BAR; PG8_SCHED;
	s_setprio 1
	v_mfma_f32_16x16x32_bf16 v[134:137], v[66:69], v[186:189], v[134:137]
	v_mfma_f32_16x16x32_bf16 v[126:129], v[152:155], v[186:189], v[126:129]
	v_mfma_f32_16x16x32_bf16 v[114:117], v[66:69], v[194:197], v[114:117]
	v_mfma_f32_16x16x32_bf16 v[110:113], v[152:155], v[194:197], v[110:113]
	v_mfma_f32_16x16x32_bf16 v[98:101], v[66:69], v[202:205], v[98:101]
	v_mfma_f32_16x16x32_bf16 v[94:97], v[152:155], v[202:205], v[94:97]
	v_mfma_f32_16x16x32_bf16 v[82:85], v[66:69], v[210:213], v[82:85]
	v_mfma_f32_16x16x32_bf16 v[78:81], v[152:155], v[210:213], v[78:81]
	v_mfma_f32_16x16x32_bf16 v[134:137], v[118:121], v[190:193], v[134:137]
	v_mfma_f32_16x16x32_bf16 v[126:129], v[162:165], v[190:193], v[126:129]
	v_mfma_f32_16x16x32_bf16 v[114:117], v[118:121], v[198:201], v[114:117]
	v_mfma_f32_16x16x32_bf16 v[110:113], v[162:165], v[198:201], v[110:113]
	v_mfma_f32_16x16x32_bf16 v[98:101], v[118:121], v[206:209], v[98:101]
	v_mfma_f32_16x16x32_bf16 v[94:97], v[162:165], v[206:209], v[94:97]
	v_mfma_f32_16x16x32_bf16 v[82:85], v[118:121], v[214:217], v[82:85]
	v_mfma_f32_16x16x32_bf16 v[78:81], v[162:165], v[214:217], v[78:81]
	v_mfma_f32_16x16x32_bf16 v[130:133], v[166:169], v[186:189], v[130:133]
	v_mfma_f32_16x16x32_bf16 v[122:125], v[174:177], v[186:189], v[122:125]
	v_mfma_f32_16x16x32_bf16 v[106:109], v[166:169], v[194:197], v[106:109]
	v_mfma_f32_16x16x32_bf16 v[102:105], v[174:177], v[194:197], v[102:105]
	v_mfma_f32_16x16x32_bf16 v[90:93], v[166:169], v[202:205], v[90:93]
	v_mfma_f32_16x16x32_bf16 v[86:89], v[174:177], v[202:205], v[86:89]
	v_mfma_f32_16x16x32_bf16 v[74:77], v[166:169], v[210:213], v[74:77]
	v_mfma_f32_16x16x32_bf16 v[70:73], v[174:177], v[210:213], v[70:73]
	v_mfma_f32_16x16x32_bf16 v[130:133], v[170:173], v[190:193], v[130:133]
	v_mfma_f32_16x16x32_bf16 v[122:125], v[180:183], v[190:193], v[122:125]
	v_mfma_f32_16x16x32_bf16 v[106:109], v[170:173], v[198:201], v[106:109]
	v_mfma_f32_16x16x32_bf16 v[102:105], v[180:183], v[198:201], v[102:105]
	v_mfma_f32_16x16x32_bf16 v[90:93], v[170:173], v[206:209], v[90:93]
	v_mfma_f32_16x16x32_bf16 v[86:89], v[180:183], v[206:209], v[86:89]
	v_mfma_f32_16x16x32_bf16 v[74:77], v[170:173], v[214:217], v[74:77]
	v_mfma_f32_16x16x32_bf16 v[70:73], v[180:183], v[214:217], v[70:73]
	s_setprio 0
	s_barrier
	s_add_i32 s50, s50, s36
	v_lshl_add_u64 v[156:157], s[26:27], 0, v[142:143]
	s_mov_b32 m0, s50
	ds_read_b128 v[186:189], v160 offset:16384
	ds_read_b128 v[190:193], v160 offset:17408
	ds_read_b128 v[194:197], v160 offset:18432
	ds_read_b128 v[198:201], v160 offset:19456
	ds_read_b128 v[202:205], v160 offset:20480
	ds_read_b128 v[206:209], v160 offset:21504
	ds_read_b128 v[210:213], v160 offset:22528
	ds_read_b128 v[214:217], v160 offset:23552
	global_load_lds_dwordx4 v[156:157], off
	s_add_i32 m0, s50, 0x2000
	s_add_u32 s50, s26, 0x40000
	v_lshl_add_u64 v[218:219], s[26:27], 0, v[138:139]
	s_addc_u32 s51, s27, 0
	s_add_i32 s52, s52, s36
	global_load_lds_dwordx4 v[218:219], off
	v_lshl_add_u64 v[220:221], s[50:51], 0, v[142:143]
	s_mov_b32 m0, s52
	v_lshl_add_u64 v[222:223], s[28:29], 0, v[140:141]
	global_load_lds_dwordx4 v[220:221], off
	s_add_i32 m0, s52, 0x2000
	s_nop 0
	global_load_lds_dwordx4 v138, s[50:51]
	v_lshl_add_u64 v[220:221], s[28:29], 0, v[144:145]
	s_mov_b32 m0, s33
	s_nop 0
	global_load_lds_dwordx4 v[220:221], off
	s_mov_b32 m0, s38
	s_nop 0
	global_load_lds_dwordx4 v[222:223], off
	s_waitcnt vmcnt(8) lgkmcnt(0)
	s_barrier
	s_setprio 1
	v_mfma_f32_16x16x32_bf16 v[62:65], v[66:69], v[186:189], v[62:65]
	v_mfma_f32_16x16x32_bf16 v[58:61], v[152:155], v[186:189], v[58:61]
	v_mfma_f32_16x16x32_bf16 v[46:49], v[66:69], v[194:197], v[46:49]
	v_mfma_f32_16x16x32_bf16 v[42:45], v[152:155], v[194:197], v[42:45]
	v_mfma_f32_16x16x32_bf16 v[30:33], v[66:69], v[202:205], v[30:33]
	v_mfma_f32_16x16x32_bf16 v[26:29], v[152:155], v[202:205], v[26:29]
	v_mfma_f32_16x16x32_bf16 v[14:17], v[66:69], v[210:213], v[14:17]
	v_mfma_f32_16x16x32_bf16 v[10:13], v[152:155], v[210:213], v[10:13]
	v_mfma_f32_16x16x32_bf16 v[62:65], v[118:121], v[190:193], v[62:65]
	v_mfma_f32_16x16x32_bf16 v[58:61], v[162:165], v[190:193], v[58:61]
	v_mfma_f32_16x16x32_bf16 v[46:49], v[118:121], v[198:201], v[46:49]
	v_mfma_f32_16x16x32_bf16 v[42:45], v[162:165], v[198:201], v[42:45]
	v_mfma_f32_16x16x32_bf16 v[30:33], v[118:121], v[206:209], v[30:33]
	v_mfma_f32_16x16x32_bf16 v[26:29], v[162:165], v[206:209], v[26:29]
	v_mfma_f32_16x16x32_bf16 v[14:17], v[118:121], v[214:217], v[14:17]
	v_mfma_f32_16x16x32_bf16 v[10:13], v[162:165], v[214:217], v[10:13]
	v_mfma_f32_16x16x32_bf16 v[54:57], v[166:169], v[186:189], v[54:57]
	v_mfma_f32_16x16x32_bf16 v[50:53], v[174:177], v[186:189], v[50:53]
	v_mfma_f32_16x16x32_bf16 v[38:41], v[166:169], v[194:197], v[38:41]
	v_mfma_f32_16x16x32_bf16 v[34:37], v[174:177], v[194:197], v[34:37]
	v_mfma_f32_16x16x32_bf16 v[22:25], v[166:169], v[202:205], v[22:25]
	v_mfma_f32_16x16x32_bf16 v[18:21], v[174:177], v[202:205], v[18:21]
	v_mfma_f32_16x16x32_bf16 v[6:9], v[166:169], v[210:213], v[6:9]
	v_mfma_f32_16x16x32_bf16 v[2:5], v[174:177], v[210:213], v[2:5]
	v_mfma_f32_16x16x32_bf16 v[54:57], v[170:173], v[190:193], v[54:57]
	v_mfma_f32_16x16x32_bf16 v[50:53], v[180:183], v[190:193], v[50:53]
	v_mfma_f32_16x16x32_bf16 v[38:41], v[170:173], v[198:201], v[38:41]
	v_mfma_f32_16x16x32_bf16 v[34:37], v[180:183], v[198:201], v[34:37]
	v_mfma_f32_16x16x32_bf16 v[22:25], v[170:173], v[206:209], v[22:25]
	v_mfma_f32_16x16x32_bf16 v[18:21], v[180:183], v[206:209], v[18:21]
	v_mfma_f32_16x16x32_bf16 v[6:9], v[170:173], v[214:217], v[6:9]
	v_mfma_f32_16x16x32_bf16 v[2:5], v[180:183], v[214:217], v[2:5]
	s_setprio 0
	s_barrier
; #define PG8_STAGE(bufoff, gbase, voff) do { _Pragma("unroll") for (int _i = 0; _i < 2; ++_i) \
;         __builtin_amdgcn_global_load_lds((const unsigned*)((const char*)(gbase) + (voff)[_i]), (PG8_LAS unsigned*)(lds + (bufoff) + ldsw + _i * 8192), 16, 0, 0); } while (0)
; #define PG8_LDA(dst, b, h) do { _Pragma("unroll") for (int m = 0; m < 4; ++m) _Pragma("unroll") for (int k = 0; k < 2; ++k) dst[m][k] = *(const PG8_LAS bf16x8*)(lds + PG8_SA(b, h) + aoff + m * 2048 + k * 1024); } while (0)
; #define PG8_LDB(dst, b, h) do { _Pragma("unroll") for (int n = 0; n < 2; ++n) _Pragma("unroll") for (int k = 0; k < 2; ++k) dst[n][k] = *(const PG8_LAS bf16x8*)(lds + PG8_SB(b, h) + boff + n * 2048 + k * 1024); } while (0)
; #define PG8_MMA(ai, bj, At, Bt) do { __builtin_amdgcn_s_setprio(1); _Pragma("unroll") for (int m = 0; m < 4; ++m) _Pragma("unroll") for (int n = 0; n < 2; ++n) _Pragma("unroll") for (int k = 0; k < 2; ++k) \
;         acc[ai][bj][m][n] = __builtin_amdgcn_mfma_f32_16x16x32_bf16(Bt[n][k], At[m][k], acc[ai][bj][m][n], 0, 0, 0); __builtin_amdgcn_s_setprio(0); } while (0)
; #define PG8_WAIT_V(n) asm volatile("s_waitcnt vmcnt(" #n ")" ::: "memory")
; template <class Epi, class Sched, bool ALIGN_EPI = false, bool SP2 = false>
; __device__ __forceinline__ void gemm_phase(PG8_LAS unsigned char* lds, const Gemm g, const Sched& S, const Epi& E) {
;     ...
;             PG8_LDB(B0, 0, 0); PG8_LDB(B1, 0, 1); PG8_SCHED; PG8_LDA(At, 0, 0); PG8_STAGE(PG8_SA(1, 1), a1 + hstep, voffA);
;             PG8_WAIT_V(8); PG8_WAIT_L(0); PG8_BAR; PG8_MMA(0, 0, At, B0); PG8_MMA(0, 1, At, B1); PG8_BAR; PG8_SCHED;
;             PG8_LDA(At, 0, 1); PG8_STAGE(PG8_SB(0, 0), b2, voffB); PG8_STAGE(PG8_SB(0, 1), b2 + hstep, voffB); PG8_STAGE(PG8_SA(0, 0), a2, voffA);
;             PG8_WAIT_V(8); PG8_WAIT_L(0); PG8_BAR; PG8_MMA(1, 0, At, B0); PG8_MMA(1, 1, At, B1); PG8_BAR; PG8_SCHED;
;             PG8_LDB(B0, 1, 0); PG8_LDB(B1, 1, 1); PG8_SCHED; PG8_LDA(At, 1, 0); PG8_STAGE(PG8_SA(0, 1), a2 + hstep, voffA);
;             PG8_WAIT_V(8); PG8_WAIT_L(0); PG8_BAR; PG8_MMA(0, 0, At, B0); PG8_MMA(0, 1, At, B1); PG8_BAR; PG8_SCHED;
;             PG8_LDA(At, 1, 1); PG8_STAGE(PG8_SB(1, 0), b3, voffB); PG8_STAGE(PG8_SB(1, 1), b3 + hstep, voffB); PG8_STAGE(PG8_SA(1, 0), a3, voffA);
;             PG8_WAIT_V(8); PG8_WAIT_L(0); PG8_BAR; PG8_MMA(1, 0, At, B0); PG8_MMA(1, 1, At, B1); PG8_BAR; PG8_SCHED;
	s_add_i32 s50, 0, 0x18000
	v_add_u32_e32 v161, s50, v158
	s_add_i32 s51, 0, 0x1c000
	ds_read_b128 v[66:69], v161
	ds_read_b128 v[118:121], v161 offset:1024
	ds_read_b128 v[152:155], v161 offset:2048
	ds_read_b128 v[162:165], v161 offset:3072
	v_add_u32_e32 v161, s51, v158
	ds_read_b128 v[166:169], v161
	ds_read_b128 v[170:173], v161 offset:1024
	ds_read_b128 v[174:177], v161 offset:2048
	ds_read_b128 v[180:183], v161 offset:3072
	s_add_u32 s28, s28, 0x40000
	s_addc_u32 s29, s29, 0
	s_mov_b32 m0, s39
	ds_read_b128 v[186:189], v160 offset:32768
	ds_read_b128 v[190:193], v160 offset:33792
	ds_read_b128 v[194:197], v160 offset:34816
	ds_read_b128 v[198:201], v160 offset:35840
	ds_read_b128 v[202:205], v160 offset:36864
	ds_read_b128 v[206:209], v160 offset:37888
	ds_read_b128 v[210:213], v160 offset:38912
	ds_read_b128 v[214:217], v160 offset:39936
	global_load_lds_dwordx4 v144, s[28:29]
	v_lshl_add_u64 v[240:241], s[28:29], 0, v[140:141]
	s_mov_b32 m0, s40
	s_nop 0
	global_load_lds_dwordx4 v[240:241], off
	s_waitcnt vmcnt(8) lgkmcnt(0)
	s_barrier
	s_setprio 1
	v_mfma_f32_16x16x32_bf16 v[134:137], v[66:69], v[186:189], v[134:137]
	v_mfma_f32_16x16x32_bf16 v[126:129], v[152:155], v[186:189], v[126:129]
	v_mfma_f32_16x16x32_bf16 v[114:117], v[66:69], v[194:197], v[114:117]
	v_mfma_f32_16x16x32_bf16 v[110:113], v[152:155], v[194:197], v[110:113]
	v_mfma_f32_16x16x32_bf16 v[98:101], v[66:69], v[202:205], v[98:101]
	v_mfma_f32_16x16x32_bf16 v[94:97], v[152:155], v[202:205], v[94:97]
	v_mfma_f32_16x16x32_bf16 v[82:85], v[66:69], v[210:213], v[82:85]
	v_mfma_f32_16x16x32_bf16 v[78:81], v[152:155], v[210:213], v[78:81]
	v_mfma_f32_16x16x32_bf16 v[134:137], v[118:121], v[190:193], v[134:137]
	v_mfma_f32_16x16x32_bf16 v[126:129], v[162:165], v[190:193], v[126:129]
	v_mfma_f32_16x16x32_bf16 v[114:117], v[118:121], v[198:201], v[114:117]
	v_mfma_f32_16x16x32_bf16 v[110:113], v[162:165], v[198:201], v[110:113]
	v_mfma_f32_16x16x32_bf16 v[98:101], v[118:121], v[206:209], v[98:101]
	v_mfma_f32_16x16x32_bf16 v[94:97], v[162:165], v[206:209], v[94:97]
	v_mfma_f32_16x16x32_bf16 v[82:85], v[118:121], v[214:217], v[82:85]
	v_mfma_f32_16x16x32_bf16 v[78:81], v[162:165], v[214:217], v[78:81]
	v_mfma_f32_16x16x32_bf16 v[130:133], v[166:169], v[186:189], v[130:133]
	v_mfma_f32_16x16x32_bf16 v[122:125], v[174:177], v[186:189], v[122:125]
	v_mfma_f32_16x16x32_bf16 v[106:109], v[166:169], v[194:197], v[106:109]
	v_mfma_f32_16x16x32_bf16 v[102:105], v[174:177], v[194:197], v[102:105]
	v_mfma_f32_16x16x32_bf16 v[90:93], v[166:169], v[202:205], v[90:93]
	v_mfma_f32_16x16x32_bf16 v[86:89], v[174:177], v[202:205], v[86:89]
	v_mfma_f32_16x16x32_bf16 v[74:77], v[166:169], v[210:213], v[74:77]
	v_mfma_f32_16x16x32_bf16 v[70:73], v[174:177], v[210:213], v[70:73]
	v_mfma_f32_16x16x32_bf16 v[130:133], v[170:173], v[190:193], v[130:133]
	v_mfma_f32_16x16x32_bf16 v[122:125], v[180:183], v[190:193], v[122:125]
	v_mfma_f32_16x16x32_bf16 v[106:109], v[170:173], v[198:201], v[106:109]
	v_mfma_f32_16x16x32_bf16 v[102:105], v[180:183], v[198:201], v[102:105]
	v_mfma_f32_16x16x32_bf16 v[90:93], v[170:173], v[206:209], v[90:93]
	v_mfma_f32_16x16x32_bf16 v[86:89], v[180:183], v[206:209], v[86:89]
	v_mfma_f32_16x16x32_bf16 v[74:77], v[170:173], v[214:217], v[74:77]
	v_mfma_f32_16x16x32_bf16 v[70:73], v[180:183], v[214:217], v[70:73]
	s_setprio 0
	s_barrier
	s_add_i32 s28, s50, s36
	v_lshl_add_u64 v[156:157], v[156:157], 0, s[80:81]
	s_mov_b32 m0, s28
	ds_read_b128 v[186:189], v160 offset:49152
	ds_read_b128 v[190:193], v160 offset:50176
	ds_read_b128 v[194:197], v160 offset:51200
	ds_read_b128 v[198:201], v160 offset:52224
	ds_read_b128 v[202:205], v160 offset:53248
	ds_read_b128 v[206:209], v160 offset:54272
	ds_read_b128 v[210:213], v160 offset:55296
	ds_read_b128 v[214:217], v160 offset:56320
	global_load_lds_dwordx4 v[156:157], off
	s_add_i32 m0, s28, 0x2000
	s_add_u32 s26, s26, 0x40080
	v_lshl_add_u64 v[156:157], v[218:219], 0, s[80:81]
	s_addc_u32 s27, s27, 0
	s_add_i32 s28, s51, s36
	global_load_lds_dwordx4 v[156:157], off
	s_mov_b32 m0, s28
	s_nop 0
	global_load_lds_dwordx4 v142, s[26:27]
	s_add_i32 m0, s28, 0x2000
	s_nop 0
	global_load_lds_dwordx4 v138, s[26:27]
	v_lshl_add_u64 v[156:157], v[220:221], 0, s[80:81]
	s_mov_b32 m0, s41
	s_nop 0
	global_load_lds_dwordx4 v[156:157], off
	v_lshl_add_u64 v[156:157], v[222:223], 0, s[80:81]
	s_mov_b32 m0, s42
	s_nop 0
	global_load_lds_dwordx4 v[156:157], off
	s_waitcnt vmcnt(8) lgkmcnt(0)
	s_barrier
	s_setprio 1
	v_mfma_f32_16x16x32_bf16 v[62:65], v[66:69], v[186:189], v[62:65]
	v_mfma_f32_16x16x32_bf16 v[58:61], v[152:155], v[186:189], v[58:61]
	v_mfma_f32_16x16x32_bf16 v[46:49], v[66:69], v[194:197], v[46:49]
	v_mfma_f32_16x16x32_bf16 v[42:45], v[152:155], v[194:197], v[42:45]
	v_mfma_f32_16x16x32_bf16 v[30:33], v[66:69], v[202:205], v[30:33]
	v_mfma_f32_16x16x32_bf16 v[26:29], v[152:155], v[202:205], v[26:29]
	v_mfma_f32_16x16x32_bf16 v[14:17], v[66:69], v[210:213], v[14:17]
	v_mfma_f32_16x16x32_bf16 v[10:13], v[152:155], v[210:213], v[10:13]
	v_mfma_f32_16x16x32_bf16 v[62:65], v[118:121], v[190:193], v[62:65]
	v_mfma_f32_16x16x32_bf16 v[58:61], v[162:165], v[190:193], v[58:61]
	v_mfma_f32_16x16x32_bf16 v[46:49], v[118:121], v[198:201], v[46:49]
	v_mfma_f32_16x16x32_bf16 v[42:45], v[162:165], v[198:201], v[42:45]
	v_mfma_f32_16x16x32_bf16 v[30:33], v[118:121], v[206:209], v[30:33]
	v_mfma_f32_16x16x32_bf16 v[26:29], v[162:165], v[206:209], v[26:29]
	v_mfma_f32_16x16x32_bf16 v[14:17], v[118:121], v[214:217], v[14:17]
	v_mfma_f32_16x16x32_bf16 v[10:13], v[162:165], v[214:217], v[10:13]
	v_mfma_f32_16x16x32_bf16 v[54:57], v[166:169], v[186:189], v[54:57]
	v_mfma_f32_16x16x32_bf16 v[50:53], v[174:177], v[186:189], v[50:53]
	v_mfma_f32_16x16x32_bf16 v[38:41], v[166:169], v[194:197], v[38:41]
	v_mfma_f32_16x16x32_bf16 v[34:37], v[174:177], v[194:197], v[34:37]
	v_mfma_f32_16x16x32_bf16 v[22:25], v[166:169], v[202:205], v[22:25]
	v_mfma_f32_16x16x32_bf16 v[18:21], v[174:177], v[202:205], v[18:21]
	v_mfma_f32_16x16x32_bf16 v[6:9], v[166:169], v[210:213], v[6:9]
	v_mfma_f32_16x16x32_bf16 v[2:5], v[174:177], v[210:213], v[2:5]
	v_mfma_f32_16x16x32_bf16 v[54:57], v[170:173], v[190:193], v[54:57]
	v_mfma_f32_16x16x32_bf16 v[50:53], v[180:183], v[190:193], v[50:53]
	v_mfma_f32_16x16x32_bf16 v[38:41], v[170:173], v[198:201], v[38:41]
	v_mfma_f32_16x16x32_bf16 v[34:37], v[180:183], v[198:201], v[34:37]
	v_mfma_f32_16x16x32_bf16 v[22:25], v[170:173], v[206:209], v[22:25]
	v_mfma_f32_16x16x32_bf16 v[18:21], v[180:183], v[206:209], v[18:21]
	v_mfma_f32_16x16x32_bf16 v[6:9], v[170:173], v[214:217], v[6:9]
	v_mfma_f32_16x16x32_bf16 v[2:5], v[180:183], v[214:217], v[2:5]
	s_setprio 0
	s_barrier
	s_add_i32 s49, s49, 2
	s_add_u32 s24, s24, 0x100
	s_addc_u32 s25, s25, 0
	s_add_u32 s47, s47, 0x100
	s_addc_u32 s48, s48, 0
	s_cmp_gt_u32 s49, 13
	s_cbranch_scc0 .LBB0_1249
	s_and_b64 vcc, exec, s[12:13]
	s_cbranch_vccz .LBB0_1252
	s_barrier

; #define PG8_STAGE(bufoff, gbase, voff) do { _Pragma("unroll") for (int _i = 0; _i < 2; ++_i) \
;         __builtin_amdgcn_global_load_lds((const unsigned*)((const char*)(gbase) + (voff)[_i]), (PG8_LAS unsigned*)(lds + (bufoff) + ldsw + _i * 8192), 16, 0, 0); } while (0)
; #define PG8_LDA(dst, b, h) do { _Pragma("unroll") for (int m = 0; m < 4; ++m) _Pragma("unroll") for (int k = 0; k < 2; ++k) dst[m][k] = *(const PG8_LAS bf16x8*)(lds + PG8_SA(b, h) + aoff + m * 2048 + k * 1024); } while (0)
; #define PG8_LDB(dst, b, h) do { _Pragma("unroll") for (int n = 0; n < 2; ++n) _Pragma("unroll") for (int k = 0; k < 2; ++k) dst[n][k] = *(const PG8_LAS bf16x8*)(lds + PG8_SB(b, h) + boff + n * 2048 + k * 1024); } while (0)
; #define PG8_MMA(ai, bj, At, Bt) do { __builtin_amdgcn_s_setprio(1); _Pragma("unroll") for (int m = 0; m < 4; ++m) _Pragma("unroll") for (int n = 0; n < 2; ++n) _Pragma("unroll") for (int k = 0; k < 2; ++k) \
;         acc[ai][bj][m][n] = __builtin_amdgcn_mfma_f32_16x16x32_bf16(Bt[n][k], At[m][k], acc[ai][bj][m][n], 0, 0, 0); __builtin_amdgcn_s_setprio(0); } while (0)
; #define PG8_WAIT_V(n) asm volatile("s_waitcnt vmcnt(" #n ")" ::: "memory")
; #define PG8_WAIT_L(n) asm volatile("s_waitcnt lgkmcnt(" #n ")" ::: "memory")
; #define PG8_BAR __builtin_amdgcn_s_barrier()
; #define PG8_SCHED __builtin_amdgcn_sched_barrier(0)
; template <class Epi, class Sched, bool ALIGN_EPI = false, bool SP2 = false>
; __device__ __forceinline__ void gemm_phase(PG8_LAS unsigned char* lds, const Gemm g, const Sched& S, const Epi& E) {
;     ...
;             PG8_LDB(B0, 0, 0); PG8_LDB(B1, 0, 1); PG8_SCHED; PG8_LDA(At, 0, 0); PG8_STAGE(PG8_SA(1, 1), a1 + hstep, voffA);
;             PG8_WAIT_V(8); PG8_WAIT_L(0); PG8_BAR; PG8_MMA(0, 0, At, B0); PG8_MMA(0, 1, At, B1); PG8_BAR; PG8_SCHED;
;             PG8_LDA(At, 0, 1); PG8_STAGE(PG8_SB(0, 0), b2, voffB); PG8_STAGE(PG8_SB(0, 1), b2 + hstep, voffB); PG8_STAGE(PG8_SA(0, 0), a2, voffA);
;             PG8_WAIT_V(8); PG8_WAIT_L(0); PG8_BAR; PG8_MMA(1, 0, At, B0); PG8_MMA(1, 1, At, B1); PG8_BAR; PG8_SCHED;
.LBB0_1329:
	s_add_u32 s49, s22, 0x100
	s_addc_u32 s50, s23, 0
	s_mov_b32 s51, -2
	s_add_u32 s22, s20, 0x100
	s_addc_u32 s23, s21, 0
	s_add_i32 s52, 0, 0x10000
	s_cmp_eq_u32 s51, 40
	s_cselect_b32 s27, s7, s23
	s_cselect_b32 s26, s6, s22
	v_add_u32_e32 v157, s52, v154
	s_cselect_b32 s25, s19, s50
	s_cselect_b32 s24, s18, s49
	s_add_i32 s53, 0, 0x14000
	ds_read_b128 v[142:145], v157
	ds_read_b128 v[146:149], v157 offset:1024
	ds_read_b128 v[150:153], v157 offset:2048
	ds_read_b128 v[158:161], v157 offset:3072
	v_add_u32_e32 v157, s53, v154
	ds_read_b128 v[162:165], v157
	ds_read_b128 v[166:169], v157 offset:1024
	ds_read_b128 v[170:173], v157 offset:2048
	ds_read_b128 v[174:177], v157 offset:3072
	v_lshl_add_u64 v[214:215], s[20:21], 0, v[138:139]
	s_add_i32 m0, s37, 0xc000
	ds_read_b128 v[180:183], v156
	ds_read_b128 v[186:189], v156 offset:1024
	ds_read_b128 v[190:193], v156 offset:2048
	ds_read_b128 v[194:197], v156 offset:3072
	ds_read_b128 v[198:201], v156 offset:4096
	ds_read_b128 v[202:205], v156 offset:5120
	ds_read_b128 v[206:209], v156 offset:6144
	ds_read_b128 v[210:213], v156 offset:7168
	global_load_lds_dwordx4 v[214:215], off
	v_lshl_add_u64 v[214:215], s[20:21], 0, v[140:141]
	s_add_i32 m0, s37, 0xe000
	s_nop 0
	global_load_lds_dwordx4 v[214:215], off
	s_waitcnt vmcnt(8) lgkmcnt(0)
	s_barrier
	s_setprio 1
	v_mfma_f32_16x16x32_bf16 v[126:129], v[142:145], v[180:183], 0
	v_mfma_f32_16x16x32_bf16 v[122:125], v[150:153], v[180:183], 0
	v_mfma_f32_16x16x32_bf16 v[114:117], v[142:145], v[190:193], 0
	v_mfma_f32_16x16x32_bf16 v[106:109], v[150:153], v[190:193], 0
	v_mfma_f32_16x16x32_bf16 v[98:101], v[142:145], v[198:201], 0
	v_mfma_f32_16x16x32_bf16 v[90:93], v[150:153], v[198:201], 0
	v_mfma_f32_16x16x32_bf16 v[82:85], v[142:145], v[206:209], 0
	v_mfma_f32_16x16x32_bf16 v[74:77], v[150:153], v[206:209], 0
	v_mfma_f32_16x16x32_bf16 v[126:129], v[146:149], v[186:189], v[126:129]
	v_mfma_f32_16x16x32_bf16 v[122:125], v[158:161], v[186:189], v[122:125]
	v_mfma_f32_16x16x32_bf16 v[114:117], v[146:149], v[194:197], v[114:117]
	v_mfma_f32_16x16x32_bf16 v[106:109], v[158:161], v[194:197], v[106:109]
	v_mfma_f32_16x16x32_bf16 v[98:101], v[146:149], v[202:205], v[98:101]
	v_mfma_f32_16x16x32_bf16 v[90:93], v[158:161], v[202:205], v[90:93]
	v_mfma_f32_16x16x32_bf16 v[82:85], v[146:149], v[210:213], v[82:85]
	v_mfma_f32_16x16x32_bf16 v[74:77], v[158:161], v[210:213], v[74:77]
	v_mfma_f32_16x16x32_bf16 v[118:121], v[162:165], v[180:183], 0
	v_mfma_f32_16x16x32_bf16 v[110:113], v[170:173], v[180:183], 0
	v_mfma_f32_16x16x32_bf16 v[102:105], v[162:165], v[190:193], 0
	v_mfma_f32_16x16x32_bf16 v[94:97], v[170:173], v[190:193], 0
	v_mfma_f32_16x16x32_bf16 v[86:89], v[162:165], v[198:201], 0
	v_mfma_f32_16x16x32_bf16 v[78:81], v[170:173], v[198:201], 0
	v_mfma_f32_16x16x32_bf16 v[70:73], v[162:165], v[206:209], 0
	v_mfma_f32_16x16x32_bf16 v[66:69], v[170:173], v[206:209], 0
	v_mfma_f32_16x16x32_bf16 v[118:121], v[166:169], v[186:189], v[118:121]
	v_mfma_f32_16x16x32_bf16 v[110:113], v[174:177], v[186:189], v[110:113]
	v_mfma_f32_16x16x32_bf16 v[102:105], v[166:169], v[194:197], v[102:105]
	v_mfma_f32_16x16x32_bf16 v[94:97], v[174:177], v[194:197], v[94:97]
	v_mfma_f32_16x16x32_bf16 v[86:89], v[166:169], v[202:205], v[86:89]
	v_mfma_f32_16x16x32_bf16 v[78:81], v[174:177], v[202:205], v[78:81]
	v_mfma_f32_16x16x32_bf16 v[70:73], v[166:169], v[210:213], v[70:73]
	v_mfma_f32_16x16x32_bf16 v[66:69], v[174:177], v[210:213], v[66:69]
	s_setprio 0
	s_barrier
	s_add_i32 s20, s52, s36
	v_lshl_add_u64 v[214:215], s[24:25], 0, v[132:133]
	s_mov_b32 m0, s20
	ds_read_b128 v[180:183], v156 offset:16384
	ds_read_b128 v[186:189], v156 offset:17408
	ds_read_b128 v[190:193], v156 offset:18432
	ds_read_b128 v[194:197], v156 offset:19456
	ds_read_b128 v[198:201], v156 offset:20480
	ds_read_b128 v[202:205], v156 offset:21504
	ds_read_b128 v[206:209], v156 offset:22528
	ds_read_b128 v[210:213], v156 offset:23552
	global_load_lds_dwordx4 v[214:215], off
	s_add_i32 m0, s20, 0x2000
	s_add_u32 s20, s24, 0xb0000
	v_lshl_add_u64 v[216:217], s[24:25], 0, v[136:137]
	s_addc_u32 s21, s25, 0
	s_add_i32 s52, s53, s36
	global_load_lds_dwordx4 v[216:217], off
	v_lshl_add_u64 v[218:219], s[20:21], 0, v[132:133]
	s_mov_b32 m0, s52
	v_lshl_add_u64 v[220:221], s[26:27], 0, v[134:135]
	global_load_lds_dwordx4 v[218:219], off
	s_add_i32 m0, s52, 0x2000
	s_nop 0
	global_load_lds_dwordx4 v136, s[20:21]
	v_lshl_add_u64 v[218:219], s[26:27], 0, v[130:131]
	s_mov_b32 m0, s37
	s_nop 0
	global_load_lds_dwordx4 v[218:219], off
	s_mov_b32 m0, s38
	s_nop 0
	global_load_lds_dwordx4 v[220:221], off
	s_waitcnt vmcnt(8) lgkmcnt(0)
	s_barrier
; #define PG8_STAGE(bufoff, gbase, voff) do { _Pragma("unroll") for (int _i = 0; _i < 2; ++_i) \
;         __builtin_amdgcn_global_load_lds((const unsigned*)((const char*)(gbase) + (voff)[_i]), (PG8_LAS unsigned*)(lds + (bufoff) + ldsw + _i * 8192), 16, 0, 0); } while (0)
; #define PG8_LDA(dst, b, h) do { _Pragma("unroll") for (int m = 0; m < 4; ++m) _Pragma("unroll") for (int k = 0; k < 2; ++k) dst[m][k] = *(const PG8_LAS bf16x8*)(lds + PG8_SA(b, h) + aoff + m * 2048 + k * 1024); } while (0)
; #define PG8_LDB(dst, b, h) do { _Pragma("unroll") for (int n = 0; n < 2; ++n) _Pragma("unroll") for (int k = 0; k < 2; ++k) dst[n][k] = *(const PG8_LAS bf16x8*)(lds + PG8_SB(b, h) + boff + n * 2048 + k * 1024); } while (0)
; #define PG8_MMA(ai, bj, At, Bt) do { __builtin_amdgcn_s_setprio(1); _Pragma("unroll") for (int m = 0; m < 4; ++m) _Pragma("unroll") for (int n = 0; n < 2; ++n) _Pragma("unroll") for (int k = 0; k < 2; ++k) \
;         acc[ai][bj][m][n] = __builtin_amdgcn_mfma_f32_16x16x32_bf16(Bt[n][k], At[m][k], acc[ai][bj][m][n], 0, 0, 0); __builtin_amdgcn_s_setprio(0); } while (0)
; #define PG8_WAIT_V(n) asm volatile("s_waitcnt vmcnt(" #n ")" ::: "memory")
; template <class Epi, class Sched, bool ALIGN_EPI = false, bool SP2 = false>
; __device__ __forceinline__ void gemm_phase(PG8_LAS unsigned char* lds, const Gemm g, const Sched& S, const Epi& E) {
;     ...
;             PG8_LDB(B0, 0, 0); PG8_LDB(B1, 0, 1); PG8_SCHED; PG8_LDA(At, 0, 0); PG8_STAGE(PG8_SA(1, 1), a1 + hstep, voffA);
;             PG8_WAIT_V(8); PG8_WAIT_L(0); PG8_BAR; PG8_MMA(0, 0, At, B0); PG8_MMA(0, 1, At, B1); PG8_BAR; PG8_SCHED;
;             PG8_LDA(At, 0, 1); PG8_STAGE(PG8_SB(0, 0), b2, voffB); PG8_STAGE(PG8_SB(0, 1), b2 + hstep, voffB); PG8_STAGE(PG8_SA(0, 0), a2, voffA);
;             PG8_WAIT_V(8); PG8_WAIT_L(0); PG8_BAR; PG8_MMA(1, 0, At, B0); PG8_MMA(1, 1, At, B1); PG8_BAR; PG8_SCHED;
;             PG8_LDB(B0, 1, 0); PG8_LDB(B1, 1, 1); PG8_SCHED; PG8_LDA(At, 1, 0); PG8_STAGE(PG8_SA(0, 1), a2 + hstep, voffA);
;             PG8_WAIT_V(8); PG8_WAIT_L(0); PG8_BAR; PG8_MMA(0, 0, At, B0); PG8_MMA(0, 1, At, B1); PG8_BAR; PG8_SCHED;
;             PG8_LDA(At, 1, 1); PG8_STAGE(PG8_SB(1, 0), b3, voffB); PG8_STAGE(PG8_SB(1, 1), b3 + hstep, voffB); PG8_STAGE(PG8_SA(1, 0), a3, voffA);
;             PG8_WAIT_V(8); PG8_WAIT_L(0); PG8_BAR; PG8_MMA(1, 0, At, B0); PG8_MMA(1, 1, At, B1); PG8_BAR; PG8_SCHED;
	s_setprio 1
	v_mfma_f32_16x16x32_bf16 v[62:65], v[142:145], v[180:183], 0
	v_mfma_f32_16x16x32_bf16 v[58:61], v[150:153], v[180:183], 0
	v_mfma_f32_16x16x32_bf16 v[50:53], v[142:145], v[190:193], 0
	v_mfma_f32_16x16x32_bf16 v[42:45], v[150:153], v[190:193], 0
	v_mfma_f32_16x16x32_bf16 v[34:37], v[142:145], v[198:201], 0
	v_mfma_f32_16x16x32_bf16 v[26:29], v[150:153], v[198:201], 0
	v_mfma_f32_16x16x32_bf16 v[18:21], v[142:145], v[206:209], 0
	v_mfma_f32_16x16x32_bf16 v[10:13], v[150:153], v[206:209], 0
	v_mfma_f32_16x16x32_bf16 v[62:65], v[146:149], v[186:189], v[62:65]
	v_mfma_f32_16x16x32_bf16 v[58:61], v[158:161], v[186:189], v[58:61]
	v_mfma_f32_16x16x32_bf16 v[50:53], v[146:149], v[194:197], v[50:53]
	v_mfma_f32_16x16x32_bf16 v[42:45], v[158:161], v[194:197], v[42:45]
	v_mfma_f32_16x16x32_bf16 v[34:37], v[146:149], v[202:205], v[34:37]
	v_mfma_f32_16x16x32_bf16 v[26:29], v[158:161], v[202:205], v[26:29]
	v_mfma_f32_16x16x32_bf16 v[18:21], v[146:149], v[210:213], v[18:21]
	v_mfma_f32_16x16x32_bf16 v[10:13], v[158:161], v[210:213], v[10:13]
	v_mfma_f32_16x16x32_bf16 v[54:57], v[162:165], v[180:183], 0
	v_mfma_f32_16x16x32_bf16 v[46:49], v[170:173], v[180:183], 0
	v_mfma_f32_16x16x32_bf16 v[38:41], v[162:165], v[190:193], 0
	v_mfma_f32_16x16x32_bf16 v[30:33], v[170:173], v[190:193], 0
	v_mfma_f32_16x16x32_bf16 v[22:25], v[162:165], v[198:201], 0
	v_mfma_f32_16x16x32_bf16 v[14:17], v[170:173], v[198:201], 0
	v_mfma_f32_16x16x32_bf16 v[6:9], v[162:165], v[206:209], 0
	v_mfma_f32_16x16x32_bf16 v[2:5], v[170:173], v[206:209], 0
	v_mfma_f32_16x16x32_bf16 v[54:57], v[166:169], v[186:189], v[54:57]
	v_mfma_f32_16x16x32_bf16 v[46:49], v[174:177], v[186:189], v[46:49]
	v_mfma_f32_16x16x32_bf16 v[38:41], v[166:169], v[194:197], v[38:41]
	v_mfma_f32_16x16x32_bf16 v[30:33], v[174:177], v[194:197], v[30:33]
	v_mfma_f32_16x16x32_bf16 v[22:25], v[166:169], v[202:205], v[22:25]
	v_mfma_f32_16x16x32_bf16 v[14:17], v[174:177], v[202:205], v[14:17]
	v_mfma_f32_16x16x32_bf16 v[6:9], v[166:169], v[210:213], v[6:9]
	v_mfma_f32_16x16x32_bf16 v[2:5], v[174:177], v[210:213], v[2:5]
	s_setprio 0
	s_barrier
	s_add_i32 s52, 0, 0x18000
	v_add_u32_e32 v157, s52, v154
	s_add_i32 s53, 0, 0x1c000
	ds_read_b128 v[142:145], v157
	ds_read_b128 v[146:149], v157 offset:1024
	ds_read_b128 v[150:153], v157 offset:2048
	ds_read_b128 v[158:161], v157 offset:3072
	v_add_u32_e32 v157, s53, v154
	ds_read_b128 v[162:165], v157
	ds_read_b128 v[166:169], v157 offset:1024
	ds_read_b128 v[170:173], v157 offset:2048
	ds_read_b128 v[174:177], v157 offset:3072
	s_add_u32 s20, s26, 0xb0000
	s_addc_u32 s21, s27, 0
	s_mov_b32 m0, s39
	ds_read_b128 v[180:183], v156 offset:32768
	ds_read_b128 v[186:189], v156 offset:33792
	ds_read_b128 v[190:193], v156 offset:34816
	ds_read_b128 v[194:197], v156 offset:35840
	ds_read_b128 v[198:201], v156 offset:36864
	ds_read_b128 v[202:205], v156 offset:37888
	ds_read_b128 v[206:209], v156 offset:38912
	ds_read_b128 v[210:213], v156 offset:39936
	global_load_lds_dwordx4 v130, s[20:21]
	v_lshl_add_u64 v[222:223], s[20:21], 0, v[134:135]
	s_mov_b32 m0, s40
	s_nop 0
	global_load_lds_dwordx4 v[222:223], off
	s_waitcnt vmcnt(8) lgkmcnt(0)
	s_barrier
	s_setprio 1
	v_mfma_f32_16x16x32_bf16 v[126:129], v[142:145], v[180:183], v[126:129]
	v_mfma_f32_16x16x32_bf16 v[122:125], v[150:153], v[180:183], v[122:125]
	v_mfma_f32_16x16x32_bf16 v[114:117], v[142:145], v[190:193], v[114:117]
	v_mfma_f32_16x16x32_bf16 v[106:109], v[150:153], v[190:193], v[106:109]
	v_mfma_f32_16x16x32_bf16 v[98:101], v[142:145], v[198:201], v[98:101]
	v_mfma_f32_16x16x32_bf16 v[90:93], v[150:153], v[198:201], v[90:93]
	v_mfma_f32_16x16x32_bf16 v[82:85], v[142:145], v[206:209], v[82:85]
	v_mfma_f32_16x16x32_bf16 v[74:77], v[150:153], v[206:209], v[74:77]
	v_mfma_f32_16x16x32_bf16 v[126:129], v[146:149], v[186:189], v[126:129]
	v_mfma_f32_16x16x32_bf16 v[122:125], v[158:161], v[186:189], v[122:125]
	v_mfma_f32_16x16x32_bf16 v[114:117], v[146:149], v[194:197], v[114:117]
	v_mfma_f32_16x16x32_bf16 v[106:109], v[158:161], v[194:197], v[106:109]
	v_mfma_f32_16x16x32_bf16 v[98:101], v[146:149], v[202:205], v[98:101]
	v_mfma_f32_16x16x32_bf16 v[90:93], v[158:161], v[202:205], v[90:93]
	v_mfma_f32_16x16x32_bf16 v[82:85], v[146:149], v[210:213], v[82:85]
	v_mfma_f32_16x16x32_bf16 v[74:77], v[158:161], v[210:213], v[74:77]
	v_mfma_f32_16x16x32_bf16 v[118:121], v[162:165], v[180:183], v[118:121]
	v_mfma_f32_16x16x32_bf16 v[110:113], v[170:173], v[180:183], v[110:113]
	v_mfma_f32_16x16x32_bf16 v[102:105], v[162:165], v[190:193], v[102:105]
	v_mfma_f32_16x16x32_bf16 v[94:97], v[170:173], v[190:193], v[94:97]
	v_mfma_f32_16x16x32_bf16 v[86:89], v[162:165], v[198:201], v[86:89]
	v_mfma_f32_16x16x32_bf16 v[78:81], v[170:173], v[198:201], v[78:81]
	v_mfma_f32_16x16x32_bf16 v[70:73], v[162:165], v[206:209], v[70:73]
	v_mfma_f32_16x16x32_bf16 v[66:69], v[170:173], v[206:209], v[66:69]
	v_mfma_f32_16x16x32_bf16 v[118:121], v[166:169], v[186:189], v[118:121]
	v_mfma_f32_16x16x32_bf16 v[110:113], v[174:177], v[186:189], v[110:113]
	v_mfma_f32_16x16x32_bf16 v[102:105], v[166:169], v[194:197], v[102:105]
	v_mfma_f32_16x16x32_bf16 v[94:97], v[174:177], v[194:197], v[94:97]
	v_mfma_f32_16x16x32_bf16 v[86:89], v[166:169], v[202:205], v[86:89]
	v_mfma_f32_16x16x32_bf16 v[78:81], v[174:177], v[202:205], v[78:81]
	v_mfma_f32_16x16x32_bf16 v[70:73], v[166:169], v[210:213], v[70:73]
	v_mfma_f32_16x16x32_bf16 v[66:69], v[174:177], v[210:213], v[66:69]
	s_setprio 0
	s_barrier
; #define PG8_STAGE(bufoff, gbase, voff) do { _Pragma("unroll") for (int _i = 0; _i < 2; ++_i) \
;         __builtin_amdgcn_global_load_lds((const unsigned*)((const char*)(gbase) + (voff)[_i]), (PG8_LAS unsigned*)(lds + (bufoff) + ldsw + _i * 8192), 16, 0, 0); } while (0)
; #define PG8_LDA(dst, b, h) do { _Pragma("unroll") for (int m = 0; m < 4; ++m) _Pragma("unroll") for (int k = 0; k < 2; ++k) dst[m][k] = *(const PG8_LAS bf16x8*)(lds + PG8_SA(b, h) + aoff + m * 2048 + k * 1024); } while (0)
; #define PG8_LDB(dst, b, h) do { _Pragma("unroll") for (int n = 0; n < 2; ++n) _Pragma("unroll") for (int k = 0; k < 2; ++k) dst[n][k] = *(const PG8_LAS bf16x8*)(lds + PG8_SB(b, h) + boff + n * 2048 + k * 1024); } while (0)
; #define PG8_MMA(ai, bj, At, Bt) do { __builtin_amdgcn_s_setprio(1); _Pragma("unroll") for (int m = 0; m < 4; ++m) _Pragma("unroll") for (int n = 0; n < 2; ++n) _Pragma("unroll") for (int k = 0; k < 2; ++k) \
;         acc[ai][bj][m][n] = __builtin_amdgcn_mfma_f32_16x16x32_bf16(Bt[n][k], At[m][k], acc[ai][bj][m][n], 0, 0, 0); __builtin_amdgcn_s_setprio(0); } while (0)
; #define PG8_WAIT_V(n) asm volatile("s_waitcnt vmcnt(" #n ")" ::: "memory")
; template <class Epi, class Sched, bool ALIGN_EPI = false, bool SP2 = false>
; __device__ __forceinline__ void gemm_phase(PG8_LAS unsigned char* lds, const Gemm g, const Sched& S, const Epi& E) {
;     ...
;             PG8_LDB(B0, 0, 0); PG8_LDB(B1, 0, 1); PG8_SCHED; PG8_LDA(At, 0, 0); PG8_STAGE(PG8_SA(1, 1), a1 + hstep, voffA);
;             PG8_WAIT_V(8); PG8_WAIT_L(0); PG8_BAR; PG8_MMA(0, 0, At, B0); PG8_MMA(0, 1, At, B1); PG8_BAR; PG8_SCHED;
;             PG8_LDA(At, 0, 1); PG8_STAGE(PG8_SB(0, 0), b2, voffB); PG8_STAGE(PG8_SB(0, 1), b2 + hstep, voffB); PG8_STAGE(PG8_SA(0, 0), a2, voffA);
;             PG8_WAIT_V(8); PG8_WAIT_L(0); PG8_BAR; PG8_MMA(1, 0, At, B0); PG8_MMA(1, 1, At, B1); PG8_BAR; PG8_SCHED;
;             PG8_LDB(B0, 1, 0); PG8_LDB(B1, 1, 1); PG8_SCHED; PG8_LDA(At, 1, 0); PG8_STAGE(PG8_SA(0, 1), a2 + hstep, voffA);
;             PG8_WAIT_V(8); PG8_WAIT_L(0); PG8_BAR; PG8_MMA(0, 0, At, B0); PG8_MMA(0, 1, At, B1); PG8_BAR; PG8_SCHED;
;             PG8_LDA(At, 1, 1); PG8_STAGE(PG8_SB(1, 0), b3, voffB); PG8_STAGE(PG8_SB(1, 1), b3 + hstep, voffB); PG8_STAGE(PG8_SA(1, 0), a3, voffA);
;             PG8_WAIT_V(8); PG8_WAIT_L(0); PG8_BAR; PG8_MMA(1, 0, At, B0); PG8_MMA(1, 1, At, B1); PG8_BAR; PG8_SCHED;
	s_add_i32 s20, s52, s36
	v_lshl_add_u64 v[214:215], v[214:215], 0, s[80:81]
	s_mov_b32 m0, s20
	ds_read_b128 v[180:183], v156 offset:49152
	ds_read_b128 v[186:189], v156 offset:50176
	ds_read_b128 v[190:193], v156 offset:51200
	ds_read_b128 v[194:197], v156 offset:52224
	ds_read_b128 v[198:201], v156 offset:53248
	ds_read_b128 v[202:205], v156 offset:54272
	ds_read_b128 v[206:209], v156 offset:55296
	ds_read_b128 v[210:213], v156 offset:56320
	global_load_lds_dwordx4 v[214:215], off
	s_add_i32 m0, s20, 0x2000
	s_add_u32 s20, s24, 0xb0080
	v_lshl_add_u64 v[214:215], v[216:217], 0, s[80:81]
	s_addc_u32 s21, s25, 0
	s_add_i32 s24, s53, s36
	global_load_lds_dwordx4 v[214:215], off
	s_mov_b32 m0, s24
	s_nop 0
	global_load_lds_dwordx4 v132, s[20:21]
	s_add_i32 m0, s24, 0x2000
	s_nop 0
	global_load_lds_dwordx4 v136, s[20:21]
	v_lshl_add_u64 v[214:215], v[218:219], 0, s[80:81]
	s_mov_b32 m0, s41
	s_nop 0
	global_load_lds_dwordx4 v[214:215], off
	v_lshl_add_u64 v[214:215], v[220:221], 0, s[80:81]
	s_mov_b32 m0, s42
	s_nop 0
	global_load_lds_dwordx4 v[214:215], off
	s_waitcnt vmcnt(8) lgkmcnt(0)
	s_barrier
	s_setprio 1
	v_mfma_f32_16x16x32_bf16 v[62:65], v[142:145], v[180:183], v[62:65]
	v_mfma_f32_16x16x32_bf16 v[58:61], v[150:153], v[180:183], v[58:61]
	v_mfma_f32_16x16x32_bf16 v[50:53], v[142:145], v[190:193], v[50:53]
	v_mfma_f32_16x16x32_bf16 v[42:45], v[150:153], v[190:193], v[42:45]
	v_mfma_f32_16x16x32_bf16 v[34:37], v[142:145], v[198:201], v[34:37]
	v_mfma_f32_16x16x32_bf16 v[26:29], v[150:153], v[198:201], v[26:29]
	v_mfma_f32_16x16x32_bf16 v[18:21], v[142:145], v[206:209], v[18:21]
	v_mfma_f32_16x16x32_bf16 v[10:13], v[150:153], v[206:209], v[10:13]
	v_mfma_f32_16x16x32_bf16 v[62:65], v[146:149], v[186:189], v[62:65]
	v_mfma_f32_16x16x32_bf16 v[58:61], v[158:161], v[186:189], v[58:61]
	v_mfma_f32_16x16x32_bf16 v[50:53], v[146:149], v[194:197], v[50:53]
	v_mfma_f32_16x16x32_bf16 v[42:45], v[158:161], v[194:197], v[42:45]
	v_mfma_f32_16x16x32_bf16 v[34:37], v[146:149], v[202:205], v[34:37]
	v_mfma_f32_16x16x32_bf16 v[26:29], v[158:161], v[202:205], v[26:29]
	v_mfma_f32_16x16x32_bf16 v[18:21], v[146:149], v[210:213], v[18:21]
	v_mfma_f32_16x16x32_bf16 v[10:13], v[158:161], v[210:213], v[10:13]
	v_mfma_f32_16x16x32_bf16 v[54:57], v[162:165], v[180:183], v[54:57]
	v_mfma_f32_16x16x32_bf16 v[46:49], v[170:173], v[180:183], v[46:49]
	v_mfma_f32_16x16x32_bf16 v[38:41], v[162:165], v[190:193], v[38:41]
	v_mfma_f32_16x16x32_bf16 v[30:33], v[170:173], v[190:193], v[30:33]
	v_mfma_f32_16x16x32_bf16 v[22:25], v[162:165], v[198:201], v[22:25]
	v_mfma_f32_16x16x32_bf16 v[14:17], v[170:173], v[198:201], v[14:17]
	v_mfma_f32_16x16x32_bf16 v[6:9], v[162:165], v[206:209], v[6:9]
	v_mfma_f32_16x16x32_bf16 v[2:5], v[170:173], v[206:209], v[2:5]
	v_mfma_f32_16x16x32_bf16 v[54:57], v[166:169], v[186:189], v[54:57]
	v_mfma_f32_16x16x32_bf16 v[46:49], v[174:177], v[186:189], v[46:49]
	v_mfma_f32_16x16x32_bf16 v[38:41], v[166:169], v[194:197], v[38:41]
	v_mfma_f32_16x16x32_bf16 v[30:33], v[174:177], v[194:197], v[30:33]
	v_mfma_f32_16x16x32_bf16 v[22:25], v[166:169], v[202:205], v[22:25]
	v_mfma_f32_16x16x32_bf16 v[14:17], v[174:177], v[202:205], v[14:17]
	v_mfma_f32_16x16x32_bf16 v[6:9], v[166:169], v[210:213], v[6:9]
	v_mfma_f32_16x16x32_bf16 v[2:5], v[174:177], v[210:213], v[2:5]
	s_setprio 0
	s_barrier
	s_add_i32 s51, s51, 2
	s_add_u32 s49, s49, 0x100
	s_addc_u32 s50, s50, 0
	s_cmp_gt_u32 s51, 41
	s_mov_b64 s[20:21], s[22:23]
	s_branch .LBB0_1330
.LBB0_1330:
	s_add_u32 s22, s20, 0x100
	s_addc_u32 s23, s21, 0
	s_add_i32 s52, 0, 0x10000
	s_cmp_eq_u32 s51, 40
	s_cselect_b32 s27, s7, s23
	s_cselect_b32 s26, s6, s22
	v_add_u32_e32 v157, s52, v154
	s_cselect_b32 s25, s19, s50
	s_cselect_b32 s24, s18, s49
	s_add_i32 s53, 0, 0x14000
	ds_read_b128 v[142:145], v157
	ds_read_b128 v[146:149], v157 offset:1024
	ds_read_b128 v[150:153], v157 offset:2048
	ds_read_b128 v[158:161], v157 offset:3072
	v_add_u32_e32 v157, s53, v154
	ds_read_b128 v[162:165], v157
	ds_read_b128 v[166:169], v157 offset:1024
	ds_read_b128 v[170:173], v157 offset:2048
	ds_read_b128 v[174:177], v157 offset:3072
	v_lshl_add_u64 v[214:215], s[20:21], 0, v[138:139]
	s_add_i32 m0, s37, 0xc000
	ds_read_b128 v[180:183], v156
	ds_read_b128 v[186:189], v156 offset:1024
	ds_read_b128 v[190:193], v156 offset:2048
	ds_read_b128 v[194:197], v156 offset:3072
	ds_read_b128 v[198:201], v156 offset:4096
	ds_read_b128 v[202:205], v156 offset:5120
	ds_read_b128 v[206:209], v156 offset:6144
	ds_read_b128 v[210:213], v156 offset:7168
	global_load_lds_dwordx4 v[214:215], off
	v_lshl_add_u64 v[214:215], s[20:21], 0, v[140:141]
	s_add_i32 m0, s37, 0xe000
	s_nop 0
	global_load_lds_dwordx4 v[214:215], off
	s_waitcnt vmcnt(8) lgkmcnt(0)
	s_barrier
; #define PG8_STAGE(bufoff, gbase, voff) do { _Pragma("unroll") for (int _i = 0; _i < 2; ++_i) \
;         __builtin_amdgcn_global_load_lds((const unsigned*)((const char*)(gbase) + (voff)[_i]), (PG8_LAS unsigned*)(lds + (bufoff) + ldsw + _i * 8192), 16, 0, 0); } while (0)
; #define PG8_LDA(dst, b, h) do { _Pragma("unroll") for (int m = 0; m < 4; ++m) _Pragma("unroll") for (int k = 0; k < 2; ++k) dst[m][k] = *(const PG8_LAS bf16x8*)(lds + PG8_SA(b, h) + aoff + m * 2048 + k * 1024); } while (0)
; #define PG8_LDB(dst, b, h) do { _Pragma("unroll") for (int n = 0; n < 2; ++n) _Pragma("unroll") for (int k = 0; k < 2; ++k) dst[n][k] = *(const PG8_LAS bf16x8*)(lds + PG8_SB(b, h) + boff + n * 2048 + k * 1024); } while (0)
; #define PG8_MMA(ai, bj, At, Bt) do { __builtin_amdgcn_s_setprio(1); _Pragma("unroll") for (int m = 0; m < 4; ++m) _Pragma("unroll") for (int n = 0; n < 2; ++n) _Pragma("unroll") for (int k = 0; k < 2; ++k) \
;         acc[ai][bj][m][n] = __builtin_amdgcn_mfma_f32_16x16x32_bf16(Bt[n][k], At[m][k], acc[ai][bj][m][n], 0, 0, 0); __builtin_amdgcn_s_setprio(0); } while (0)
; #define PG8_WAIT_V(n) asm volatile("s_waitcnt vmcnt(" #n ")" ::: "memory")
; template <class Epi, class Sched, bool ALIGN_EPI = false, bool SP2 = false>
; __device__ __forceinline__ void gemm_phase(PG8_LAS unsigned char* lds, const Gemm g, const Sched& S, const Epi& E) {
;     ...
;             PG8_LDB(B0, 0, 0); PG8_LDB(B1, 0, 1); PG8_SCHED; PG8_LDA(At, 0, 0); PG8_STAGE(PG8_SA(1, 1), a1 + hstep, voffA);
;             PG8_WAIT_V(8); PG8_WAIT_L(0); PG8_BAR; PG8_MMA(0, 0, At, B0); PG8_MMA(0, 1, At, B1); PG8_BAR; PG8_SCHED;
;             PG8_LDA(At, 0, 1); PG8_STAGE(PG8_SB(0, 0), b2, voffB); PG8_STAGE(PG8_SB(0, 1), b2 + hstep, voffB); PG8_STAGE(PG8_SA(0, 0), a2, voffA);
;             PG8_WAIT_V(8); PG8_WAIT_L(0); PG8_BAR; PG8_MMA(1, 0, At, B0); PG8_MMA(1, 1, At, B1); PG8_BAR; PG8_SCHED;
;             PG8_LDB(B0, 1, 0); PG8_LDB(B1, 1, 1); PG8_SCHED; PG8_LDA(At, 1, 0); PG8_STAGE(PG8_SA(0, 1), a2 + hstep, voffA);
;             PG8_WAIT_V(8); PG8_WAIT_L(0); PG8_BAR; PG8_MMA(0, 0, At, B0); PG8_MMA(0, 1, At, B1); PG8_BAR; PG8_SCHED;
;             PG8_LDA(At, 1, 1); PG8_STAGE(PG8_SB(1, 0), b3, voffB); PG8_STAGE(PG8_SB(1, 1), b3 + hstep, voffB); PG8_STAGE(PG8_SA(1, 0), a3, voffA);
;             PG8_WAIT_V(8); PG8_WAIT_L(0); PG8_BAR; PG8_MMA(1, 0, At, B0); PG8_MMA(1, 1, At, B1); PG8_BAR; PG8_SCHED;
	s_setprio 1
	v_mfma_f32_16x16x32_bf16 v[126:129], v[142:145], v[180:183], v[126:129]
	v_mfma_f32_16x16x32_bf16 v[122:125], v[150:153], v[180:183], v[122:125]
	v_mfma_f32_16x16x32_bf16 v[114:117], v[142:145], v[190:193], v[114:117]
	v_mfma_f32_16x16x32_bf16 v[106:109], v[150:153], v[190:193], v[106:109]
	v_mfma_f32_16x16x32_bf16 v[98:101], v[142:145], v[198:201], v[98:101]
	v_mfma_f32_16x16x32_bf16 v[90:93], v[150:153], v[198:201], v[90:93]
	v_mfma_f32_16x16x32_bf16 v[82:85], v[142:145], v[206:209], v[82:85]
	v_mfma_f32_16x16x32_bf16 v[74:77], v[150:153], v[206:209], v[74:77]
	v_mfma_f32_16x16x32_bf16 v[126:129], v[146:149], v[186:189], v[126:129]
	v_mfma_f32_16x16x32_bf16 v[122:125], v[158:161], v[186:189], v[122:125]
	v_mfma_f32_16x16x32_bf16 v[114:117], v[146:149], v[194:197], v[114:117]
	v_mfma_f32_16x16x32_bf16 v[106:109], v[158:161], v[194:197], v[106:109]
	v_mfma_f32_16x16x32_bf16 v[98:101], v[146:149], v[202:205], v[98:101]
	v_mfma_f32_16x16x32_bf16 v[90:93], v[158:161], v[202:205], v[90:93]
	v_mfma_f32_16x16x32_bf16 v[82:85], v[146:149], v[210:213], v[82:85]
	v_mfma_f32_16x16x32_bf16 v[74:77], v[158:161], v[210:213], v[74:77]
	v_mfma_f32_16x16x32_bf16 v[118:121], v[162:165], v[180:183], v[118:121]
	v_mfma_f32_16x16x32_bf16 v[110:113], v[170:173], v[180:183], v[110:113]
	v_mfma_f32_16x16x32_bf16 v[102:105], v[162:165], v[190:193], v[102:105]
	v_mfma_f32_16x16x32_bf16 v[94:97], v[170:173], v[190:193], v[94:97]
	v_mfma_f32_16x16x32_bf16 v[86:89], v[162:165], v[198:201], v[86:89]
	v_mfma_f32_16x16x32_bf16 v[78:81], v[170:173], v[198:201], v[78:81]
	v_mfma_f32_16x16x32_bf16 v[70:73], v[162:165], v[206:209], v[70:73]
	v_mfma_f32_16x16x32_bf16 v[66:69], v[170:173], v[206:209], v[66:69]
	v_mfma_f32_16x16x32_bf16 v[118:121], v[166:169], v[186:189], v[118:121]
	v_mfma_f32_16x16x32_bf16 v[110:113], v[174:177], v[186:189], v[110:113]
	v_mfma_f32_16x16x32_bf16 v[102:105], v[166:169], v[194:197], v[102:105]
	v_mfma_f32_16x16x32_bf16 v[94:97], v[174:177], v[194:197], v[94:97]
	v_mfma_f32_16x16x32_bf16 v[86:89], v[166:169], v[202:205], v[86:89]
	v_mfma_f32_16x16x32_bf16 v[78:81], v[174:177], v[202:205], v[78:81]
	v_mfma_f32_16x16x32_bf16 v[70:73], v[166:169], v[210:213], v[70:73]
	v_mfma_f32_16x16x32_bf16 v[66:69], v[174:177], v[210:213], v[66:69]
	s_setprio 0
	s_barrier
	s_add_i32 s20, s52, s36
	v_lshl_add_u64 v[214:215], s[24:25], 0, v[132:133]
	s_mov_b32 m0, s20
	ds_read_b128 v[180:183], v156 offset:16384
	ds_read_b128 v[186:189], v156 offset:17408
	ds_read_b128 v[190:193], v156 offset:18432
	ds_read_b128 v[194:197], v156 offset:19456
	ds_read_b128 v[198:201], v156 offset:20480
	ds_read_b128 v[202:205], v156 offset:21504
	ds_read_b128 v[206:209], v156 offset:22528
	ds_read_b128 v[210:213], v156 offset:23552
	global_load_lds_dwordx4 v[214:215], off
	s_add_i32 m0, s20, 0x2000
	s_add_u32 s20, s24, 0xb0000
	v_lshl_add_u64 v[216:217], s[24:25], 0, v[136:137]
	s_addc_u32 s21, s25, 0
	s_add_i32 s52, s53, s36
	global_load_lds_dwordx4 v[216:217], off
	v_lshl_add_u64 v[218:219], s[20:21], 0, v[132:133]
	s_mov_b32 m0, s52
	v_lshl_add_u64 v[220:221], s[26:27], 0, v[134:135]
	global_load_lds_dwordx4 v[218:219], off
	s_add_i32 m0, s52, 0x2000
	s_nop 0
	global_load_lds_dwordx4 v136, s[20:21]
	v_lshl_add_u64 v[218:219], s[26:27], 0, v[130:131]
	s_mov_b32 m0, s37
	s_nop 0
	global_load_lds_dwordx4 v[218:219], off
	s_mov_b32 m0, s38
	s_nop 0
	global_load_lds_dwordx4 v[220:221], off
	s_waitcnt vmcnt(8) lgkmcnt(0)
	s_barrier
	s_setprio 1
	v_mfma_f32_16x16x32_bf16 v[62:65], v[142:145], v[180:183], v[62:65]
	v_mfma_f32_16x16x32_bf16 v[58:61], v[150:153], v[180:183], v[58:61]
	v_mfma_f32_16x16x32_bf16 v[50:53], v[142:145], v[190:193], v[50:53]
	v_mfma_f32_16x16x32_bf16 v[42:45], v[150:153], v[190:193], v[42:45]
	v_mfma_f32_16x16x32_bf16 v[34:37], v[142:145], v[198:201], v[34:37]
	v_mfma_f32_16x16x32_bf16 v[26:29], v[150:153], v[198:201], v[26:29]
	v_mfma_f32_16x16x32_bf16 v[18:21], v[142:145], v[206:209], v[18:21]
	v_mfma_f32_16x16x32_bf16 v[10:13], v[150:153], v[206:209], v[10:13]
	v_mfma_f32_16x16x32_bf16 v[62:65], v[146:149], v[186:189], v[62:65]
	v_mfma_f32_16x16x32_bf16 v[58:61], v[158:161], v[186:189], v[58:61]
	v_mfma_f32_16x16x32_bf16 v[50:53], v[146:149], v[194:197], v[50:53]
	v_mfma_f32_16x16x32_bf16 v[42:45], v[158:161], v[194:197], v[42:45]
	v_mfma_f32_16x16x32_bf16 v[34:37], v[146:149], v[202:205], v[34:37]
	v_mfma_f32_16x16x32_bf16 v[26:29], v[158:161], v[202:205], v[26:29]
	v_mfma_f32_16x16x32_bf16 v[18:21], v[146:149], v[210:213], v[18:21]
	v_mfma_f32_16x16x32_bf16 v[10:13], v[158:161], v[210:213], v[10:13]
	v_mfma_f32_16x16x32_bf16 v[54:57], v[162:165], v[180:183], v[54:57]
	v_mfma_f32_16x16x32_bf16 v[46:49], v[170:173], v[180:183], v[46:49]
	v_mfma_f32_16x16x32_bf16 v[38:41], v[162:165], v[190:193], v[38:41]
	v_mfma_f32_16x16x32_bf16 v[30:33], v[170:173], v[190:193], v[30:33]
	v_mfma_f32_16x16x32_bf16 v[22:25], v[162:165], v[198:201], v[22:25]
	v_mfma_f32_16x16x32_bf16 v[14:17], v[170:173], v[198:201], v[14:17]
	v_mfma_f32_16x16x32_bf16 v[6:9], v[162:165], v[206:209], v[6:9]
	v_mfma_f32_16x16x32_bf16 v[2:5], v[170:173], v[206:209], v[2:5]
	v_mfma_f32_16x16x32_bf16 v[54:57], v[166:169], v[186:189], v[54:57]
	v_mfma_f32_16x16x32_bf16 v[46:49], v[174:177], v[186:189], v[46:49]
	v_mfma_f32_16x16x32_bf16 v[38:41], v[166:169], v[194:197], v[38:41]
	v_mfma_f32_16x16x32_bf16 v[30:33], v[174:177], v[194:197], v[30:33]
	v_mfma_f32_16x16x32_bf16 v[22:25], v[166:169], v[202:205], v[22:25]
	v_mfma_f32_16x16x32_bf16 v[14:17], v[174:177], v[202:205], v[14:17]
	v_mfma_f32_16x16x32_bf16 v[6:9], v[166:169], v[210:213], v[6:9]
	v_mfma_f32_16x16x32_bf16 v[2:5], v[174:177], v[210:213], v[2:5]
	s_setprio 0
	s_barrier
; #define PG8_STAGE(bufoff, gbase, voff) do { _Pragma("unroll") for (int _i = 0; _i < 2; ++_i) \
;         __builtin_amdgcn_global_load_lds((const unsigned*)((const char*)(gbase) + (voff)[_i]), (PG8_LAS unsigned*)(lds + (bufoff) + ldsw + _i * 8192), 16, 0, 0); } while (0)
; #define PG8_LDA(dst, b, h) do { _Pragma("unroll") for (int m = 0; m < 4; ++m) _Pragma("unroll") for (int k = 0; k < 2; ++k) dst[m][k] = *(const PG8_LAS bf16x8*)(lds + PG8_SA(b, h) + aoff + m * 2048 + k * 1024); } while (0)
; #define PG8_LDB(dst, b, h) do { _Pragma("unroll") for (int n = 0; n < 2; ++n) _Pragma("unroll") for (int k = 0; k < 2; ++k) dst[n][k] = *(const PG8_LAS bf16x8*)(lds + PG8_SB(b, h) + boff + n * 2048 + k * 1024); } while (0)
; #define PG8_MMA(ai, bj, At, Bt) do { __builtin_amdgcn_s_setprio(1); _Pragma("unroll") for (int m = 0; m < 4; ++m) _Pragma("unroll") for (int n = 0; n < 2; ++n) _Pragma("unroll") for (int k = 0; k < 2; ++k) \
;         acc[ai][bj][m][n] = __builtin_amdgcn_mfma_f32_16x16x32_bf16(Bt[n][k], At[m][k], acc[ai][bj][m][n], 0, 0, 0); __builtin_amdgcn_s_setprio(0); } while (0)
; #define PG8_WAIT_V(n) asm volatile("s_waitcnt vmcnt(" #n ")" ::: "memory")
; template <class Epi, class Sched, bool ALIGN_EPI = false, bool SP2 = false>
; __device__ __forceinline__ void gemm_phase(PG8_LAS unsigned char* lds, const Gemm g, const Sched& S, const Epi& E) {
;     ...
;             PG8_LDB(B0, 0, 0); PG8_LDB(B1, 0, 1); PG8_SCHED; PG8_LDA(At, 0, 0); PG8_STAGE(PG8_SA(1, 1), a1 + hstep, voffA);
;             PG8_WAIT_V(8); PG8_WAIT_L(0); PG8_BAR; PG8_MMA(0, 0, At, B0); PG8_MMA(0, 1, At, B1); PG8_BAR; PG8_SCHED;
;             PG8_LDA(At, 0, 1); PG8_STAGE(PG8_SB(0, 0), b2, voffB); PG8_STAGE(PG8_SB(0, 1), b2 + hstep, voffB); PG8_STAGE(PG8_SA(0, 0), a2, voffA);
;             PG8_WAIT_V(8); PG8_WAIT_L(0); PG8_BAR; PG8_MMA(1, 0, At, B0); PG8_MMA(1, 1, At, B1); PG8_BAR; PG8_SCHED;
;             PG8_LDB(B0, 1, 0); PG8_LDB(B1, 1, 1); PG8_SCHED; PG8_LDA(At, 1, 0); PG8_STAGE(PG8_SA(0, 1), a2 + hstep, voffA);
;             PG8_WAIT_V(8); PG8_WAIT_L(0); PG8_BAR; PG8_MMA(0, 0, At, B0); PG8_MMA(0, 1, At, B1); PG8_BAR; PG8_SCHED;
;             PG8_LDA(At, 1, 1); PG8_STAGE(PG8_SB(1, 0), b3, voffB); PG8_STAGE(PG8_SB(1, 1), b3 + hstep, voffB); PG8_STAGE(PG8_SA(1, 0), a3, voffA);
;             PG8_WAIT_V(8); PG8_WAIT_L(0); PG8_BAR; PG8_MMA(1, 0, At, B0); PG8_MMA(1, 1, At, B1); PG8_BAR; PG8_SCHED;
	s_add_i32 s52, 0, 0x18000
	v_add_u32_e32 v157, s52, v154
	s_add_i32 s53, 0, 0x1c000
	ds_read_b128 v[142:145], v157
	ds_read_b128 v[146:149], v157 offset:1024
	ds_read_b128 v[150:153], v157 offset:2048
	ds_read_b128 v[158:161], v157 offset:3072
	v_add_u32_e32 v157, s53, v154
	ds_read_b128 v[162:165], v157
	ds_read_b128 v[166:169], v157 offset:1024
	ds_read_b128 v[170:173], v157 offset:2048
	ds_read_b128 v[174:177], v157 offset:3072
	s_add_u32 s20, s26, 0xb0000
	s_addc_u32 s21, s27, 0
	s_mov_b32 m0, s39
	ds_read_b128 v[180:183], v156 offset:32768
	ds_read_b128 v[186:189], v156 offset:33792
	ds_read_b128 v[190:193], v156 offset:34816
	ds_read_b128 v[194:197], v156 offset:35840
	ds_read_b128 v[198:201], v156 offset:36864
	ds_read_b128 v[202:205], v156 offset:37888
	ds_read_b128 v[206:209], v156 offset:38912
	ds_read_b128 v[210:213], v156 offset:39936
	global_load_lds_dwordx4 v130, s[20:21]
	v_lshl_add_u64 v[222:223], s[20:21], 0, v[134:135]
	s_mov_b32 m0, s40
	s_nop 0
	global_load_lds_dwordx4 v[222:223], off
	s_waitcnt vmcnt(8) lgkmcnt(0)
	s_barrier
	s_setprio 1
	v_mfma_f32_16x16x32_bf16 v[126:129], v[142:145], v[180:183], v[126:129]
	v_mfma_f32_16x16x32_bf16 v[122:125], v[150:153], v[180:183], v[122:125]
	v_mfma_f32_16x16x32_bf16 v[114:117], v[142:145], v[190:193], v[114:117]
	v_mfma_f32_16x16x32_bf16 v[106:109], v[150:153], v[190:193], v[106:109]
	v_mfma_f32_16x16x32_bf16 v[98:101], v[142:145], v[198:201], v[98:101]
	v_mfma_f32_16x16x32_bf16 v[90:93], v[150:153], v[198:201], v[90:93]
	v_mfma_f32_16x16x32_bf16 v[82:85], v[142:145], v[206:209], v[82:85]
	v_mfma_f32_16x16x32_bf16 v[74:77], v[150:153], v[206:209], v[74:77]
	v_mfma_f32_16x16x32_bf16 v[126:129], v[146:149], v[186:189], v[126:129]
	v_mfma_f32_16x16x32_bf16 v[122:125], v[158:161], v[186:189], v[122:125]
	v_mfma_f32_16x16x32_bf16 v[114:117], v[146:149], v[194:197], v[114:117]
	v_mfma_f32_16x16x32_bf16 v[106:109], v[158:161], v[194:197], v[106:109]
	v_mfma_f32_16x16x32_bf16 v[98:101], v[146:149], v[202:205], v[98:101]
	v_mfma_f32_16x16x32_bf16 v[90:93], v[158:161], v[202:205], v[90:93]
	v_mfma_f32_16x16x32_bf16 v[82:85], v[146:149], v[210:213], v[82:85]
	v_mfma_f32_16x16x32_bf16 v[74:77], v[158:161], v[210:213], v[74:77]
	v_mfma_f32_16x16x32_bf16 v[118:121], v[162:165], v[180:183], v[118:121]
	v_mfma_f32_16x16x32_bf16 v[110:113], v[170:173], v[180:183], v[110:113]
	v_mfma_f32_16x16x32_bf16 v[102:105], v[162:165], v[190:193], v[102:105]
	v_mfma_f32_16x16x32_bf16 v[94:97], v[170:173], v[190:193], v[94:97]
	v_mfma_f32_16x16x32_bf16 v[86:89], v[162:165], v[198:201], v[86:89]
	v_mfma_f32_16x16x32_bf16 v[78:81], v[170:173], v[198:201], v[78:81]
	v_mfma_f32_16x16x32_bf16 v[70:73], v[162:165], v[206:209], v[70:73]
	v_mfma_f32_16x16x32_bf16 v[66:69], v[170:173], v[206:209], v[66:69]
	v_mfma_f32_16x16x32_bf16 v[118:121], v[166:169], v[186:189], v[118:121]
	v_mfma_f32_16x16x32_bf16 v[110:113], v[174:177], v[186:189], v[110:113]
	v_mfma_f32_16x16x32_bf16 v[102:105], v[166:169], v[194:197], v[102:105]
	v_mfma_f32_16x16x32_bf16 v[94:97], v[174:177], v[194:197], v[94:97]
	v_mfma_f32_16x16x32_bf16 v[86:89], v[166:169], v[202:205], v[86:89]
	v_mfma_f32_16x16x32_bf16 v[78:81], v[174:177], v[202:205], v[78:81]
	v_mfma_f32_16x16x32_bf16 v[70:73], v[166:169], v[210:213], v[70:73]
	v_mfma_f32_16x16x32_bf16 v[66:69], v[174:177], v[210:213], v[66:69]
	s_setprio 0
	s_barrier
	s_add_i32 s20, s52, s36
	v_lshl_add_u64 v[214:215], v[214:215], 0, s[80:81]
	s_mov_b32 m0, s20
	ds_read_b128 v[180:183], v156 offset:49152
	ds_read_b128 v[186:189], v156 offset:50176
	ds_read_b128 v[190:193], v156 offset:51200
	ds_read_b128 v[194:197], v156 offset:52224
	ds_read_b128 v[198:201], v156 offset:53248
	ds_read_b128 v[202:205], v156 offset:54272
	ds_read_b128 v[206:209], v156 offset:55296
	ds_read_b128 v[210:213], v156 offset:56320
	global_load_lds_dwordx4 v[214:215], off
	s_add_i32 m0, s20, 0x2000
	s_add_u32 s20, s24, 0xb0080
	v_lshl_add_u64 v[214:215], v[216:217], 0, s[80:81]
	s_addc_u32 s21, s25, 0
	s_add_i32 s24, s53, s36
	global_load_lds_dwordx4 v[214:215], off
	s_mov_b32 m0, s24
	s_nop 0
	global_load_lds_dwordx4 v132, s[20:21]
	s_add_i32 m0, s24, 0x2000
	s_nop 0
	global_load_lds_dwordx4 v136, s[20:21]
	v_lshl_add_u64 v[214:215], v[218:219], 0, s[80:81]
	s_mov_b32 m0, s41
	s_nop 0
	global_load_lds_dwordx4 v[214:215], off
	v_lshl_add_u64 v[214:215], v[220:221], 0, s[80:81]
	s_mov_b32 m0, s42
	s_nop 0
	global_load_lds_dwordx4 v[214:215], off
	s_waitcnt vmcnt(8) lgkmcnt(0)
	s_barrier
	s_setprio 1
	v_mfma_f32_16x16x32_bf16 v[62:65], v[142:145], v[180:183], v[62:65]
	v_mfma_f32_16x16x32_bf16 v[58:61], v[150:153], v[180:183], v[58:61]
	v_mfma_f32_16x16x32_bf16 v[50:53], v[142:145], v[190:193], v[50:53]
	v_mfma_f32_16x16x32_bf16 v[42:45], v[150:153], v[190:193], v[42:45]
	v_mfma_f32_16x16x32_bf16 v[34:37], v[142:145], v[198:201], v[34:37]
	v_mfma_f32_16x16x32_bf16 v[26:29], v[150:153], v[198:201], v[26:29]
	v_mfma_f32_16x16x32_bf16 v[18:21], v[142:145], v[206:209], v[18:21]
	v_mfma_f32_16x16x32_bf16 v[10:13], v[150:153], v[206:209], v[10:13]
	v_mfma_f32_16x16x32_bf16 v[62:65], v[146:149], v[186:189], v[62:65]
	v_mfma_f32_16x16x32_bf16 v[58:61], v[158:161], v[186:189], v[58:61]
	v_mfma_f32_16x16x32_bf16 v[50:53], v[146:149], v[194:197], v[50:53]
	v_mfma_f32_16x16x32_bf16 v[42:45], v[158:161], v[194:197], v[42:45]
	v_mfma_f32_16x16x32_bf16 v[34:37], v[146:149], v[202:205], v[34:37]
	v_mfma_f32_16x16x32_bf16 v[26:29], v[158:161], v[202:205], v[26:29]
	v_mfma_f32_16x16x32_bf16 v[18:21], v[146:149], v[210:213], v[18:21]
	v_mfma_f32_16x16x32_bf16 v[10:13], v[158:161], v[210:213], v[10:13]
	v_mfma_f32_16x16x32_bf16 v[54:57], v[162:165], v[180:183], v[54:57]
	v_mfma_f32_16x16x32_bf16 v[46:49], v[170:173], v[180:183], v[46:49]
	v_mfma_f32_16x16x32_bf16 v[38:41], v[162:165], v[190:193], v[38:41]
	v_mfma_f32_16x16x32_bf16 v[30:33], v[170:173], v[190:193], v[30:33]
	v_mfma_f32_16x16x32_bf16 v[22:25], v[162:165], v[198:201], v[22:25]
	v_mfma_f32_16x16x32_bf16 v[14:17], v[170:173], v[198:201], v[14:17]
	v_mfma_f32_16x16x32_bf16 v[6:9], v[162:165], v[206:209], v[6:9]
	v_mfma_f32_16x16x32_bf16 v[2:5], v[170:173], v[206:209], v[2:5]
	v_mfma_f32_16x16x32_bf16 v[54:57], v[166:169], v[186:189], v[54:57]
	v_mfma_f32_16x16x32_bf16 v[46:49], v[174:177], v[186:189], v[46:49]
	v_mfma_f32_16x16x32_bf16 v[38:41], v[166:169], v[194:197], v[38:41]
	v_mfma_f32_16x16x32_bf16 v[30:33], v[174:177], v[194:197], v[30:33]
	v_mfma_f32_16x16x32_bf16 v[22:25], v[166:169], v[202:205], v[22:25]
	v_mfma_f32_16x16x32_bf16 v[14:17], v[174:177], v[202:205], v[14:17]
	v_mfma_f32_16x16x32_bf16 v[6:9], v[166:169], v[210:213], v[6:9]
	v_mfma_f32_16x16x32_bf16 v[2:5], v[174:177], v[210:213], v[2:5]
	s_setprio 0
	s_barrier
	s_add_i32 s51, s51, 2
	s_add_u32 s49, s49, 0x100
	s_addc_u32 s50, s50, 0
	s_cmp_gt_u32 s51, 41
	s_mov_b64 s[20:21], s[22:23]
	s_cbranch_scc0 .LBB0_1330
	s_and_b64 vcc, exec, s[16:17]
	s_cbranch_vccz .LBB0_1333
	s_barrier

; #define PG8_STAGE(bufoff, gbase, voff) do { _Pragma("unroll") for (int _i = 0; _i < 2; ++_i) \
;         __builtin_amdgcn_global_load_lds((const unsigned*)((const char*)(gbase) + (voff)[_i]), (PG8_LAS unsigned*)(lds + (bufoff) + ldsw + _i * 8192), 16, 0, 0); } while (0)
; #define PG8_LDA(dst, b, h) do { _Pragma("unroll") for (int m = 0; m < 4; ++m) _Pragma("unroll") for (int k = 0; k < 2; ++k) dst[m][k] = *(const PG8_LAS bf16x8*)(lds + PG8_SA(b, h) + aoff + m * 2048 + k * 1024); } while (0)
; #define PG8_LDB(dst, b, h) do { _Pragma("unroll") for (int n = 0; n < 2; ++n) _Pragma("unroll") for (int k = 0; k < 2; ++k) dst[n][k] = *(const PG8_LAS bf16x8*)(lds + PG8_SB(b, h) + boff + n * 2048 + k * 1024); } while (0)
; #define PG8_MMA(ai, bj, At, Bt) do { __builtin_amdgcn_s_setprio(1); _Pragma("unroll") for (int m = 0; m < 4; ++m) _Pragma("unroll") for (int n = 0; n < 2; ++n) _Pragma("unroll") for (int k = 0; k < 2; ++k) \
;         acc[ai][bj][m][n] = __builtin_amdgcn_mfma_f32_16x16x32_bf16(Bt[n][k], At[m][k], acc[ai][bj][m][n], 0, 0, 0); __builtin_amdgcn_s_setprio(0); } while (0)
; #define PG8_WAIT_V(n) asm volatile("s_waitcnt vmcnt(" #n ")" ::: "memory")
; #define PG8_WAIT_L(n) asm volatile("s_waitcnt lgkmcnt(" #n ")" ::: "memory")
; #define PG8_BAR __builtin_amdgcn_s_barrier()
; #define PG8_SCHED __builtin_amdgcn_sched_barrier(0)
; template <class Epi, class Sched, bool ALIGN_EPI = false, bool SP2 = false>
; __device__ __forceinline__ void gemm_phase(PG8_LAS unsigned char* lds, const Gemm g, const Sched& S, const Epi& E) {
;     ...
;             PG8_LDB(B0, 0, 0); PG8_LDB(B1, 0, 1); PG8_SCHED; PG8_LDA(At, 0, 0); PG8_STAGE(PG8_SA(1, 1), a1 + hstep, voffA);
;             PG8_WAIT_V(8); PG8_WAIT_L(0); PG8_BAR; PG8_MMA(0, 0, At, B0); PG8_MMA(0, 1, At, B1); PG8_BAR; PG8_SCHED;
;             PG8_LDA(At, 0, 1); PG8_STAGE(PG8_SB(0, 0), b2, voffB); PG8_STAGE(PG8_SB(0, 1), b2 + hstep, voffB); PG8_STAGE(PG8_SA(0, 0), a2, voffA);
;             PG8_WAIT_V(8); PG8_WAIT_L(0); PG8_BAR; PG8_MMA(1, 0, At, B0); PG8_MMA(1, 1, At, B1); PG8_BAR; PG8_SCHED;
.LBB0_1359:
	s_add_u32 s47, s20, 0x100
	s_addc_u32 s48, s21, 0
	s_mov_b32 s49, -2
	s_add_u32 s20, s18, 0x100
	s_addc_u32 s21, s19, 0
	s_add_i32 s50, 0, 0x10000
	s_cmp_eq_u32 s49, 40
	s_cselect_b32 s25, s7, s21
	s_cselect_b32 s24, s6, s20
	v_add_u32_e32 v146, s50, v148
	s_cselect_b32 s23, s17, s48
	s_cselect_b32 s22, s16, s47
	s_add_i32 s51, 0, 0x14000
	ds_read_b128 v[142:145], v146
	ds_read_b128 v[152:155], v146 offset:1024
	ds_read_b128 v[156:159], v146 offset:2048
	ds_read_b128 v[160:163], v146 offset:3072
	v_add_u32_e32 v146, s51, v148
	ds_read_b128 v[164:167], v146
	ds_read_b128 v[168:171], v146 offset:1024
	ds_read_b128 v[172:175], v146 offset:2048
	ds_read_b128 v[180:183], v146 offset:3072
	v_lshl_add_u64 v[146:147], s[18:19], 0, v[138:139]
	s_add_i32 m0, s33, 0xc000
	ds_read_b128 v[186:189], v150
	ds_read_b128 v[190:193], v150 offset:1024
	ds_read_b128 v[194:197], v150 offset:2048
	ds_read_b128 v[198:201], v150 offset:3072
	ds_read_b128 v[202:205], v150 offset:4096
	ds_read_b128 v[206:209], v150 offset:5120
	ds_read_b128 v[210:213], v150 offset:6144
	ds_read_b128 v[214:217], v150 offset:7168
	global_load_lds_dwordx4 v[146:147], off
	v_lshl_add_u64 v[146:147], s[18:19], 0, v[140:141]
	s_add_i32 m0, s33, 0xe000
	s_nop 0
	global_load_lds_dwordx4 v[146:147], off
	s_waitcnt vmcnt(8) lgkmcnt(0)
	s_barrier
	s_setprio 1
	v_mfma_f32_16x16x32_bf16 v[126:129], v[142:145], v[186:189], 0
	v_mfma_f32_16x16x32_bf16 v[122:125], v[156:159], v[186:189], 0
	v_mfma_f32_16x16x32_bf16 v[114:117], v[142:145], v[194:197], 0
	v_mfma_f32_16x16x32_bf16 v[106:109], v[156:159], v[194:197], 0
	v_mfma_f32_16x16x32_bf16 v[98:101], v[142:145], v[202:205], 0
	v_mfma_f32_16x16x32_bf16 v[90:93], v[156:159], v[202:205], 0
	v_mfma_f32_16x16x32_bf16 v[82:85], v[142:145], v[210:213], 0
	v_mfma_f32_16x16x32_bf16 v[74:77], v[156:159], v[210:213], 0
	v_mfma_f32_16x16x32_bf16 v[126:129], v[152:155], v[190:193], v[126:129]
	v_mfma_f32_16x16x32_bf16 v[122:125], v[160:163], v[190:193], v[122:125]
	v_mfma_f32_16x16x32_bf16 v[114:117], v[152:155], v[198:201], v[114:117]
	v_mfma_f32_16x16x32_bf16 v[106:109], v[160:163], v[198:201], v[106:109]
	v_mfma_f32_16x16x32_bf16 v[98:101], v[152:155], v[206:209], v[98:101]
	v_mfma_f32_16x16x32_bf16 v[90:93], v[160:163], v[206:209], v[90:93]
	v_mfma_f32_16x16x32_bf16 v[82:85], v[152:155], v[214:217], v[82:85]
	v_mfma_f32_16x16x32_bf16 v[74:77], v[160:163], v[214:217], v[74:77]
	v_mfma_f32_16x16x32_bf16 v[118:121], v[164:167], v[186:189], 0
	v_mfma_f32_16x16x32_bf16 v[110:113], v[172:175], v[186:189], 0
	v_mfma_f32_16x16x32_bf16 v[102:105], v[164:167], v[194:197], 0
	v_mfma_f32_16x16x32_bf16 v[94:97], v[172:175], v[194:197], 0
	v_mfma_f32_16x16x32_bf16 v[86:89], v[164:167], v[202:205], 0
	v_mfma_f32_16x16x32_bf16 v[78:81], v[172:175], v[202:205], 0
	v_mfma_f32_16x16x32_bf16 v[70:73], v[164:167], v[210:213], 0
	v_mfma_f32_16x16x32_bf16 v[66:69], v[172:175], v[210:213], 0
	v_mfma_f32_16x16x32_bf16 v[118:121], v[168:171], v[190:193], v[118:121]
	v_mfma_f32_16x16x32_bf16 v[110:113], v[180:183], v[190:193], v[110:113]
	v_mfma_f32_16x16x32_bf16 v[102:105], v[168:171], v[198:201], v[102:105]
	v_mfma_f32_16x16x32_bf16 v[94:97], v[180:183], v[198:201], v[94:97]
	v_mfma_f32_16x16x32_bf16 v[86:89], v[168:171], v[206:209], v[86:89]
	v_mfma_f32_16x16x32_bf16 v[78:81], v[180:183], v[206:209], v[78:81]
	v_mfma_f32_16x16x32_bf16 v[70:73], v[168:171], v[214:217], v[70:73]
	v_mfma_f32_16x16x32_bf16 v[66:69], v[180:183], v[214:217], v[66:69]
	s_setprio 0
	s_barrier
	s_add_i32 s18, s50, s27
	v_lshl_add_u64 v[146:147], s[22:23], 0, v[132:133]
	s_mov_b32 m0, s18
	ds_read_b128 v[186:189], v150 offset:16384
	ds_read_b128 v[190:193], v150 offset:17408
	ds_read_b128 v[194:197], v150 offset:18432
	ds_read_b128 v[198:201], v150 offset:19456
	ds_read_b128 v[202:205], v150 offset:20480
	ds_read_b128 v[206:209], v150 offset:21504
	ds_read_b128 v[210:213], v150 offset:22528
	ds_read_b128 v[214:217], v150 offset:23552
	global_load_lds_dwordx4 v[146:147], off
	s_add_i32 m0, s18, 0x2000
	s_add_u32 s18, s22, 0xb0000
	v_lshl_add_u64 v[176:177], s[22:23], 0, v[136:137]
	s_addc_u32 s19, s23, 0
	s_add_i32 s50, s51, s27
	global_load_lds_dwordx4 v[176:177], off
	v_lshl_add_u64 v[218:219], s[18:19], 0, v[132:133]
	s_mov_b32 m0, s50
	v_lshl_add_u64 v[220:221], s[24:25], 0, v[134:135]
	global_load_lds_dwordx4 v[218:219], off
	s_add_i32 m0, s50, 0x2000
	s_nop 0
	global_load_lds_dwordx4 v136, s[18:19]
	v_lshl_add_u64 v[218:219], s[24:25], 0, v[130:131]
	s_mov_b32 m0, s33
	s_nop 0
	global_load_lds_dwordx4 v[218:219], off
	s_mov_b32 m0, s36
	s_nop 0
	global_load_lds_dwordx4 v[220:221], off
	s_waitcnt vmcnt(8) lgkmcnt(0)
	s_barrier
; #define PG8_STAGE(bufoff, gbase, voff) do { _Pragma("unroll") for (int _i = 0; _i < 2; ++_i) \
;         __builtin_amdgcn_global_load_lds((const unsigned*)((const char*)(gbase) + (voff)[_i]), (PG8_LAS unsigned*)(lds + (bufoff) + ldsw + _i * 8192), 16, 0, 0); } while (0)
; #define PG8_LDA(dst, b, h) do { _Pragma("unroll") for (int m = 0; m < 4; ++m) _Pragma("unroll") for (int k = 0; k < 2; ++k) dst[m][k] = *(const PG8_LAS bf16x8*)(lds + PG8_SA(b, h) + aoff + m * 2048 + k * 1024); } while (0)
; #define PG8_LDB(dst, b, h) do { _Pragma("unroll") for (int n = 0; n < 2; ++n) _Pragma("unroll") for (int k = 0; k < 2; ++k) dst[n][k] = *(const PG8_LAS bf16x8*)(lds + PG8_SB(b, h) + boff + n * 2048 + k * 1024); } while (0)
; #define PG8_MMA(ai, bj, At, Bt) do { __builtin_amdgcn_s_setprio(1); _Pragma("unroll") for (int m = 0; m < 4; ++m) _Pragma("unroll") for (int n = 0; n < 2; ++n) _Pragma("unroll") for (int k = 0; k < 2; ++k) \
;         acc[ai][bj][m][n] = __builtin_amdgcn_mfma_f32_16x16x32_bf16(Bt[n][k], At[m][k], acc[ai][bj][m][n], 0, 0, 0); __builtin_amdgcn_s_setprio(0); } while (0)
; #define PG8_WAIT_V(n) asm volatile("s_waitcnt vmcnt(" #n ")" ::: "memory")
; template <class Epi, class Sched, bool ALIGN_EPI = false, bool SP2 = false>
; __device__ __forceinline__ void gemm_phase(PG8_LAS unsigned char* lds, const Gemm g, const Sched& S, const Epi& E) {
;     ...
;             PG8_LDB(B0, 0, 0); PG8_LDB(B1, 0, 1); PG8_SCHED; PG8_LDA(At, 0, 0); PG8_STAGE(PG8_SA(1, 1), a1 + hstep, voffA);
;             PG8_WAIT_V(8); PG8_WAIT_L(0); PG8_BAR; PG8_MMA(0, 0, At, B0); PG8_MMA(0, 1, At, B1); PG8_BAR; PG8_SCHED;
;             PG8_LDA(At, 0, 1); PG8_STAGE(PG8_SB(0, 0), b2, voffB); PG8_STAGE(PG8_SB(0, 1), b2 + hstep, voffB); PG8_STAGE(PG8_SA(0, 0), a2, voffA);
;             PG8_WAIT_V(8); PG8_WAIT_L(0); PG8_BAR; PG8_MMA(1, 0, At, B0); PG8_MMA(1, 1, At, B1); PG8_BAR; PG8_SCHED;
;             PG8_LDB(B0, 1, 0); PG8_LDB(B1, 1, 1); PG8_SCHED; PG8_LDA(At, 1, 0); PG8_STAGE(PG8_SA(0, 1), a2 + hstep, voffA);
;             PG8_WAIT_V(8); PG8_WAIT_L(0); PG8_BAR; PG8_MMA(0, 0, At, B0); PG8_MMA(0, 1, At, B1); PG8_BAR; PG8_SCHED;
;             PG8_LDA(At, 1, 1); PG8_STAGE(PG8_SB(1, 0), b3, voffB); PG8_STAGE(PG8_SB(1, 1), b3 + hstep, voffB); PG8_STAGE(PG8_SA(1, 0), a3, voffA);
;             PG8_WAIT_V(8); PG8_WAIT_L(0); PG8_BAR; PG8_MMA(1, 0, At, B0); PG8_MMA(1, 1, At, B1); PG8_BAR; PG8_SCHED;
	s_setprio 1
	v_mfma_f32_16x16x32_bf16 v[62:65], v[142:145], v[186:189], 0
	v_mfma_f32_16x16x32_bf16 v[58:61], v[156:159], v[186:189], 0
	v_mfma_f32_16x16x32_bf16 v[50:53], v[142:145], v[194:197], 0
	v_mfma_f32_16x16x32_bf16 v[42:45], v[156:159], v[194:197], 0
	v_mfma_f32_16x16x32_bf16 v[34:37], v[142:145], v[202:205], 0
	v_mfma_f32_16x16x32_bf16 v[26:29], v[156:159], v[202:205], 0
	v_mfma_f32_16x16x32_bf16 v[18:21], v[142:145], v[210:213], 0
	v_mfma_f32_16x16x32_bf16 v[10:13], v[156:159], v[210:213], 0
	v_mfma_f32_16x16x32_bf16 v[62:65], v[152:155], v[190:193], v[62:65]
	v_mfma_f32_16x16x32_bf16 v[58:61], v[160:163], v[190:193], v[58:61]
	v_mfma_f32_16x16x32_bf16 v[50:53], v[152:155], v[198:201], v[50:53]
	v_mfma_f32_16x16x32_bf16 v[42:45], v[160:163], v[198:201], v[42:45]
	v_mfma_f32_16x16x32_bf16 v[34:37], v[152:155], v[206:209], v[34:37]
	v_mfma_f32_16x16x32_bf16 v[26:29], v[160:163], v[206:209], v[26:29]
	v_mfma_f32_16x16x32_bf16 v[18:21], v[152:155], v[214:217], v[18:21]
	v_mfma_f32_16x16x32_bf16 v[10:13], v[160:163], v[214:217], v[10:13]
	v_mfma_f32_16x16x32_bf16 v[54:57], v[164:167], v[186:189], 0
	v_mfma_f32_16x16x32_bf16 v[46:49], v[172:175], v[186:189], 0
	v_mfma_f32_16x16x32_bf16 v[38:41], v[164:167], v[194:197], 0
	v_mfma_f32_16x16x32_bf16 v[30:33], v[172:175], v[194:197], 0
	v_mfma_f32_16x16x32_bf16 v[22:25], v[164:167], v[202:205], 0
	v_mfma_f32_16x16x32_bf16 v[14:17], v[172:175], v[202:205], 0
	v_mfma_f32_16x16x32_bf16 v[6:9], v[164:167], v[210:213], 0
	v_mfma_f32_16x16x32_bf16 v[2:5], v[172:175], v[210:213], 0
	v_mfma_f32_16x16x32_bf16 v[54:57], v[168:171], v[190:193], v[54:57]
	v_mfma_f32_16x16x32_bf16 v[46:49], v[180:183], v[190:193], v[46:49]
	v_mfma_f32_16x16x32_bf16 v[38:41], v[168:171], v[198:201], v[38:41]
	v_mfma_f32_16x16x32_bf16 v[30:33], v[180:183], v[198:201], v[30:33]
	v_mfma_f32_16x16x32_bf16 v[22:25], v[168:171], v[206:209], v[22:25]
	v_mfma_f32_16x16x32_bf16 v[14:17], v[180:183], v[206:209], v[14:17]
	v_mfma_f32_16x16x32_bf16 v[6:9], v[168:171], v[214:217], v[6:9]
	v_mfma_f32_16x16x32_bf16 v[2:5], v[180:183], v[214:217], v[2:5]
	s_setprio 0
	s_barrier
	s_add_i32 s50, 0, 0x18000
	v_add_u32_e32 v151, s50, v148
	s_add_i32 s51, 0, 0x1c000
	ds_read_b128 v[142:145], v151
	ds_read_b128 v[152:155], v151 offset:1024
	ds_read_b128 v[156:159], v151 offset:2048
	ds_read_b128 v[160:163], v151 offset:3072
	v_add_u32_e32 v151, s51, v148
	ds_read_b128 v[164:167], v151
	ds_read_b128 v[168:171], v151 offset:1024
	ds_read_b128 v[172:175], v151 offset:2048
	ds_read_b128 v[180:183], v151 offset:3072
	s_add_u32 s18, s24, 0xb0000
	s_addc_u32 s19, s25, 0
	s_mov_b32 m0, s37
	ds_read_b128 v[186:189], v150 offset:32768
	ds_read_b128 v[190:193], v150 offset:33792
	ds_read_b128 v[194:197], v150 offset:34816
	ds_read_b128 v[198:201], v150 offset:35840
	ds_read_b128 v[202:205], v150 offset:36864
	ds_read_b128 v[206:209], v150 offset:37888
	ds_read_b128 v[210:213], v150 offset:38912
	ds_read_b128 v[214:217], v150 offset:39936
	global_load_lds_dwordx4 v130, s[18:19]
	v_lshl_add_u64 v[222:223], s[18:19], 0, v[134:135]
	s_mov_b32 m0, s38
	s_nop 0
	global_load_lds_dwordx4 v[222:223], off
	s_waitcnt vmcnt(8) lgkmcnt(0)
	s_barrier
	s_setprio 1
	v_mfma_f32_16x16x32_bf16 v[126:129], v[142:145], v[186:189], v[126:129]
	v_mfma_f32_16x16x32_bf16 v[122:125], v[156:159], v[186:189], v[122:125]
	v_mfma_f32_16x16x32_bf16 v[114:117], v[142:145], v[194:197], v[114:117]
	v_mfma_f32_16x16x32_bf16 v[106:109], v[156:159], v[194:197], v[106:109]
	v_mfma_f32_16x16x32_bf16 v[98:101], v[142:145], v[202:205], v[98:101]
	v_mfma_f32_16x16x32_bf16 v[90:93], v[156:159], v[202:205], v[90:93]
	v_mfma_f32_16x16x32_bf16 v[82:85], v[142:145], v[210:213], v[82:85]
	v_mfma_f32_16x16x32_bf16 v[74:77], v[156:159], v[210:213], v[74:77]
	v_mfma_f32_16x16x32_bf16 v[126:129], v[152:155], v[190:193], v[126:129]
	v_mfma_f32_16x16x32_bf16 v[122:125], v[160:163], v[190:193], v[122:125]
	v_mfma_f32_16x16x32_bf16 v[114:117], v[152:155], v[198:201], v[114:117]
	v_mfma_f32_16x16x32_bf16 v[106:109], v[160:163], v[198:201], v[106:109]
	v_mfma_f32_16x16x32_bf16 v[98:101], v[152:155], v[206:209], v[98:101]
	v_mfma_f32_16x16x32_bf16 v[90:93], v[160:163], v[206:209], v[90:93]
	v_mfma_f32_16x16x32_bf16 v[82:85], v[152:155], v[214:217], v[82:85]
	v_mfma_f32_16x16x32_bf16 v[74:77], v[160:163], v[214:217], v[74:77]
	v_mfma_f32_16x16x32_bf16 v[118:121], v[164:167], v[186:189], v[118:121]
	v_mfma_f32_16x16x32_bf16 v[110:113], v[172:175], v[186:189], v[110:113]
	v_mfma_f32_16x16x32_bf16 v[102:105], v[164:167], v[194:197], v[102:105]
	v_mfma_f32_16x16x32_bf16 v[94:97], v[172:175], v[194:197], v[94:97]
	v_mfma_f32_16x16x32_bf16 v[86:89], v[164:167], v[202:205], v[86:89]
	v_mfma_f32_16x16x32_bf16 v[78:81], v[172:175], v[202:205], v[78:81]
	v_mfma_f32_16x16x32_bf16 v[70:73], v[164:167], v[210:213], v[70:73]
	v_mfma_f32_16x16x32_bf16 v[66:69], v[172:175], v[210:213], v[66:69]
	v_mfma_f32_16x16x32_bf16 v[118:121], v[168:171], v[190:193], v[118:121]
	v_mfma_f32_16x16x32_bf16 v[110:113], v[180:183], v[190:193], v[110:113]
	v_mfma_f32_16x16x32_bf16 v[102:105], v[168:171], v[198:201], v[102:105]
	v_mfma_f32_16x16x32_bf16 v[94:97], v[180:183], v[198:201], v[94:97]
	v_mfma_f32_16x16x32_bf16 v[86:89], v[168:171], v[206:209], v[86:89]
	v_mfma_f32_16x16x32_bf16 v[78:81], v[180:183], v[206:209], v[78:81]
	v_mfma_f32_16x16x32_bf16 v[70:73], v[168:171], v[214:217], v[70:73]
	v_mfma_f32_16x16x32_bf16 v[66:69], v[180:183], v[214:217], v[66:69]
	s_setprio 0
	s_barrier
; #define PG8_STAGE(bufoff, gbase, voff) do { _Pragma("unroll") for (int _i = 0; _i < 2; ++_i) \
;         __builtin_amdgcn_global_load_lds((const unsigned*)((const char*)(gbase) + (voff)[_i]), (PG8_LAS unsigned*)(lds + (bufoff) + ldsw + _i * 8192), 16, 0, 0); } while (0)
; #define PG8_LDA(dst, b, h) do { _Pragma("unroll") for (int m = 0; m < 4; ++m) _Pragma("unroll") for (int k = 0; k < 2; ++k) dst[m][k] = *(const PG8_LAS bf16x8*)(lds + PG8_SA(b, h) + aoff + m * 2048 + k * 1024); } while (0)
; #define PG8_LDB(dst, b, h) do { _Pragma("unroll") for (int n = 0; n < 2; ++n) _Pragma("unroll") for (int k = 0; k < 2; ++k) dst[n][k] = *(const PG8_LAS bf16x8*)(lds + PG8_SB(b, h) + boff + n * 2048 + k * 1024); } while (0)
; #define PG8_MMA(ai, bj, At, Bt) do { __builtin_amdgcn_s_setprio(1); _Pragma("unroll") for (int m = 0; m < 4; ++m) _Pragma("unroll") for (int n = 0; n < 2; ++n) _Pragma("unroll") for (int k = 0; k < 2; ++k) \
;         acc[ai][bj][m][n] = __builtin_amdgcn_mfma_f32_16x16x32_bf16(Bt[n][k], At[m][k], acc[ai][bj][m][n], 0, 0, 0); __builtin_amdgcn_s_setprio(0); } while (0)
; #define PG8_WAIT_V(n) asm volatile("s_waitcnt vmcnt(" #n ")" ::: "memory")
; template <class Epi, class Sched, bool ALIGN_EPI = false, bool SP2 = false>
; __device__ __forceinline__ void gemm_phase(PG8_LAS unsigned char* lds, const Gemm g, const Sched& S, const Epi& E) {
;     ...
;             PG8_LDB(B0, 0, 0); PG8_LDB(B1, 0, 1); PG8_SCHED; PG8_LDA(At, 0, 0); PG8_STAGE(PG8_SA(1, 1), a1 + hstep, voffA);
;             PG8_WAIT_V(8); PG8_WAIT_L(0); PG8_BAR; PG8_MMA(0, 0, At, B0); PG8_MMA(0, 1, At, B1); PG8_BAR; PG8_SCHED;
;             PG8_LDA(At, 0, 1); PG8_STAGE(PG8_SB(0, 0), b2, voffB); PG8_STAGE(PG8_SB(0, 1), b2 + hstep, voffB); PG8_STAGE(PG8_SA(0, 0), a2, voffA);
;             PG8_WAIT_V(8); PG8_WAIT_L(0); PG8_BAR; PG8_MMA(1, 0, At, B0); PG8_MMA(1, 1, At, B1); PG8_BAR; PG8_SCHED;
;             PG8_LDB(B0, 1, 0); PG8_LDB(B1, 1, 1); PG8_SCHED; PG8_LDA(At, 1, 0); PG8_STAGE(PG8_SA(0, 1), a2 + hstep, voffA);
;             PG8_WAIT_V(8); PG8_WAIT_L(0); PG8_BAR; PG8_MMA(0, 0, At, B0); PG8_MMA(0, 1, At, B1); PG8_BAR; PG8_SCHED;
;             PG8_LDA(At, 1, 1); PG8_STAGE(PG8_SB(1, 0), b3, voffB); PG8_STAGE(PG8_SB(1, 1), b3 + hstep, voffB); PG8_STAGE(PG8_SA(1, 0), a3, voffA);
;             PG8_WAIT_V(8); PG8_WAIT_L(0); PG8_BAR; PG8_MMA(1, 0, At, B0); PG8_MMA(1, 1, At, B1); PG8_BAR; PG8_SCHED;
	s_add_i32 s18, s50, s27
	v_lshl_add_u64 v[146:147], v[146:147], 0, s[80:81]
	s_mov_b32 m0, s18
	ds_read_b128 v[186:189], v150 offset:49152
	ds_read_b128 v[190:193], v150 offset:50176
	ds_read_b128 v[194:197], v150 offset:51200
	ds_read_b128 v[198:201], v150 offset:52224
	ds_read_b128 v[202:205], v150 offset:53248
	ds_read_b128 v[206:209], v150 offset:54272
	ds_read_b128 v[210:213], v150 offset:55296
	ds_read_b128 v[214:217], v150 offset:56320
	global_load_lds_dwordx4 v[146:147], off
	s_add_i32 m0, s18, 0x2000
	s_add_u32 s18, s22, 0xb0080
	v_lshl_add_u64 v[146:147], v[176:177], 0, s[80:81]
	s_addc_u32 s19, s23, 0
	s_add_i32 s22, s51, s27
	global_load_lds_dwordx4 v[146:147], off
	s_mov_b32 m0, s22
	s_nop 0
	global_load_lds_dwordx4 v132, s[18:19]
	s_add_i32 m0, s22, 0x2000
	s_nop 0
	global_load_lds_dwordx4 v136, s[18:19]
	v_lshl_add_u64 v[146:147], v[218:219], 0, s[80:81]
	s_mov_b32 m0, s39
	s_nop 0
	global_load_lds_dwordx4 v[146:147], off
	v_lshl_add_u64 v[146:147], v[220:221], 0, s[80:81]
	s_mov_b32 m0, s40
	s_nop 0
	global_load_lds_dwordx4 v[146:147], off
	s_waitcnt vmcnt(8) lgkmcnt(0)
	s_barrier
	s_setprio 1
	v_mfma_f32_16x16x32_bf16 v[62:65], v[142:145], v[186:189], v[62:65]
	v_mfma_f32_16x16x32_bf16 v[58:61], v[156:159], v[186:189], v[58:61]
	v_mfma_f32_16x16x32_bf16 v[50:53], v[142:145], v[194:197], v[50:53]
	v_mfma_f32_16x16x32_bf16 v[42:45], v[156:159], v[194:197], v[42:45]
	v_mfma_f32_16x16x32_bf16 v[34:37], v[142:145], v[202:205], v[34:37]
	v_mfma_f32_16x16x32_bf16 v[26:29], v[156:159], v[202:205], v[26:29]
	v_mfma_f32_16x16x32_bf16 v[18:21], v[142:145], v[210:213], v[18:21]
	v_mfma_f32_16x16x32_bf16 v[10:13], v[156:159], v[210:213], v[10:13]
	v_mfma_f32_16x16x32_bf16 v[62:65], v[152:155], v[190:193], v[62:65]
	v_mfma_f32_16x16x32_bf16 v[58:61], v[160:163], v[190:193], v[58:61]
	v_mfma_f32_16x16x32_bf16 v[50:53], v[152:155], v[198:201], v[50:53]
	v_mfma_f32_16x16x32_bf16 v[42:45], v[160:163], v[198:201], v[42:45]
	v_mfma_f32_16x16x32_bf16 v[34:37], v[152:155], v[206:209], v[34:37]
	v_mfma_f32_16x16x32_bf16 v[26:29], v[160:163], v[206:209], v[26:29]
	v_mfma_f32_16x16x32_bf16 v[18:21], v[152:155], v[214:217], v[18:21]
	v_mfma_f32_16x16x32_bf16 v[10:13], v[160:163], v[214:217], v[10:13]
	v_mfma_f32_16x16x32_bf16 v[54:57], v[164:167], v[186:189], v[54:57]
	v_mfma_f32_16x16x32_bf16 v[46:49], v[172:175], v[186:189], v[46:49]
	v_mfma_f32_16x16x32_bf16 v[38:41], v[164:167], v[194:197], v[38:41]
	v_mfma_f32_16x16x32_bf16 v[30:33], v[172:175], v[194:197], v[30:33]
	v_mfma_f32_16x16x32_bf16 v[22:25], v[164:167], v[202:205], v[22:25]
	v_mfma_f32_16x16x32_bf16 v[14:17], v[172:175], v[202:205], v[14:17]
	v_mfma_f32_16x16x32_bf16 v[6:9], v[164:167], v[210:213], v[6:9]
	v_mfma_f32_16x16x32_bf16 v[2:5], v[172:175], v[210:213], v[2:5]
	v_mfma_f32_16x16x32_bf16 v[54:57], v[168:171], v[190:193], v[54:57]
	v_mfma_f32_16x16x32_bf16 v[46:49], v[180:183], v[190:193], v[46:49]
	v_mfma_f32_16x16x32_bf16 v[38:41], v[168:171], v[198:201], v[38:41]
	v_mfma_f32_16x16x32_bf16 v[30:33], v[180:183], v[198:201], v[30:33]
	v_mfma_f32_16x16x32_bf16 v[22:25], v[168:171], v[206:209], v[22:25]
	v_mfma_f32_16x16x32_bf16 v[14:17], v[180:183], v[206:209], v[14:17]
	v_mfma_f32_16x16x32_bf16 v[6:9], v[168:171], v[214:217], v[6:9]
	v_mfma_f32_16x16x32_bf16 v[2:5], v[180:183], v[214:217], v[2:5]
	s_setprio 0
	s_barrier
	s_add_i32 s49, s49, 2
	s_add_u32 s47, s47, 0x100
	s_addc_u32 s48, s48, 0
	s_cmp_gt_u32 s49, 41
	s_mov_b64 s[18:19], s[20:21]
	s_branch .LBB0_1360
.LBB0_1360:
	s_add_u32 s20, s18, 0x100
	s_addc_u32 s21, s19, 0
	s_add_i32 s50, 0, 0x10000
	s_cmp_eq_u32 s49, 40
	s_cselect_b32 s25, s7, s21
	s_cselect_b32 s24, s6, s20
	v_add_u32_e32 v146, s50, v148
	s_cselect_b32 s23, s17, s48
	s_cselect_b32 s22, s16, s47
	s_add_i32 s51, 0, 0x14000
	ds_read_b128 v[142:145], v146
	ds_read_b128 v[152:155], v146 offset:1024
	ds_read_b128 v[156:159], v146 offset:2048
	ds_read_b128 v[160:163], v146 offset:3072
	v_add_u32_e32 v146, s51, v148
	ds_read_b128 v[164:167], v146
	ds_read_b128 v[168:171], v146 offset:1024
	ds_read_b128 v[172:175], v146 offset:2048
	ds_read_b128 v[180:183], v146 offset:3072
	v_lshl_add_u64 v[146:147], s[18:19], 0, v[138:139]
	s_add_i32 m0, s33, 0xc000
	ds_read_b128 v[186:189], v150
	ds_read_b128 v[190:193], v150 offset:1024
	ds_read_b128 v[194:197], v150 offset:2048
	ds_read_b128 v[198:201], v150 offset:3072
	ds_read_b128 v[202:205], v150 offset:4096
	ds_read_b128 v[206:209], v150 offset:5120
	ds_read_b128 v[210:213], v150 offset:6144
	ds_read_b128 v[214:217], v150 offset:7168
	global_load_lds_dwordx4 v[146:147], off
	v_lshl_add_u64 v[146:147], s[18:19], 0, v[140:141]
	s_add_i32 m0, s33, 0xe000
	s_nop 0
	global_load_lds_dwordx4 v[146:147], off
	s_waitcnt vmcnt(8) lgkmcnt(0)
	s_barrier
; #define PG8_STAGE(bufoff, gbase, voff) do { _Pragma("unroll") for (int _i = 0; _i < 2; ++_i) \
;         __builtin_amdgcn_global_load_lds((const unsigned*)((const char*)(gbase) + (voff)[_i]), (PG8_LAS unsigned*)(lds + (bufoff) + ldsw + _i * 8192), 16, 0, 0); } while (0)
; #define PG8_LDA(dst, b, h) do { _Pragma("unroll") for (int m = 0; m < 4; ++m) _Pragma("unroll") for (int k = 0; k < 2; ++k) dst[m][k] = *(const PG8_LAS bf16x8*)(lds + PG8_SA(b, h) + aoff + m * 2048 + k * 1024); } while (0)
; #define PG8_LDB(dst, b, h) do { _Pragma("unroll") for (int n = 0; n < 2; ++n) _Pragma("unroll") for (int k = 0; k < 2; ++k) dst[n][k] = *(const PG8_LAS bf16x8*)(lds + PG8_SB(b, h) + boff + n * 2048 + k * 1024); } while (0)
; #define PG8_MMA(ai, bj, At, Bt) do { __builtin_amdgcn_s_setprio(1); _Pragma("unroll") for (int m = 0; m < 4; ++m) _Pragma("unroll") for (int n = 0; n < 2; ++n) _Pragma("unroll") for (int k = 0; k < 2; ++k) \
;         acc[ai][bj][m][n] = __builtin_amdgcn_mfma_f32_16x16x32_bf16(Bt[n][k], At[m][k], acc[ai][bj][m][n], 0, 0, 0); __builtin_amdgcn_s_setprio(0); } while (0)
; #define PG8_WAIT_V(n) asm volatile("s_waitcnt vmcnt(" #n ")" ::: "memory")
; template <class Epi, class Sched, bool ALIGN_EPI = false, bool SP2 = false>
; __device__ __forceinline__ void gemm_phase(PG8_LAS unsigned char* lds, const Gemm g, const Sched& S, const Epi& E) {
;     ...
;             PG8_LDB(B0, 0, 0); PG8_LDB(B1, 0, 1); PG8_SCHED; PG8_LDA(At, 0, 0); PG8_STAGE(PG8_SA(1, 1), a1 + hstep, voffA);
;             PG8_WAIT_V(8); PG8_WAIT_L(0); PG8_BAR; PG8_MMA(0, 0, At, B0); PG8_MMA(0, 1, At, B1); PG8_BAR; PG8_SCHED;
;             PG8_LDA(At, 0, 1); PG8_STAGE(PG8_SB(0, 0), b2, voffB); PG8_STAGE(PG8_SB(0, 1), b2 + hstep, voffB); PG8_STAGE(PG8_SA(0, 0), a2, voffA);
;             PG8_WAIT_V(8); PG8_WAIT_L(0); PG8_BAR; PG8_MMA(1, 0, At, B0); PG8_MMA(1, 1, At, B1); PG8_BAR; PG8_SCHED;
;             PG8_LDB(B0, 1, 0); PG8_LDB(B1, 1, 1); PG8_SCHED; PG8_LDA(At, 1, 0); PG8_STAGE(PG8_SA(0, 1), a2 + hstep, voffA);
;             PG8_WAIT_V(8); PG8_WAIT_L(0); PG8_BAR; PG8_MMA(0, 0, At, B0); PG8_MMA(0, 1, At, B1); PG8_BAR; PG8_SCHED;
;             PG8_LDA(At, 1, 1); PG8_STAGE(PG8_SB(1, 0), b3, voffB); PG8_STAGE(PG8_SB(1, 1), b3 + hstep, voffB); PG8_STAGE(PG8_SA(1, 0), a3, voffA);
;             PG8_WAIT_V(8); PG8_WAIT_L(0); PG8_BAR; PG8_MMA(1, 0, At, B0); PG8_MMA(1, 1, At, B1); PG8_BAR; PG8_SCHED;
	s_setprio 1
	v_mfma_f32_16x16x32_bf16 v[126:129], v[142:145], v[186:189], v[126:129]
	v_mfma_f32_16x16x32_bf16 v[122:125], v[156:159], v[186:189], v[122:125]
	v_mfma_f32_16x16x32_bf16 v[114:117], v[142:145], v[194:197], v[114:117]
	v_mfma_f32_16x16x32_bf16 v[106:109], v[156:159], v[194:197], v[106:109]
	v_mfma_f32_16x16x32_bf16 v[98:101], v[142:145], v[202:205], v[98:101]
	v_mfma_f32_16x16x32_bf16 v[90:93], v[156:159], v[202:205], v[90:93]
	v_mfma_f32_16x16x32_bf16 v[82:85], v[142:145], v[210:213], v[82:85]
	v_mfma_f32_16x16x32_bf16 v[74:77], v[156:159], v[210:213], v[74:77]
	v_mfma_f32_16x16x32_bf16 v[126:129], v[152:155], v[190:193], v[126:129]
	v_mfma_f32_16x16x32_bf16 v[122:125], v[160:163], v[190:193], v[122:125]
	v_mfma_f32_16x16x32_bf16 v[114:117], v[152:155], v[198:201], v[114:117]
	v_mfma_f32_16x16x32_bf16 v[106:109], v[160:163], v[198:201], v[106:109]
	v_mfma_f32_16x16x32_bf16 v[98:101], v[152:155], v[206:209], v[98:101]
	v_mfma_f32_16x16x32_bf16 v[90:93], v[160:163], v[206:209], v[90:93]
	v_mfma_f32_16x16x32_bf16 v[82:85], v[152:155], v[214:217], v[82:85]
	v_mfma_f32_16x16x32_bf16 v[74:77], v[160:163], v[214:217], v[74:77]
	v_mfma_f32_16x16x32_bf16 v[118:121], v[164:167], v[186:189], v[118:121]
	v_mfma_f32_16x16x32_bf16 v[110:113], v[172:175], v[186:189], v[110:113]
	v_mfma_f32_16x16x32_bf16 v[102:105], v[164:167], v[194:197], v[102:105]
	v_mfma_f32_16x16x32_bf16 v[94:97], v[172:175], v[194:197], v[94:97]
	v_mfma_f32_16x16x32_bf16 v[86:89], v[164:167], v[202:205], v[86:89]
	v_mfma_f32_16x16x32_bf16 v[78:81], v[172:175], v[202:205], v[78:81]
	v_mfma_f32_16x16x32_bf16 v[70:73], v[164:167], v[210:213], v[70:73]
	v_mfma_f32_16x16x32_bf16 v[66:69], v[172:175], v[210:213], v[66:69]
	v_mfma_f32_16x16x32_bf16 v[118:121], v[168:171], v[190:193], v[118:121]
	v_mfma_f32_16x16x32_bf16 v[110:113], v[180:183], v[190:193], v[110:113]
	v_mfma_f32_16x16x32_bf16 v[102:105], v[168:171], v[198:201], v[102:105]
	v_mfma_f32_16x16x32_bf16 v[94:97], v[180:183], v[198:201], v[94:97]
	v_mfma_f32_16x16x32_bf16 v[86:89], v[168:171], v[206:209], v[86:89]
	v_mfma_f32_16x16x32_bf16 v[78:81], v[180:183], v[206:209], v[78:81]
	v_mfma_f32_16x16x32_bf16 v[70:73], v[168:171], v[214:217], v[70:73]
	v_mfma_f32_16x16x32_bf16 v[66:69], v[180:183], v[214:217], v[66:69]
	s_setprio 0
	s_barrier
	s_add_i32 s18, s50, s27
	v_lshl_add_u64 v[146:147], s[22:23], 0, v[132:133]
	s_mov_b32 m0, s18
	ds_read_b128 v[186:189], v150 offset:16384
	ds_read_b128 v[190:193], v150 offset:17408
	ds_read_b128 v[194:197], v150 offset:18432
	ds_read_b128 v[198:201], v150 offset:19456
	ds_read_b128 v[202:205], v150 offset:20480
	ds_read_b128 v[206:209], v150 offset:21504
	ds_read_b128 v[210:213], v150 offset:22528
	ds_read_b128 v[214:217], v150 offset:23552
	global_load_lds_dwordx4 v[146:147], off
	s_add_i32 m0, s18, 0x2000
	s_add_u32 s18, s22, 0xb0000
	v_lshl_add_u64 v[176:177], s[22:23], 0, v[136:137]
	s_addc_u32 s19, s23, 0
	s_add_i32 s50, s51, s27
	global_load_lds_dwordx4 v[176:177], off
	v_lshl_add_u64 v[218:219], s[18:19], 0, v[132:133]
	s_mov_b32 m0, s50
	v_lshl_add_u64 v[220:221], s[24:25], 0, v[134:135]
	global_load_lds_dwordx4 v[218:219], off
	s_add_i32 m0, s50, 0x2000
	s_nop 0
	global_load_lds_dwordx4 v136, s[18:19]
	v_lshl_add_u64 v[218:219], s[24:25], 0, v[130:131]
	s_mov_b32 m0, s33
	s_nop 0
	global_load_lds_dwordx4 v[218:219], off
	s_mov_b32 m0, s36
	s_nop 0
	global_load_lds_dwordx4 v[220:221], off
	s_waitcnt vmcnt(8) lgkmcnt(0)
	s_barrier
	s_setprio 1
	v_mfma_f32_16x16x32_bf16 v[62:65], v[142:145], v[186:189], v[62:65]
	v_mfma_f32_16x16x32_bf16 v[58:61], v[156:159], v[186:189], v[58:61]
	v_mfma_f32_16x16x32_bf16 v[50:53], v[142:145], v[194:197], v[50:53]
	v_mfma_f32_16x16x32_bf16 v[42:45], v[156:159], v[194:197], v[42:45]
	v_mfma_f32_16x16x32_bf16 v[34:37], v[142:145], v[202:205], v[34:37]
	v_mfma_f32_16x16x32_bf16 v[26:29], v[156:159], v[202:205], v[26:29]
	v_mfma_f32_16x16x32_bf16 v[18:21], v[142:145], v[210:213], v[18:21]
	v_mfma_f32_16x16x32_bf16 v[10:13], v[156:159], v[210:213], v[10:13]
	v_mfma_f32_16x16x32_bf16 v[62:65], v[152:155], v[190:193], v[62:65]
	v_mfma_f32_16x16x32_bf16 v[58:61], v[160:163], v[190:193], v[58:61]
	v_mfma_f32_16x16x32_bf16 v[50:53], v[152:155], v[198:201], v[50:53]
	v_mfma_f32_16x16x32_bf16 v[42:45], v[160:163], v[198:201], v[42:45]
	v_mfma_f32_16x16x32_bf16 v[34:37], v[152:155], v[206:209], v[34:37]
	v_mfma_f32_16x16x32_bf16 v[26:29], v[160:163], v[206:209], v[26:29]
	v_mfma_f32_16x16x32_bf16 v[18:21], v[152:155], v[214:217], v[18:21]
	v_mfma_f32_16x16x32_bf16 v[10:13], v[160:163], v[214:217], v[10:13]
	v_mfma_f32_16x16x32_bf16 v[54:57], v[164:167], v[186:189], v[54:57]
	v_mfma_f32_16x16x32_bf16 v[46:49], v[172:175], v[186:189], v[46:49]
	v_mfma_f32_16x16x32_bf16 v[38:41], v[164:167], v[194:197], v[38:41]
	v_mfma_f32_16x16x32_bf16 v[30:33], v[172:175], v[194:197], v[30:33]
	v_mfma_f32_16x16x32_bf16 v[22:25], v[164:167], v[202:205], v[22:25]
	v_mfma_f32_16x16x32_bf16 v[14:17], v[172:175], v[202:205], v[14:17]
	v_mfma_f32_16x16x32_bf16 v[6:9], v[164:167], v[210:213], v[6:9]
	v_mfma_f32_16x16x32_bf16 v[2:5], v[172:175], v[210:213], v[2:5]
	v_mfma_f32_16x16x32_bf16 v[54:57], v[168:171], v[190:193], v[54:57]
	v_mfma_f32_16x16x32_bf16 v[46:49], v[180:183], v[190:193], v[46:49]
	v_mfma_f32_16x16x32_bf16 v[38:41], v[168:171], v[198:201], v[38:41]
	v_mfma_f32_16x16x32_bf16 v[30:33], v[180:183], v[198:201], v[30:33]
	v_mfma_f32_16x16x32_bf16 v[22:25], v[168:171], v[206:209], v[22:25]
	v_mfma_f32_16x16x32_bf16 v[14:17], v[180:183], v[206:209], v[14:17]
	v_mfma_f32_16x16x32_bf16 v[6:9], v[168:171], v[214:217], v[6:9]
	v_mfma_f32_16x16x32_bf16 v[2:5], v[180:183], v[214:217], v[2:5]
	s_setprio 0
	s_barrier
; #define PG8_STAGE(bufoff, gbase, voff) do { _Pragma("unroll") for (int _i = 0; _i < 2; ++_i) \
;         __builtin_amdgcn_global_load_lds((const unsigned*)((const char*)(gbase) + (voff)[_i]), (PG8_LAS unsigned*)(lds + (bufoff) + ldsw + _i * 8192), 16, 0, 0); } while (0)
; #define PG8_LDA(dst, b, h) do { _Pragma("unroll") for (int m = 0; m < 4; ++m) _Pragma("unroll") for (int k = 0; k < 2; ++k) dst[m][k] = *(const PG8_LAS bf16x8*)(lds + PG8_SA(b, h) + aoff + m * 2048 + k * 1024); } while (0)
; #define PG8_LDB(dst, b, h) do { _Pragma("unroll") for (int n = 0; n < 2; ++n) _Pragma("unroll") for (int k = 0; k < 2; ++k) dst[n][k] = *(const PG8_LAS bf16x8*)(lds + PG8_SB(b, h) + boff + n * 2048 + k * 1024); } while (0)
; #define PG8_MMA(ai, bj, At, Bt) do { __builtin_amdgcn_s_setprio(1); _Pragma("unroll") for (int m = 0; m < 4; ++m) _Pragma("unroll") for (int n = 0; n < 2; ++n) _Pragma("unroll") for (int k = 0; k < 2; ++k) \
;         acc[ai][bj][m][n] = __builtin_amdgcn_mfma_f32_16x16x32_bf16(Bt[n][k], At[m][k], acc[ai][bj][m][n], 0, 0, 0); __builtin_amdgcn_s_setprio(0); } while (0)
; #define PG8_WAIT_V(n) asm volatile("s_waitcnt vmcnt(" #n ")" ::: "memory")
; template <class Epi, class Sched, bool ALIGN_EPI = false, bool SP2 = false>
; __device__ __forceinline__ void gemm_phase(PG8_LAS unsigned char* lds, const Gemm g, const Sched& S, const Epi& E) {
;     ...
;             PG8_LDB(B0, 0, 0); PG8_LDB(B1, 0, 1); PG8_SCHED; PG8_LDA(At, 0, 0); PG8_STAGE(PG8_SA(1, 1), a1 + hstep, voffA);
;             PG8_WAIT_V(8); PG8_WAIT_L(0); PG8_BAR; PG8_MMA(0, 0, At, B0); PG8_MMA(0, 1, At, B1); PG8_BAR; PG8_SCHED;
;             PG8_LDA(At, 0, 1); PG8_STAGE(PG8_SB(0, 0), b2, voffB); PG8_STAGE(PG8_SB(0, 1), b2 + hstep, voffB); PG8_STAGE(PG8_SA(0, 0), a2, voffA);
;             PG8_WAIT_V(8); PG8_WAIT_L(0); PG8_BAR; PG8_MMA(1, 0, At, B0); PG8_MMA(1, 1, At, B1); PG8_BAR; PG8_SCHED;
;             PG8_LDB(B0, 1, 0); PG8_LDB(B1, 1, 1); PG8_SCHED; PG8_LDA(At, 1, 0); PG8_STAGE(PG8_SA(0, 1), a2 + hstep, voffA);
;             PG8_WAIT_V(8); PG8_WAIT_L(0); PG8_BAR; PG8_MMA(0, 0, At, B0); PG8_MMA(0, 1, At, B1); PG8_BAR; PG8_SCHED;
;             PG8_LDA(At, 1, 1); PG8_STAGE(PG8_SB(1, 0), b3, voffB); PG8_STAGE(PG8_SB(1, 1), b3 + hstep, voffB); PG8_STAGE(PG8_SA(1, 0), a3, voffA);
;             PG8_WAIT_V(8); PG8_WAIT_L(0); PG8_BAR; PG8_MMA(1, 0, At, B0); PG8_MMA(1, 1, At, B1); PG8_BAR; PG8_SCHED;
	s_add_i32 s50, 0, 0x18000
	v_add_u32_e32 v151, s50, v148
	s_add_i32 s51, 0, 0x1c000
	ds_read_b128 v[142:145], v151
	ds_read_b128 v[152:155], v151 offset:1024
	ds_read_b128 v[156:159], v151 offset:2048
	ds_read_b128 v[160:163], v151 offset:3072
	v_add_u32_e32 v151, s51, v148
	ds_read_b128 v[164:167], v151
	ds_read_b128 v[168:171], v151 offset:1024
	ds_read_b128 v[172:175], v151 offset:2048
	ds_read_b128 v[180:183], v151 offset:3072
	s_add_u32 s18, s24, 0xb0000
	s_addc_u32 s19, s25, 0
	s_mov_b32 m0, s37
	ds_read_b128 v[186:189], v150 offset:32768
	ds_read_b128 v[190:193], v150 offset:33792
	ds_read_b128 v[194:197], v150 offset:34816
	ds_read_b128 v[198:201], v150 offset:35840
	ds_read_b128 v[202:205], v150 offset:36864
	ds_read_b128 v[206:209], v150 offset:37888
	ds_read_b128 v[210:213], v150 offset:38912
	ds_read_b128 v[214:217], v150 offset:39936
	global_load_lds_dwordx4 v130, s[18:19]
	v_lshl_add_u64 v[222:223], s[18:19], 0, v[134:135]
	s_mov_b32 m0, s38
	s_nop 0
	global_load_lds_dwordx4 v[222:223], off
	s_waitcnt vmcnt(8) lgkmcnt(0)
	s_barrier
	s_setprio 1
	v_mfma_f32_16x16x32_bf16 v[126:129], v[142:145], v[186:189], v[126:129]
	v_mfma_f32_16x16x32_bf16 v[122:125], v[156:159], v[186:189], v[122:125]
	v_mfma_f32_16x16x32_bf16 v[114:117], v[142:145], v[194:197], v[114:117]
	v_mfma_f32_16x16x32_bf16 v[106:109], v[156:159], v[194:197], v[106:109]
	v_mfma_f32_16x16x32_bf16 v[98:101], v[142:145], v[202:205], v[98:101]
	v_mfma_f32_16x16x32_bf16 v[90:93], v[156:159], v[202:205], v[90:93]
	v_mfma_f32_16x16x32_bf16 v[82:85], v[142:145], v[210:213], v[82:85]
	v_mfma_f32_16x16x32_bf16 v[74:77], v[156:159], v[210:213], v[74:77]
	v_mfma_f32_16x16x32_bf16 v[126:129], v[152:155], v[190:193], v[126:129]
	v_mfma_f32_16x16x32_bf16 v[122:125], v[160:163], v[190:193], v[122:125]
	v_mfma_f32_16x16x32_bf16 v[114:117], v[152:155], v[198:201], v[114:117]
	v_mfma_f32_16x16x32_bf16 v[106:109], v[160:163], v[198:201], v[106:109]
	v_mfma_f32_16x16x32_bf16 v[98:101], v[152:155], v[206:209], v[98:101]
	v_mfma_f32_16x16x32_bf16 v[90:93], v[160:163], v[206:209], v[90:93]
	v_mfma_f32_16x16x32_bf16 v[82:85], v[152:155], v[214:217], v[82:85]
	v_mfma_f32_16x16x32_bf16 v[74:77], v[160:163], v[214:217], v[74:77]
	v_mfma_f32_16x16x32_bf16 v[118:121], v[164:167], v[186:189], v[118:121]
	v_mfma_f32_16x16x32_bf16 v[110:113], v[172:175], v[186:189], v[110:113]
	v_mfma_f32_16x16x32_bf16 v[102:105], v[164:167], v[194:197], v[102:105]
	v_mfma_f32_16x16x32_bf16 v[94:97], v[172:175], v[194:197], v[94:97]
	v_mfma_f32_16x16x32_bf16 v[86:89], v[164:167], v[202:205], v[86:89]
	v_mfma_f32_16x16x32_bf16 v[78:81], v[172:175], v[202:205], v[78:81]
	v_mfma_f32_16x16x32_bf16 v[70:73], v[164:167], v[210:213], v[70:73]
	v_mfma_f32_16x16x32_bf16 v[66:69], v[172:175], v[210:213], v[66:69]
	v_mfma_f32_16x16x32_bf16 v[118:121], v[168:171], v[190:193], v[118:121]
	v_mfma_f32_16x16x32_bf16 v[110:113], v[180:183], v[190:193], v[110:113]
	v_mfma_f32_16x16x32_bf16 v[102:105], v[168:171], v[198:201], v[102:105]
	v_mfma_f32_16x16x32_bf16 v[94:97], v[180:183], v[198:201], v[94:97]
	v_mfma_f32_16x16x32_bf16 v[86:89], v[168:171], v[206:209], v[86:89]
	v_mfma_f32_16x16x32_bf16 v[78:81], v[180:183], v[206:209], v[78:81]
	v_mfma_f32_16x16x32_bf16 v[70:73], v[168:171], v[214:217], v[70:73]
	v_mfma_f32_16x16x32_bf16 v[66:69], v[180:183], v[214:217], v[66:69]
	s_setprio 0
	s_barrier
	s_add_i32 s18, s50, s27
	v_lshl_add_u64 v[146:147], v[146:147], 0, s[80:81]
	s_mov_b32 m0, s18
	ds_read_b128 v[186:189], v150 offset:49152
	ds_read_b128 v[190:193], v150 offset:50176
	ds_read_b128 v[194:197], v150 offset:51200
	ds_read_b128 v[198:201], v150 offset:52224
	ds_read_b128 v[202:205], v150 offset:53248
	ds_read_b128 v[206:209], v150 offset:54272
	ds_read_b128 v[210:213], v150 offset:55296
	ds_read_b128 v[214:217], v150 offset:56320
	global_load_lds_dwordx4 v[146:147], off
	s_add_i32 m0, s18, 0x2000
	s_add_u32 s18, s22, 0xb0080
	v_lshl_add_u64 v[146:147], v[176:177], 0, s[80:81]
	s_addc_u32 s19, s23, 0
	s_add_i32 s22, s51, s27
	global_load_lds_dwordx4 v[146:147], off
	s_mov_b32 m0, s22
	s_nop 0
	global_load_lds_dwordx4 v132, s[18:19]
	s_add_i32 m0, s22, 0x2000
	s_nop 0
	global_load_lds_dwordx4 v136, s[18:19]
	v_lshl_add_u64 v[146:147], v[218:219], 0, s[80:81]
	s_mov_b32 m0, s39
	s_nop 0
	global_load_lds_dwordx4 v[146:147], off
	v_lshl_add_u64 v[146:147], v[220:221], 0, s[80:81]
	s_mov_b32 m0, s40
	s_nop 0
	global_load_lds_dwordx4 v[146:147], off
	s_waitcnt vmcnt(8) lgkmcnt(0)
	s_barrier
	s_setprio 1
	v_mfma_f32_16x16x32_bf16 v[62:65], v[142:145], v[186:189], v[62:65]
	v_mfma_f32_16x16x32_bf16 v[58:61], v[156:159], v[186:189], v[58:61]
	v_mfma_f32_16x16x32_bf16 v[50:53], v[142:145], v[194:197], v[50:53]
	v_mfma_f32_16x16x32_bf16 v[42:45], v[156:159], v[194:197], v[42:45]
	v_mfma_f32_16x16x32_bf16 v[34:37], v[142:145], v[202:205], v[34:37]
	v_mfma_f32_16x16x32_bf16 v[26:29], v[156:159], v[202:205], v[26:29]
	v_mfma_f32_16x16x32_bf16 v[18:21], v[142:145], v[210:213], v[18:21]
	v_mfma_f32_16x16x32_bf16 v[10:13], v[156:159], v[210:213], v[10:13]
	v_mfma_f32_16x16x32_bf16 v[62:65], v[152:155], v[190:193], v[62:65]
	v_mfma_f32_16x16x32_bf16 v[58:61], v[160:163], v[190:193], v[58:61]
	v_mfma_f32_16x16x32_bf16 v[50:53], v[152:155], v[198:201], v[50:53]
	v_mfma_f32_16x16x32_bf16 v[42:45], v[160:163], v[198:201], v[42:45]
	v_mfma_f32_16x16x32_bf16 v[34:37], v[152:155], v[206:209], v[34:37]
	v_mfma_f32_16x16x32_bf16 v[26:29], v[160:163], v[206:209], v[26:29]
	v_mfma_f32_16x16x32_bf16 v[18:21], v[152:155], v[214:217], v[18:21]
	v_mfma_f32_16x16x32_bf16 v[10:13], v[160:163], v[214:217], v[10:13]
	v_mfma_f32_16x16x32_bf16 v[54:57], v[164:167], v[186:189], v[54:57]
	v_mfma_f32_16x16x32_bf16 v[46:49], v[172:175], v[186:189], v[46:49]
	v_mfma_f32_16x16x32_bf16 v[38:41], v[164:167], v[194:197], v[38:41]
	v_mfma_f32_16x16x32_bf16 v[30:33], v[172:175], v[194:197], v[30:33]
	v_mfma_f32_16x16x32_bf16 v[22:25], v[164:167], v[202:205], v[22:25]
	v_mfma_f32_16x16x32_bf16 v[14:17], v[172:175], v[202:205], v[14:17]
	v_mfma_f32_16x16x32_bf16 v[6:9], v[164:167], v[210:213], v[6:9]
	v_mfma_f32_16x16x32_bf16 v[2:5], v[172:175], v[210:213], v[2:5]
	v_mfma_f32_16x16x32_bf16 v[54:57], v[168:171], v[190:193], v[54:57]
	v_mfma_f32_16x16x32_bf16 v[46:49], v[180:183], v[190:193], v[46:49]
	v_mfma_f32_16x16x32_bf16 v[38:41], v[168:171], v[198:201], v[38:41]
	v_mfma_f32_16x16x32_bf16 v[30:33], v[180:183], v[198:201], v[30:33]
	v_mfma_f32_16x16x32_bf16 v[22:25], v[168:171], v[206:209], v[22:25]
	v_mfma_f32_16x16x32_bf16 v[14:17], v[180:183], v[206:209], v[14:17]
	v_mfma_f32_16x16x32_bf16 v[6:9], v[168:171], v[214:217], v[6:9]
	v_mfma_f32_16x16x32_bf16 v[2:5], v[180:183], v[214:217], v[2:5]
	s_setprio 0
	s_barrier
	s_add_i32 s49, s49, 2
	s_add_u32 s47, s47, 0x100
	s_addc_u32 s48, s48, 0
	s_cmp_gt_u32 s49, 41
	s_mov_b64 s[18:19], s[20:21]
	s_cbranch_scc0 .LBB0_1360
	s_and_b64 vcc, exec, s[14:15]
	s_cbranch_vccz .LBB0_1363
	s_barrier
